# leading half starts its epilogue right after its last MFMA block; both halves re-align at one barrier at the END of the epilogue (pre-epilogue barrier and trailing half's last in-loop barrier moved th
# baseline (speedup 1.0000x reference)
.LBB0_146:
	s_barrier
	s_andn2_b64 vcc, exec, s[10:11]
	s_mov_b32 s75, s74
	s_mov_b32 s46, s71
	s_mov_b64 s[44:45], s[0:1]
	s_mov_b64 s[42:43], s[12:13]
	s_cbranch_vccz .LBB0_177

.Llbb_0:
	s_add_i32 s47, s44, 2
	s_add_u32 s4, s42, 0x80
	s_addc_u32 s5, s43, 0
	s_add_i32 s54, 0, 0x10000
	s_cmp_eq_u32 s69, s44
	s_cselect_b32 s45, s13, s5
	s_cselect_b32 s44, s12, s4
	s_cselect_b32 vcc_hi, s1, s11
	s_cselect_b32 vcc_lo, s0, s10
	s_add_i32 s4, 0, 0x14000
	v_add_u32_e32 v140, s54, v223
	v_add_u32_e32 v156, s4, v223
	s_waitcnt lgkmcnt(0)
	ds_read_b128 v[128:131], v140
	ds_read_b128 v[132:135], v140 offset:1024
	ds_read_b128 v[136:139], v140 offset:2048
	ds_read_b128 v[140:143], v140 offset:3072
	ds_read_b128 v[144:147], v156
	ds_read_b128 v[148:151], v156 offset:1024
	ds_read_b128 v[152:155], v156 offset:2048
	ds_read_b128 v[156:159], v156 offset:3072
	v_lshl_add_u64 v[214:215], s[42:43], 0, v[194:195]
	s_add_i32 m0, s59, 0xc000
	ds_read_b128 v[160:163], v228
	ds_read_b128 v[164:167], v228 offset:1024
	ds_read_b128 v[168:171], v228 offset:2048
	ds_read_b128 v[172:175], v228 offset:3072
	ds_read_b128 v[198:201], v228 offset:4096
	ds_read_b128 v[202:205], v228 offset:5120
	ds_read_b128 v[206:209], v228 offset:6144
	ds_read_b128 v[210:213], v228 offset:7168
	global_load_lds_dwordx4 v[214:215], off
	v_lshl_add_u64 v[214:215], s[42:43], 0, v[196:197]
	s_add_i32 m0, s59, 0xe000
	s_nop 0
	global_load_lds_dwordx4 v[214:215], off
	s_waitcnt vmcnt(8)
	s_waitcnt lgkmcnt(0)
	s_barrier
	s_waitcnt lgkmcnt(0)
	v_mfma_f32_16x16x32_bf16 v[120:123], v[128:131], v[160:163], 0
	v_mfma_f32_16x16x32_bf16 v[116:119], v[136:139], v[160:163], 0
	v_mfma_f32_16x16x32_bf16 v[108:111], v[128:131], v[168:171], 0
	v_mfma_f32_16x16x32_bf16 v[100:103], v[136:139], v[168:171], 0
	v_mfma_f32_16x16x32_bf16 v[92:95], v[128:131], v[198:201], 0
	v_mfma_f32_16x16x32_bf16 v[84:87], v[136:139], v[198:201], 0
	v_mfma_f32_16x16x32_bf16 v[76:79], v[128:131], v[206:209], 0
	v_mfma_f32_16x16x32_bf16 v[68:71], v[136:139], v[206:209], 0
	v_mfma_f32_16x16x32_bf16 v[120:123], v[132:135], v[164:167], v[120:123]
	v_mfma_f32_16x16x32_bf16 v[116:119], v[140:143], v[164:167], v[116:119]
	v_mfma_f32_16x16x32_bf16 v[108:111], v[132:135], v[172:175], v[108:111]
	v_mfma_f32_16x16x32_bf16 v[100:103], v[140:143], v[172:175], v[100:103]
	v_mfma_f32_16x16x32_bf16 v[92:95], v[132:135], v[202:205], v[92:95]
	v_mfma_f32_16x16x32_bf16 v[84:87], v[140:143], v[202:205], v[84:87]
	v_mfma_f32_16x16x32_bf16 v[76:79], v[132:135], v[210:213], v[76:79]
	v_mfma_f32_16x16x32_bf16 v[68:71], v[140:143], v[210:213], v[68:71]
	v_mfma_f32_16x16x32_bf16 v[124:127], v[144:147], v[160:163], 0
	v_mfma_f32_16x16x32_bf16 v[112:115], v[152:155], v[160:163], 0
	v_mfma_f32_16x16x32_bf16 v[104:107], v[144:147], v[168:171], 0
	v_mfma_f32_16x16x32_bf16 v[96:99], v[152:155], v[168:171], 0
	v_mfma_f32_16x16x32_bf16 v[88:91], v[144:147], v[198:201], 0
	v_mfma_f32_16x16x32_bf16 v[80:83], v[152:155], v[198:201], 0
	v_mfma_f32_16x16x32_bf16 v[72:75], v[144:147], v[206:209], 0
	v_mfma_f32_16x16x32_bf16 v[64:67], v[152:155], v[206:209], 0
	v_mfma_f32_16x16x32_bf16 v[124:127], v[148:151], v[164:167], v[124:127]
	v_mfma_f32_16x16x32_bf16 v[112:115], v[156:159], v[164:167], v[112:115]
	v_mfma_f32_16x16x32_bf16 v[104:107], v[148:151], v[172:175], v[104:107]
	v_mfma_f32_16x16x32_bf16 v[96:99], v[156:159], v[172:175], v[96:99]
	v_mfma_f32_16x16x32_bf16 v[88:91], v[148:151], v[202:205], v[88:91]
	v_mfma_f32_16x16x32_bf16 v[80:83], v[156:159], v[202:205], v[80:83]
	v_mfma_f32_16x16x32_bf16 v[72:75], v[148:151], v[210:213], v[72:75]
	v_mfma_f32_16x16x32_bf16 v[64:67], v[156:159], v[210:213], v[64:67]
	s_barrier
	s_add_i32 s5, s54, s58
	v_lshl_add_u64 v[214:215], vcc, 0, v[190:191]
	s_mov_b32 m0, s5
	ds_read_b128 v[160:163], v228 offset:16384
	ds_read_b128 v[164:167], v228 offset:17408
	ds_read_b128 v[168:171], v228 offset:18432
	ds_read_b128 v[172:175], v228 offset:19456
	ds_read_b128 v[198:201], v228 offset:20480
	ds_read_b128 v[202:205], v228 offset:21504
	ds_read_b128 v[206:209], v228 offset:22528
	ds_read_b128 v[210:213], v228 offset:23552
	global_load_lds_dwordx4 v[214:215], off
	s_add_i32 m0, s5, 0x2000
	v_lshl_add_u64 v[216:217], vcc, 0, v[186:187]
	s_add_u32 vcc_lo, vcc_lo, s24
	s_addc_u32 vcc_hi, vcc_hi, s25
	s_add_i32 s4, s4, s58
	global_load_lds_dwordx4 v[216:217], off
	v_lshl_add_u64 v[230:231], vcc, 0, v[190:191]
	s_mov_b32 m0, s4
	v_lshl_add_u64 v[232:233], vcc, 0, v[186:187]
	global_load_lds_dwordx4 v[230:231], off
	s_add_i32 m0, s4, 0x2000
	v_lshl_add_u64 v[234:235], s[44:45], 0, v[192:193]
	global_load_lds_dwordx4 v[232:233], off
	s_mov_b32 m0, s59
	v_lshl_add_u64 v[236:237], s[44:45], 0, v[188:189]
	global_load_lds_dwordx4 v[234:235], off
	s_mov_b32 m0, s60
	s_nop 0
	global_load_lds_dwordx4 v[236:237], off
	s_waitcnt vmcnt(8)
	s_waitcnt lgkmcnt(0)
	s_barrier
	s_waitcnt lgkmcnt(0)
	v_mfma_f32_16x16x32_bf16 v[60:63], v[128:131], v[160:163], 0
	v_mfma_f32_16x16x32_bf16 v[52:55], v[136:139], v[160:163], 0
	v_mfma_f32_16x16x32_bf16 v[44:47], v[128:131], v[168:171], 0
	v_mfma_f32_16x16x32_bf16 v[36:39], v[136:139], v[168:171], 0
	v_mfma_f32_16x16x32_bf16 v[28:31], v[128:131], v[198:201], 0
	v_mfma_f32_16x16x32_bf16 v[20:23], v[136:139], v[198:201], 0
	v_mfma_f32_16x16x32_bf16 v[12:15], v[128:131], v[206:209], 0
	v_mfma_f32_16x16x32_bf16 v[4:7], v[136:139], v[206:209], 0
	v_mfma_f32_16x16x32_bf16 v[60:63], v[132:135], v[164:167], v[60:63]
	v_mfma_f32_16x16x32_bf16 v[52:55], v[140:143], v[164:167], v[52:55]
	v_mfma_f32_16x16x32_bf16 v[44:47], v[132:135], v[172:175], v[44:47]
	v_mfma_f32_16x16x32_bf16 v[36:39], v[140:143], v[172:175], v[36:39]
	v_mfma_f32_16x16x32_bf16 v[28:31], v[132:135], v[202:205], v[28:31]
	v_mfma_f32_16x16x32_bf16 v[20:23], v[140:143], v[202:205], v[20:23]
	v_mfma_f32_16x16x32_bf16 v[12:15], v[132:135], v[210:213], v[12:15]
	v_mfma_f32_16x16x32_bf16 v[4:7], v[140:143], v[210:213], v[4:7]
	v_mfma_f32_16x16x32_bf16 v[56:59], v[144:147], v[160:163], 0
	v_mfma_f32_16x16x32_bf16 v[48:51], v[152:155], v[160:163], 0
	v_mfma_f32_16x16x32_bf16 v[40:43], v[144:147], v[168:171], 0
	v_mfma_f32_16x16x32_bf16 v[32:35], v[152:155], v[168:171], 0
	v_mfma_f32_16x16x32_bf16 v[24:27], v[144:147], v[198:201], 0
	v_mfma_f32_16x16x32_bf16 v[16:19], v[152:155], v[198:201], 0
	v_mfma_f32_16x16x32_bf16 v[8:11], v[144:147], v[206:209], 0
	v_mfma_f32_16x16x32_bf16 v[0:3], v[152:155], v[206:209], 0
	v_mfma_f32_16x16x32_bf16 v[56:59], v[148:151], v[164:167], v[56:59]
	v_mfma_f32_16x16x32_bf16 v[48:51], v[156:159], v[164:167], v[48:51]
	v_mfma_f32_16x16x32_bf16 v[40:43], v[148:151], v[172:175], v[40:43]
	v_mfma_f32_16x16x32_bf16 v[32:35], v[156:159], v[172:175], v[32:35]
	v_mfma_f32_16x16x32_bf16 v[24:27], v[148:151], v[202:205], v[24:27]
	v_mfma_f32_16x16x32_bf16 v[16:19], v[156:159], v[202:205], v[16:19]
	v_mfma_f32_16x16x32_bf16 v[8:11], v[148:151], v[210:213], v[8:11]
	v_mfma_f32_16x16x32_bf16 v[0:3], v[156:159], v[210:213], v[0:3]
	s_barrier
	s_add_i32 s4, 0, 0x18000
	s_add_i32 s5, 0, 0x1c000
	v_add_u32_e32 v140, s4, v223
	v_add_u32_e32 v156, s5, v223
	ds_read_b128 v[128:131], v140
	ds_read_b128 v[132:135], v140 offset:1024
	ds_read_b128 v[136:139], v140 offset:2048
	ds_read_b128 v[140:143], v140 offset:3072
	ds_read_b128 v[144:147], v156
	ds_read_b128 v[148:151], v156 offset:1024
	ds_read_b128 v[152:155], v156 offset:2048
	ds_read_b128 v[156:159], v156 offset:3072
	s_add_u32 s44, s44, s24
	s_addc_u32 s45, s45, s25
	s_mov_b32 m0, s61
	v_lshl_add_u64 v[238:239], s[44:45], 0, v[192:193]
	ds_read_b128 v[160:163], v228 offset:32768
	ds_read_b128 v[164:167], v228 offset:33792
	ds_read_b128 v[168:171], v228 offset:34816
	ds_read_b128 v[172:175], v228 offset:35840
	ds_read_b128 v[198:201], v228 offset:36864
	ds_read_b128 v[202:205], v228 offset:37888
	ds_read_b128 v[206:209], v228 offset:38912
	ds_read_b128 v[210:213], v228 offset:39936
	global_load_lds_dwordx4 v[238:239], off
	v_lshl_add_u64 v[238:239], s[44:45], 0, v[188:189]
	s_mov_b32 m0, s62
	s_nop 0
	global_load_lds_dwordx4 v[238:239], off
	s_waitcnt vmcnt(8)
	s_waitcnt lgkmcnt(0)
	s_barrier
	s_waitcnt lgkmcnt(0)
	v_mfma_f32_16x16x32_bf16 v[120:123], v[128:131], v[160:163], v[120:123]
	v_mfma_f32_16x16x32_bf16 v[116:119], v[136:139], v[160:163], v[116:119]
	v_mfma_f32_16x16x32_bf16 v[108:111], v[128:131], v[168:171], v[108:111]
	v_mfma_f32_16x16x32_bf16 v[100:103], v[136:139], v[168:171], v[100:103]
	v_mfma_f32_16x16x32_bf16 v[92:95], v[128:131], v[198:201], v[92:95]
	v_mfma_f32_16x16x32_bf16 v[84:87], v[136:139], v[198:201], v[84:87]
	v_mfma_f32_16x16x32_bf16 v[76:79], v[128:131], v[206:209], v[76:79]
	v_mfma_f32_16x16x32_bf16 v[68:71], v[136:139], v[206:209], v[68:71]
	v_mfma_f32_16x16x32_bf16 v[120:123], v[132:135], v[164:167], v[120:123]
	v_mfma_f32_16x16x32_bf16 v[116:119], v[140:143], v[164:167], v[116:119]
	v_mfma_f32_16x16x32_bf16 v[108:111], v[132:135], v[172:175], v[108:111]
	v_mfma_f32_16x16x32_bf16 v[100:103], v[140:143], v[172:175], v[100:103]
	v_mfma_f32_16x16x32_bf16 v[92:95], v[132:135], v[202:205], v[92:95]
	v_mfma_f32_16x16x32_bf16 v[84:87], v[140:143], v[202:205], v[84:87]
	v_mfma_f32_16x16x32_bf16 v[76:79], v[132:135], v[210:213], v[76:79]
	v_mfma_f32_16x16x32_bf16 v[68:71], v[140:143], v[210:213], v[68:71]
	v_mfma_f32_16x16x32_bf16 v[124:127], v[144:147], v[160:163], v[124:127]
	v_mfma_f32_16x16x32_bf16 v[112:115], v[152:155], v[160:163], v[112:115]
	v_mfma_f32_16x16x32_bf16 v[104:107], v[144:147], v[168:171], v[104:107]
	v_mfma_f32_16x16x32_bf16 v[96:99], v[152:155], v[168:171], v[96:99]
	v_mfma_f32_16x16x32_bf16 v[88:91], v[144:147], v[198:201], v[88:91]
	v_mfma_f32_16x16x32_bf16 v[80:83], v[152:155], v[198:201], v[80:83]
	v_mfma_f32_16x16x32_bf16 v[72:75], v[144:147], v[206:209], v[72:75]
	v_mfma_f32_16x16x32_bf16 v[64:67], v[152:155], v[206:209], v[64:67]
	v_mfma_f32_16x16x32_bf16 v[124:127], v[148:151], v[164:167], v[124:127]
	v_mfma_f32_16x16x32_bf16 v[112:115], v[156:159], v[164:167], v[112:115]
	v_mfma_f32_16x16x32_bf16 v[104:107], v[148:151], v[172:175], v[104:107]
	v_mfma_f32_16x16x32_bf16 v[96:99], v[156:159], v[172:175], v[96:99]
	v_mfma_f32_16x16x32_bf16 v[88:91], v[148:151], v[202:205], v[88:91]
	v_mfma_f32_16x16x32_bf16 v[80:83], v[156:159], v[202:205], v[80:83]
	v_mfma_f32_16x16x32_bf16 v[72:75], v[148:151], v[210:213], v[72:75]
	v_mfma_f32_16x16x32_bf16 v[64:67], v[156:159], v[210:213], v[64:67]
	s_barrier
	s_add_i32 s4, s4, s58
	v_lshl_add_u64 v[214:215], v[214:215], 0, s[14:15]
	s_mov_b32 m0, s4
	ds_read_b128 v[160:163], v228 offset:49152
	ds_read_b128 v[164:167], v228 offset:50176
	ds_read_b128 v[168:171], v228 offset:51200
	ds_read_b128 v[172:175], v228 offset:52224
	ds_read_b128 v[198:201], v228 offset:53248
	ds_read_b128 v[202:205], v228 offset:54272
	ds_read_b128 v[206:209], v228 offset:55296
	ds_read_b128 v[210:213], v228 offset:56320
	global_load_lds_dwordx4 v[214:215], off
	v_lshl_add_u64 v[214:215], v[216:217], 0, s[14:15]
	s_add_i32 m0, s4, 0x2000
	s_add_i32 s4, s5, s58
	global_load_lds_dwordx4 v[214:215], off
	v_lshl_add_u64 v[214:215], v[230:231], 0, s[14:15]
	s_mov_b32 m0, s4
	s_nop 0
	global_load_lds_dwordx4 v[214:215], off
	v_lshl_add_u64 v[214:215], v[232:233], 0, s[14:15]
	s_add_i32 m0, s4, 0x2000
	s_nop 0
	global_load_lds_dwordx4 v[214:215], off
	v_lshl_add_u64 v[214:215], v[234:235], 0, s[14:15]
	s_mov_b32 m0, s63
	s_nop 0
	global_load_lds_dwordx4 v[214:215], off
	v_lshl_add_u64 v[214:215], v[236:237], 0, s[14:15]
	s_mov_b32 m0, s66
	s_nop 0
	global_load_lds_dwordx4 v[214:215], off
	s_waitcnt vmcnt(8)
	s_waitcnt lgkmcnt(0)
	s_barrier
	s_waitcnt lgkmcnt(0)
	v_mfma_f32_16x16x32_bf16 v[60:63], v[128:131], v[160:163], v[60:63]
	s_add_u32 s42, s42, 0x100
	v_mfma_f32_16x16x32_bf16 v[52:55], v[136:139], v[160:163], v[52:55]
	s_addc_u32 s43, s43, 0
	v_mfma_f32_16x16x32_bf16 v[44:47], v[128:131], v[168:171], v[44:47]
	s_add_u32 s10, s10, 0x100
	v_mfma_f32_16x16x32_bf16 v[36:39], v[136:139], v[168:171], v[36:39]
	s_addc_u32 s11, s11, 0
	v_mfma_f32_16x16x32_bf16 v[28:31], v[128:131], v[198:201], v[28:31]
	s_mov_b32 s44, s47
	v_mfma_f32_16x16x32_bf16 v[20:23], v[136:139], v[198:201], v[20:23]
	s_cmp_ge_i32 s47, s67
	v_mfma_f32_16x16x32_bf16 v[12:15], v[128:131], v[206:209], v[12:15]
	s_cselect_b32 s99, 1, 0
	v_readfirstlane_b32 s98, v218
	s_bfe_u32 s98, s98, 0x10008
	s_and_b32 s98, s98, s99
	v_mfma_f32_16x16x32_bf16 v[4:7], v[136:139], v[206:209], v[4:7]
	s_add_i32 s47, s44, 2
	v_mfma_f32_16x16x32_bf16 v[60:63], v[132:135], v[164:167], v[60:63]
	s_add_u32 s4, s42, 0x80
	v_mfma_f32_16x16x32_bf16 v[52:55], v[140:143], v[164:167], v[52:55]
	s_addc_u32 s5, s43, 0
	v_mfma_f32_16x16x32_bf16 v[44:47], v[132:135], v[172:175], v[44:47]
	s_add_i32 s54, 0, 0x10000
	v_mfma_f32_16x16x32_bf16 v[36:39], v[140:143], v[172:175], v[36:39]
	s_cmp_eq_u32 s69, s44
	v_mfma_f32_16x16x32_bf16 v[28:31], v[132:135], v[202:205], v[28:31]
	s_cselect_b32 s45, s13, s5
	v_mfma_f32_16x16x32_bf16 v[20:23], v[140:143], v[202:205], v[20:23]
	s_cselect_b32 s44, s12, s4
	v_mfma_f32_16x16x32_bf16 v[12:15], v[132:135], v[210:213], v[12:15]
	s_cselect_b32 vcc_hi, s1, s11
	v_mfma_f32_16x16x32_bf16 v[4:7], v[140:143], v[210:213], v[4:7]
	s_cselect_b32 vcc_lo, s0, s10
	v_mfma_f32_16x16x32_bf16 v[56:59], v[144:147], v[160:163], v[56:59]
	s_add_i32 s4, 0, 0x14000
	v_mfma_f32_16x16x32_bf16 v[48:51], v[152:155], v[160:163], v[48:51]
	v_mfma_f32_16x16x32_bf16 v[40:43], v[144:147], v[168:171], v[40:43]
	v_mfma_f32_16x16x32_bf16 v[32:35], v[152:155], v[168:171], v[32:35]
	v_mfma_f32_16x16x32_bf16 v[24:27], v[144:147], v[198:201], v[24:27]
	v_mfma_f32_16x16x32_bf16 v[16:19], v[152:155], v[198:201], v[16:19]
	v_mfma_f32_16x16x32_bf16 v[8:11], v[144:147], v[206:209], v[8:11]
	v_mfma_f32_16x16x32_bf16 v[0:3], v[152:155], v[206:209], v[0:3]
	v_mfma_f32_16x16x32_bf16 v[56:59], v[148:151], v[164:167], v[56:59]
	v_mfma_f32_16x16x32_bf16 v[48:51], v[156:159], v[164:167], v[48:51]
	v_mfma_f32_16x16x32_bf16 v[40:43], v[148:151], v[172:175], v[40:43]
	v_mfma_f32_16x16x32_bf16 v[32:35], v[156:159], v[172:175], v[32:35]
	v_mfma_f32_16x16x32_bf16 v[24:27], v[148:151], v[202:205], v[24:27]
	v_mfma_f32_16x16x32_bf16 v[16:19], v[156:159], v[202:205], v[16:19]
	v_mfma_f32_16x16x32_bf16 v[8:11], v[148:151], v[210:213], v[8:11]
	v_mfma_f32_16x16x32_bf16 v[0:3], v[156:159], v[210:213], v[0:3]
	s_cmp_lg_u32 s98, 0
	s_cbranch_scc1 .Lskf_4_peel
	s_barrier
.Lskf_4_peel:
	s_cmp_lg_u32 s99, 0
	s_cbranch_scc1 .Lpeelx_4
.LBB0_155:
	v_add_u32_e32 v140, s54, v223
	v_add_u32_e32 v156, s4, v223
	s_waitcnt lgkmcnt(0)
	ds_read_b128 v[128:131], v140
	ds_read_b128 v[132:135], v140 offset:1024
	ds_read_b128 v[136:139], v140 offset:2048
	ds_read_b128 v[140:143], v140 offset:3072
	ds_read_b128 v[144:147], v156
	ds_read_b128 v[148:151], v156 offset:1024
	ds_read_b128 v[152:155], v156 offset:2048
	ds_read_b128 v[156:159], v156 offset:3072
	v_lshl_add_u64 v[214:215], s[42:43], 0, v[194:195]
	s_add_i32 m0, s59, 0xc000
	ds_read_b128 v[160:163], v228
	ds_read_b128 v[164:167], v228 offset:1024
	ds_read_b128 v[168:171], v228 offset:2048
	ds_read_b128 v[172:175], v228 offset:3072
	ds_read_b128 v[198:201], v228 offset:4096
	ds_read_b128 v[202:205], v228 offset:5120
	ds_read_b128 v[206:209], v228 offset:6144
	ds_read_b128 v[210:213], v228 offset:7168
	global_load_lds_dwordx4 v[214:215], off
	v_lshl_add_u64 v[214:215], s[42:43], 0, v[196:197]
	s_add_i32 m0, s59, 0xe000
	s_nop 0
	global_load_lds_dwordx4 v[214:215], off
	s_waitcnt vmcnt(8)
	s_waitcnt lgkmcnt(0)
	s_barrier
	s_waitcnt lgkmcnt(0)
	v_mfma_f32_16x16x32_bf16 v[120:123], v[128:131], v[160:163], v[120:123]
	v_mfma_f32_16x16x32_bf16 v[116:119], v[136:139], v[160:163], v[116:119]
	v_mfma_f32_16x16x32_bf16 v[108:111], v[128:131], v[168:171], v[108:111]
	v_mfma_f32_16x16x32_bf16 v[100:103], v[136:139], v[168:171], v[100:103]
	v_mfma_f32_16x16x32_bf16 v[92:95], v[128:131], v[198:201], v[92:95]
	v_mfma_f32_16x16x32_bf16 v[84:87], v[136:139], v[198:201], v[84:87]
	v_mfma_f32_16x16x32_bf16 v[76:79], v[128:131], v[206:209], v[76:79]
	v_mfma_f32_16x16x32_bf16 v[68:71], v[136:139], v[206:209], v[68:71]
	v_mfma_f32_16x16x32_bf16 v[120:123], v[132:135], v[164:167], v[120:123]
	v_mfma_f32_16x16x32_bf16 v[116:119], v[140:143], v[164:167], v[116:119]
	v_mfma_f32_16x16x32_bf16 v[108:111], v[132:135], v[172:175], v[108:111]
	v_mfma_f32_16x16x32_bf16 v[100:103], v[140:143], v[172:175], v[100:103]
	v_mfma_f32_16x16x32_bf16 v[92:95], v[132:135], v[202:205], v[92:95]
	v_mfma_f32_16x16x32_bf16 v[84:87], v[140:143], v[202:205], v[84:87]
	v_mfma_f32_16x16x32_bf16 v[76:79], v[132:135], v[210:213], v[76:79]
	v_mfma_f32_16x16x32_bf16 v[68:71], v[140:143], v[210:213], v[68:71]
	v_mfma_f32_16x16x32_bf16 v[124:127], v[144:147], v[160:163], v[124:127]
	v_mfma_f32_16x16x32_bf16 v[112:115], v[152:155], v[160:163], v[112:115]
	v_mfma_f32_16x16x32_bf16 v[104:107], v[144:147], v[168:171], v[104:107]
	v_mfma_f32_16x16x32_bf16 v[96:99], v[152:155], v[168:171], v[96:99]
	v_mfma_f32_16x16x32_bf16 v[88:91], v[144:147], v[198:201], v[88:91]
	v_mfma_f32_16x16x32_bf16 v[80:83], v[152:155], v[198:201], v[80:83]
	v_mfma_f32_16x16x32_bf16 v[72:75], v[144:147], v[206:209], v[72:75]
	v_mfma_f32_16x16x32_bf16 v[64:67], v[152:155], v[206:209], v[64:67]
	v_mfma_f32_16x16x32_bf16 v[124:127], v[148:151], v[164:167], v[124:127]
	v_mfma_f32_16x16x32_bf16 v[112:115], v[156:159], v[164:167], v[112:115]
	v_mfma_f32_16x16x32_bf16 v[104:107], v[148:151], v[172:175], v[104:107]
	v_mfma_f32_16x16x32_bf16 v[96:99], v[156:159], v[172:175], v[96:99]
	v_mfma_f32_16x16x32_bf16 v[88:91], v[148:151], v[202:205], v[88:91]
	v_mfma_f32_16x16x32_bf16 v[80:83], v[156:159], v[202:205], v[80:83]
	v_mfma_f32_16x16x32_bf16 v[72:75], v[148:151], v[210:213], v[72:75]
	v_mfma_f32_16x16x32_bf16 v[64:67], v[156:159], v[210:213], v[64:67]
	s_barrier
	s_add_i32 s5, s54, s58
	v_lshl_add_u64 v[214:215], vcc, 0, v[190:191]
	s_mov_b32 m0, s5
	ds_read_b128 v[160:163], v228 offset:16384
	ds_read_b128 v[164:167], v228 offset:17408
	ds_read_b128 v[168:171], v228 offset:18432
	ds_read_b128 v[172:175], v228 offset:19456
	ds_read_b128 v[198:201], v228 offset:20480
	ds_read_b128 v[202:205], v228 offset:21504
	ds_read_b128 v[206:209], v228 offset:22528
	ds_read_b128 v[210:213], v228 offset:23552
	global_load_lds_dwordx4 v[214:215], off
	s_add_i32 m0, s5, 0x2000
	v_lshl_add_u64 v[216:217], vcc, 0, v[186:187]
	s_add_u32 vcc_lo, vcc_lo, s24
	s_addc_u32 vcc_hi, vcc_hi, s25
	s_add_i32 s4, s4, s58
	global_load_lds_dwordx4 v[216:217], off
	v_lshl_add_u64 v[230:231], vcc, 0, v[190:191]
	s_mov_b32 m0, s4
	v_lshl_add_u64 v[232:233], vcc, 0, v[186:187]
	global_load_lds_dwordx4 v[230:231], off
	s_add_i32 m0, s4, 0x2000
	v_lshl_add_u64 v[234:235], s[44:45], 0, v[192:193]
	global_load_lds_dwordx4 v[232:233], off
	s_mov_b32 m0, s59
	v_lshl_add_u64 v[236:237], s[44:45], 0, v[188:189]
	global_load_lds_dwordx4 v[234:235], off
	s_mov_b32 m0, s60
	s_nop 0
	global_load_lds_dwordx4 v[236:237], off
	s_waitcnt vmcnt(8)
	s_waitcnt lgkmcnt(0)
	s_barrier
	s_waitcnt lgkmcnt(0)
	v_mfma_f32_16x16x32_bf16 v[60:63], v[128:131], v[160:163], v[60:63]
	v_mfma_f32_16x16x32_bf16 v[52:55], v[136:139], v[160:163], v[52:55]
	v_mfma_f32_16x16x32_bf16 v[44:47], v[128:131], v[168:171], v[44:47]
	v_mfma_f32_16x16x32_bf16 v[36:39], v[136:139], v[168:171], v[36:39]
	v_mfma_f32_16x16x32_bf16 v[28:31], v[128:131], v[198:201], v[28:31]
	v_mfma_f32_16x16x32_bf16 v[20:23], v[136:139], v[198:201], v[20:23]
	v_mfma_f32_16x16x32_bf16 v[12:15], v[128:131], v[206:209], v[12:15]
	v_mfma_f32_16x16x32_bf16 v[4:7], v[136:139], v[206:209], v[4:7]
	v_mfma_f32_16x16x32_bf16 v[60:63], v[132:135], v[164:167], v[60:63]
	v_mfma_f32_16x16x32_bf16 v[52:55], v[140:143], v[164:167], v[52:55]
	v_mfma_f32_16x16x32_bf16 v[44:47], v[132:135], v[172:175], v[44:47]
	v_mfma_f32_16x16x32_bf16 v[36:39], v[140:143], v[172:175], v[36:39]
	v_mfma_f32_16x16x32_bf16 v[28:31], v[132:135], v[202:205], v[28:31]
	v_mfma_f32_16x16x32_bf16 v[20:23], v[140:143], v[202:205], v[20:23]
	v_mfma_f32_16x16x32_bf16 v[12:15], v[132:135], v[210:213], v[12:15]
	v_mfma_f32_16x16x32_bf16 v[4:7], v[140:143], v[210:213], v[4:7]
	v_mfma_f32_16x16x32_bf16 v[56:59], v[144:147], v[160:163], v[56:59]
	v_mfma_f32_16x16x32_bf16 v[48:51], v[152:155], v[160:163], v[48:51]
	v_mfma_f32_16x16x32_bf16 v[40:43], v[144:147], v[168:171], v[40:43]
	v_mfma_f32_16x16x32_bf16 v[32:35], v[152:155], v[168:171], v[32:35]
	v_mfma_f32_16x16x32_bf16 v[24:27], v[144:147], v[198:201], v[24:27]
	v_mfma_f32_16x16x32_bf16 v[16:19], v[152:155], v[198:201], v[16:19]
	v_mfma_f32_16x16x32_bf16 v[8:11], v[144:147], v[206:209], v[8:11]
	v_mfma_f32_16x16x32_bf16 v[0:3], v[152:155], v[206:209], v[0:3]
	v_mfma_f32_16x16x32_bf16 v[56:59], v[148:151], v[164:167], v[56:59]
	v_mfma_f32_16x16x32_bf16 v[48:51], v[156:159], v[164:167], v[48:51]
	v_mfma_f32_16x16x32_bf16 v[40:43], v[148:151], v[172:175], v[40:43]
	v_mfma_f32_16x16x32_bf16 v[32:35], v[156:159], v[172:175], v[32:35]
	v_mfma_f32_16x16x32_bf16 v[24:27], v[148:151], v[202:205], v[24:27]
	v_mfma_f32_16x16x32_bf16 v[16:19], v[156:159], v[202:205], v[16:19]
	v_mfma_f32_16x16x32_bf16 v[8:11], v[148:151], v[210:213], v[8:11]
	v_mfma_f32_16x16x32_bf16 v[0:3], v[156:159], v[210:213], v[0:3]
	s_barrier
	s_add_i32 s4, 0, 0x18000
	s_add_i32 s5, 0, 0x1c000
	v_add_u32_e32 v140, s4, v223
	v_add_u32_e32 v156, s5, v223
	ds_read_b128 v[128:131], v140
	ds_read_b128 v[132:135], v140 offset:1024
	ds_read_b128 v[136:139], v140 offset:2048
	ds_read_b128 v[140:143], v140 offset:3072
	ds_read_b128 v[144:147], v156
	ds_read_b128 v[148:151], v156 offset:1024
	ds_read_b128 v[152:155], v156 offset:2048
	ds_read_b128 v[156:159], v156 offset:3072
	s_add_u32 s44, s44, s24
	s_addc_u32 s45, s45, s25
	s_mov_b32 m0, s61
	v_lshl_add_u64 v[238:239], s[44:45], 0, v[192:193]
	ds_read_b128 v[160:163], v228 offset:32768
	ds_read_b128 v[164:167], v228 offset:33792
	ds_read_b128 v[168:171], v228 offset:34816
	ds_read_b128 v[172:175], v228 offset:35840
	ds_read_b128 v[198:201], v228 offset:36864
	ds_read_b128 v[202:205], v228 offset:37888
	ds_read_b128 v[206:209], v228 offset:38912
	ds_read_b128 v[210:213], v228 offset:39936
	global_load_lds_dwordx4 v[238:239], off
	v_lshl_add_u64 v[238:239], s[44:45], 0, v[188:189]
	s_mov_b32 m0, s62
	s_nop 0
	global_load_lds_dwordx4 v[238:239], off
	s_waitcnt vmcnt(8)
	s_waitcnt lgkmcnt(0)
	s_barrier
	s_waitcnt lgkmcnt(0)
	v_mfma_f32_16x16x32_bf16 v[120:123], v[128:131], v[160:163], v[120:123]
	v_mfma_f32_16x16x32_bf16 v[116:119], v[136:139], v[160:163], v[116:119]
	v_mfma_f32_16x16x32_bf16 v[108:111], v[128:131], v[168:171], v[108:111]
	v_mfma_f32_16x16x32_bf16 v[100:103], v[136:139], v[168:171], v[100:103]
	v_mfma_f32_16x16x32_bf16 v[92:95], v[128:131], v[198:201], v[92:95]
	v_mfma_f32_16x16x32_bf16 v[84:87], v[136:139], v[198:201], v[84:87]
	v_mfma_f32_16x16x32_bf16 v[76:79], v[128:131], v[206:209], v[76:79]
	v_mfma_f32_16x16x32_bf16 v[68:71], v[136:139], v[206:209], v[68:71]
	v_mfma_f32_16x16x32_bf16 v[120:123], v[132:135], v[164:167], v[120:123]
	v_mfma_f32_16x16x32_bf16 v[116:119], v[140:143], v[164:167], v[116:119]
	v_mfma_f32_16x16x32_bf16 v[108:111], v[132:135], v[172:175], v[108:111]
	v_mfma_f32_16x16x32_bf16 v[100:103], v[140:143], v[172:175], v[100:103]
	v_mfma_f32_16x16x32_bf16 v[92:95], v[132:135], v[202:205], v[92:95]
	v_mfma_f32_16x16x32_bf16 v[84:87], v[140:143], v[202:205], v[84:87]
	v_mfma_f32_16x16x32_bf16 v[76:79], v[132:135], v[210:213], v[76:79]
	v_mfma_f32_16x16x32_bf16 v[68:71], v[140:143], v[210:213], v[68:71]
	v_mfma_f32_16x16x32_bf16 v[124:127], v[144:147], v[160:163], v[124:127]
	v_mfma_f32_16x16x32_bf16 v[112:115], v[152:155], v[160:163], v[112:115]
	v_mfma_f32_16x16x32_bf16 v[104:107], v[144:147], v[168:171], v[104:107]
	v_mfma_f32_16x16x32_bf16 v[96:99], v[152:155], v[168:171], v[96:99]
	v_mfma_f32_16x16x32_bf16 v[88:91], v[144:147], v[198:201], v[88:91]
	v_mfma_f32_16x16x32_bf16 v[80:83], v[152:155], v[198:201], v[80:83]
	v_mfma_f32_16x16x32_bf16 v[72:75], v[144:147], v[206:209], v[72:75]
	v_mfma_f32_16x16x32_bf16 v[64:67], v[152:155], v[206:209], v[64:67]
	v_mfma_f32_16x16x32_bf16 v[124:127], v[148:151], v[164:167], v[124:127]
	v_mfma_f32_16x16x32_bf16 v[112:115], v[156:159], v[164:167], v[112:115]
	v_mfma_f32_16x16x32_bf16 v[104:107], v[148:151], v[172:175], v[104:107]
	v_mfma_f32_16x16x32_bf16 v[96:99], v[156:159], v[172:175], v[96:99]
	v_mfma_f32_16x16x32_bf16 v[88:91], v[148:151], v[202:205], v[88:91]
	v_mfma_f32_16x16x32_bf16 v[80:83], v[156:159], v[202:205], v[80:83]
	v_mfma_f32_16x16x32_bf16 v[72:75], v[148:151], v[210:213], v[72:75]
	v_mfma_f32_16x16x32_bf16 v[64:67], v[156:159], v[210:213], v[64:67]
	s_barrier
	s_add_i32 s4, s4, s58
	v_lshl_add_u64 v[214:215], v[214:215], 0, s[14:15]
	s_mov_b32 m0, s4
	ds_read_b128 v[160:163], v228 offset:49152
	ds_read_b128 v[164:167], v228 offset:50176
	ds_read_b128 v[168:171], v228 offset:51200
	ds_read_b128 v[172:175], v228 offset:52224
	ds_read_b128 v[198:201], v228 offset:53248
	ds_read_b128 v[202:205], v228 offset:54272
	ds_read_b128 v[206:209], v228 offset:55296
	ds_read_b128 v[210:213], v228 offset:56320
	global_load_lds_dwordx4 v[214:215], off
	v_lshl_add_u64 v[214:215], v[216:217], 0, s[14:15]
	s_add_i32 m0, s4, 0x2000
	s_add_i32 s4, s5, s58
	global_load_lds_dwordx4 v[214:215], off
	v_lshl_add_u64 v[214:215], v[230:231], 0, s[14:15]
	s_mov_b32 m0, s4
	s_nop 0
	global_load_lds_dwordx4 v[214:215], off
	v_lshl_add_u64 v[214:215], v[232:233], 0, s[14:15]
	s_add_i32 m0, s4, 0x2000
	s_nop 0
	global_load_lds_dwordx4 v[214:215], off
	v_lshl_add_u64 v[214:215], v[234:235], 0, s[14:15]
	s_mov_b32 m0, s63
	s_nop 0
	global_load_lds_dwordx4 v[214:215], off
	v_lshl_add_u64 v[214:215], v[236:237], 0, s[14:15]
	s_mov_b32 m0, s66
	s_nop 0
	global_load_lds_dwordx4 v[214:215], off
	s_waitcnt vmcnt(8)
	s_waitcnt lgkmcnt(0)
	s_barrier
	s_waitcnt lgkmcnt(0)
	v_mfma_f32_16x16x32_bf16 v[60:63], v[128:131], v[160:163], v[60:63]
	s_add_u32 s42, s42, 0x100
	v_mfma_f32_16x16x32_bf16 v[52:55], v[136:139], v[160:163], v[52:55]
	s_addc_u32 s43, s43, 0
	v_mfma_f32_16x16x32_bf16 v[44:47], v[128:131], v[168:171], v[44:47]
	s_add_u32 s10, s10, 0x100
	v_mfma_f32_16x16x32_bf16 v[36:39], v[136:139], v[168:171], v[36:39]
	s_addc_u32 s11, s11, 0
	v_mfma_f32_16x16x32_bf16 v[28:31], v[128:131], v[198:201], v[28:31]
	s_mov_b32 s44, s47
	v_mfma_f32_16x16x32_bf16 v[20:23], v[136:139], v[198:201], v[20:23]
	s_cmp_ge_i32 s47, s67
	v_mfma_f32_16x16x32_bf16 v[12:15], v[128:131], v[206:209], v[12:15]
	s_cselect_b32 s99, 1, 0
	v_readfirstlane_b32 s98, v218
	s_bfe_u32 s98, s98, 0x10008
	s_and_b32 s98, s98, s99
	v_mfma_f32_16x16x32_bf16 v[4:7], v[136:139], v[206:209], v[4:7]
	s_add_i32 s47, s44, 2
	v_mfma_f32_16x16x32_bf16 v[60:63], v[132:135], v[164:167], v[60:63]
	s_add_u32 s4, s42, 0x80
	v_mfma_f32_16x16x32_bf16 v[52:55], v[140:143], v[164:167], v[52:55]
	s_addc_u32 s5, s43, 0
	v_mfma_f32_16x16x32_bf16 v[44:47], v[132:135], v[172:175], v[44:47]
	s_add_i32 s54, 0, 0x10000
	v_mfma_f32_16x16x32_bf16 v[36:39], v[140:143], v[172:175], v[36:39]
	s_cmp_eq_u32 s69, s44
	v_mfma_f32_16x16x32_bf16 v[28:31], v[132:135], v[202:205], v[28:31]
	s_cselect_b32 s45, s13, s5
	v_mfma_f32_16x16x32_bf16 v[20:23], v[140:143], v[202:205], v[20:23]
	s_cselect_b32 s44, s12, s4
	v_mfma_f32_16x16x32_bf16 v[12:15], v[132:135], v[210:213], v[12:15]
	s_cselect_b32 vcc_hi, s1, s11
	v_mfma_f32_16x16x32_bf16 v[4:7], v[140:143], v[210:213], v[4:7]
	s_cselect_b32 vcc_lo, s0, s10
	v_mfma_f32_16x16x32_bf16 v[56:59], v[144:147], v[160:163], v[56:59]
	s_add_i32 s4, 0, 0x14000
	v_mfma_f32_16x16x32_bf16 v[48:51], v[152:155], v[160:163], v[48:51]
	v_mfma_f32_16x16x32_bf16 v[40:43], v[144:147], v[168:171], v[40:43]
	v_mfma_f32_16x16x32_bf16 v[32:35], v[152:155], v[168:171], v[32:35]
	v_mfma_f32_16x16x32_bf16 v[24:27], v[144:147], v[198:201], v[24:27]
	v_mfma_f32_16x16x32_bf16 v[16:19], v[152:155], v[198:201], v[16:19]
	v_mfma_f32_16x16x32_bf16 v[8:11], v[144:147], v[206:209], v[8:11]
	v_mfma_f32_16x16x32_bf16 v[0:3], v[152:155], v[206:209], v[0:3]
	v_mfma_f32_16x16x32_bf16 v[56:59], v[148:151], v[164:167], v[56:59]
	v_mfma_f32_16x16x32_bf16 v[48:51], v[156:159], v[164:167], v[48:51]
	v_mfma_f32_16x16x32_bf16 v[40:43], v[148:151], v[172:175], v[40:43]
	v_mfma_f32_16x16x32_bf16 v[32:35], v[156:159], v[172:175], v[32:35]
	v_mfma_f32_16x16x32_bf16 v[24:27], v[148:151], v[202:205], v[24:27]
	v_mfma_f32_16x16x32_bf16 v[16:19], v[156:159], v[202:205], v[16:19]
	v_mfma_f32_16x16x32_bf16 v[8:11], v[148:151], v[210:213], v[8:11]
	v_mfma_f32_16x16x32_bf16 v[0:3], v[156:159], v[210:213], v[0:3]
	s_cmp_lg_u32 s98, 0
	s_cbranch_scc1 .Lskf_4_loop
	s_barrier
.Lskf_4_loop:
	s_cmp_lg_u32 s99, 0
	s_cbranch_scc0 .LBB0_155

.LBB0_161:
	s_nop 0
	s_lshl_b32 s42, s46, 8
	s_add_i32 s42, s42, s68
	s_cmp_eq_u32 s46, s96
	s_cbranch_scc1 .LBB0_158

.LBB0_249:
	s_barrier
	s_andn2_b64 vcc, exec, s[10:11]
	s_mov_b32 s16, s66
	s_mov_b32 s68, s67
	s_mov_b64 s[34:35], s[28:29]
	s_mov_b64 s[30:31], s[26:27]
	s_cbranch_vccz .LBB0_284

.Llbb_1:
	s_add_i32 s44, s34, 2
	s_add_u32 s4, s30, 0x80
	s_addc_u32 s5, s31, 0
	s_add_i32 s45, 0, 0x10000
	s_cmp_eq_u32 s62, s34
	s_cselect_b32 s35, s27, s5
	s_cselect_b32 s34, s26, s4
	s_cselect_b32 s5, s29, s11
	s_cselect_b32 s4, s28, s10
	s_add_i32 s54, 0, 0x14000
	v_add_u32_e32 v140, s45, v195
	v_add_u32_e32 v166, s54, v195
	ds_read_b128 v[128:131], v140
	ds_read_b128 v[132:135], v140 offset:1024
	ds_read_b128 v[136:139], v140 offset:2048
	ds_read_b128 v[140:143], v140 offset:3072
	ds_read_b128 v[144:147], v166
	ds_read_b128 v[148:151], v166 offset:1024
	ds_read_b128 v[152:155], v166 offset:2048
	ds_read_b128 v[166:169], v166 offset:3072
	v_lshl_add_u64 v[174:175], s[30:31], 0, v[162:163]
	s_add_i32 m0, s38, 0xc000
	ds_read_b128 v[170:173], v197
	ds_read_b128 v[186:189], v197 offset:1024
	ds_read_b128 v[190:193], v197 offset:2048
	ds_read_b128 v[198:201], v197 offset:3072
	ds_read_b128 v[202:205], v197 offset:4096
	ds_read_b128 v[206:209], v197 offset:5120
	ds_read_b128 v[210:213], v197 offset:6144
	ds_read_b128 v[214:217], v197 offset:7168
	global_load_lds_dwordx4 v[174:175], off
	v_lshl_add_u64 v[174:175], s[30:31], 0, v[164:165]
	s_add_i32 m0, s38, 0xe000
	s_nop 0
	global_load_lds_dwordx4 v[174:175], off
	s_waitcnt vmcnt(8)
	s_waitcnt lgkmcnt(0)
	s_barrier
	s_waitcnt lgkmcnt(0)
	v_mfma_f32_16x16x32_bf16 v[120:123], v[128:131], v[170:173], 0
	v_mfma_f32_16x16x32_bf16 v[124:127], v[136:139], v[170:173], 0
	v_mfma_f32_16x16x32_bf16 v[108:111], v[128:131], v[190:193], 0
	v_mfma_f32_16x16x32_bf16 v[104:107], v[136:139], v[190:193], 0
	v_mfma_f32_16x16x32_bf16 v[92:95], v[128:131], v[202:205], 0
	v_mfma_f32_16x16x32_bf16 v[88:91], v[136:139], v[202:205], 0
	v_mfma_f32_16x16x32_bf16 v[76:79], v[128:131], v[210:213], 0
	v_mfma_f32_16x16x32_bf16 v[72:75], v[136:139], v[210:213], 0
	v_mfma_f32_16x16x32_bf16 v[120:123], v[132:135], v[186:189], v[120:123]
	v_mfma_f32_16x16x32_bf16 v[124:127], v[140:143], v[186:189], v[124:127]
	v_mfma_f32_16x16x32_bf16 v[108:111], v[132:135], v[198:201], v[108:111]
	v_mfma_f32_16x16x32_bf16 v[104:107], v[140:143], v[198:201], v[104:107]
	v_mfma_f32_16x16x32_bf16 v[92:95], v[132:135], v[206:209], v[92:95]
	v_mfma_f32_16x16x32_bf16 v[88:91], v[140:143], v[206:209], v[88:91]
	v_mfma_f32_16x16x32_bf16 v[76:79], v[132:135], v[214:217], v[76:79]
	v_mfma_f32_16x16x32_bf16 v[72:75], v[140:143], v[214:217], v[72:75]
	v_mfma_f32_16x16x32_bf16 v[116:119], v[144:147], v[170:173], 0
	v_mfma_f32_16x16x32_bf16 v[112:115], v[152:155], v[170:173], 0
	v_mfma_f32_16x16x32_bf16 v[100:103], v[144:147], v[190:193], 0
	v_mfma_f32_16x16x32_bf16 v[96:99], v[152:155], v[190:193], 0
	v_mfma_f32_16x16x32_bf16 v[84:87], v[144:147], v[202:205], 0
	v_mfma_f32_16x16x32_bf16 v[80:83], v[152:155], v[202:205], 0
	v_mfma_f32_16x16x32_bf16 v[68:71], v[144:147], v[210:213], 0
	v_mfma_f32_16x16x32_bf16 v[64:67], v[152:155], v[210:213], 0
	v_mfma_f32_16x16x32_bf16 v[116:119], v[148:151], v[186:189], v[116:119]
	v_mfma_f32_16x16x32_bf16 v[112:115], v[166:169], v[186:189], v[112:115]
	v_mfma_f32_16x16x32_bf16 v[100:103], v[148:151], v[198:201], v[100:103]
	v_mfma_f32_16x16x32_bf16 v[96:99], v[166:169], v[198:201], v[96:99]
	v_mfma_f32_16x16x32_bf16 v[84:87], v[148:151], v[206:209], v[84:87]
	v_mfma_f32_16x16x32_bf16 v[80:83], v[166:169], v[206:209], v[80:83]
	v_mfma_f32_16x16x32_bf16 v[68:71], v[148:151], v[214:217], v[68:71]
	v_mfma_f32_16x16x32_bf16 v[64:67], v[166:169], v[214:217], v[64:67]
	s_barrier
	s_add_i32 s45, s45, s37
	v_lshl_add_u64 v[174:175], s[4:5], 0, v[176:177]
	s_mov_b32 m0, s45
	ds_read_b128 v[170:173], v197 offset:16384
	ds_read_b128 v[186:189], v197 offset:17408
	ds_read_b128 v[190:193], v197 offset:18432
	ds_read_b128 v[198:201], v197 offset:19456
	ds_read_b128 v[202:205], v197 offset:20480
	ds_read_b128 v[206:209], v197 offset:21504
	ds_read_b128 v[210:213], v197 offset:22528
	ds_read_b128 v[214:217], v197 offset:23552
	global_load_lds_dwordx4 v[174:175], off
	s_add_i32 m0, s45, 0x2000
	v_lshl_add_u64 v[222:223], s[4:5], 0, v[156:157]
	s_add_u32 s4, s4, s0
	s_addc_u32 s5, s5, s1
	s_add_i32 s45, s54, s37
	global_load_lds_dwordx4 v[222:223], off
	v_lshl_add_u64 v[224:225], s[4:5], 0, v[176:177]
	s_mov_b32 m0, s45
	v_lshl_add_u64 v[226:227], s[4:5], 0, v[156:157]
	global_load_lds_dwordx4 v[224:225], off
	s_add_i32 m0, s45, 0x2000
	v_lshl_add_u64 v[228:229], s[34:35], 0, v[160:161]
	global_load_lds_dwordx4 v[226:227], off
	s_mov_b32 m0, s38
	v_lshl_add_u64 v[230:231], s[34:35], 0, v[158:159]
	global_load_lds_dwordx4 v[228:229], off
	s_mov_b32 m0, s39
	s_nop 0
	global_load_lds_dwordx4 v[230:231], off
	s_waitcnt vmcnt(8)
	s_waitcnt lgkmcnt(0)
	s_barrier
	s_waitcnt lgkmcnt(0)
	v_mfma_f32_16x16x32_bf16 v[60:63], v[128:131], v[170:173], 0
	v_mfma_f32_16x16x32_bf16 v[56:59], v[136:139], v[170:173], 0
	v_mfma_f32_16x16x32_bf16 v[44:47], v[128:131], v[190:193], 0
	v_mfma_f32_16x16x32_bf16 v[40:43], v[136:139], v[190:193], 0
	v_mfma_f32_16x16x32_bf16 v[28:31], v[128:131], v[202:205], 0
	v_mfma_f32_16x16x32_bf16 v[24:27], v[136:139], v[202:205], 0
	v_mfma_f32_16x16x32_bf16 v[12:15], v[128:131], v[210:213], 0
	v_mfma_f32_16x16x32_bf16 v[8:11], v[136:139], v[210:213], 0
	v_mfma_f32_16x16x32_bf16 v[60:63], v[132:135], v[186:189], v[60:63]
	v_mfma_f32_16x16x32_bf16 v[56:59], v[140:143], v[186:189], v[56:59]
	v_mfma_f32_16x16x32_bf16 v[44:47], v[132:135], v[198:201], v[44:47]
	v_mfma_f32_16x16x32_bf16 v[40:43], v[140:143], v[198:201], v[40:43]
	v_mfma_f32_16x16x32_bf16 v[28:31], v[132:135], v[206:209], v[28:31]
	v_mfma_f32_16x16x32_bf16 v[24:27], v[140:143], v[206:209], v[24:27]
	v_mfma_f32_16x16x32_bf16 v[12:15], v[132:135], v[214:217], v[12:15]
	v_mfma_f32_16x16x32_bf16 v[8:11], v[140:143], v[214:217], v[8:11]
	v_mfma_f32_16x16x32_bf16 v[52:55], v[144:147], v[170:173], 0
	v_mfma_f32_16x16x32_bf16 v[48:51], v[152:155], v[170:173], 0
	v_mfma_f32_16x16x32_bf16 v[36:39], v[144:147], v[190:193], 0
	v_mfma_f32_16x16x32_bf16 v[32:35], v[152:155], v[190:193], 0
	v_mfma_f32_16x16x32_bf16 v[20:23], v[144:147], v[202:205], 0
	v_mfma_f32_16x16x32_bf16 v[16:19], v[152:155], v[202:205], 0
	v_mfma_f32_16x16x32_bf16 v[4:7], v[144:147], v[210:213], 0
	v_mfma_f32_16x16x32_bf16 v[0:3], v[152:155], v[210:213], 0
	v_mfma_f32_16x16x32_bf16 v[52:55], v[148:151], v[186:189], v[52:55]
	v_mfma_f32_16x16x32_bf16 v[48:51], v[166:169], v[186:189], v[48:51]
	v_mfma_f32_16x16x32_bf16 v[36:39], v[148:151], v[198:201], v[36:39]
	v_mfma_f32_16x16x32_bf16 v[32:35], v[166:169], v[198:201], v[32:35]
	v_mfma_f32_16x16x32_bf16 v[20:23], v[148:151], v[206:209], v[20:23]
	v_mfma_f32_16x16x32_bf16 v[16:19], v[166:169], v[206:209], v[16:19]
	v_mfma_f32_16x16x32_bf16 v[4:7], v[148:151], v[214:217], v[4:7]
	v_mfma_f32_16x16x32_bf16 v[0:3], v[166:169], v[214:217], v[0:3]
	s_barrier
	s_add_i32 s45, 0, 0x18000
	s_add_i32 s54, 0, 0x1c000
	v_add_u32_e32 v140, s45, v195
	v_add_u32_e32 v166, s54, v195
	ds_read_b128 v[128:131], v140
	ds_read_b128 v[132:135], v140 offset:1024
	ds_read_b128 v[136:139], v140 offset:2048
	ds_read_b128 v[140:143], v140 offset:3072
	ds_read_b128 v[144:147], v166
	ds_read_b128 v[148:151], v166 offset:1024
	ds_read_b128 v[152:155], v166 offset:2048
	ds_read_b128 v[166:169], v166 offset:3072
	s_add_u32 s4, s34, s0
	s_addc_u32 s5, s35, s1
	s_mov_b32 m0, s48
	v_lshl_add_u64 v[232:233], s[4:5], 0, v[160:161]
	ds_read_b128 v[170:173], v197 offset:32768
	ds_read_b128 v[186:189], v197 offset:33792
	ds_read_b128 v[190:193], v197 offset:34816
	ds_read_b128 v[198:201], v197 offset:35840
	ds_read_b128 v[202:205], v197 offset:36864
	ds_read_b128 v[206:209], v197 offset:37888
	ds_read_b128 v[210:213], v197 offset:38912
	ds_read_b128 v[214:217], v197 offset:39936
	global_load_lds_dwordx4 v[232:233], off
	v_lshl_add_u64 v[232:233], s[4:5], 0, v[158:159]
	s_mov_b32 m0, s49
	s_nop 0
	global_load_lds_dwordx4 v[232:233], off
	s_waitcnt vmcnt(8)
	s_waitcnt lgkmcnt(0)
	s_barrier
	s_waitcnt lgkmcnt(0)
	v_mfma_f32_16x16x32_bf16 v[120:123], v[128:131], v[170:173], v[120:123]
	v_mfma_f32_16x16x32_bf16 v[124:127], v[136:139], v[170:173], v[124:127]
	v_mfma_f32_16x16x32_bf16 v[108:111], v[128:131], v[190:193], v[108:111]
	v_mfma_f32_16x16x32_bf16 v[104:107], v[136:139], v[190:193], v[104:107]
	v_mfma_f32_16x16x32_bf16 v[92:95], v[128:131], v[202:205], v[92:95]
	v_mfma_f32_16x16x32_bf16 v[88:91], v[136:139], v[202:205], v[88:91]
	v_mfma_f32_16x16x32_bf16 v[76:79], v[128:131], v[210:213], v[76:79]
	v_mfma_f32_16x16x32_bf16 v[72:75], v[136:139], v[210:213], v[72:75]
	v_mfma_f32_16x16x32_bf16 v[120:123], v[132:135], v[186:189], v[120:123]
	v_mfma_f32_16x16x32_bf16 v[124:127], v[140:143], v[186:189], v[124:127]
	v_mfma_f32_16x16x32_bf16 v[108:111], v[132:135], v[198:201], v[108:111]
	v_mfma_f32_16x16x32_bf16 v[104:107], v[140:143], v[198:201], v[104:107]
	v_mfma_f32_16x16x32_bf16 v[92:95], v[132:135], v[206:209], v[92:95]
	v_mfma_f32_16x16x32_bf16 v[88:91], v[140:143], v[206:209], v[88:91]
	v_mfma_f32_16x16x32_bf16 v[76:79], v[132:135], v[214:217], v[76:79]
	v_mfma_f32_16x16x32_bf16 v[72:75], v[140:143], v[214:217], v[72:75]
	v_mfma_f32_16x16x32_bf16 v[116:119], v[144:147], v[170:173], v[116:119]
	v_mfma_f32_16x16x32_bf16 v[112:115], v[152:155], v[170:173], v[112:115]
	v_mfma_f32_16x16x32_bf16 v[100:103], v[144:147], v[190:193], v[100:103]
	v_mfma_f32_16x16x32_bf16 v[96:99], v[152:155], v[190:193], v[96:99]
	v_mfma_f32_16x16x32_bf16 v[84:87], v[144:147], v[202:205], v[84:87]
	v_mfma_f32_16x16x32_bf16 v[80:83], v[152:155], v[202:205], v[80:83]
	v_mfma_f32_16x16x32_bf16 v[68:71], v[144:147], v[210:213], v[68:71]
	v_mfma_f32_16x16x32_bf16 v[64:67], v[152:155], v[210:213], v[64:67]
	v_mfma_f32_16x16x32_bf16 v[116:119], v[148:151], v[186:189], v[116:119]
	v_mfma_f32_16x16x32_bf16 v[112:115], v[166:169], v[186:189], v[112:115]
	v_mfma_f32_16x16x32_bf16 v[100:103], v[148:151], v[198:201], v[100:103]
	v_mfma_f32_16x16x32_bf16 v[96:99], v[166:169], v[198:201], v[96:99]
	v_mfma_f32_16x16x32_bf16 v[84:87], v[148:151], v[206:209], v[84:87]
	v_mfma_f32_16x16x32_bf16 v[80:83], v[166:169], v[206:209], v[80:83]
	v_mfma_f32_16x16x32_bf16 v[68:71], v[148:151], v[214:217], v[68:71]
	v_mfma_f32_16x16x32_bf16 v[64:67], v[166:169], v[214:217], v[64:67]
	s_barrier
	s_add_i32 s4, s45, s37
	v_lshl_add_u64 v[174:175], v[174:175], 0, s[14:15]
	s_mov_b32 m0, s4
	ds_read_b128 v[170:173], v197 offset:49152
	ds_read_b128 v[186:189], v197 offset:50176
	ds_read_b128 v[190:193], v197 offset:51200
	ds_read_b128 v[198:201], v197 offset:52224
	ds_read_b128 v[202:205], v197 offset:53248
	ds_read_b128 v[206:209], v197 offset:54272
	ds_read_b128 v[210:213], v197 offset:55296
	ds_read_b128 v[214:217], v197 offset:56320
	global_load_lds_dwordx4 v[174:175], off
	v_lshl_add_u64 v[174:175], v[222:223], 0, s[14:15]
	s_add_i32 m0, s4, 0x2000
	s_add_i32 s4, s54, s37
	global_load_lds_dwordx4 v[174:175], off
	v_lshl_add_u64 v[174:175], v[224:225], 0, s[14:15]
	s_mov_b32 m0, s4
	s_nop 0
	global_load_lds_dwordx4 v[174:175], off
	v_lshl_add_u64 v[174:175], v[226:227], 0, s[14:15]
	s_add_i32 m0, s4, 0x2000
	s_nop 0
	global_load_lds_dwordx4 v[174:175], off
	v_lshl_add_u64 v[174:175], v[228:229], 0, s[14:15]
	s_mov_b32 m0, s60
	s_nop 0
	global_load_lds_dwordx4 v[174:175], off
	v_lshl_add_u64 v[174:175], v[230:231], 0, s[14:15]
	s_mov_b32 m0, s61
	s_nop 0
	global_load_lds_dwordx4 v[174:175], off
	s_waitcnt vmcnt(8)
	s_waitcnt lgkmcnt(0)
	s_barrier
	s_waitcnt lgkmcnt(0)
	v_mfma_f32_16x16x32_bf16 v[60:63], v[128:131], v[170:173], v[60:63]
	s_add_u32 s30, s30, 0x100
	v_mfma_f32_16x16x32_bf16 v[56:59], v[136:139], v[170:173], v[56:59]
	s_addc_u32 s31, s31, 0
	v_mfma_f32_16x16x32_bf16 v[44:47], v[128:131], v[190:193], v[44:47]
	s_add_u32 s10, s10, 0x100
	v_mfma_f32_16x16x32_bf16 v[40:43], v[136:139], v[190:193], v[40:43]
	s_addc_u32 s11, s11, 0
	v_mfma_f32_16x16x32_bf16 v[28:31], v[128:131], v[202:205], v[28:31]
	s_mov_b32 s34, s44
	v_mfma_f32_16x16x32_bf16 v[24:27], v[136:139], v[202:205], v[24:27]
	s_cmp_ge_i32 s44, s59
	v_mfma_f32_16x16x32_bf16 v[12:15], v[128:131], v[210:213], v[12:15]
	s_cselect_b32 s99, 1, 0
	v_readfirstlane_b32 s98, v218
	s_bfe_u32 s98, s98, 0x10008
	s_and_b32 s98, s98, s99
	v_mfma_f32_16x16x32_bf16 v[8:11], v[136:139], v[210:213], v[8:11]
	s_add_i32 s44, s34, 2
	v_mfma_f32_16x16x32_bf16 v[60:63], v[132:135], v[186:189], v[60:63]
	s_add_u32 s4, s30, 0x80
	v_mfma_f32_16x16x32_bf16 v[56:59], v[140:143], v[186:189], v[56:59]
	s_addc_u32 s5, s31, 0
	v_mfma_f32_16x16x32_bf16 v[44:47], v[132:135], v[198:201], v[44:47]
	s_add_i32 s45, 0, 0x10000
	v_mfma_f32_16x16x32_bf16 v[40:43], v[140:143], v[198:201], v[40:43]
	s_cmp_eq_u32 s62, s34
	v_mfma_f32_16x16x32_bf16 v[28:31], v[132:135], v[206:209], v[28:31]
	s_cselect_b32 s35, s27, s5
	v_mfma_f32_16x16x32_bf16 v[24:27], v[140:143], v[206:209], v[24:27]
	s_cselect_b32 s34, s26, s4
	v_mfma_f32_16x16x32_bf16 v[12:15], v[132:135], v[214:217], v[12:15]
	s_cselect_b32 s5, s29, s11
	v_mfma_f32_16x16x32_bf16 v[8:11], v[140:143], v[214:217], v[8:11]
	s_cselect_b32 s4, s28, s10
	v_mfma_f32_16x16x32_bf16 v[52:55], v[144:147], v[170:173], v[52:55]
	s_add_i32 s54, 0, 0x14000
	v_mfma_f32_16x16x32_bf16 v[48:51], v[152:155], v[170:173], v[48:51]
	v_mfma_f32_16x16x32_bf16 v[36:39], v[144:147], v[190:193], v[36:39]
	v_mfma_f32_16x16x32_bf16 v[32:35], v[152:155], v[190:193], v[32:35]
	v_mfma_f32_16x16x32_bf16 v[20:23], v[144:147], v[202:205], v[20:23]
	v_mfma_f32_16x16x32_bf16 v[16:19], v[152:155], v[202:205], v[16:19]
	v_mfma_f32_16x16x32_bf16 v[4:7], v[144:147], v[210:213], v[4:7]
	v_mfma_f32_16x16x32_bf16 v[0:3], v[152:155], v[210:213], v[0:3]
	v_mfma_f32_16x16x32_bf16 v[52:55], v[148:151], v[186:189], v[52:55]
	v_mfma_f32_16x16x32_bf16 v[48:51], v[166:169], v[186:189], v[48:51]
	v_mfma_f32_16x16x32_bf16 v[36:39], v[148:151], v[198:201], v[36:39]
	v_mfma_f32_16x16x32_bf16 v[32:35], v[166:169], v[198:201], v[32:35]
	v_mfma_f32_16x16x32_bf16 v[20:23], v[148:151], v[206:209], v[20:23]
	v_mfma_f32_16x16x32_bf16 v[16:19], v[166:169], v[206:209], v[16:19]
	v_mfma_f32_16x16x32_bf16 v[4:7], v[148:151], v[214:217], v[4:7]
	v_mfma_f32_16x16x32_bf16 v[0:3], v[166:169], v[214:217], v[0:3]
	s_cmp_lg_u32 s98, 0
	s_cbranch_scc1 .Lskf_5_peel
	s_barrier

.LBB0_262:
	v_add_u32_e32 v140, s45, v195
	v_add_u32_e32 v166, s54, v195
	ds_read_b128 v[128:131], v140
	ds_read_b128 v[132:135], v140 offset:1024
	ds_read_b128 v[136:139], v140 offset:2048
	ds_read_b128 v[140:143], v140 offset:3072
	ds_read_b128 v[144:147], v166
	ds_read_b128 v[148:151], v166 offset:1024
	ds_read_b128 v[152:155], v166 offset:2048
	ds_read_b128 v[166:169], v166 offset:3072
	v_lshl_add_u64 v[174:175], s[30:31], 0, v[162:163]
	s_add_i32 m0, s38, 0xc000
	ds_read_b128 v[170:173], v197
	ds_read_b128 v[186:189], v197 offset:1024
	ds_read_b128 v[190:193], v197 offset:2048
	ds_read_b128 v[198:201], v197 offset:3072
	ds_read_b128 v[202:205], v197 offset:4096
	ds_read_b128 v[206:209], v197 offset:5120
	ds_read_b128 v[210:213], v197 offset:6144
	ds_read_b128 v[214:217], v197 offset:7168
	global_load_lds_dwordx4 v[174:175], off
	v_lshl_add_u64 v[174:175], s[30:31], 0, v[164:165]
	s_add_i32 m0, s38, 0xe000
	s_nop 0
	global_load_lds_dwordx4 v[174:175], off
	s_waitcnt vmcnt(8)
	s_waitcnt lgkmcnt(0)
	s_barrier
	s_waitcnt lgkmcnt(0)
	v_mfma_f32_16x16x32_bf16 v[120:123], v[128:131], v[170:173], v[120:123]
	v_mfma_f32_16x16x32_bf16 v[124:127], v[136:139], v[170:173], v[124:127]
	v_mfma_f32_16x16x32_bf16 v[108:111], v[128:131], v[190:193], v[108:111]
	v_mfma_f32_16x16x32_bf16 v[104:107], v[136:139], v[190:193], v[104:107]
	v_mfma_f32_16x16x32_bf16 v[92:95], v[128:131], v[202:205], v[92:95]
	v_mfma_f32_16x16x32_bf16 v[88:91], v[136:139], v[202:205], v[88:91]
	v_mfma_f32_16x16x32_bf16 v[76:79], v[128:131], v[210:213], v[76:79]
	v_mfma_f32_16x16x32_bf16 v[72:75], v[136:139], v[210:213], v[72:75]
	v_mfma_f32_16x16x32_bf16 v[120:123], v[132:135], v[186:189], v[120:123]
	v_mfma_f32_16x16x32_bf16 v[124:127], v[140:143], v[186:189], v[124:127]
	v_mfma_f32_16x16x32_bf16 v[108:111], v[132:135], v[198:201], v[108:111]
	v_mfma_f32_16x16x32_bf16 v[104:107], v[140:143], v[198:201], v[104:107]
	v_mfma_f32_16x16x32_bf16 v[92:95], v[132:135], v[206:209], v[92:95]
	v_mfma_f32_16x16x32_bf16 v[88:91], v[140:143], v[206:209], v[88:91]
	v_mfma_f32_16x16x32_bf16 v[76:79], v[132:135], v[214:217], v[76:79]
	v_mfma_f32_16x16x32_bf16 v[72:75], v[140:143], v[214:217], v[72:75]
	v_mfma_f32_16x16x32_bf16 v[116:119], v[144:147], v[170:173], v[116:119]
	v_mfma_f32_16x16x32_bf16 v[112:115], v[152:155], v[170:173], v[112:115]
	v_mfma_f32_16x16x32_bf16 v[100:103], v[144:147], v[190:193], v[100:103]
	v_mfma_f32_16x16x32_bf16 v[96:99], v[152:155], v[190:193], v[96:99]
	v_mfma_f32_16x16x32_bf16 v[84:87], v[144:147], v[202:205], v[84:87]
	v_mfma_f32_16x16x32_bf16 v[80:83], v[152:155], v[202:205], v[80:83]
	v_mfma_f32_16x16x32_bf16 v[68:71], v[144:147], v[210:213], v[68:71]
	v_mfma_f32_16x16x32_bf16 v[64:67], v[152:155], v[210:213], v[64:67]
	v_mfma_f32_16x16x32_bf16 v[116:119], v[148:151], v[186:189], v[116:119]
	v_mfma_f32_16x16x32_bf16 v[112:115], v[166:169], v[186:189], v[112:115]
	v_mfma_f32_16x16x32_bf16 v[100:103], v[148:151], v[198:201], v[100:103]
	v_mfma_f32_16x16x32_bf16 v[96:99], v[166:169], v[198:201], v[96:99]
	v_mfma_f32_16x16x32_bf16 v[84:87], v[148:151], v[206:209], v[84:87]
	v_mfma_f32_16x16x32_bf16 v[80:83], v[166:169], v[206:209], v[80:83]
	v_mfma_f32_16x16x32_bf16 v[68:71], v[148:151], v[214:217], v[68:71]
	v_mfma_f32_16x16x32_bf16 v[64:67], v[166:169], v[214:217], v[64:67]
	s_barrier
	s_add_i32 s45, s45, s37
	v_lshl_add_u64 v[174:175], s[4:5], 0, v[176:177]
	s_mov_b32 m0, s45
	ds_read_b128 v[170:173], v197 offset:16384
	ds_read_b128 v[186:189], v197 offset:17408
	ds_read_b128 v[190:193], v197 offset:18432
	ds_read_b128 v[198:201], v197 offset:19456
	ds_read_b128 v[202:205], v197 offset:20480
	ds_read_b128 v[206:209], v197 offset:21504
	ds_read_b128 v[210:213], v197 offset:22528
	ds_read_b128 v[214:217], v197 offset:23552
	global_load_lds_dwordx4 v[174:175], off
	s_add_i32 m0, s45, 0x2000
	v_lshl_add_u64 v[222:223], s[4:5], 0, v[156:157]
	s_add_u32 s4, s4, s0
	s_addc_u32 s5, s5, s1
	s_add_i32 s45, s54, s37
	global_load_lds_dwordx4 v[222:223], off
	v_lshl_add_u64 v[224:225], s[4:5], 0, v[176:177]
	s_mov_b32 m0, s45
	v_lshl_add_u64 v[226:227], s[4:5], 0, v[156:157]
	global_load_lds_dwordx4 v[224:225], off
	s_add_i32 m0, s45, 0x2000
	v_lshl_add_u64 v[228:229], s[34:35], 0, v[160:161]
	global_load_lds_dwordx4 v[226:227], off
	s_mov_b32 m0, s38
	v_lshl_add_u64 v[230:231], s[34:35], 0, v[158:159]
	global_load_lds_dwordx4 v[228:229], off
	s_mov_b32 m0, s39
	s_nop 0
	global_load_lds_dwordx4 v[230:231], off
	s_waitcnt vmcnt(8)
	s_waitcnt lgkmcnt(0)
	s_barrier
	s_waitcnt lgkmcnt(0)
	v_mfma_f32_16x16x32_bf16 v[60:63], v[128:131], v[170:173], v[60:63]
	v_mfma_f32_16x16x32_bf16 v[56:59], v[136:139], v[170:173], v[56:59]
	v_mfma_f32_16x16x32_bf16 v[44:47], v[128:131], v[190:193], v[44:47]
	v_mfma_f32_16x16x32_bf16 v[40:43], v[136:139], v[190:193], v[40:43]
	v_mfma_f32_16x16x32_bf16 v[28:31], v[128:131], v[202:205], v[28:31]
	v_mfma_f32_16x16x32_bf16 v[24:27], v[136:139], v[202:205], v[24:27]
	v_mfma_f32_16x16x32_bf16 v[12:15], v[128:131], v[210:213], v[12:15]
	v_mfma_f32_16x16x32_bf16 v[8:11], v[136:139], v[210:213], v[8:11]
	v_mfma_f32_16x16x32_bf16 v[60:63], v[132:135], v[186:189], v[60:63]
	v_mfma_f32_16x16x32_bf16 v[56:59], v[140:143], v[186:189], v[56:59]
	v_mfma_f32_16x16x32_bf16 v[44:47], v[132:135], v[198:201], v[44:47]
	v_mfma_f32_16x16x32_bf16 v[40:43], v[140:143], v[198:201], v[40:43]
	v_mfma_f32_16x16x32_bf16 v[28:31], v[132:135], v[206:209], v[28:31]
	v_mfma_f32_16x16x32_bf16 v[24:27], v[140:143], v[206:209], v[24:27]
	v_mfma_f32_16x16x32_bf16 v[12:15], v[132:135], v[214:217], v[12:15]
	v_mfma_f32_16x16x32_bf16 v[8:11], v[140:143], v[214:217], v[8:11]
	v_mfma_f32_16x16x32_bf16 v[52:55], v[144:147], v[170:173], v[52:55]
	v_mfma_f32_16x16x32_bf16 v[48:51], v[152:155], v[170:173], v[48:51]
	v_mfma_f32_16x16x32_bf16 v[36:39], v[144:147], v[190:193], v[36:39]
	v_mfma_f32_16x16x32_bf16 v[32:35], v[152:155], v[190:193], v[32:35]
	v_mfma_f32_16x16x32_bf16 v[20:23], v[144:147], v[202:205], v[20:23]
	v_mfma_f32_16x16x32_bf16 v[16:19], v[152:155], v[202:205], v[16:19]
	v_mfma_f32_16x16x32_bf16 v[4:7], v[144:147], v[210:213], v[4:7]
	v_mfma_f32_16x16x32_bf16 v[0:3], v[152:155], v[210:213], v[0:3]
	v_mfma_f32_16x16x32_bf16 v[52:55], v[148:151], v[186:189], v[52:55]
	v_mfma_f32_16x16x32_bf16 v[48:51], v[166:169], v[186:189], v[48:51]
	v_mfma_f32_16x16x32_bf16 v[36:39], v[148:151], v[198:201], v[36:39]
	v_mfma_f32_16x16x32_bf16 v[32:35], v[166:169], v[198:201], v[32:35]
	v_mfma_f32_16x16x32_bf16 v[20:23], v[148:151], v[206:209], v[20:23]
	v_mfma_f32_16x16x32_bf16 v[16:19], v[166:169], v[206:209], v[16:19]
	v_mfma_f32_16x16x32_bf16 v[4:7], v[148:151], v[214:217], v[4:7]
	v_mfma_f32_16x16x32_bf16 v[0:3], v[166:169], v[214:217], v[0:3]
	s_barrier
	s_add_i32 s45, 0, 0x18000
	s_add_i32 s54, 0, 0x1c000
	v_add_u32_e32 v140, s45, v195
	v_add_u32_e32 v166, s54, v195
	ds_read_b128 v[128:131], v140
	ds_read_b128 v[132:135], v140 offset:1024
	ds_read_b128 v[136:139], v140 offset:2048
	ds_read_b128 v[140:143], v140 offset:3072
	ds_read_b128 v[144:147], v166
	ds_read_b128 v[148:151], v166 offset:1024
	ds_read_b128 v[152:155], v166 offset:2048
	ds_read_b128 v[166:169], v166 offset:3072
	s_add_u32 s4, s34, s0
	s_addc_u32 s5, s35, s1
	s_mov_b32 m0, s48
	v_lshl_add_u64 v[232:233], s[4:5], 0, v[160:161]
	ds_read_b128 v[170:173], v197 offset:32768
	ds_read_b128 v[186:189], v197 offset:33792
	ds_read_b128 v[190:193], v197 offset:34816
	ds_read_b128 v[198:201], v197 offset:35840
	ds_read_b128 v[202:205], v197 offset:36864
	ds_read_b128 v[206:209], v197 offset:37888
	ds_read_b128 v[210:213], v197 offset:38912
	ds_read_b128 v[214:217], v197 offset:39936
	global_load_lds_dwordx4 v[232:233], off
	v_lshl_add_u64 v[232:233], s[4:5], 0, v[158:159]
	s_mov_b32 m0, s49
	s_nop 0
	global_load_lds_dwordx4 v[232:233], off
	s_waitcnt vmcnt(8)
	s_waitcnt lgkmcnt(0)
	s_barrier
	s_waitcnt lgkmcnt(0)
	v_mfma_f32_16x16x32_bf16 v[120:123], v[128:131], v[170:173], v[120:123]
	v_mfma_f32_16x16x32_bf16 v[124:127], v[136:139], v[170:173], v[124:127]
	v_mfma_f32_16x16x32_bf16 v[108:111], v[128:131], v[190:193], v[108:111]
	v_mfma_f32_16x16x32_bf16 v[104:107], v[136:139], v[190:193], v[104:107]
	v_mfma_f32_16x16x32_bf16 v[92:95], v[128:131], v[202:205], v[92:95]
	v_mfma_f32_16x16x32_bf16 v[88:91], v[136:139], v[202:205], v[88:91]
	v_mfma_f32_16x16x32_bf16 v[76:79], v[128:131], v[210:213], v[76:79]
	v_mfma_f32_16x16x32_bf16 v[72:75], v[136:139], v[210:213], v[72:75]
	v_mfma_f32_16x16x32_bf16 v[120:123], v[132:135], v[186:189], v[120:123]
	v_mfma_f32_16x16x32_bf16 v[124:127], v[140:143], v[186:189], v[124:127]
	v_mfma_f32_16x16x32_bf16 v[108:111], v[132:135], v[198:201], v[108:111]
	v_mfma_f32_16x16x32_bf16 v[104:107], v[140:143], v[198:201], v[104:107]
	v_mfma_f32_16x16x32_bf16 v[92:95], v[132:135], v[206:209], v[92:95]
	v_mfma_f32_16x16x32_bf16 v[88:91], v[140:143], v[206:209], v[88:91]
	v_mfma_f32_16x16x32_bf16 v[76:79], v[132:135], v[214:217], v[76:79]
	v_mfma_f32_16x16x32_bf16 v[72:75], v[140:143], v[214:217], v[72:75]
	v_mfma_f32_16x16x32_bf16 v[116:119], v[144:147], v[170:173], v[116:119]
	v_mfma_f32_16x16x32_bf16 v[112:115], v[152:155], v[170:173], v[112:115]
	v_mfma_f32_16x16x32_bf16 v[100:103], v[144:147], v[190:193], v[100:103]
	v_mfma_f32_16x16x32_bf16 v[96:99], v[152:155], v[190:193], v[96:99]
	v_mfma_f32_16x16x32_bf16 v[84:87], v[144:147], v[202:205], v[84:87]
	v_mfma_f32_16x16x32_bf16 v[80:83], v[152:155], v[202:205], v[80:83]
	v_mfma_f32_16x16x32_bf16 v[68:71], v[144:147], v[210:213], v[68:71]
	v_mfma_f32_16x16x32_bf16 v[64:67], v[152:155], v[210:213], v[64:67]
	v_mfma_f32_16x16x32_bf16 v[116:119], v[148:151], v[186:189], v[116:119]
	v_mfma_f32_16x16x32_bf16 v[112:115], v[166:169], v[186:189], v[112:115]
	v_mfma_f32_16x16x32_bf16 v[100:103], v[148:151], v[198:201], v[100:103]
	v_mfma_f32_16x16x32_bf16 v[96:99], v[166:169], v[198:201], v[96:99]
	v_mfma_f32_16x16x32_bf16 v[84:87], v[148:151], v[206:209], v[84:87]
	v_mfma_f32_16x16x32_bf16 v[80:83], v[166:169], v[206:209], v[80:83]
	v_mfma_f32_16x16x32_bf16 v[68:71], v[148:151], v[214:217], v[68:71]
	v_mfma_f32_16x16x32_bf16 v[64:67], v[166:169], v[214:217], v[64:67]
	s_barrier
	s_add_i32 s4, s45, s37
	v_lshl_add_u64 v[174:175], v[174:175], 0, s[14:15]
	s_mov_b32 m0, s4
	ds_read_b128 v[170:173], v197 offset:49152
	ds_read_b128 v[186:189], v197 offset:50176
	ds_read_b128 v[190:193], v197 offset:51200
	ds_read_b128 v[198:201], v197 offset:52224
	ds_read_b128 v[202:205], v197 offset:53248
	ds_read_b128 v[206:209], v197 offset:54272
	ds_read_b128 v[210:213], v197 offset:55296
	ds_read_b128 v[214:217], v197 offset:56320
	global_load_lds_dwordx4 v[174:175], off
	v_lshl_add_u64 v[174:175], v[222:223], 0, s[14:15]
	s_add_i32 m0, s4, 0x2000
	s_add_i32 s4, s54, s37
	global_load_lds_dwordx4 v[174:175], off
	v_lshl_add_u64 v[174:175], v[224:225], 0, s[14:15]
	s_mov_b32 m0, s4
	s_nop 0
	global_load_lds_dwordx4 v[174:175], off
	v_lshl_add_u64 v[174:175], v[226:227], 0, s[14:15]
	s_add_i32 m0, s4, 0x2000
	s_nop 0
	global_load_lds_dwordx4 v[174:175], off
	v_lshl_add_u64 v[174:175], v[228:229], 0, s[14:15]
	s_mov_b32 m0, s60
	s_nop 0
	global_load_lds_dwordx4 v[174:175], off
	v_lshl_add_u64 v[174:175], v[230:231], 0, s[14:15]
	s_mov_b32 m0, s61
	s_nop 0
	global_load_lds_dwordx4 v[174:175], off
	s_waitcnt vmcnt(8)
	s_waitcnt lgkmcnt(0)
	s_barrier
	s_waitcnt lgkmcnt(0)
	v_mfma_f32_16x16x32_bf16 v[60:63], v[128:131], v[170:173], v[60:63]
	s_add_u32 s30, s30, 0x100
	v_mfma_f32_16x16x32_bf16 v[56:59], v[136:139], v[170:173], v[56:59]
	s_addc_u32 s31, s31, 0
	v_mfma_f32_16x16x32_bf16 v[44:47], v[128:131], v[190:193], v[44:47]
	s_add_u32 s10, s10, 0x100
	v_mfma_f32_16x16x32_bf16 v[40:43], v[136:139], v[190:193], v[40:43]
	s_addc_u32 s11, s11, 0
	v_mfma_f32_16x16x32_bf16 v[28:31], v[128:131], v[202:205], v[28:31]
	s_mov_b32 s34, s44
	v_mfma_f32_16x16x32_bf16 v[24:27], v[136:139], v[202:205], v[24:27]
	s_cmp_ge_i32 s44, s59
	v_mfma_f32_16x16x32_bf16 v[12:15], v[128:131], v[210:213], v[12:15]
	s_cselect_b32 s99, 1, 0
	v_readfirstlane_b32 s98, v218
	s_bfe_u32 s98, s98, 0x10008
	s_and_b32 s98, s98, s99
	v_mfma_f32_16x16x32_bf16 v[8:11], v[136:139], v[210:213], v[8:11]
	s_add_i32 s44, s34, 2
	v_mfma_f32_16x16x32_bf16 v[60:63], v[132:135], v[186:189], v[60:63]
	s_add_u32 s4, s30, 0x80
	v_mfma_f32_16x16x32_bf16 v[56:59], v[140:143], v[186:189], v[56:59]
	s_addc_u32 s5, s31, 0
	v_mfma_f32_16x16x32_bf16 v[44:47], v[132:135], v[198:201], v[44:47]
	s_add_i32 s45, 0, 0x10000
	v_mfma_f32_16x16x32_bf16 v[40:43], v[140:143], v[198:201], v[40:43]
	s_cmp_eq_u32 s62, s34
	v_mfma_f32_16x16x32_bf16 v[28:31], v[132:135], v[206:209], v[28:31]
	s_cselect_b32 s35, s27, s5
	v_mfma_f32_16x16x32_bf16 v[24:27], v[140:143], v[206:209], v[24:27]
	s_cselect_b32 s34, s26, s4
	v_mfma_f32_16x16x32_bf16 v[12:15], v[132:135], v[214:217], v[12:15]
	s_cselect_b32 s5, s29, s11
	v_mfma_f32_16x16x32_bf16 v[8:11], v[140:143], v[214:217], v[8:11]
	s_cselect_b32 s4, s28, s10
	v_mfma_f32_16x16x32_bf16 v[52:55], v[144:147], v[170:173], v[52:55]
	s_add_i32 s54, 0, 0x14000
	v_mfma_f32_16x16x32_bf16 v[48:51], v[152:155], v[170:173], v[48:51]
	v_mfma_f32_16x16x32_bf16 v[36:39], v[144:147], v[190:193], v[36:39]
	v_mfma_f32_16x16x32_bf16 v[32:35], v[152:155], v[190:193], v[32:35]
	v_mfma_f32_16x16x32_bf16 v[20:23], v[144:147], v[202:205], v[20:23]
	v_mfma_f32_16x16x32_bf16 v[16:19], v[152:155], v[202:205], v[16:19]
	v_mfma_f32_16x16x32_bf16 v[4:7], v[144:147], v[210:213], v[4:7]
	v_mfma_f32_16x16x32_bf16 v[0:3], v[152:155], v[210:213], v[0:3]
	v_mfma_f32_16x16x32_bf16 v[52:55], v[148:151], v[186:189], v[52:55]
	v_mfma_f32_16x16x32_bf16 v[48:51], v[166:169], v[186:189], v[48:51]
	v_mfma_f32_16x16x32_bf16 v[36:39], v[148:151], v[198:201], v[36:39]
	v_mfma_f32_16x16x32_bf16 v[32:35], v[166:169], v[198:201], v[32:35]
	v_mfma_f32_16x16x32_bf16 v[20:23], v[148:151], v[206:209], v[20:23]
	v_mfma_f32_16x16x32_bf16 v[16:19], v[166:169], v[206:209], v[16:19]
	v_mfma_f32_16x16x32_bf16 v[4:7], v[148:151], v[214:217], v[4:7]
	v_mfma_f32_16x16x32_bf16 v[0:3], v[166:169], v[214:217], v[0:3]
	s_cmp_lg_u32 s98, 0
	s_cbranch_scc1 .Lskf_5_loop
	s_barrier

.Lpeelx_5:
.LBB0_263:
	s_and_b64 vcc, exec, s[24:25]
	s_cbranch_vccz .LBB0_265
	s_nop 0

.LBB0_292:
	s_barrier
	s_andn2_b64 vcc, exec, s[10:11]
	s_mov_b32 s66, s67
	s_mov_b32 s16, s68
	s_mov_b64 s[34:35], s[28:29]
	s_mov_b64 s[30:31], s[26:27]
	s_cbranch_vccz .LBB0_327

.Llbb_2:
	s_add_i32 s44, s34, 2
	s_add_u32 s4, s30, 0x80
	s_addc_u32 s5, s31, 0
	s_add_i32 s45, 0, 0x10000
	s_cmp_eq_u32 s62, s34
	s_cselect_b32 s35, s27, s5
	s_cselect_b32 s34, s26, s4
	s_cselect_b32 s5, s29, s11
	s_cselect_b32 s4, s28, s10
	s_add_i32 s54, 0, 0x14000
	v_add_u32_e32 v140, s45, v163
	v_add_u32_e32 v170, s54, v163
	ds_read_b128 v[128:131], v140
	ds_read_b128 v[132:135], v140 offset:1024
	ds_read_b128 v[136:139], v140 offset:2048
	ds_read_b128 v[140:143], v140 offset:3072
	ds_read_b128 v[154:157], v170
	ds_read_b128 v[158:161], v170 offset:1024
	ds_read_b128 v[166:169], v170 offset:2048
	ds_read_b128 v[170:173], v170 offset:3072
	v_lshl_add_u64 v[174:175], s[30:31], 0, v[150:151]
	s_add_i32 m0, s38, 0xc000
	ds_read_b128 v[186:189], v165
	ds_read_b128 v[190:193], v165 offset:1024
	ds_read_b128 v[194:197], v165 offset:2048
	ds_read_b128 v[198:201], v165 offset:3072
	ds_read_b128 v[202:205], v165 offset:4096
	ds_read_b128 v[206:209], v165 offset:5120
	ds_read_b128 v[210:213], v165 offset:6144
	ds_read_b128 v[214:217], v165 offset:7168
	global_load_lds_dwordx4 v[174:175], off
	v_lshl_add_u64 v[174:175], s[30:31], 0, v[152:153]
	s_add_i32 m0, s38, 0xe000
	s_nop 0
	global_load_lds_dwordx4 v[174:175], off
	s_waitcnt vmcnt(8)
	s_waitcnt lgkmcnt(0)
	s_barrier
	s_waitcnt lgkmcnt(0)
	v_mfma_f32_16x16x32_bf16 v[124:127], v[128:131], v[186:189], 0
	v_mfma_f32_16x16x32_bf16 v[120:123], v[136:139], v[186:189], 0
	v_mfma_f32_16x16x32_bf16 v[108:111], v[128:131], v[194:197], 0
	v_mfma_f32_16x16x32_bf16 v[104:107], v[136:139], v[194:197], 0
	v_mfma_f32_16x16x32_bf16 v[92:95], v[128:131], v[202:205], 0
	v_mfma_f32_16x16x32_bf16 v[88:91], v[136:139], v[202:205], 0
	v_mfma_f32_16x16x32_bf16 v[76:79], v[128:131], v[210:213], 0
	v_mfma_f32_16x16x32_bf16 v[72:75], v[136:139], v[210:213], 0
	v_mfma_f32_16x16x32_bf16 v[124:127], v[132:135], v[190:193], v[124:127]
	v_mfma_f32_16x16x32_bf16 v[120:123], v[140:143], v[190:193], v[120:123]
	v_mfma_f32_16x16x32_bf16 v[108:111], v[132:135], v[198:201], v[108:111]
	v_mfma_f32_16x16x32_bf16 v[104:107], v[140:143], v[198:201], v[104:107]
	v_mfma_f32_16x16x32_bf16 v[92:95], v[132:135], v[206:209], v[92:95]
	v_mfma_f32_16x16x32_bf16 v[88:91], v[140:143], v[206:209], v[88:91]
	v_mfma_f32_16x16x32_bf16 v[76:79], v[132:135], v[214:217], v[76:79]
	v_mfma_f32_16x16x32_bf16 v[72:75], v[140:143], v[214:217], v[72:75]
	v_mfma_f32_16x16x32_bf16 v[116:119], v[154:157], v[186:189], 0
	v_mfma_f32_16x16x32_bf16 v[112:115], v[166:169], v[186:189], 0
	v_mfma_f32_16x16x32_bf16 v[100:103], v[154:157], v[194:197], 0
	v_mfma_f32_16x16x32_bf16 v[96:99], v[166:169], v[194:197], 0
	v_mfma_f32_16x16x32_bf16 v[84:87], v[154:157], v[202:205], 0
	v_mfma_f32_16x16x32_bf16 v[80:83], v[166:169], v[202:205], 0
	v_mfma_f32_16x16x32_bf16 v[68:71], v[154:157], v[210:213], 0
	v_mfma_f32_16x16x32_bf16 v[64:67], v[166:169], v[210:213], 0
	v_mfma_f32_16x16x32_bf16 v[116:119], v[158:161], v[190:193], v[116:119]
	v_mfma_f32_16x16x32_bf16 v[112:115], v[170:173], v[190:193], v[112:115]
	v_mfma_f32_16x16x32_bf16 v[100:103], v[158:161], v[198:201], v[100:103]
	v_mfma_f32_16x16x32_bf16 v[96:99], v[170:173], v[198:201], v[96:99]
	v_mfma_f32_16x16x32_bf16 v[84:87], v[158:161], v[206:209], v[84:87]
	v_mfma_f32_16x16x32_bf16 v[80:83], v[170:173], v[206:209], v[80:83]
	v_mfma_f32_16x16x32_bf16 v[68:71], v[158:161], v[214:217], v[68:71]
	v_mfma_f32_16x16x32_bf16 v[64:67], v[170:173], v[214:217], v[64:67]
	s_barrier
	s_add_i32 s45, s45, s37
	v_lshl_add_u64 v[174:175], s[4:5], 0, v[176:177]
	s_mov_b32 m0, s45
	ds_read_b128 v[186:189], v165 offset:16384
	ds_read_b128 v[190:193], v165 offset:17408
	ds_read_b128 v[194:197], v165 offset:18432
	ds_read_b128 v[198:201], v165 offset:19456
	ds_read_b128 v[202:205], v165 offset:20480
	ds_read_b128 v[206:209], v165 offset:21504
	ds_read_b128 v[210:213], v165 offset:22528
	ds_read_b128 v[214:217], v165 offset:23552
	global_load_lds_dwordx4 v[174:175], off
	s_add_i32 m0, s45, 0x2000
	v_lshl_add_u64 v[222:223], s[4:5], 0, v[144:145]
	s_add_u32 s4, s4, s0
	s_addc_u32 s5, s5, s1
	s_add_i32 s45, s54, s37
	global_load_lds_dwordx4 v[222:223], off
	v_lshl_add_u64 v[224:225], s[4:5], 0, v[176:177]
	s_mov_b32 m0, s45
	v_lshl_add_u64 v[226:227], s[4:5], 0, v[144:145]
	global_load_lds_dwordx4 v[224:225], off
	s_add_i32 m0, s45, 0x2000
	v_lshl_add_u64 v[228:229], s[34:35], 0, v[148:149]
	global_load_lds_dwordx4 v[226:227], off
	s_mov_b32 m0, s38
	v_lshl_add_u64 v[230:231], s[34:35], 0, v[146:147]
	global_load_lds_dwordx4 v[228:229], off
	s_mov_b32 m0, s39
	s_nop 0
	global_load_lds_dwordx4 v[230:231], off
	s_waitcnt vmcnt(8)
	s_waitcnt lgkmcnt(0)
	s_barrier
	s_waitcnt lgkmcnt(0)
	v_mfma_f32_16x16x32_bf16 v[60:63], v[128:131], v[186:189], 0
	v_mfma_f32_16x16x32_bf16 v[56:59], v[136:139], v[186:189], 0
	v_mfma_f32_16x16x32_bf16 v[44:47], v[128:131], v[194:197], 0
	v_mfma_f32_16x16x32_bf16 v[40:43], v[136:139], v[194:197], 0
	v_mfma_f32_16x16x32_bf16 v[28:31], v[128:131], v[202:205], 0
	v_mfma_f32_16x16x32_bf16 v[24:27], v[136:139], v[202:205], 0
	v_mfma_f32_16x16x32_bf16 v[12:15], v[128:131], v[210:213], 0
	v_mfma_f32_16x16x32_bf16 v[8:11], v[136:139], v[210:213], 0
	v_mfma_f32_16x16x32_bf16 v[60:63], v[132:135], v[190:193], v[60:63]
	v_mfma_f32_16x16x32_bf16 v[56:59], v[140:143], v[190:193], v[56:59]
	v_mfma_f32_16x16x32_bf16 v[44:47], v[132:135], v[198:201], v[44:47]
	v_mfma_f32_16x16x32_bf16 v[40:43], v[140:143], v[198:201], v[40:43]
	v_mfma_f32_16x16x32_bf16 v[28:31], v[132:135], v[206:209], v[28:31]
	v_mfma_f32_16x16x32_bf16 v[24:27], v[140:143], v[206:209], v[24:27]
	v_mfma_f32_16x16x32_bf16 v[12:15], v[132:135], v[214:217], v[12:15]
	v_mfma_f32_16x16x32_bf16 v[8:11], v[140:143], v[214:217], v[8:11]
	v_mfma_f32_16x16x32_bf16 v[52:55], v[154:157], v[186:189], 0
	v_mfma_f32_16x16x32_bf16 v[48:51], v[166:169], v[186:189], 0
	v_mfma_f32_16x16x32_bf16 v[36:39], v[154:157], v[194:197], 0
	v_mfma_f32_16x16x32_bf16 v[32:35], v[166:169], v[194:197], 0
	v_mfma_f32_16x16x32_bf16 v[20:23], v[154:157], v[202:205], 0
	v_mfma_f32_16x16x32_bf16 v[16:19], v[166:169], v[202:205], 0
	v_mfma_f32_16x16x32_bf16 v[4:7], v[154:157], v[210:213], 0
	v_mfma_f32_16x16x32_bf16 v[0:3], v[166:169], v[210:213], 0
	v_mfma_f32_16x16x32_bf16 v[52:55], v[158:161], v[190:193], v[52:55]
	v_mfma_f32_16x16x32_bf16 v[48:51], v[170:173], v[190:193], v[48:51]
	v_mfma_f32_16x16x32_bf16 v[36:39], v[158:161], v[198:201], v[36:39]
	v_mfma_f32_16x16x32_bf16 v[32:35], v[170:173], v[198:201], v[32:35]
	v_mfma_f32_16x16x32_bf16 v[20:23], v[158:161], v[206:209], v[20:23]
	v_mfma_f32_16x16x32_bf16 v[16:19], v[170:173], v[206:209], v[16:19]
	v_mfma_f32_16x16x32_bf16 v[4:7], v[158:161], v[214:217], v[4:7]
	v_mfma_f32_16x16x32_bf16 v[0:3], v[170:173], v[214:217], v[0:3]
	s_barrier
	s_add_i32 s45, 0, 0x18000
	s_add_i32 s54, 0, 0x1c000
	v_add_u32_e32 v140, s45, v163
	v_add_u32_e32 v170, s54, v163
	ds_read_b128 v[128:131], v140
	ds_read_b128 v[132:135], v140 offset:1024
	ds_read_b128 v[136:139], v140 offset:2048
	ds_read_b128 v[140:143], v140 offset:3072
	ds_read_b128 v[154:157], v170
	ds_read_b128 v[158:161], v170 offset:1024
	ds_read_b128 v[166:169], v170 offset:2048
	ds_read_b128 v[170:173], v170 offset:3072
	s_add_u32 s4, s34, s0
	s_addc_u32 s5, s35, s1
	s_mov_b32 m0, s48
	v_lshl_add_u64 v[232:233], s[4:5], 0, v[148:149]
	ds_read_b128 v[186:189], v165 offset:32768
	ds_read_b128 v[190:193], v165 offset:33792
	ds_read_b128 v[194:197], v165 offset:34816
	ds_read_b128 v[198:201], v165 offset:35840
	ds_read_b128 v[202:205], v165 offset:36864
	ds_read_b128 v[206:209], v165 offset:37888
	ds_read_b128 v[210:213], v165 offset:38912
	ds_read_b128 v[214:217], v165 offset:39936
	global_load_lds_dwordx4 v[232:233], off
	v_lshl_add_u64 v[232:233], s[4:5], 0, v[146:147]
	s_mov_b32 m0, s49
	s_nop 0
	global_load_lds_dwordx4 v[232:233], off
	s_waitcnt vmcnt(8)
	s_waitcnt lgkmcnt(0)
	s_barrier
	s_waitcnt lgkmcnt(0)
	v_mfma_f32_16x16x32_bf16 v[124:127], v[128:131], v[186:189], v[124:127]
	v_mfma_f32_16x16x32_bf16 v[120:123], v[136:139], v[186:189], v[120:123]
	v_mfma_f32_16x16x32_bf16 v[108:111], v[128:131], v[194:197], v[108:111]
	v_mfma_f32_16x16x32_bf16 v[104:107], v[136:139], v[194:197], v[104:107]
	v_mfma_f32_16x16x32_bf16 v[92:95], v[128:131], v[202:205], v[92:95]
	v_mfma_f32_16x16x32_bf16 v[88:91], v[136:139], v[202:205], v[88:91]
	v_mfma_f32_16x16x32_bf16 v[76:79], v[128:131], v[210:213], v[76:79]
	v_mfma_f32_16x16x32_bf16 v[72:75], v[136:139], v[210:213], v[72:75]
	v_mfma_f32_16x16x32_bf16 v[124:127], v[132:135], v[190:193], v[124:127]
	v_mfma_f32_16x16x32_bf16 v[120:123], v[140:143], v[190:193], v[120:123]
	v_mfma_f32_16x16x32_bf16 v[108:111], v[132:135], v[198:201], v[108:111]
	v_mfma_f32_16x16x32_bf16 v[104:107], v[140:143], v[198:201], v[104:107]
	v_mfma_f32_16x16x32_bf16 v[92:95], v[132:135], v[206:209], v[92:95]
	v_mfma_f32_16x16x32_bf16 v[88:91], v[140:143], v[206:209], v[88:91]
	v_mfma_f32_16x16x32_bf16 v[76:79], v[132:135], v[214:217], v[76:79]
	v_mfma_f32_16x16x32_bf16 v[72:75], v[140:143], v[214:217], v[72:75]
	v_mfma_f32_16x16x32_bf16 v[116:119], v[154:157], v[186:189], v[116:119]
	v_mfma_f32_16x16x32_bf16 v[112:115], v[166:169], v[186:189], v[112:115]
	v_mfma_f32_16x16x32_bf16 v[100:103], v[154:157], v[194:197], v[100:103]
	v_mfma_f32_16x16x32_bf16 v[96:99], v[166:169], v[194:197], v[96:99]
	v_mfma_f32_16x16x32_bf16 v[84:87], v[154:157], v[202:205], v[84:87]
	v_mfma_f32_16x16x32_bf16 v[80:83], v[166:169], v[202:205], v[80:83]
	v_mfma_f32_16x16x32_bf16 v[68:71], v[154:157], v[210:213], v[68:71]
	v_mfma_f32_16x16x32_bf16 v[64:67], v[166:169], v[210:213], v[64:67]
	v_mfma_f32_16x16x32_bf16 v[116:119], v[158:161], v[190:193], v[116:119]
	v_mfma_f32_16x16x32_bf16 v[112:115], v[170:173], v[190:193], v[112:115]
	v_mfma_f32_16x16x32_bf16 v[100:103], v[158:161], v[198:201], v[100:103]
	v_mfma_f32_16x16x32_bf16 v[96:99], v[170:173], v[198:201], v[96:99]
	v_mfma_f32_16x16x32_bf16 v[84:87], v[158:161], v[206:209], v[84:87]
	v_mfma_f32_16x16x32_bf16 v[80:83], v[170:173], v[206:209], v[80:83]
	v_mfma_f32_16x16x32_bf16 v[68:71], v[158:161], v[214:217], v[68:71]
	v_mfma_f32_16x16x32_bf16 v[64:67], v[170:173], v[214:217], v[64:67]
	s_barrier
	s_add_i32 s4, s45, s37
	v_lshl_add_u64 v[174:175], v[174:175], 0, s[14:15]
	s_mov_b32 m0, s4
	ds_read_b128 v[186:189], v165 offset:49152
	ds_read_b128 v[190:193], v165 offset:50176
	ds_read_b128 v[194:197], v165 offset:51200
	ds_read_b128 v[198:201], v165 offset:52224
	ds_read_b128 v[202:205], v165 offset:53248
	ds_read_b128 v[206:209], v165 offset:54272
	ds_read_b128 v[210:213], v165 offset:55296
	ds_read_b128 v[214:217], v165 offset:56320
	global_load_lds_dwordx4 v[174:175], off
	v_lshl_add_u64 v[174:175], v[222:223], 0, s[14:15]
	s_add_i32 m0, s4, 0x2000
	s_add_i32 s4, s54, s37
	global_load_lds_dwordx4 v[174:175], off
	v_lshl_add_u64 v[174:175], v[224:225], 0, s[14:15]
	s_mov_b32 m0, s4
	s_nop 0
	global_load_lds_dwordx4 v[174:175], off
	v_lshl_add_u64 v[174:175], v[226:227], 0, s[14:15]
	s_add_i32 m0, s4, 0x2000
	s_nop 0
	global_load_lds_dwordx4 v[174:175], off
	v_lshl_add_u64 v[174:175], v[228:229], 0, s[14:15]
	s_mov_b32 m0, s60
	s_nop 0
	global_load_lds_dwordx4 v[174:175], off
	v_lshl_add_u64 v[174:175], v[230:231], 0, s[14:15]
	s_mov_b32 m0, s61
	s_nop 0
	global_load_lds_dwordx4 v[174:175], off
	s_waitcnt vmcnt(8)
	s_waitcnt lgkmcnt(0)
	s_barrier
	s_waitcnt lgkmcnt(0)
	v_mfma_f32_16x16x32_bf16 v[60:63], v[128:131], v[186:189], v[60:63]
	s_add_u32 s30, s30, 0x100
	v_mfma_f32_16x16x32_bf16 v[56:59], v[136:139], v[186:189], v[56:59]
	s_addc_u32 s31, s31, 0
	v_mfma_f32_16x16x32_bf16 v[44:47], v[128:131], v[194:197], v[44:47]
	s_add_u32 s10, s10, 0x100
	v_mfma_f32_16x16x32_bf16 v[40:43], v[136:139], v[194:197], v[40:43]
	s_addc_u32 s11, s11, 0
	v_mfma_f32_16x16x32_bf16 v[28:31], v[128:131], v[202:205], v[28:31]
	s_mov_b32 s34, s44
	v_mfma_f32_16x16x32_bf16 v[24:27], v[136:139], v[202:205], v[24:27]
	s_cmp_ge_i32 s44, s59
	v_mfma_f32_16x16x32_bf16 v[12:15], v[128:131], v[210:213], v[12:15]
	s_cselect_b32 s99, 1, 0
	v_readfirstlane_b32 s98, v218
	s_bfe_u32 s98, s98, 0x10008
	s_and_b32 s98, s98, s99
	v_mfma_f32_16x16x32_bf16 v[8:11], v[136:139], v[210:213], v[8:11]
	s_add_i32 s44, s34, 2
	v_mfma_f32_16x16x32_bf16 v[60:63], v[132:135], v[190:193], v[60:63]
	s_add_u32 s4, s30, 0x80
	v_mfma_f32_16x16x32_bf16 v[56:59], v[140:143], v[190:193], v[56:59]
	s_addc_u32 s5, s31, 0
	v_mfma_f32_16x16x32_bf16 v[44:47], v[132:135], v[198:201], v[44:47]
	s_add_i32 s45, 0, 0x10000
	v_mfma_f32_16x16x32_bf16 v[40:43], v[140:143], v[198:201], v[40:43]
	s_cmp_eq_u32 s62, s34
	v_mfma_f32_16x16x32_bf16 v[28:31], v[132:135], v[206:209], v[28:31]
	s_cselect_b32 s35, s27, s5
	v_mfma_f32_16x16x32_bf16 v[24:27], v[140:143], v[206:209], v[24:27]
	s_cselect_b32 s34, s26, s4
	v_mfma_f32_16x16x32_bf16 v[12:15], v[132:135], v[214:217], v[12:15]
	s_cselect_b32 s5, s29, s11
	v_mfma_f32_16x16x32_bf16 v[8:11], v[140:143], v[214:217], v[8:11]
	s_cselect_b32 s4, s28, s10
	v_mfma_f32_16x16x32_bf16 v[52:55], v[154:157], v[186:189], v[52:55]
	s_add_i32 s54, 0, 0x14000
	v_mfma_f32_16x16x32_bf16 v[48:51], v[166:169], v[186:189], v[48:51]
	v_mfma_f32_16x16x32_bf16 v[36:39], v[154:157], v[194:197], v[36:39]
	v_mfma_f32_16x16x32_bf16 v[32:35], v[166:169], v[194:197], v[32:35]
	v_mfma_f32_16x16x32_bf16 v[20:23], v[154:157], v[202:205], v[20:23]
	v_mfma_f32_16x16x32_bf16 v[16:19], v[166:169], v[202:205], v[16:19]
	v_mfma_f32_16x16x32_bf16 v[4:7], v[154:157], v[210:213], v[4:7]
	v_mfma_f32_16x16x32_bf16 v[0:3], v[166:169], v[210:213], v[0:3]
	v_mfma_f32_16x16x32_bf16 v[52:55], v[158:161], v[190:193], v[52:55]
	v_mfma_f32_16x16x32_bf16 v[48:51], v[170:173], v[190:193], v[48:51]
	v_mfma_f32_16x16x32_bf16 v[36:39], v[158:161], v[198:201], v[36:39]
	v_mfma_f32_16x16x32_bf16 v[32:35], v[170:173], v[198:201], v[32:35]
	v_mfma_f32_16x16x32_bf16 v[20:23], v[158:161], v[206:209], v[20:23]
	v_mfma_f32_16x16x32_bf16 v[16:19], v[170:173], v[206:209], v[16:19]
	v_mfma_f32_16x16x32_bf16 v[4:7], v[158:161], v[214:217], v[4:7]
	v_mfma_f32_16x16x32_bf16 v[0:3], v[170:173], v[214:217], v[0:3]
	s_cmp_lg_u32 s98, 0
	s_cbranch_scc1 .Lskf_6_peel
	s_barrier

.LBB0_305:
	v_add_u32_e32 v140, s45, v163
	v_add_u32_e32 v170, s54, v163
	ds_read_b128 v[128:131], v140
	ds_read_b128 v[132:135], v140 offset:1024
	ds_read_b128 v[136:139], v140 offset:2048
	ds_read_b128 v[140:143], v140 offset:3072
	ds_read_b128 v[154:157], v170
	ds_read_b128 v[158:161], v170 offset:1024
	ds_read_b128 v[166:169], v170 offset:2048
	ds_read_b128 v[170:173], v170 offset:3072
	v_lshl_add_u64 v[174:175], s[30:31], 0, v[150:151]
	s_add_i32 m0, s38, 0xc000
	ds_read_b128 v[186:189], v165
	ds_read_b128 v[190:193], v165 offset:1024
	ds_read_b128 v[194:197], v165 offset:2048
	ds_read_b128 v[198:201], v165 offset:3072
	ds_read_b128 v[202:205], v165 offset:4096
	ds_read_b128 v[206:209], v165 offset:5120
	ds_read_b128 v[210:213], v165 offset:6144
	ds_read_b128 v[214:217], v165 offset:7168
	global_load_lds_dwordx4 v[174:175], off
	v_lshl_add_u64 v[174:175], s[30:31], 0, v[152:153]
	s_add_i32 m0, s38, 0xe000
	s_nop 0
	global_load_lds_dwordx4 v[174:175], off
	s_waitcnt vmcnt(8)
	s_waitcnt lgkmcnt(0)
	s_barrier
	s_waitcnt lgkmcnt(0)
	v_mfma_f32_16x16x32_bf16 v[124:127], v[128:131], v[186:189], v[124:127]
	v_mfma_f32_16x16x32_bf16 v[120:123], v[136:139], v[186:189], v[120:123]
	v_mfma_f32_16x16x32_bf16 v[108:111], v[128:131], v[194:197], v[108:111]
	v_mfma_f32_16x16x32_bf16 v[104:107], v[136:139], v[194:197], v[104:107]
	v_mfma_f32_16x16x32_bf16 v[92:95], v[128:131], v[202:205], v[92:95]
	v_mfma_f32_16x16x32_bf16 v[88:91], v[136:139], v[202:205], v[88:91]
	v_mfma_f32_16x16x32_bf16 v[76:79], v[128:131], v[210:213], v[76:79]
	v_mfma_f32_16x16x32_bf16 v[72:75], v[136:139], v[210:213], v[72:75]
	v_mfma_f32_16x16x32_bf16 v[124:127], v[132:135], v[190:193], v[124:127]
	v_mfma_f32_16x16x32_bf16 v[120:123], v[140:143], v[190:193], v[120:123]
	v_mfma_f32_16x16x32_bf16 v[108:111], v[132:135], v[198:201], v[108:111]
	v_mfma_f32_16x16x32_bf16 v[104:107], v[140:143], v[198:201], v[104:107]
	v_mfma_f32_16x16x32_bf16 v[92:95], v[132:135], v[206:209], v[92:95]
	v_mfma_f32_16x16x32_bf16 v[88:91], v[140:143], v[206:209], v[88:91]
	v_mfma_f32_16x16x32_bf16 v[76:79], v[132:135], v[214:217], v[76:79]
	v_mfma_f32_16x16x32_bf16 v[72:75], v[140:143], v[214:217], v[72:75]
	v_mfma_f32_16x16x32_bf16 v[116:119], v[154:157], v[186:189], v[116:119]
	v_mfma_f32_16x16x32_bf16 v[112:115], v[166:169], v[186:189], v[112:115]
	v_mfma_f32_16x16x32_bf16 v[100:103], v[154:157], v[194:197], v[100:103]
	v_mfma_f32_16x16x32_bf16 v[96:99], v[166:169], v[194:197], v[96:99]
	v_mfma_f32_16x16x32_bf16 v[84:87], v[154:157], v[202:205], v[84:87]
	v_mfma_f32_16x16x32_bf16 v[80:83], v[166:169], v[202:205], v[80:83]
	v_mfma_f32_16x16x32_bf16 v[68:71], v[154:157], v[210:213], v[68:71]
	v_mfma_f32_16x16x32_bf16 v[64:67], v[166:169], v[210:213], v[64:67]
	v_mfma_f32_16x16x32_bf16 v[116:119], v[158:161], v[190:193], v[116:119]
	v_mfma_f32_16x16x32_bf16 v[112:115], v[170:173], v[190:193], v[112:115]
	v_mfma_f32_16x16x32_bf16 v[100:103], v[158:161], v[198:201], v[100:103]
	v_mfma_f32_16x16x32_bf16 v[96:99], v[170:173], v[198:201], v[96:99]
	v_mfma_f32_16x16x32_bf16 v[84:87], v[158:161], v[206:209], v[84:87]
	v_mfma_f32_16x16x32_bf16 v[80:83], v[170:173], v[206:209], v[80:83]
	v_mfma_f32_16x16x32_bf16 v[68:71], v[158:161], v[214:217], v[68:71]
	v_mfma_f32_16x16x32_bf16 v[64:67], v[170:173], v[214:217], v[64:67]
	s_barrier
	s_add_i32 s45, s45, s37
	v_lshl_add_u64 v[174:175], s[4:5], 0, v[176:177]
	s_mov_b32 m0, s45
	ds_read_b128 v[186:189], v165 offset:16384
	ds_read_b128 v[190:193], v165 offset:17408
	ds_read_b128 v[194:197], v165 offset:18432
	ds_read_b128 v[198:201], v165 offset:19456
	ds_read_b128 v[202:205], v165 offset:20480
	ds_read_b128 v[206:209], v165 offset:21504
	ds_read_b128 v[210:213], v165 offset:22528
	ds_read_b128 v[214:217], v165 offset:23552
	global_load_lds_dwordx4 v[174:175], off
	s_add_i32 m0, s45, 0x2000
	v_lshl_add_u64 v[222:223], s[4:5], 0, v[144:145]
	s_add_u32 s4, s4, s0
	s_addc_u32 s5, s5, s1
	s_add_i32 s45, s54, s37
	global_load_lds_dwordx4 v[222:223], off
	v_lshl_add_u64 v[224:225], s[4:5], 0, v[176:177]
	s_mov_b32 m0, s45
	v_lshl_add_u64 v[226:227], s[4:5], 0, v[144:145]
	global_load_lds_dwordx4 v[224:225], off
	s_add_i32 m0, s45, 0x2000
	v_lshl_add_u64 v[228:229], s[34:35], 0, v[148:149]
	global_load_lds_dwordx4 v[226:227], off
	s_mov_b32 m0, s38
	v_lshl_add_u64 v[230:231], s[34:35], 0, v[146:147]
	global_load_lds_dwordx4 v[228:229], off
	s_mov_b32 m0, s39
	s_nop 0
	global_load_lds_dwordx4 v[230:231], off
	s_waitcnt vmcnt(8)
	s_waitcnt lgkmcnt(0)
	s_barrier
	s_waitcnt lgkmcnt(0)
	v_mfma_f32_16x16x32_bf16 v[60:63], v[128:131], v[186:189], v[60:63]
	v_mfma_f32_16x16x32_bf16 v[56:59], v[136:139], v[186:189], v[56:59]
	v_mfma_f32_16x16x32_bf16 v[44:47], v[128:131], v[194:197], v[44:47]
	v_mfma_f32_16x16x32_bf16 v[40:43], v[136:139], v[194:197], v[40:43]
	v_mfma_f32_16x16x32_bf16 v[28:31], v[128:131], v[202:205], v[28:31]
	v_mfma_f32_16x16x32_bf16 v[24:27], v[136:139], v[202:205], v[24:27]
	v_mfma_f32_16x16x32_bf16 v[12:15], v[128:131], v[210:213], v[12:15]
	v_mfma_f32_16x16x32_bf16 v[8:11], v[136:139], v[210:213], v[8:11]
	v_mfma_f32_16x16x32_bf16 v[60:63], v[132:135], v[190:193], v[60:63]
	v_mfma_f32_16x16x32_bf16 v[56:59], v[140:143], v[190:193], v[56:59]
	v_mfma_f32_16x16x32_bf16 v[44:47], v[132:135], v[198:201], v[44:47]
	v_mfma_f32_16x16x32_bf16 v[40:43], v[140:143], v[198:201], v[40:43]
	v_mfma_f32_16x16x32_bf16 v[28:31], v[132:135], v[206:209], v[28:31]
	v_mfma_f32_16x16x32_bf16 v[24:27], v[140:143], v[206:209], v[24:27]
	v_mfma_f32_16x16x32_bf16 v[12:15], v[132:135], v[214:217], v[12:15]
	v_mfma_f32_16x16x32_bf16 v[8:11], v[140:143], v[214:217], v[8:11]
	v_mfma_f32_16x16x32_bf16 v[52:55], v[154:157], v[186:189], v[52:55]
	v_mfma_f32_16x16x32_bf16 v[48:51], v[166:169], v[186:189], v[48:51]
	v_mfma_f32_16x16x32_bf16 v[36:39], v[154:157], v[194:197], v[36:39]
	v_mfma_f32_16x16x32_bf16 v[32:35], v[166:169], v[194:197], v[32:35]
	v_mfma_f32_16x16x32_bf16 v[20:23], v[154:157], v[202:205], v[20:23]
	v_mfma_f32_16x16x32_bf16 v[16:19], v[166:169], v[202:205], v[16:19]
	v_mfma_f32_16x16x32_bf16 v[4:7], v[154:157], v[210:213], v[4:7]
	v_mfma_f32_16x16x32_bf16 v[0:3], v[166:169], v[210:213], v[0:3]
	v_mfma_f32_16x16x32_bf16 v[52:55], v[158:161], v[190:193], v[52:55]
	v_mfma_f32_16x16x32_bf16 v[48:51], v[170:173], v[190:193], v[48:51]
	v_mfma_f32_16x16x32_bf16 v[36:39], v[158:161], v[198:201], v[36:39]
	v_mfma_f32_16x16x32_bf16 v[32:35], v[170:173], v[198:201], v[32:35]
	v_mfma_f32_16x16x32_bf16 v[20:23], v[158:161], v[206:209], v[20:23]
	v_mfma_f32_16x16x32_bf16 v[16:19], v[170:173], v[206:209], v[16:19]
	v_mfma_f32_16x16x32_bf16 v[4:7], v[158:161], v[214:217], v[4:7]
	v_mfma_f32_16x16x32_bf16 v[0:3], v[170:173], v[214:217], v[0:3]
	s_barrier
	s_add_i32 s45, 0, 0x18000
	s_add_i32 s54, 0, 0x1c000
	v_add_u32_e32 v140, s45, v163
	v_add_u32_e32 v170, s54, v163
	ds_read_b128 v[128:131], v140
	ds_read_b128 v[132:135], v140 offset:1024
	ds_read_b128 v[136:139], v140 offset:2048
	ds_read_b128 v[140:143], v140 offset:3072
	ds_read_b128 v[154:157], v170
	ds_read_b128 v[158:161], v170 offset:1024
	ds_read_b128 v[166:169], v170 offset:2048
	ds_read_b128 v[170:173], v170 offset:3072
	s_add_u32 s4, s34, s0
	s_addc_u32 s5, s35, s1
	s_mov_b32 m0, s48
	v_lshl_add_u64 v[232:233], s[4:5], 0, v[148:149]
	ds_read_b128 v[186:189], v165 offset:32768
	ds_read_b128 v[190:193], v165 offset:33792
	ds_read_b128 v[194:197], v165 offset:34816
	ds_read_b128 v[198:201], v165 offset:35840
	ds_read_b128 v[202:205], v165 offset:36864
	ds_read_b128 v[206:209], v165 offset:37888
	ds_read_b128 v[210:213], v165 offset:38912
	ds_read_b128 v[214:217], v165 offset:39936
	global_load_lds_dwordx4 v[232:233], off
	v_lshl_add_u64 v[232:233], s[4:5], 0, v[146:147]
	s_mov_b32 m0, s49
	s_nop 0
	global_load_lds_dwordx4 v[232:233], off
	s_waitcnt vmcnt(8)
	s_waitcnt lgkmcnt(0)
	s_barrier
	s_waitcnt lgkmcnt(0)
	v_mfma_f32_16x16x32_bf16 v[124:127], v[128:131], v[186:189], v[124:127]
	v_mfma_f32_16x16x32_bf16 v[120:123], v[136:139], v[186:189], v[120:123]
	v_mfma_f32_16x16x32_bf16 v[108:111], v[128:131], v[194:197], v[108:111]
	v_mfma_f32_16x16x32_bf16 v[104:107], v[136:139], v[194:197], v[104:107]
	v_mfma_f32_16x16x32_bf16 v[92:95], v[128:131], v[202:205], v[92:95]
	v_mfma_f32_16x16x32_bf16 v[88:91], v[136:139], v[202:205], v[88:91]
	v_mfma_f32_16x16x32_bf16 v[76:79], v[128:131], v[210:213], v[76:79]
	v_mfma_f32_16x16x32_bf16 v[72:75], v[136:139], v[210:213], v[72:75]
	v_mfma_f32_16x16x32_bf16 v[124:127], v[132:135], v[190:193], v[124:127]
	v_mfma_f32_16x16x32_bf16 v[120:123], v[140:143], v[190:193], v[120:123]
	v_mfma_f32_16x16x32_bf16 v[108:111], v[132:135], v[198:201], v[108:111]
	v_mfma_f32_16x16x32_bf16 v[104:107], v[140:143], v[198:201], v[104:107]
	v_mfma_f32_16x16x32_bf16 v[92:95], v[132:135], v[206:209], v[92:95]
	v_mfma_f32_16x16x32_bf16 v[88:91], v[140:143], v[206:209], v[88:91]
	v_mfma_f32_16x16x32_bf16 v[76:79], v[132:135], v[214:217], v[76:79]
	v_mfma_f32_16x16x32_bf16 v[72:75], v[140:143], v[214:217], v[72:75]
	v_mfma_f32_16x16x32_bf16 v[116:119], v[154:157], v[186:189], v[116:119]
	v_mfma_f32_16x16x32_bf16 v[112:115], v[166:169], v[186:189], v[112:115]
	v_mfma_f32_16x16x32_bf16 v[100:103], v[154:157], v[194:197], v[100:103]
	v_mfma_f32_16x16x32_bf16 v[96:99], v[166:169], v[194:197], v[96:99]
	v_mfma_f32_16x16x32_bf16 v[84:87], v[154:157], v[202:205], v[84:87]
	v_mfma_f32_16x16x32_bf16 v[80:83], v[166:169], v[202:205], v[80:83]
	v_mfma_f32_16x16x32_bf16 v[68:71], v[154:157], v[210:213], v[68:71]
	v_mfma_f32_16x16x32_bf16 v[64:67], v[166:169], v[210:213], v[64:67]
	v_mfma_f32_16x16x32_bf16 v[116:119], v[158:161], v[190:193], v[116:119]
	v_mfma_f32_16x16x32_bf16 v[112:115], v[170:173], v[190:193], v[112:115]
	v_mfma_f32_16x16x32_bf16 v[100:103], v[158:161], v[198:201], v[100:103]
	v_mfma_f32_16x16x32_bf16 v[96:99], v[170:173], v[198:201], v[96:99]
	v_mfma_f32_16x16x32_bf16 v[84:87], v[158:161], v[206:209], v[84:87]
	v_mfma_f32_16x16x32_bf16 v[80:83], v[170:173], v[206:209], v[80:83]
	v_mfma_f32_16x16x32_bf16 v[68:71], v[158:161], v[214:217], v[68:71]
	v_mfma_f32_16x16x32_bf16 v[64:67], v[170:173], v[214:217], v[64:67]
	s_barrier
	s_add_i32 s4, s45, s37
	v_lshl_add_u64 v[174:175], v[174:175], 0, s[14:15]
	s_mov_b32 m0, s4
	ds_read_b128 v[186:189], v165 offset:49152
	ds_read_b128 v[190:193], v165 offset:50176
	ds_read_b128 v[194:197], v165 offset:51200
	ds_read_b128 v[198:201], v165 offset:52224
	ds_read_b128 v[202:205], v165 offset:53248
	ds_read_b128 v[206:209], v165 offset:54272
	ds_read_b128 v[210:213], v165 offset:55296
	ds_read_b128 v[214:217], v165 offset:56320
	global_load_lds_dwordx4 v[174:175], off
	v_lshl_add_u64 v[174:175], v[222:223], 0, s[14:15]
	s_add_i32 m0, s4, 0x2000
	s_add_i32 s4, s54, s37
	global_load_lds_dwordx4 v[174:175], off
	v_lshl_add_u64 v[174:175], v[224:225], 0, s[14:15]
	s_mov_b32 m0, s4
	s_nop 0
	global_load_lds_dwordx4 v[174:175], off
	v_lshl_add_u64 v[174:175], v[226:227], 0, s[14:15]
	s_add_i32 m0, s4, 0x2000
	s_nop 0
	global_load_lds_dwordx4 v[174:175], off
	v_lshl_add_u64 v[174:175], v[228:229], 0, s[14:15]
	s_mov_b32 m0, s60
	s_nop 0
	global_load_lds_dwordx4 v[174:175], off
	v_lshl_add_u64 v[174:175], v[230:231], 0, s[14:15]
	s_mov_b32 m0, s61
	s_nop 0
	global_load_lds_dwordx4 v[174:175], off
	s_waitcnt vmcnt(8)
	s_waitcnt lgkmcnt(0)
	s_barrier
	s_waitcnt lgkmcnt(0)
	v_mfma_f32_16x16x32_bf16 v[60:63], v[128:131], v[186:189], v[60:63]
	s_add_u32 s30, s30, 0x100
	v_mfma_f32_16x16x32_bf16 v[56:59], v[136:139], v[186:189], v[56:59]
	s_addc_u32 s31, s31, 0
	v_mfma_f32_16x16x32_bf16 v[44:47], v[128:131], v[194:197], v[44:47]
	s_add_u32 s10, s10, 0x100
	v_mfma_f32_16x16x32_bf16 v[40:43], v[136:139], v[194:197], v[40:43]
	s_addc_u32 s11, s11, 0
	v_mfma_f32_16x16x32_bf16 v[28:31], v[128:131], v[202:205], v[28:31]
	s_mov_b32 s34, s44
	v_mfma_f32_16x16x32_bf16 v[24:27], v[136:139], v[202:205], v[24:27]
	s_cmp_ge_i32 s44, s59
	v_mfma_f32_16x16x32_bf16 v[12:15], v[128:131], v[210:213], v[12:15]
	s_cselect_b32 s99, 1, 0
	v_readfirstlane_b32 s98, v218
	s_bfe_u32 s98, s98, 0x10008
	s_and_b32 s98, s98, s99
	v_mfma_f32_16x16x32_bf16 v[8:11], v[136:139], v[210:213], v[8:11]
	s_add_i32 s44, s34, 2
	v_mfma_f32_16x16x32_bf16 v[60:63], v[132:135], v[190:193], v[60:63]
	s_add_u32 s4, s30, 0x80
	v_mfma_f32_16x16x32_bf16 v[56:59], v[140:143], v[190:193], v[56:59]
	s_addc_u32 s5, s31, 0
	v_mfma_f32_16x16x32_bf16 v[44:47], v[132:135], v[198:201], v[44:47]
	s_add_i32 s45, 0, 0x10000
	v_mfma_f32_16x16x32_bf16 v[40:43], v[140:143], v[198:201], v[40:43]
	s_cmp_eq_u32 s62, s34
	v_mfma_f32_16x16x32_bf16 v[28:31], v[132:135], v[206:209], v[28:31]
	s_cselect_b32 s35, s27, s5
	v_mfma_f32_16x16x32_bf16 v[24:27], v[140:143], v[206:209], v[24:27]
	s_cselect_b32 s34, s26, s4
	v_mfma_f32_16x16x32_bf16 v[12:15], v[132:135], v[214:217], v[12:15]
	s_cselect_b32 s5, s29, s11
	v_mfma_f32_16x16x32_bf16 v[8:11], v[140:143], v[214:217], v[8:11]
	s_cselect_b32 s4, s28, s10
	v_mfma_f32_16x16x32_bf16 v[52:55], v[154:157], v[186:189], v[52:55]
	s_add_i32 s54, 0, 0x14000
	v_mfma_f32_16x16x32_bf16 v[48:51], v[166:169], v[186:189], v[48:51]
	v_mfma_f32_16x16x32_bf16 v[36:39], v[154:157], v[194:197], v[36:39]
	v_mfma_f32_16x16x32_bf16 v[32:35], v[166:169], v[194:197], v[32:35]
	v_mfma_f32_16x16x32_bf16 v[20:23], v[154:157], v[202:205], v[20:23]
	v_mfma_f32_16x16x32_bf16 v[16:19], v[166:169], v[202:205], v[16:19]
	v_mfma_f32_16x16x32_bf16 v[4:7], v[154:157], v[210:213], v[4:7]
	v_mfma_f32_16x16x32_bf16 v[0:3], v[166:169], v[210:213], v[0:3]
	v_mfma_f32_16x16x32_bf16 v[52:55], v[158:161], v[190:193], v[52:55]
	v_mfma_f32_16x16x32_bf16 v[48:51], v[170:173], v[190:193], v[48:51]
	v_mfma_f32_16x16x32_bf16 v[36:39], v[158:161], v[198:201], v[36:39]
	v_mfma_f32_16x16x32_bf16 v[32:35], v[170:173], v[198:201], v[32:35]
	v_mfma_f32_16x16x32_bf16 v[20:23], v[158:161], v[206:209], v[20:23]
	v_mfma_f32_16x16x32_bf16 v[16:19], v[170:173], v[206:209], v[16:19]
	v_mfma_f32_16x16x32_bf16 v[4:7], v[158:161], v[214:217], v[4:7]
	v_mfma_f32_16x16x32_bf16 v[0:3], v[170:173], v[214:217], v[0:3]
	s_cmp_lg_u32 s98, 0
	s_cbranch_scc1 .Lskf_6_loop
	s_barrier

.Lpeelx_6:
.LBB0_306:
	s_mov_b64 s[46:47], s[90:91]
	s_mov_b64 s[96:97], s[88:89]
	s_mov_b64 s[54:55], s[86:87]
	s_mov_b64 s[70:71], s[84:85]
	s_mov_b64 s[64:65], s[82:83]
	s_mov_b64 s[44:45], s[80:81]
	s_mov_b64 s[34:35], s[78:79]
	s_mov_b64 s[30:31], s[76:77]
	s_and_b64 vcc, exec, s[24:25]
	s_cbranch_vccz .LBB0_308
	s_nop 0

.LBB0_385:
	s_barrier
	s_andn2_b64 vcc, exec, s[10:11]
	s_mov_b32 s67, s63
	s_mov_b32 s68, s66
	s_mov_b64 s[30:31], s[26:27]
	s_mov_b64 s[28:29], s[24:25]
	s_cbranch_vccz .LBB0_404

.Llbb_3:
	s_add_i32 s44, s30, 2
	s_add_u32 s4, s28, 0x80
	s_addc_u32 s5, s29, 0
	s_add_i32 s45, 0, 0x10000
	s_cmp_eq_u32 s61, s30
	s_cselect_b32 s31, s25, s5
	s_cselect_b32 s30, s24, s4
	s_cselect_b32 s5, s27, s11
	s_cselect_b32 s4, s26, s10
	s_add_i32 s54, 0, 0x14000
	v_add_u32_e32 v156, s45, v151
	v_add_u32_e32 v172, s54, v151
	ds_read_b128 v[128:131], v156
	ds_read_b128 v[142:145], v156 offset:1024
	ds_read_b128 v[146:149], v156 offset:2048
	ds_read_b128 v[156:159], v156 offset:3072
	ds_read_b128 v[160:163], v172
	ds_read_b128 v[164:167], v172 offset:1024
	ds_read_b128 v[168:171], v172 offset:2048
	ds_read_b128 v[172:175], v172 offset:3072
	v_lshl_add_u64 v[222:223], s[28:29], 0, v[138:139]
	s_add_i32 m0, s37, 0xc000
	ds_read_b128 v[186:189], v155
	ds_read_b128 v[190:193], v155 offset:1024
	ds_read_b128 v[194:197], v155 offset:2048
	ds_read_b128 v[198:201], v155 offset:3072
	ds_read_b128 v[202:205], v155 offset:4096
	ds_read_b128 v[206:209], v155 offset:5120
	ds_read_b128 v[210:213], v155 offset:6144
	ds_read_b128 v[214:217], v155 offset:7168
	global_load_lds_dwordx4 v[222:223], off
	v_lshl_add_u64 v[222:223], s[28:29], 0, v[140:141]
	s_add_i32 m0, s37, 0xe000
	s_nop 0
	global_load_lds_dwordx4 v[222:223], off
	s_waitcnt vmcnt(8)
	s_waitcnt lgkmcnt(0)
	s_barrier
	s_waitcnt lgkmcnt(0)
	v_mfma_f32_16x16x32_bf16 v[120:123], v[128:131], v[186:189], 0
	v_mfma_f32_16x16x32_bf16 v[116:119], v[146:149], v[186:189], 0
	v_mfma_f32_16x16x32_bf16 v[108:111], v[128:131], v[194:197], 0
	v_mfma_f32_16x16x32_bf16 v[100:103], v[146:149], v[194:197], 0
	v_mfma_f32_16x16x32_bf16 v[92:95], v[128:131], v[202:205], 0
	v_mfma_f32_16x16x32_bf16 v[84:87], v[146:149], v[202:205], 0
	v_mfma_f32_16x16x32_bf16 v[76:79], v[128:131], v[210:213], 0
	v_mfma_f32_16x16x32_bf16 v[68:71], v[146:149], v[210:213], 0
	v_mfma_f32_16x16x32_bf16 v[120:123], v[142:145], v[190:193], v[120:123]
	v_mfma_f32_16x16x32_bf16 v[116:119], v[156:159], v[190:193], v[116:119]
	v_mfma_f32_16x16x32_bf16 v[108:111], v[142:145], v[198:201], v[108:111]
	v_mfma_f32_16x16x32_bf16 v[100:103], v[156:159], v[198:201], v[100:103]
	v_mfma_f32_16x16x32_bf16 v[92:95], v[142:145], v[206:209], v[92:95]
	v_mfma_f32_16x16x32_bf16 v[84:87], v[156:159], v[206:209], v[84:87]
	v_mfma_f32_16x16x32_bf16 v[76:79], v[142:145], v[214:217], v[76:79]
	v_mfma_f32_16x16x32_bf16 v[68:71], v[156:159], v[214:217], v[68:71]
	v_mfma_f32_16x16x32_bf16 v[124:127], v[160:163], v[186:189], 0
	v_mfma_f32_16x16x32_bf16 v[112:115], v[168:171], v[186:189], 0
	v_mfma_f32_16x16x32_bf16 v[104:107], v[160:163], v[194:197], 0
	v_mfma_f32_16x16x32_bf16 v[96:99], v[168:171], v[194:197], 0
	v_mfma_f32_16x16x32_bf16 v[88:91], v[160:163], v[202:205], 0
	v_mfma_f32_16x16x32_bf16 v[80:83], v[168:171], v[202:205], 0
	v_mfma_f32_16x16x32_bf16 v[72:75], v[160:163], v[210:213], 0
	v_mfma_f32_16x16x32_bf16 v[64:67], v[168:171], v[210:213], 0
	v_mfma_f32_16x16x32_bf16 v[124:127], v[164:167], v[190:193], v[124:127]
	v_mfma_f32_16x16x32_bf16 v[112:115], v[172:175], v[190:193], v[112:115]
	v_mfma_f32_16x16x32_bf16 v[104:107], v[164:167], v[198:201], v[104:107]
	v_mfma_f32_16x16x32_bf16 v[96:99], v[172:175], v[198:201], v[96:99]
	v_mfma_f32_16x16x32_bf16 v[88:91], v[164:167], v[206:209], v[88:91]
	v_mfma_f32_16x16x32_bf16 v[80:83], v[172:175], v[206:209], v[80:83]
	v_mfma_f32_16x16x32_bf16 v[72:75], v[164:167], v[214:217], v[72:75]
	v_mfma_f32_16x16x32_bf16 v[64:67], v[172:175], v[214:217], v[64:67]
	s_barrier
	s_add_i32 s45, s45, s36
	v_lshl_add_u64 v[222:223], s[4:5], 0, v[176:177]
	s_mov_b32 m0, s45
	ds_read_b128 v[186:189], v155 offset:16384
	ds_read_b128 v[190:193], v155 offset:17408
	ds_read_b128 v[194:197], v155 offset:18432
	ds_read_b128 v[198:201], v155 offset:19456
	ds_read_b128 v[202:205], v155 offset:20480
	ds_read_b128 v[206:209], v155 offset:21504
	ds_read_b128 v[210:213], v155 offset:22528
	ds_read_b128 v[214:217], v155 offset:23552
	global_load_lds_dwordx4 v[222:223], off
	s_add_i32 m0, s45, 0x2000
	v_lshl_add_u64 v[224:225], s[4:5], 0, v[132:133]
	s_add_u32 s4, s4, s6
	s_addc_u32 s5, s5, s7
	s_add_i32 s45, s54, s36
	global_load_lds_dwordx4 v[224:225], off
	v_lshl_add_u64 v[226:227], s[4:5], 0, v[176:177]
	s_mov_b32 m0, s45
	v_lshl_add_u64 v[228:229], s[4:5], 0, v[132:133]
	global_load_lds_dwordx4 v[226:227], off
	s_add_i32 m0, s45, 0x2000
	v_lshl_add_u64 v[230:231], s[30:31], 0, v[136:137]
	global_load_lds_dwordx4 v[228:229], off
	s_mov_b32 m0, s37
	v_lshl_add_u64 v[232:233], s[30:31], 0, v[134:135]
	global_load_lds_dwordx4 v[230:231], off
	s_mov_b32 m0, s38
	s_nop 0
	global_load_lds_dwordx4 v[232:233], off
	s_waitcnt vmcnt(8)
	s_waitcnt lgkmcnt(0)
	s_barrier
	s_waitcnt lgkmcnt(0)
	v_mfma_f32_16x16x32_bf16 v[60:63], v[128:131], v[186:189], 0
	v_mfma_f32_16x16x32_bf16 v[52:55], v[146:149], v[186:189], 0
	v_mfma_f32_16x16x32_bf16 v[44:47], v[128:131], v[194:197], 0
	v_mfma_f32_16x16x32_bf16 v[36:39], v[146:149], v[194:197], 0
	v_mfma_f32_16x16x32_bf16 v[28:31], v[128:131], v[202:205], 0
	v_mfma_f32_16x16x32_bf16 v[20:23], v[146:149], v[202:205], 0
	v_mfma_f32_16x16x32_bf16 v[12:15], v[128:131], v[210:213], 0
	v_mfma_f32_16x16x32_bf16 v[4:7], v[146:149], v[210:213], 0
	v_mfma_f32_16x16x32_bf16 v[60:63], v[142:145], v[190:193], v[60:63]
	v_mfma_f32_16x16x32_bf16 v[52:55], v[156:159], v[190:193], v[52:55]
	v_mfma_f32_16x16x32_bf16 v[44:47], v[142:145], v[198:201], v[44:47]
	v_mfma_f32_16x16x32_bf16 v[36:39], v[156:159], v[198:201], v[36:39]
	v_mfma_f32_16x16x32_bf16 v[28:31], v[142:145], v[206:209], v[28:31]
	v_mfma_f32_16x16x32_bf16 v[20:23], v[156:159], v[206:209], v[20:23]
	v_mfma_f32_16x16x32_bf16 v[12:15], v[142:145], v[214:217], v[12:15]
	v_mfma_f32_16x16x32_bf16 v[4:7], v[156:159], v[214:217], v[4:7]
	v_mfma_f32_16x16x32_bf16 v[56:59], v[160:163], v[186:189], 0
	v_mfma_f32_16x16x32_bf16 v[48:51], v[168:171], v[186:189], 0
	v_mfma_f32_16x16x32_bf16 v[40:43], v[160:163], v[194:197], 0
	v_mfma_f32_16x16x32_bf16 v[32:35], v[168:171], v[194:197], 0
	v_mfma_f32_16x16x32_bf16 v[24:27], v[160:163], v[202:205], 0
	v_mfma_f32_16x16x32_bf16 v[16:19], v[168:171], v[202:205], 0
	v_mfma_f32_16x16x32_bf16 v[8:11], v[160:163], v[210:213], 0
	v_mfma_f32_16x16x32_bf16 v[0:3], v[168:171], v[210:213], 0
	v_mfma_f32_16x16x32_bf16 v[56:59], v[164:167], v[190:193], v[56:59]
	v_mfma_f32_16x16x32_bf16 v[48:51], v[172:175], v[190:193], v[48:51]
	v_mfma_f32_16x16x32_bf16 v[40:43], v[164:167], v[198:201], v[40:43]
	v_mfma_f32_16x16x32_bf16 v[32:35], v[172:175], v[198:201], v[32:35]
	v_mfma_f32_16x16x32_bf16 v[24:27], v[164:167], v[206:209], v[24:27]
	v_mfma_f32_16x16x32_bf16 v[16:19], v[172:175], v[206:209], v[16:19]
	v_mfma_f32_16x16x32_bf16 v[8:11], v[164:167], v[214:217], v[8:11]
	v_mfma_f32_16x16x32_bf16 v[0:3], v[172:175], v[214:217], v[0:3]
	s_barrier
	s_add_i32 s45, 0, 0x18000
	s_add_i32 s54, 0, 0x1c000
	v_add_u32_e32 v156, s45, v151
	v_add_u32_e32 v172, s54, v151
	ds_read_b128 v[128:131], v156
	ds_read_b128 v[142:145], v156 offset:1024
	ds_read_b128 v[146:149], v156 offset:2048
	ds_read_b128 v[156:159], v156 offset:3072
	ds_read_b128 v[160:163], v172
	ds_read_b128 v[164:167], v172 offset:1024
	ds_read_b128 v[168:171], v172 offset:2048
	ds_read_b128 v[172:175], v172 offset:3072
	s_add_u32 s4, s30, s6
	s_addc_u32 s5, s31, s7
	s_mov_b32 m0, s39
	v_lshl_add_u64 v[234:235], s[4:5], 0, v[136:137]
	ds_read_b128 v[186:189], v155 offset:32768
	ds_read_b128 v[190:193], v155 offset:33792
	ds_read_b128 v[194:197], v155 offset:34816
	ds_read_b128 v[198:201], v155 offset:35840
	ds_read_b128 v[202:205], v155 offset:36864
	ds_read_b128 v[206:209], v155 offset:37888
	ds_read_b128 v[210:213], v155 offset:38912
	ds_read_b128 v[214:217], v155 offset:39936
	global_load_lds_dwordx4 v[234:235], off
	v_lshl_add_u64 v[234:235], s[4:5], 0, v[134:135]
	s_mov_b32 m0, s48
	s_nop 0
	global_load_lds_dwordx4 v[234:235], off
	s_waitcnt vmcnt(8)
	s_waitcnt lgkmcnt(0)
	s_barrier
	s_waitcnt lgkmcnt(0)
	v_mfma_f32_16x16x32_bf16 v[120:123], v[128:131], v[186:189], v[120:123]
	v_mfma_f32_16x16x32_bf16 v[116:119], v[146:149], v[186:189], v[116:119]
	v_mfma_f32_16x16x32_bf16 v[108:111], v[128:131], v[194:197], v[108:111]
	v_mfma_f32_16x16x32_bf16 v[100:103], v[146:149], v[194:197], v[100:103]
	v_mfma_f32_16x16x32_bf16 v[92:95], v[128:131], v[202:205], v[92:95]
	v_mfma_f32_16x16x32_bf16 v[84:87], v[146:149], v[202:205], v[84:87]
	v_mfma_f32_16x16x32_bf16 v[76:79], v[128:131], v[210:213], v[76:79]
	v_mfma_f32_16x16x32_bf16 v[68:71], v[146:149], v[210:213], v[68:71]
	v_mfma_f32_16x16x32_bf16 v[120:123], v[142:145], v[190:193], v[120:123]
	v_mfma_f32_16x16x32_bf16 v[116:119], v[156:159], v[190:193], v[116:119]
	v_mfma_f32_16x16x32_bf16 v[108:111], v[142:145], v[198:201], v[108:111]
	v_mfma_f32_16x16x32_bf16 v[100:103], v[156:159], v[198:201], v[100:103]
	v_mfma_f32_16x16x32_bf16 v[92:95], v[142:145], v[206:209], v[92:95]
	v_mfma_f32_16x16x32_bf16 v[84:87], v[156:159], v[206:209], v[84:87]
	v_mfma_f32_16x16x32_bf16 v[76:79], v[142:145], v[214:217], v[76:79]
	v_mfma_f32_16x16x32_bf16 v[68:71], v[156:159], v[214:217], v[68:71]
	v_mfma_f32_16x16x32_bf16 v[124:127], v[160:163], v[186:189], v[124:127]
	v_mfma_f32_16x16x32_bf16 v[112:115], v[168:171], v[186:189], v[112:115]
	v_mfma_f32_16x16x32_bf16 v[104:107], v[160:163], v[194:197], v[104:107]
	v_mfma_f32_16x16x32_bf16 v[96:99], v[168:171], v[194:197], v[96:99]
	v_mfma_f32_16x16x32_bf16 v[88:91], v[160:163], v[202:205], v[88:91]
	v_mfma_f32_16x16x32_bf16 v[80:83], v[168:171], v[202:205], v[80:83]
	v_mfma_f32_16x16x32_bf16 v[72:75], v[160:163], v[210:213], v[72:75]
	v_mfma_f32_16x16x32_bf16 v[64:67], v[168:171], v[210:213], v[64:67]
	v_mfma_f32_16x16x32_bf16 v[124:127], v[164:167], v[190:193], v[124:127]
	v_mfma_f32_16x16x32_bf16 v[112:115], v[172:175], v[190:193], v[112:115]
	v_mfma_f32_16x16x32_bf16 v[104:107], v[164:167], v[198:201], v[104:107]
	v_mfma_f32_16x16x32_bf16 v[96:99], v[172:175], v[198:201], v[96:99]
	v_mfma_f32_16x16x32_bf16 v[88:91], v[164:167], v[206:209], v[88:91]
	v_mfma_f32_16x16x32_bf16 v[80:83], v[172:175], v[206:209], v[80:83]
	v_mfma_f32_16x16x32_bf16 v[72:75], v[164:167], v[214:217], v[72:75]
	v_mfma_f32_16x16x32_bf16 v[64:67], v[172:175], v[214:217], v[64:67]
	s_barrier
	s_add_i32 s4, s45, s36
	v_lshl_add_u64 v[222:223], v[222:223], 0, s[14:15]
	s_mov_b32 m0, s4
	ds_read_b128 v[186:189], v155 offset:49152
	ds_read_b128 v[190:193], v155 offset:50176
	ds_read_b128 v[194:197], v155 offset:51200
	ds_read_b128 v[198:201], v155 offset:52224
	ds_read_b128 v[202:205], v155 offset:53248
	ds_read_b128 v[206:209], v155 offset:54272
	ds_read_b128 v[210:213], v155 offset:55296
	ds_read_b128 v[214:217], v155 offset:56320
	global_load_lds_dwordx4 v[222:223], off
	v_lshl_add_u64 v[222:223], v[224:225], 0, s[14:15]
	s_add_i32 m0, s4, 0x2000
	s_add_i32 s4, s54, s36
	global_load_lds_dwordx4 v[222:223], off
	v_lshl_add_u64 v[222:223], v[226:227], 0, s[14:15]
	s_mov_b32 m0, s4
	s_nop 0
	global_load_lds_dwordx4 v[222:223], off
	v_lshl_add_u64 v[222:223], v[228:229], 0, s[14:15]
	s_add_i32 m0, s4, 0x2000
	s_nop 0
	global_load_lds_dwordx4 v[222:223], off
	v_lshl_add_u64 v[222:223], v[230:231], 0, s[14:15]
	s_mov_b32 m0, s59
	s_nop 0
	global_load_lds_dwordx4 v[222:223], off
	v_lshl_add_u64 v[222:223], v[232:233], 0, s[14:15]
	s_mov_b32 m0, s60
	s_nop 0
	global_load_lds_dwordx4 v[222:223], off
	s_waitcnt vmcnt(8)
	s_waitcnt lgkmcnt(0)
	s_barrier
	s_waitcnt lgkmcnt(0)
	v_mfma_f32_16x16x32_bf16 v[60:63], v[128:131], v[186:189], v[60:63]
	s_add_u32 s28, s28, 0x100
	v_mfma_f32_16x16x32_bf16 v[52:55], v[146:149], v[186:189], v[52:55]
	s_addc_u32 s29, s29, 0
	v_mfma_f32_16x16x32_bf16 v[44:47], v[128:131], v[194:197], v[44:47]
	s_add_u32 s10, s10, 0x100
	v_mfma_f32_16x16x32_bf16 v[36:39], v[146:149], v[194:197], v[36:39]
	s_addc_u32 s11, s11, 0
	v_mfma_f32_16x16x32_bf16 v[28:31], v[128:131], v[202:205], v[28:31]
	s_mov_b32 s30, s44
	v_mfma_f32_16x16x32_bf16 v[20:23], v[146:149], v[202:205], v[20:23]
	s_cmp_ge_i32 s44, s49
	v_mfma_f32_16x16x32_bf16 v[12:15], v[128:131], v[210:213], v[12:15]
	s_cselect_b32 s99, 1, 0
	v_readfirstlane_b32 s98, v218
	s_bfe_u32 s98, s98, 0x10008
	s_and_b32 s98, s98, s99
	v_mfma_f32_16x16x32_bf16 v[4:7], v[146:149], v[210:213], v[4:7]
	s_add_i32 s44, s30, 2
	v_mfma_f32_16x16x32_bf16 v[60:63], v[142:145], v[190:193], v[60:63]
	s_add_u32 s4, s28, 0x80
	v_mfma_f32_16x16x32_bf16 v[52:55], v[156:159], v[190:193], v[52:55]
	s_addc_u32 s5, s29, 0
	v_mfma_f32_16x16x32_bf16 v[44:47], v[142:145], v[198:201], v[44:47]
	s_add_i32 s45, 0, 0x10000
	v_mfma_f32_16x16x32_bf16 v[36:39], v[156:159], v[198:201], v[36:39]
	s_cmp_eq_u32 s61, s30
	v_mfma_f32_16x16x32_bf16 v[28:31], v[142:145], v[206:209], v[28:31]
	s_cselect_b32 s31, s25, s5
	v_mfma_f32_16x16x32_bf16 v[20:23], v[156:159], v[206:209], v[20:23]
	s_cselect_b32 s30, s24, s4
	v_mfma_f32_16x16x32_bf16 v[12:15], v[142:145], v[214:217], v[12:15]
	s_cselect_b32 s5, s27, s11
	v_mfma_f32_16x16x32_bf16 v[4:7], v[156:159], v[214:217], v[4:7]
	s_cselect_b32 s4, s26, s10
	v_mfma_f32_16x16x32_bf16 v[56:59], v[160:163], v[186:189], v[56:59]
	s_add_i32 s54, 0, 0x14000
	v_mfma_f32_16x16x32_bf16 v[48:51], v[168:171], v[186:189], v[48:51]
	v_mfma_f32_16x16x32_bf16 v[40:43], v[160:163], v[194:197], v[40:43]
	v_mfma_f32_16x16x32_bf16 v[32:35], v[168:171], v[194:197], v[32:35]
	v_mfma_f32_16x16x32_bf16 v[24:27], v[160:163], v[202:205], v[24:27]
	v_mfma_f32_16x16x32_bf16 v[16:19], v[168:171], v[202:205], v[16:19]
	v_mfma_f32_16x16x32_bf16 v[8:11], v[160:163], v[210:213], v[8:11]
	v_mfma_f32_16x16x32_bf16 v[0:3], v[168:171], v[210:213], v[0:3]
	v_mfma_f32_16x16x32_bf16 v[56:59], v[164:167], v[190:193], v[56:59]
	v_mfma_f32_16x16x32_bf16 v[48:51], v[172:175], v[190:193], v[48:51]
	v_mfma_f32_16x16x32_bf16 v[40:43], v[164:167], v[198:201], v[40:43]
	v_mfma_f32_16x16x32_bf16 v[32:35], v[172:175], v[198:201], v[32:35]
	v_mfma_f32_16x16x32_bf16 v[24:27], v[164:167], v[206:209], v[24:27]
	v_mfma_f32_16x16x32_bf16 v[16:19], v[172:175], v[206:209], v[16:19]
	v_mfma_f32_16x16x32_bf16 v[8:11], v[164:167], v[214:217], v[8:11]
	v_mfma_f32_16x16x32_bf16 v[0:3], v[172:175], v[214:217], v[0:3]
	s_cmp_lg_u32 s98, 0
	s_cbranch_scc1 .Lskf_7_peel
	s_barrier

.LBB0_394:
	v_add_u32_e32 v156, s45, v151
	v_add_u32_e32 v172, s54, v151
	ds_read_b128 v[128:131], v156
	ds_read_b128 v[142:145], v156 offset:1024
	ds_read_b128 v[146:149], v156 offset:2048
	ds_read_b128 v[156:159], v156 offset:3072
	ds_read_b128 v[160:163], v172
	ds_read_b128 v[164:167], v172 offset:1024
	ds_read_b128 v[168:171], v172 offset:2048
	ds_read_b128 v[172:175], v172 offset:3072
	v_lshl_add_u64 v[222:223], s[28:29], 0, v[138:139]
	s_add_i32 m0, s37, 0xc000
	ds_read_b128 v[186:189], v155
	ds_read_b128 v[190:193], v155 offset:1024
	ds_read_b128 v[194:197], v155 offset:2048
	ds_read_b128 v[198:201], v155 offset:3072
	ds_read_b128 v[202:205], v155 offset:4096
	ds_read_b128 v[206:209], v155 offset:5120
	ds_read_b128 v[210:213], v155 offset:6144
	ds_read_b128 v[214:217], v155 offset:7168
	global_load_lds_dwordx4 v[222:223], off
	v_lshl_add_u64 v[222:223], s[28:29], 0, v[140:141]
	s_add_i32 m0, s37, 0xe000
	s_nop 0
	global_load_lds_dwordx4 v[222:223], off
	s_waitcnt vmcnt(8)
	s_waitcnt lgkmcnt(0)
	s_barrier
	s_waitcnt lgkmcnt(0)
	v_mfma_f32_16x16x32_bf16 v[120:123], v[128:131], v[186:189], v[120:123]
	v_mfma_f32_16x16x32_bf16 v[116:119], v[146:149], v[186:189], v[116:119]
	v_mfma_f32_16x16x32_bf16 v[108:111], v[128:131], v[194:197], v[108:111]
	v_mfma_f32_16x16x32_bf16 v[100:103], v[146:149], v[194:197], v[100:103]
	v_mfma_f32_16x16x32_bf16 v[92:95], v[128:131], v[202:205], v[92:95]
	v_mfma_f32_16x16x32_bf16 v[84:87], v[146:149], v[202:205], v[84:87]
	v_mfma_f32_16x16x32_bf16 v[76:79], v[128:131], v[210:213], v[76:79]
	v_mfma_f32_16x16x32_bf16 v[68:71], v[146:149], v[210:213], v[68:71]
	v_mfma_f32_16x16x32_bf16 v[120:123], v[142:145], v[190:193], v[120:123]
	v_mfma_f32_16x16x32_bf16 v[116:119], v[156:159], v[190:193], v[116:119]
	v_mfma_f32_16x16x32_bf16 v[108:111], v[142:145], v[198:201], v[108:111]
	v_mfma_f32_16x16x32_bf16 v[100:103], v[156:159], v[198:201], v[100:103]
	v_mfma_f32_16x16x32_bf16 v[92:95], v[142:145], v[206:209], v[92:95]
	v_mfma_f32_16x16x32_bf16 v[84:87], v[156:159], v[206:209], v[84:87]
	v_mfma_f32_16x16x32_bf16 v[76:79], v[142:145], v[214:217], v[76:79]
	v_mfma_f32_16x16x32_bf16 v[68:71], v[156:159], v[214:217], v[68:71]
	v_mfma_f32_16x16x32_bf16 v[124:127], v[160:163], v[186:189], v[124:127]
	v_mfma_f32_16x16x32_bf16 v[112:115], v[168:171], v[186:189], v[112:115]
	v_mfma_f32_16x16x32_bf16 v[104:107], v[160:163], v[194:197], v[104:107]
	v_mfma_f32_16x16x32_bf16 v[96:99], v[168:171], v[194:197], v[96:99]
	v_mfma_f32_16x16x32_bf16 v[88:91], v[160:163], v[202:205], v[88:91]
	v_mfma_f32_16x16x32_bf16 v[80:83], v[168:171], v[202:205], v[80:83]
	v_mfma_f32_16x16x32_bf16 v[72:75], v[160:163], v[210:213], v[72:75]
	v_mfma_f32_16x16x32_bf16 v[64:67], v[168:171], v[210:213], v[64:67]
	v_mfma_f32_16x16x32_bf16 v[124:127], v[164:167], v[190:193], v[124:127]
	v_mfma_f32_16x16x32_bf16 v[112:115], v[172:175], v[190:193], v[112:115]
	v_mfma_f32_16x16x32_bf16 v[104:107], v[164:167], v[198:201], v[104:107]
	v_mfma_f32_16x16x32_bf16 v[96:99], v[172:175], v[198:201], v[96:99]
	v_mfma_f32_16x16x32_bf16 v[88:91], v[164:167], v[206:209], v[88:91]
	v_mfma_f32_16x16x32_bf16 v[80:83], v[172:175], v[206:209], v[80:83]
	v_mfma_f32_16x16x32_bf16 v[72:75], v[164:167], v[214:217], v[72:75]
	v_mfma_f32_16x16x32_bf16 v[64:67], v[172:175], v[214:217], v[64:67]
	s_barrier
	s_add_i32 s45, s45, s36
	v_lshl_add_u64 v[222:223], s[4:5], 0, v[176:177]
	s_mov_b32 m0, s45
	ds_read_b128 v[186:189], v155 offset:16384
	ds_read_b128 v[190:193], v155 offset:17408
	ds_read_b128 v[194:197], v155 offset:18432
	ds_read_b128 v[198:201], v155 offset:19456
	ds_read_b128 v[202:205], v155 offset:20480
	ds_read_b128 v[206:209], v155 offset:21504
	ds_read_b128 v[210:213], v155 offset:22528
	ds_read_b128 v[214:217], v155 offset:23552
	global_load_lds_dwordx4 v[222:223], off
	s_add_i32 m0, s45, 0x2000
	v_lshl_add_u64 v[224:225], s[4:5], 0, v[132:133]
	s_add_u32 s4, s4, s6
	s_addc_u32 s5, s5, s7
	s_add_i32 s45, s54, s36
	global_load_lds_dwordx4 v[224:225], off
	v_lshl_add_u64 v[226:227], s[4:5], 0, v[176:177]
	s_mov_b32 m0, s45
	v_lshl_add_u64 v[228:229], s[4:5], 0, v[132:133]
	global_load_lds_dwordx4 v[226:227], off
	s_add_i32 m0, s45, 0x2000
	v_lshl_add_u64 v[230:231], s[30:31], 0, v[136:137]
	global_load_lds_dwordx4 v[228:229], off
	s_mov_b32 m0, s37
	v_lshl_add_u64 v[232:233], s[30:31], 0, v[134:135]
	global_load_lds_dwordx4 v[230:231], off
	s_mov_b32 m0, s38
	s_nop 0
	global_load_lds_dwordx4 v[232:233], off
	s_waitcnt vmcnt(8)
	s_waitcnt lgkmcnt(0)
	s_barrier
	s_waitcnt lgkmcnt(0)
	v_mfma_f32_16x16x32_bf16 v[60:63], v[128:131], v[186:189], v[60:63]
	v_mfma_f32_16x16x32_bf16 v[52:55], v[146:149], v[186:189], v[52:55]
	v_mfma_f32_16x16x32_bf16 v[44:47], v[128:131], v[194:197], v[44:47]
	v_mfma_f32_16x16x32_bf16 v[36:39], v[146:149], v[194:197], v[36:39]
	v_mfma_f32_16x16x32_bf16 v[28:31], v[128:131], v[202:205], v[28:31]
	v_mfma_f32_16x16x32_bf16 v[20:23], v[146:149], v[202:205], v[20:23]
	v_mfma_f32_16x16x32_bf16 v[12:15], v[128:131], v[210:213], v[12:15]
	v_mfma_f32_16x16x32_bf16 v[4:7], v[146:149], v[210:213], v[4:7]
	v_mfma_f32_16x16x32_bf16 v[60:63], v[142:145], v[190:193], v[60:63]
	v_mfma_f32_16x16x32_bf16 v[52:55], v[156:159], v[190:193], v[52:55]
	v_mfma_f32_16x16x32_bf16 v[44:47], v[142:145], v[198:201], v[44:47]
	v_mfma_f32_16x16x32_bf16 v[36:39], v[156:159], v[198:201], v[36:39]
	v_mfma_f32_16x16x32_bf16 v[28:31], v[142:145], v[206:209], v[28:31]
	v_mfma_f32_16x16x32_bf16 v[20:23], v[156:159], v[206:209], v[20:23]
	v_mfma_f32_16x16x32_bf16 v[12:15], v[142:145], v[214:217], v[12:15]
	v_mfma_f32_16x16x32_bf16 v[4:7], v[156:159], v[214:217], v[4:7]
	v_mfma_f32_16x16x32_bf16 v[56:59], v[160:163], v[186:189], v[56:59]
	v_mfma_f32_16x16x32_bf16 v[48:51], v[168:171], v[186:189], v[48:51]
	v_mfma_f32_16x16x32_bf16 v[40:43], v[160:163], v[194:197], v[40:43]
	v_mfma_f32_16x16x32_bf16 v[32:35], v[168:171], v[194:197], v[32:35]
	v_mfma_f32_16x16x32_bf16 v[24:27], v[160:163], v[202:205], v[24:27]
	v_mfma_f32_16x16x32_bf16 v[16:19], v[168:171], v[202:205], v[16:19]
	v_mfma_f32_16x16x32_bf16 v[8:11], v[160:163], v[210:213], v[8:11]
	v_mfma_f32_16x16x32_bf16 v[0:3], v[168:171], v[210:213], v[0:3]
	v_mfma_f32_16x16x32_bf16 v[56:59], v[164:167], v[190:193], v[56:59]
	v_mfma_f32_16x16x32_bf16 v[48:51], v[172:175], v[190:193], v[48:51]
	v_mfma_f32_16x16x32_bf16 v[40:43], v[164:167], v[198:201], v[40:43]
	v_mfma_f32_16x16x32_bf16 v[32:35], v[172:175], v[198:201], v[32:35]
	v_mfma_f32_16x16x32_bf16 v[24:27], v[164:167], v[206:209], v[24:27]
	v_mfma_f32_16x16x32_bf16 v[16:19], v[172:175], v[206:209], v[16:19]
	v_mfma_f32_16x16x32_bf16 v[8:11], v[164:167], v[214:217], v[8:11]
	v_mfma_f32_16x16x32_bf16 v[0:3], v[172:175], v[214:217], v[0:3]
	s_barrier
	s_add_i32 s45, 0, 0x18000
	s_add_i32 s54, 0, 0x1c000
	v_add_u32_e32 v156, s45, v151
	v_add_u32_e32 v172, s54, v151
	ds_read_b128 v[128:131], v156
	ds_read_b128 v[142:145], v156 offset:1024
	ds_read_b128 v[146:149], v156 offset:2048
	ds_read_b128 v[156:159], v156 offset:3072
	ds_read_b128 v[160:163], v172
	ds_read_b128 v[164:167], v172 offset:1024
	ds_read_b128 v[168:171], v172 offset:2048
	ds_read_b128 v[172:175], v172 offset:3072
	s_add_u32 s4, s30, s6
	s_addc_u32 s5, s31, s7
	s_mov_b32 m0, s39
	v_lshl_add_u64 v[234:235], s[4:5], 0, v[136:137]
	ds_read_b128 v[186:189], v155 offset:32768
	ds_read_b128 v[190:193], v155 offset:33792
	ds_read_b128 v[194:197], v155 offset:34816
	ds_read_b128 v[198:201], v155 offset:35840
	ds_read_b128 v[202:205], v155 offset:36864
	ds_read_b128 v[206:209], v155 offset:37888
	ds_read_b128 v[210:213], v155 offset:38912
	ds_read_b128 v[214:217], v155 offset:39936
	global_load_lds_dwordx4 v[234:235], off
	v_lshl_add_u64 v[234:235], s[4:5], 0, v[134:135]
	s_mov_b32 m0, s48
	s_nop 0
	global_load_lds_dwordx4 v[234:235], off
	s_waitcnt vmcnt(8)
	s_waitcnt lgkmcnt(0)
	s_barrier
	s_waitcnt lgkmcnt(0)
	v_mfma_f32_16x16x32_bf16 v[120:123], v[128:131], v[186:189], v[120:123]
	v_mfma_f32_16x16x32_bf16 v[116:119], v[146:149], v[186:189], v[116:119]
	v_mfma_f32_16x16x32_bf16 v[108:111], v[128:131], v[194:197], v[108:111]
	v_mfma_f32_16x16x32_bf16 v[100:103], v[146:149], v[194:197], v[100:103]
	v_mfma_f32_16x16x32_bf16 v[92:95], v[128:131], v[202:205], v[92:95]
	v_mfma_f32_16x16x32_bf16 v[84:87], v[146:149], v[202:205], v[84:87]
	v_mfma_f32_16x16x32_bf16 v[76:79], v[128:131], v[210:213], v[76:79]
	v_mfma_f32_16x16x32_bf16 v[68:71], v[146:149], v[210:213], v[68:71]
	v_mfma_f32_16x16x32_bf16 v[120:123], v[142:145], v[190:193], v[120:123]
	v_mfma_f32_16x16x32_bf16 v[116:119], v[156:159], v[190:193], v[116:119]
	v_mfma_f32_16x16x32_bf16 v[108:111], v[142:145], v[198:201], v[108:111]
	v_mfma_f32_16x16x32_bf16 v[100:103], v[156:159], v[198:201], v[100:103]
	v_mfma_f32_16x16x32_bf16 v[92:95], v[142:145], v[206:209], v[92:95]
	v_mfma_f32_16x16x32_bf16 v[84:87], v[156:159], v[206:209], v[84:87]
	v_mfma_f32_16x16x32_bf16 v[76:79], v[142:145], v[214:217], v[76:79]
	v_mfma_f32_16x16x32_bf16 v[68:71], v[156:159], v[214:217], v[68:71]
	v_mfma_f32_16x16x32_bf16 v[124:127], v[160:163], v[186:189], v[124:127]
	v_mfma_f32_16x16x32_bf16 v[112:115], v[168:171], v[186:189], v[112:115]
	v_mfma_f32_16x16x32_bf16 v[104:107], v[160:163], v[194:197], v[104:107]
	v_mfma_f32_16x16x32_bf16 v[96:99], v[168:171], v[194:197], v[96:99]
	v_mfma_f32_16x16x32_bf16 v[88:91], v[160:163], v[202:205], v[88:91]
	v_mfma_f32_16x16x32_bf16 v[80:83], v[168:171], v[202:205], v[80:83]
	v_mfma_f32_16x16x32_bf16 v[72:75], v[160:163], v[210:213], v[72:75]
	v_mfma_f32_16x16x32_bf16 v[64:67], v[168:171], v[210:213], v[64:67]
	v_mfma_f32_16x16x32_bf16 v[124:127], v[164:167], v[190:193], v[124:127]
	v_mfma_f32_16x16x32_bf16 v[112:115], v[172:175], v[190:193], v[112:115]
	v_mfma_f32_16x16x32_bf16 v[104:107], v[164:167], v[198:201], v[104:107]
	v_mfma_f32_16x16x32_bf16 v[96:99], v[172:175], v[198:201], v[96:99]
	v_mfma_f32_16x16x32_bf16 v[88:91], v[164:167], v[206:209], v[88:91]
	v_mfma_f32_16x16x32_bf16 v[80:83], v[172:175], v[206:209], v[80:83]
	v_mfma_f32_16x16x32_bf16 v[72:75], v[164:167], v[214:217], v[72:75]
	v_mfma_f32_16x16x32_bf16 v[64:67], v[172:175], v[214:217], v[64:67]
	s_barrier
	s_add_i32 s4, s45, s36
	v_lshl_add_u64 v[222:223], v[222:223], 0, s[14:15]
	s_mov_b32 m0, s4
	ds_read_b128 v[186:189], v155 offset:49152
	ds_read_b128 v[190:193], v155 offset:50176
	ds_read_b128 v[194:197], v155 offset:51200
	ds_read_b128 v[198:201], v155 offset:52224
	ds_read_b128 v[202:205], v155 offset:53248
	ds_read_b128 v[206:209], v155 offset:54272
	ds_read_b128 v[210:213], v155 offset:55296
	ds_read_b128 v[214:217], v155 offset:56320
	global_load_lds_dwordx4 v[222:223], off
	v_lshl_add_u64 v[222:223], v[224:225], 0, s[14:15]
	s_add_i32 m0, s4, 0x2000
	s_add_i32 s4, s54, s36
	global_load_lds_dwordx4 v[222:223], off
	v_lshl_add_u64 v[222:223], v[226:227], 0, s[14:15]
	s_mov_b32 m0, s4
	s_nop 0
	global_load_lds_dwordx4 v[222:223], off
	v_lshl_add_u64 v[222:223], v[228:229], 0, s[14:15]
	s_add_i32 m0, s4, 0x2000
	s_nop 0
	global_load_lds_dwordx4 v[222:223], off
	v_lshl_add_u64 v[222:223], v[230:231], 0, s[14:15]
	s_mov_b32 m0, s59
	s_nop 0
	global_load_lds_dwordx4 v[222:223], off
	v_lshl_add_u64 v[222:223], v[232:233], 0, s[14:15]
	s_mov_b32 m0, s60
	s_nop 0
	global_load_lds_dwordx4 v[222:223], off
	s_waitcnt vmcnt(8)
	s_waitcnt lgkmcnt(0)
	s_barrier
	s_waitcnt lgkmcnt(0)
	v_mfma_f32_16x16x32_bf16 v[60:63], v[128:131], v[186:189], v[60:63]
	s_add_u32 s28, s28, 0x100
	v_mfma_f32_16x16x32_bf16 v[52:55], v[146:149], v[186:189], v[52:55]
	s_addc_u32 s29, s29, 0
	v_mfma_f32_16x16x32_bf16 v[44:47], v[128:131], v[194:197], v[44:47]
	s_add_u32 s10, s10, 0x100
	v_mfma_f32_16x16x32_bf16 v[36:39], v[146:149], v[194:197], v[36:39]
	s_addc_u32 s11, s11, 0
	v_mfma_f32_16x16x32_bf16 v[28:31], v[128:131], v[202:205], v[28:31]
	s_mov_b32 s30, s44
	v_mfma_f32_16x16x32_bf16 v[20:23], v[146:149], v[202:205], v[20:23]
	s_cmp_ge_i32 s44, s49
	v_mfma_f32_16x16x32_bf16 v[12:15], v[128:131], v[210:213], v[12:15]
	s_cselect_b32 s99, 1, 0
	v_readfirstlane_b32 s98, v218
	s_bfe_u32 s98, s98, 0x10008
	s_and_b32 s98, s98, s99
	v_mfma_f32_16x16x32_bf16 v[4:7], v[146:149], v[210:213], v[4:7]
	s_add_i32 s44, s30, 2
	v_mfma_f32_16x16x32_bf16 v[60:63], v[142:145], v[190:193], v[60:63]
	s_add_u32 s4, s28, 0x80
	v_mfma_f32_16x16x32_bf16 v[52:55], v[156:159], v[190:193], v[52:55]
	s_addc_u32 s5, s29, 0
	v_mfma_f32_16x16x32_bf16 v[44:47], v[142:145], v[198:201], v[44:47]
	s_add_i32 s45, 0, 0x10000
	v_mfma_f32_16x16x32_bf16 v[36:39], v[156:159], v[198:201], v[36:39]
	s_cmp_eq_u32 s61, s30
	v_mfma_f32_16x16x32_bf16 v[28:31], v[142:145], v[206:209], v[28:31]
	s_cselect_b32 s31, s25, s5
	v_mfma_f32_16x16x32_bf16 v[20:23], v[156:159], v[206:209], v[20:23]
	s_cselect_b32 s30, s24, s4
	v_mfma_f32_16x16x32_bf16 v[12:15], v[142:145], v[214:217], v[12:15]
	s_cselect_b32 s5, s27, s11
	v_mfma_f32_16x16x32_bf16 v[4:7], v[156:159], v[214:217], v[4:7]
	s_cselect_b32 s4, s26, s10
	v_mfma_f32_16x16x32_bf16 v[56:59], v[160:163], v[186:189], v[56:59]
	s_add_i32 s54, 0, 0x14000
	v_mfma_f32_16x16x32_bf16 v[48:51], v[168:171], v[186:189], v[48:51]
	v_mfma_f32_16x16x32_bf16 v[40:43], v[160:163], v[194:197], v[40:43]
	v_mfma_f32_16x16x32_bf16 v[32:35], v[168:171], v[194:197], v[32:35]
	v_mfma_f32_16x16x32_bf16 v[24:27], v[160:163], v[202:205], v[24:27]
	v_mfma_f32_16x16x32_bf16 v[16:19], v[168:171], v[202:205], v[16:19]
	v_mfma_f32_16x16x32_bf16 v[8:11], v[160:163], v[210:213], v[8:11]
	v_mfma_f32_16x16x32_bf16 v[0:3], v[168:171], v[210:213], v[0:3]
	v_mfma_f32_16x16x32_bf16 v[56:59], v[164:167], v[190:193], v[56:59]
	v_mfma_f32_16x16x32_bf16 v[48:51], v[172:175], v[190:193], v[48:51]
	v_mfma_f32_16x16x32_bf16 v[40:43], v[164:167], v[198:201], v[40:43]
	v_mfma_f32_16x16x32_bf16 v[32:35], v[172:175], v[198:201], v[32:35]
	v_mfma_f32_16x16x32_bf16 v[24:27], v[164:167], v[206:209], v[24:27]
	v_mfma_f32_16x16x32_bf16 v[16:19], v[172:175], v[206:209], v[16:19]
	v_mfma_f32_16x16x32_bf16 v[8:11], v[164:167], v[214:217], v[8:11]
	v_mfma_f32_16x16x32_bf16 v[0:3], v[172:175], v[214:217], v[0:3]
	s_cmp_lg_u32 s98, 0
	s_cbranch_scc1 .Lskf_7_loop
	s_barrier

.Lpeelx_7:
.LBB0_395:
	s_and_b64 vcc, exec, s[22:23]
	s_cbranch_vccz .LBB0_397
	s_nop 0

.LBB0_462:
	s_barrier
	s_andn2_b64 vcc, exec, s[10:11]
	s_mov_b32 s16, s63
	s_mov_b32 s67, s66
	s_mov_b64 s[30:31], s[26:27]
	s_mov_b64 s[28:29], s[24:25]
	s_cbranch_vccz .LBB0_497

.Llbb_4:
	s_add_i32 s44, s30, 2
	s_add_u32 s4, s28, 0x80
	s_addc_u32 s5, s29, 0
	s_add_i32 s45, 0, 0x10000
	s_cmp_eq_u32 s61, s30
	s_cselect_b32 s31, s25, s5
	s_cselect_b32 s30, s24, s4
	s_cselect_b32 s5, s27, s11
	s_cselect_b32 s4, s26, s10
	s_add_i32 s54, 0, 0x14000
	v_add_u32_e32 v140, s45, v195
	v_add_u32_e32 v166, s54, v195
	ds_read_b128 v[128:131], v140
	ds_read_b128 v[132:135], v140 offset:1024
	ds_read_b128 v[136:139], v140 offset:2048
	ds_read_b128 v[140:143], v140 offset:3072
	ds_read_b128 v[144:147], v166
	ds_read_b128 v[148:151], v166 offset:1024
	ds_read_b128 v[152:155], v166 offset:2048
	ds_read_b128 v[166:169], v166 offset:3072
	v_lshl_add_u64 v[174:175], s[28:29], 0, v[162:163]
	s_add_i32 m0, s38, 0xc000
	ds_read_b128 v[170:173], v197
	ds_read_b128 v[186:189], v197 offset:1024
	ds_read_b128 v[190:193], v197 offset:2048
	ds_read_b128 v[198:201], v197 offset:3072
	ds_read_b128 v[202:205], v197 offset:4096
	ds_read_b128 v[206:209], v197 offset:5120
	ds_read_b128 v[210:213], v197 offset:6144
	ds_read_b128 v[214:217], v197 offset:7168
	global_load_lds_dwordx4 v[174:175], off
	v_lshl_add_u64 v[174:175], s[28:29], 0, v[164:165]
	s_add_i32 m0, s38, 0xe000
	s_nop 0
	global_load_lds_dwordx4 v[174:175], off
	s_waitcnt vmcnt(8)
	s_waitcnt lgkmcnt(0)
	s_barrier
	s_waitcnt lgkmcnt(0)
	v_mfma_f32_16x16x32_bf16 v[120:123], v[128:131], v[170:173], 0
	v_mfma_f32_16x16x32_bf16 v[124:127], v[136:139], v[170:173], 0
	v_mfma_f32_16x16x32_bf16 v[108:111], v[128:131], v[190:193], 0
	v_mfma_f32_16x16x32_bf16 v[104:107], v[136:139], v[190:193], 0
	v_mfma_f32_16x16x32_bf16 v[92:95], v[128:131], v[202:205], 0
	v_mfma_f32_16x16x32_bf16 v[88:91], v[136:139], v[202:205], 0
	v_mfma_f32_16x16x32_bf16 v[76:79], v[128:131], v[210:213], 0
	v_mfma_f32_16x16x32_bf16 v[72:75], v[136:139], v[210:213], 0
	v_mfma_f32_16x16x32_bf16 v[120:123], v[132:135], v[186:189], v[120:123]
	v_mfma_f32_16x16x32_bf16 v[124:127], v[140:143], v[186:189], v[124:127]
	v_mfma_f32_16x16x32_bf16 v[108:111], v[132:135], v[198:201], v[108:111]
	v_mfma_f32_16x16x32_bf16 v[104:107], v[140:143], v[198:201], v[104:107]
	v_mfma_f32_16x16x32_bf16 v[92:95], v[132:135], v[206:209], v[92:95]
	v_mfma_f32_16x16x32_bf16 v[88:91], v[140:143], v[206:209], v[88:91]
	v_mfma_f32_16x16x32_bf16 v[76:79], v[132:135], v[214:217], v[76:79]
	v_mfma_f32_16x16x32_bf16 v[72:75], v[140:143], v[214:217], v[72:75]
	v_mfma_f32_16x16x32_bf16 v[116:119], v[144:147], v[170:173], 0
	v_mfma_f32_16x16x32_bf16 v[112:115], v[152:155], v[170:173], 0
	v_mfma_f32_16x16x32_bf16 v[100:103], v[144:147], v[190:193], 0
	v_mfma_f32_16x16x32_bf16 v[96:99], v[152:155], v[190:193], 0
	v_mfma_f32_16x16x32_bf16 v[84:87], v[144:147], v[202:205], 0
	v_mfma_f32_16x16x32_bf16 v[80:83], v[152:155], v[202:205], 0
	v_mfma_f32_16x16x32_bf16 v[68:71], v[144:147], v[210:213], 0
	v_mfma_f32_16x16x32_bf16 v[64:67], v[152:155], v[210:213], 0
	v_mfma_f32_16x16x32_bf16 v[116:119], v[148:151], v[186:189], v[116:119]
	v_mfma_f32_16x16x32_bf16 v[112:115], v[166:169], v[186:189], v[112:115]
	v_mfma_f32_16x16x32_bf16 v[100:103], v[148:151], v[198:201], v[100:103]
	v_mfma_f32_16x16x32_bf16 v[96:99], v[166:169], v[198:201], v[96:99]
	v_mfma_f32_16x16x32_bf16 v[84:87], v[148:151], v[206:209], v[84:87]
	v_mfma_f32_16x16x32_bf16 v[80:83], v[166:169], v[206:209], v[80:83]
	v_mfma_f32_16x16x32_bf16 v[68:71], v[148:151], v[214:217], v[68:71]
	v_mfma_f32_16x16x32_bf16 v[64:67], v[166:169], v[214:217], v[64:67]
	s_barrier
	s_add_i32 s45, s45, s37
	v_lshl_add_u64 v[174:175], s[4:5], 0, v[176:177]
	s_mov_b32 m0, s45
	ds_read_b128 v[170:173], v197 offset:16384
	ds_read_b128 v[186:189], v197 offset:17408
	ds_read_b128 v[190:193], v197 offset:18432
	ds_read_b128 v[198:201], v197 offset:19456
	ds_read_b128 v[202:205], v197 offset:20480
	ds_read_b128 v[206:209], v197 offset:21504
	ds_read_b128 v[210:213], v197 offset:22528
	ds_read_b128 v[214:217], v197 offset:23552
	global_load_lds_dwordx4 v[174:175], off
	s_add_i32 m0, s45, 0x2000
	v_lshl_add_u64 v[222:223], s[4:5], 0, v[156:157]
	s_add_u32 s4, s4, s6
	s_addc_u32 s5, s5, s7
	s_add_i32 s45, s54, s37
	global_load_lds_dwordx4 v[222:223], off
	v_lshl_add_u64 v[224:225], s[4:5], 0, v[176:177]
	s_mov_b32 m0, s45
	v_lshl_add_u64 v[226:227], s[4:5], 0, v[156:157]
	global_load_lds_dwordx4 v[224:225], off
	s_add_i32 m0, s45, 0x2000
	v_lshl_add_u64 v[228:229], s[30:31], 0, v[160:161]
	global_load_lds_dwordx4 v[226:227], off
	s_mov_b32 m0, s38
	v_lshl_add_u64 v[230:231], s[30:31], 0, v[158:159]
	global_load_lds_dwordx4 v[228:229], off
	s_mov_b32 m0, s39
	s_nop 0
	global_load_lds_dwordx4 v[230:231], off
	s_waitcnt vmcnt(8)
	s_waitcnt lgkmcnt(0)
	s_barrier
	s_waitcnt lgkmcnt(0)
	v_mfma_f32_16x16x32_bf16 v[60:63], v[128:131], v[170:173], 0
	v_mfma_f32_16x16x32_bf16 v[56:59], v[136:139], v[170:173], 0
	v_mfma_f32_16x16x32_bf16 v[44:47], v[128:131], v[190:193], 0
	v_mfma_f32_16x16x32_bf16 v[40:43], v[136:139], v[190:193], 0
	v_mfma_f32_16x16x32_bf16 v[28:31], v[128:131], v[202:205], 0
	v_mfma_f32_16x16x32_bf16 v[24:27], v[136:139], v[202:205], 0
	v_mfma_f32_16x16x32_bf16 v[12:15], v[128:131], v[210:213], 0
	v_mfma_f32_16x16x32_bf16 v[8:11], v[136:139], v[210:213], 0
	v_mfma_f32_16x16x32_bf16 v[60:63], v[132:135], v[186:189], v[60:63]
	v_mfma_f32_16x16x32_bf16 v[56:59], v[140:143], v[186:189], v[56:59]
	v_mfma_f32_16x16x32_bf16 v[44:47], v[132:135], v[198:201], v[44:47]
	v_mfma_f32_16x16x32_bf16 v[40:43], v[140:143], v[198:201], v[40:43]
	v_mfma_f32_16x16x32_bf16 v[28:31], v[132:135], v[206:209], v[28:31]
	v_mfma_f32_16x16x32_bf16 v[24:27], v[140:143], v[206:209], v[24:27]
	v_mfma_f32_16x16x32_bf16 v[12:15], v[132:135], v[214:217], v[12:15]
	v_mfma_f32_16x16x32_bf16 v[8:11], v[140:143], v[214:217], v[8:11]
	v_mfma_f32_16x16x32_bf16 v[52:55], v[144:147], v[170:173], 0
	v_mfma_f32_16x16x32_bf16 v[48:51], v[152:155], v[170:173], 0
	v_mfma_f32_16x16x32_bf16 v[36:39], v[144:147], v[190:193], 0
	v_mfma_f32_16x16x32_bf16 v[32:35], v[152:155], v[190:193], 0
	v_mfma_f32_16x16x32_bf16 v[20:23], v[144:147], v[202:205], 0
	v_mfma_f32_16x16x32_bf16 v[16:19], v[152:155], v[202:205], 0
	v_mfma_f32_16x16x32_bf16 v[4:7], v[144:147], v[210:213], 0
	v_mfma_f32_16x16x32_bf16 v[0:3], v[152:155], v[210:213], 0
	v_mfma_f32_16x16x32_bf16 v[52:55], v[148:151], v[186:189], v[52:55]
	v_mfma_f32_16x16x32_bf16 v[48:51], v[166:169], v[186:189], v[48:51]
	v_mfma_f32_16x16x32_bf16 v[36:39], v[148:151], v[198:201], v[36:39]
	v_mfma_f32_16x16x32_bf16 v[32:35], v[166:169], v[198:201], v[32:35]
	v_mfma_f32_16x16x32_bf16 v[20:23], v[148:151], v[206:209], v[20:23]
	v_mfma_f32_16x16x32_bf16 v[16:19], v[166:169], v[206:209], v[16:19]
	v_mfma_f32_16x16x32_bf16 v[4:7], v[148:151], v[214:217], v[4:7]
	v_mfma_f32_16x16x32_bf16 v[0:3], v[166:169], v[214:217], v[0:3]
	s_barrier
	s_add_i32 s45, 0, 0x18000
	s_add_i32 s54, 0, 0x1c000
	v_add_u32_e32 v140, s45, v195
	v_add_u32_e32 v166, s54, v195
	ds_read_b128 v[128:131], v140
	ds_read_b128 v[132:135], v140 offset:1024
	ds_read_b128 v[136:139], v140 offset:2048
	ds_read_b128 v[140:143], v140 offset:3072
	ds_read_b128 v[144:147], v166
	ds_read_b128 v[148:151], v166 offset:1024
	ds_read_b128 v[152:155], v166 offset:2048
	ds_read_b128 v[166:169], v166 offset:3072
	s_add_u32 s4, s30, s6
	s_addc_u32 s5, s31, s7
	s_mov_b32 m0, s48
	v_lshl_add_u64 v[232:233], s[4:5], 0, v[160:161]
	ds_read_b128 v[170:173], v197 offset:32768
	ds_read_b128 v[186:189], v197 offset:33792
	ds_read_b128 v[190:193], v197 offset:34816
	ds_read_b128 v[198:201], v197 offset:35840
	ds_read_b128 v[202:205], v197 offset:36864
	ds_read_b128 v[206:209], v197 offset:37888
	ds_read_b128 v[210:213], v197 offset:38912
	ds_read_b128 v[214:217], v197 offset:39936
	global_load_lds_dwordx4 v[232:233], off
	v_lshl_add_u64 v[232:233], s[4:5], 0, v[158:159]
	s_mov_b32 m0, s49
	s_nop 0
	global_load_lds_dwordx4 v[232:233], off
	s_waitcnt vmcnt(8)
	s_waitcnt lgkmcnt(0)
	s_barrier
	s_waitcnt lgkmcnt(0)
	v_mfma_f32_16x16x32_bf16 v[120:123], v[128:131], v[170:173], v[120:123]
	v_mfma_f32_16x16x32_bf16 v[124:127], v[136:139], v[170:173], v[124:127]
	v_mfma_f32_16x16x32_bf16 v[108:111], v[128:131], v[190:193], v[108:111]
	v_mfma_f32_16x16x32_bf16 v[104:107], v[136:139], v[190:193], v[104:107]
	v_mfma_f32_16x16x32_bf16 v[92:95], v[128:131], v[202:205], v[92:95]
	v_mfma_f32_16x16x32_bf16 v[88:91], v[136:139], v[202:205], v[88:91]
	v_mfma_f32_16x16x32_bf16 v[76:79], v[128:131], v[210:213], v[76:79]
	v_mfma_f32_16x16x32_bf16 v[72:75], v[136:139], v[210:213], v[72:75]
	v_mfma_f32_16x16x32_bf16 v[120:123], v[132:135], v[186:189], v[120:123]
	v_mfma_f32_16x16x32_bf16 v[124:127], v[140:143], v[186:189], v[124:127]
	v_mfma_f32_16x16x32_bf16 v[108:111], v[132:135], v[198:201], v[108:111]
	v_mfma_f32_16x16x32_bf16 v[104:107], v[140:143], v[198:201], v[104:107]
	v_mfma_f32_16x16x32_bf16 v[92:95], v[132:135], v[206:209], v[92:95]
	v_mfma_f32_16x16x32_bf16 v[88:91], v[140:143], v[206:209], v[88:91]
	v_mfma_f32_16x16x32_bf16 v[76:79], v[132:135], v[214:217], v[76:79]
	v_mfma_f32_16x16x32_bf16 v[72:75], v[140:143], v[214:217], v[72:75]
	v_mfma_f32_16x16x32_bf16 v[116:119], v[144:147], v[170:173], v[116:119]
	v_mfma_f32_16x16x32_bf16 v[112:115], v[152:155], v[170:173], v[112:115]
	v_mfma_f32_16x16x32_bf16 v[100:103], v[144:147], v[190:193], v[100:103]
	v_mfma_f32_16x16x32_bf16 v[96:99], v[152:155], v[190:193], v[96:99]
	v_mfma_f32_16x16x32_bf16 v[84:87], v[144:147], v[202:205], v[84:87]
	v_mfma_f32_16x16x32_bf16 v[80:83], v[152:155], v[202:205], v[80:83]
	v_mfma_f32_16x16x32_bf16 v[68:71], v[144:147], v[210:213], v[68:71]
	v_mfma_f32_16x16x32_bf16 v[64:67], v[152:155], v[210:213], v[64:67]
	v_mfma_f32_16x16x32_bf16 v[116:119], v[148:151], v[186:189], v[116:119]
	v_mfma_f32_16x16x32_bf16 v[112:115], v[166:169], v[186:189], v[112:115]
	v_mfma_f32_16x16x32_bf16 v[100:103], v[148:151], v[198:201], v[100:103]
	v_mfma_f32_16x16x32_bf16 v[96:99], v[166:169], v[198:201], v[96:99]
	v_mfma_f32_16x16x32_bf16 v[84:87], v[148:151], v[206:209], v[84:87]
	v_mfma_f32_16x16x32_bf16 v[80:83], v[166:169], v[206:209], v[80:83]
	v_mfma_f32_16x16x32_bf16 v[68:71], v[148:151], v[214:217], v[68:71]
	v_mfma_f32_16x16x32_bf16 v[64:67], v[166:169], v[214:217], v[64:67]
	s_barrier
	s_add_i32 s4, s45, s37
	v_lshl_add_u64 v[174:175], v[174:175], 0, s[14:15]
	s_mov_b32 m0, s4
	ds_read_b128 v[170:173], v197 offset:49152
	ds_read_b128 v[186:189], v197 offset:50176
	ds_read_b128 v[190:193], v197 offset:51200
	ds_read_b128 v[198:201], v197 offset:52224
	ds_read_b128 v[202:205], v197 offset:53248
	ds_read_b128 v[206:209], v197 offset:54272
	ds_read_b128 v[210:213], v197 offset:55296
	ds_read_b128 v[214:217], v197 offset:56320
	global_load_lds_dwordx4 v[174:175], off
	v_lshl_add_u64 v[174:175], v[222:223], 0, s[14:15]
	s_add_i32 m0, s4, 0x2000
	s_add_i32 s4, s54, s37
	global_load_lds_dwordx4 v[174:175], off
	v_lshl_add_u64 v[174:175], v[224:225], 0, s[14:15]
	s_mov_b32 m0, s4
	s_nop 0
	global_load_lds_dwordx4 v[174:175], off
	v_lshl_add_u64 v[174:175], v[226:227], 0, s[14:15]
	s_add_i32 m0, s4, 0x2000
	s_nop 0
	global_load_lds_dwordx4 v[174:175], off
	v_lshl_add_u64 v[174:175], v[228:229], 0, s[14:15]
	s_mov_b32 m0, s59
	s_nop 0
	global_load_lds_dwordx4 v[174:175], off
	v_lshl_add_u64 v[174:175], v[230:231], 0, s[14:15]
	s_mov_b32 m0, s60
	s_nop 0
	global_load_lds_dwordx4 v[174:175], off
	s_waitcnt vmcnt(8)
	s_waitcnt lgkmcnt(0)
	s_barrier
	s_waitcnt lgkmcnt(0)
	v_mfma_f32_16x16x32_bf16 v[60:63], v[128:131], v[170:173], v[60:63]
	s_add_u32 s28, s28, 0x100
	v_mfma_f32_16x16x32_bf16 v[56:59], v[136:139], v[170:173], v[56:59]
	s_addc_u32 s29, s29, 0
	v_mfma_f32_16x16x32_bf16 v[44:47], v[128:131], v[190:193], v[44:47]
	s_add_u32 s10, s10, 0x100
	v_mfma_f32_16x16x32_bf16 v[40:43], v[136:139], v[190:193], v[40:43]
	s_addc_u32 s11, s11, 0
	v_mfma_f32_16x16x32_bf16 v[28:31], v[128:131], v[202:205], v[28:31]
	s_mov_b32 s30, s44
	v_mfma_f32_16x16x32_bf16 v[24:27], v[136:139], v[202:205], v[24:27]
	s_cmp_ge_i32 s44, s58
	v_mfma_f32_16x16x32_bf16 v[12:15], v[128:131], v[210:213], v[12:15]
	s_cselect_b32 s99, 1, 0
	v_readfirstlane_b32 s98, v218
	s_bfe_u32 s98, s98, 0x10008
	s_and_b32 s98, s98, s99
	v_mfma_f32_16x16x32_bf16 v[8:11], v[136:139], v[210:213], v[8:11]
	s_add_i32 s44, s30, 2
	v_mfma_f32_16x16x32_bf16 v[60:63], v[132:135], v[186:189], v[60:63]
	s_add_u32 s4, s28, 0x80
	v_mfma_f32_16x16x32_bf16 v[56:59], v[140:143], v[186:189], v[56:59]
	s_addc_u32 s5, s29, 0
	v_mfma_f32_16x16x32_bf16 v[44:47], v[132:135], v[198:201], v[44:47]
	s_add_i32 s45, 0, 0x10000
	v_mfma_f32_16x16x32_bf16 v[40:43], v[140:143], v[198:201], v[40:43]
	s_cmp_eq_u32 s61, s30
	v_mfma_f32_16x16x32_bf16 v[28:31], v[132:135], v[206:209], v[28:31]
	s_cselect_b32 s31, s25, s5
	v_mfma_f32_16x16x32_bf16 v[24:27], v[140:143], v[206:209], v[24:27]
	s_cselect_b32 s30, s24, s4
	v_mfma_f32_16x16x32_bf16 v[12:15], v[132:135], v[214:217], v[12:15]
	s_cselect_b32 s5, s27, s11
	v_mfma_f32_16x16x32_bf16 v[8:11], v[140:143], v[214:217], v[8:11]
	s_cselect_b32 s4, s26, s10
	v_mfma_f32_16x16x32_bf16 v[52:55], v[144:147], v[170:173], v[52:55]
	s_add_i32 s54, 0, 0x14000
	v_mfma_f32_16x16x32_bf16 v[48:51], v[152:155], v[170:173], v[48:51]
	v_mfma_f32_16x16x32_bf16 v[36:39], v[144:147], v[190:193], v[36:39]
	v_mfma_f32_16x16x32_bf16 v[32:35], v[152:155], v[190:193], v[32:35]
	v_mfma_f32_16x16x32_bf16 v[20:23], v[144:147], v[202:205], v[20:23]
	v_mfma_f32_16x16x32_bf16 v[16:19], v[152:155], v[202:205], v[16:19]
	v_mfma_f32_16x16x32_bf16 v[4:7], v[144:147], v[210:213], v[4:7]
	v_mfma_f32_16x16x32_bf16 v[0:3], v[152:155], v[210:213], v[0:3]
	v_mfma_f32_16x16x32_bf16 v[52:55], v[148:151], v[186:189], v[52:55]
	v_mfma_f32_16x16x32_bf16 v[48:51], v[166:169], v[186:189], v[48:51]
	v_mfma_f32_16x16x32_bf16 v[36:39], v[148:151], v[198:201], v[36:39]
	v_mfma_f32_16x16x32_bf16 v[32:35], v[166:169], v[198:201], v[32:35]
	v_mfma_f32_16x16x32_bf16 v[20:23], v[148:151], v[206:209], v[20:23]
	v_mfma_f32_16x16x32_bf16 v[16:19], v[166:169], v[206:209], v[16:19]
	v_mfma_f32_16x16x32_bf16 v[4:7], v[148:151], v[214:217], v[4:7]
	v_mfma_f32_16x16x32_bf16 v[0:3], v[166:169], v[214:217], v[0:3]
	s_cmp_lg_u32 s98, 0
	s_cbranch_scc1 .Lskf_8_peel
	s_barrier

.LBB0_475:
	v_add_u32_e32 v140, s45, v195
	v_add_u32_e32 v166, s54, v195
	ds_read_b128 v[128:131], v140
	ds_read_b128 v[132:135], v140 offset:1024
	ds_read_b128 v[136:139], v140 offset:2048
	ds_read_b128 v[140:143], v140 offset:3072
	ds_read_b128 v[144:147], v166
	ds_read_b128 v[148:151], v166 offset:1024
	ds_read_b128 v[152:155], v166 offset:2048
	ds_read_b128 v[166:169], v166 offset:3072
	v_lshl_add_u64 v[174:175], s[28:29], 0, v[162:163]
	s_add_i32 m0, s38, 0xc000
	ds_read_b128 v[170:173], v197
	ds_read_b128 v[186:189], v197 offset:1024
	ds_read_b128 v[190:193], v197 offset:2048
	ds_read_b128 v[198:201], v197 offset:3072
	ds_read_b128 v[202:205], v197 offset:4096
	ds_read_b128 v[206:209], v197 offset:5120
	ds_read_b128 v[210:213], v197 offset:6144
	ds_read_b128 v[214:217], v197 offset:7168
	global_load_lds_dwordx4 v[174:175], off
	v_lshl_add_u64 v[174:175], s[28:29], 0, v[164:165]
	s_add_i32 m0, s38, 0xe000
	s_nop 0
	global_load_lds_dwordx4 v[174:175], off
	s_waitcnt vmcnt(8)
	s_waitcnt lgkmcnt(0)
	s_barrier
	s_waitcnt lgkmcnt(0)
	v_mfma_f32_16x16x32_bf16 v[120:123], v[128:131], v[170:173], v[120:123]
	v_mfma_f32_16x16x32_bf16 v[124:127], v[136:139], v[170:173], v[124:127]
	v_mfma_f32_16x16x32_bf16 v[108:111], v[128:131], v[190:193], v[108:111]
	v_mfma_f32_16x16x32_bf16 v[104:107], v[136:139], v[190:193], v[104:107]
	v_mfma_f32_16x16x32_bf16 v[92:95], v[128:131], v[202:205], v[92:95]
	v_mfma_f32_16x16x32_bf16 v[88:91], v[136:139], v[202:205], v[88:91]
	v_mfma_f32_16x16x32_bf16 v[76:79], v[128:131], v[210:213], v[76:79]
	v_mfma_f32_16x16x32_bf16 v[72:75], v[136:139], v[210:213], v[72:75]
	v_mfma_f32_16x16x32_bf16 v[120:123], v[132:135], v[186:189], v[120:123]
	v_mfma_f32_16x16x32_bf16 v[124:127], v[140:143], v[186:189], v[124:127]
	v_mfma_f32_16x16x32_bf16 v[108:111], v[132:135], v[198:201], v[108:111]
	v_mfma_f32_16x16x32_bf16 v[104:107], v[140:143], v[198:201], v[104:107]
	v_mfma_f32_16x16x32_bf16 v[92:95], v[132:135], v[206:209], v[92:95]
	v_mfma_f32_16x16x32_bf16 v[88:91], v[140:143], v[206:209], v[88:91]
	v_mfma_f32_16x16x32_bf16 v[76:79], v[132:135], v[214:217], v[76:79]
	v_mfma_f32_16x16x32_bf16 v[72:75], v[140:143], v[214:217], v[72:75]
	v_mfma_f32_16x16x32_bf16 v[116:119], v[144:147], v[170:173], v[116:119]
	v_mfma_f32_16x16x32_bf16 v[112:115], v[152:155], v[170:173], v[112:115]
	v_mfma_f32_16x16x32_bf16 v[100:103], v[144:147], v[190:193], v[100:103]
	v_mfma_f32_16x16x32_bf16 v[96:99], v[152:155], v[190:193], v[96:99]
	v_mfma_f32_16x16x32_bf16 v[84:87], v[144:147], v[202:205], v[84:87]
	v_mfma_f32_16x16x32_bf16 v[80:83], v[152:155], v[202:205], v[80:83]
	v_mfma_f32_16x16x32_bf16 v[68:71], v[144:147], v[210:213], v[68:71]
	v_mfma_f32_16x16x32_bf16 v[64:67], v[152:155], v[210:213], v[64:67]
	v_mfma_f32_16x16x32_bf16 v[116:119], v[148:151], v[186:189], v[116:119]
	v_mfma_f32_16x16x32_bf16 v[112:115], v[166:169], v[186:189], v[112:115]
	v_mfma_f32_16x16x32_bf16 v[100:103], v[148:151], v[198:201], v[100:103]
	v_mfma_f32_16x16x32_bf16 v[96:99], v[166:169], v[198:201], v[96:99]
	v_mfma_f32_16x16x32_bf16 v[84:87], v[148:151], v[206:209], v[84:87]
	v_mfma_f32_16x16x32_bf16 v[80:83], v[166:169], v[206:209], v[80:83]
	v_mfma_f32_16x16x32_bf16 v[68:71], v[148:151], v[214:217], v[68:71]
	v_mfma_f32_16x16x32_bf16 v[64:67], v[166:169], v[214:217], v[64:67]
	s_barrier
	s_add_i32 s45, s45, s37
	v_lshl_add_u64 v[174:175], s[4:5], 0, v[176:177]
	s_mov_b32 m0, s45
	ds_read_b128 v[170:173], v197 offset:16384
	ds_read_b128 v[186:189], v197 offset:17408
	ds_read_b128 v[190:193], v197 offset:18432
	ds_read_b128 v[198:201], v197 offset:19456
	ds_read_b128 v[202:205], v197 offset:20480
	ds_read_b128 v[206:209], v197 offset:21504
	ds_read_b128 v[210:213], v197 offset:22528
	ds_read_b128 v[214:217], v197 offset:23552
	global_load_lds_dwordx4 v[174:175], off
	s_add_i32 m0, s45, 0x2000
	v_lshl_add_u64 v[222:223], s[4:5], 0, v[156:157]
	s_add_u32 s4, s4, s6
	s_addc_u32 s5, s5, s7
	s_add_i32 s45, s54, s37
	global_load_lds_dwordx4 v[222:223], off
	v_lshl_add_u64 v[224:225], s[4:5], 0, v[176:177]
	s_mov_b32 m0, s45
	v_lshl_add_u64 v[226:227], s[4:5], 0, v[156:157]
	global_load_lds_dwordx4 v[224:225], off
	s_add_i32 m0, s45, 0x2000
	v_lshl_add_u64 v[228:229], s[30:31], 0, v[160:161]
	global_load_lds_dwordx4 v[226:227], off
	s_mov_b32 m0, s38
	v_lshl_add_u64 v[230:231], s[30:31], 0, v[158:159]
	global_load_lds_dwordx4 v[228:229], off
	s_mov_b32 m0, s39
	s_nop 0
	global_load_lds_dwordx4 v[230:231], off
	s_waitcnt vmcnt(8)
	s_waitcnt lgkmcnt(0)
	s_barrier
	s_waitcnt lgkmcnt(0)
	v_mfma_f32_16x16x32_bf16 v[60:63], v[128:131], v[170:173], v[60:63]
	v_mfma_f32_16x16x32_bf16 v[56:59], v[136:139], v[170:173], v[56:59]
	v_mfma_f32_16x16x32_bf16 v[44:47], v[128:131], v[190:193], v[44:47]
	v_mfma_f32_16x16x32_bf16 v[40:43], v[136:139], v[190:193], v[40:43]
	v_mfma_f32_16x16x32_bf16 v[28:31], v[128:131], v[202:205], v[28:31]
	v_mfma_f32_16x16x32_bf16 v[24:27], v[136:139], v[202:205], v[24:27]
	v_mfma_f32_16x16x32_bf16 v[12:15], v[128:131], v[210:213], v[12:15]
	v_mfma_f32_16x16x32_bf16 v[8:11], v[136:139], v[210:213], v[8:11]
	v_mfma_f32_16x16x32_bf16 v[60:63], v[132:135], v[186:189], v[60:63]
	v_mfma_f32_16x16x32_bf16 v[56:59], v[140:143], v[186:189], v[56:59]
	v_mfma_f32_16x16x32_bf16 v[44:47], v[132:135], v[198:201], v[44:47]
	v_mfma_f32_16x16x32_bf16 v[40:43], v[140:143], v[198:201], v[40:43]
	v_mfma_f32_16x16x32_bf16 v[28:31], v[132:135], v[206:209], v[28:31]
	v_mfma_f32_16x16x32_bf16 v[24:27], v[140:143], v[206:209], v[24:27]
	v_mfma_f32_16x16x32_bf16 v[12:15], v[132:135], v[214:217], v[12:15]
	v_mfma_f32_16x16x32_bf16 v[8:11], v[140:143], v[214:217], v[8:11]
	v_mfma_f32_16x16x32_bf16 v[52:55], v[144:147], v[170:173], v[52:55]
	v_mfma_f32_16x16x32_bf16 v[48:51], v[152:155], v[170:173], v[48:51]
	v_mfma_f32_16x16x32_bf16 v[36:39], v[144:147], v[190:193], v[36:39]
	v_mfma_f32_16x16x32_bf16 v[32:35], v[152:155], v[190:193], v[32:35]
	v_mfma_f32_16x16x32_bf16 v[20:23], v[144:147], v[202:205], v[20:23]
	v_mfma_f32_16x16x32_bf16 v[16:19], v[152:155], v[202:205], v[16:19]
	v_mfma_f32_16x16x32_bf16 v[4:7], v[144:147], v[210:213], v[4:7]
	v_mfma_f32_16x16x32_bf16 v[0:3], v[152:155], v[210:213], v[0:3]
	v_mfma_f32_16x16x32_bf16 v[52:55], v[148:151], v[186:189], v[52:55]
	v_mfma_f32_16x16x32_bf16 v[48:51], v[166:169], v[186:189], v[48:51]
	v_mfma_f32_16x16x32_bf16 v[36:39], v[148:151], v[198:201], v[36:39]
	v_mfma_f32_16x16x32_bf16 v[32:35], v[166:169], v[198:201], v[32:35]
	v_mfma_f32_16x16x32_bf16 v[20:23], v[148:151], v[206:209], v[20:23]
	v_mfma_f32_16x16x32_bf16 v[16:19], v[166:169], v[206:209], v[16:19]
	v_mfma_f32_16x16x32_bf16 v[4:7], v[148:151], v[214:217], v[4:7]
	v_mfma_f32_16x16x32_bf16 v[0:3], v[166:169], v[214:217], v[0:3]
	s_barrier
	s_add_i32 s45, 0, 0x18000
	s_add_i32 s54, 0, 0x1c000
	v_add_u32_e32 v140, s45, v195
	v_add_u32_e32 v166, s54, v195
	ds_read_b128 v[128:131], v140
	ds_read_b128 v[132:135], v140 offset:1024
	ds_read_b128 v[136:139], v140 offset:2048
	ds_read_b128 v[140:143], v140 offset:3072
	ds_read_b128 v[144:147], v166
	ds_read_b128 v[148:151], v166 offset:1024
	ds_read_b128 v[152:155], v166 offset:2048
	ds_read_b128 v[166:169], v166 offset:3072
	s_add_u32 s4, s30, s6
	s_addc_u32 s5, s31, s7
	s_mov_b32 m0, s48
	v_lshl_add_u64 v[232:233], s[4:5], 0, v[160:161]
	ds_read_b128 v[170:173], v197 offset:32768
	ds_read_b128 v[186:189], v197 offset:33792
	ds_read_b128 v[190:193], v197 offset:34816
	ds_read_b128 v[198:201], v197 offset:35840
	ds_read_b128 v[202:205], v197 offset:36864
	ds_read_b128 v[206:209], v197 offset:37888
	ds_read_b128 v[210:213], v197 offset:38912
	ds_read_b128 v[214:217], v197 offset:39936
	global_load_lds_dwordx4 v[232:233], off
	v_lshl_add_u64 v[232:233], s[4:5], 0, v[158:159]
	s_mov_b32 m0, s49
	s_nop 0
	global_load_lds_dwordx4 v[232:233], off
	s_waitcnt vmcnt(8)
	s_waitcnt lgkmcnt(0)
	s_barrier
	s_waitcnt lgkmcnt(0)
	v_mfma_f32_16x16x32_bf16 v[120:123], v[128:131], v[170:173], v[120:123]
	v_mfma_f32_16x16x32_bf16 v[124:127], v[136:139], v[170:173], v[124:127]
	v_mfma_f32_16x16x32_bf16 v[108:111], v[128:131], v[190:193], v[108:111]
	v_mfma_f32_16x16x32_bf16 v[104:107], v[136:139], v[190:193], v[104:107]
	v_mfma_f32_16x16x32_bf16 v[92:95], v[128:131], v[202:205], v[92:95]
	v_mfma_f32_16x16x32_bf16 v[88:91], v[136:139], v[202:205], v[88:91]
	v_mfma_f32_16x16x32_bf16 v[76:79], v[128:131], v[210:213], v[76:79]
	v_mfma_f32_16x16x32_bf16 v[72:75], v[136:139], v[210:213], v[72:75]
	v_mfma_f32_16x16x32_bf16 v[120:123], v[132:135], v[186:189], v[120:123]
	v_mfma_f32_16x16x32_bf16 v[124:127], v[140:143], v[186:189], v[124:127]
	v_mfma_f32_16x16x32_bf16 v[108:111], v[132:135], v[198:201], v[108:111]
	v_mfma_f32_16x16x32_bf16 v[104:107], v[140:143], v[198:201], v[104:107]
	v_mfma_f32_16x16x32_bf16 v[92:95], v[132:135], v[206:209], v[92:95]
	v_mfma_f32_16x16x32_bf16 v[88:91], v[140:143], v[206:209], v[88:91]
	v_mfma_f32_16x16x32_bf16 v[76:79], v[132:135], v[214:217], v[76:79]
	v_mfma_f32_16x16x32_bf16 v[72:75], v[140:143], v[214:217], v[72:75]
	v_mfma_f32_16x16x32_bf16 v[116:119], v[144:147], v[170:173], v[116:119]
	v_mfma_f32_16x16x32_bf16 v[112:115], v[152:155], v[170:173], v[112:115]
	v_mfma_f32_16x16x32_bf16 v[100:103], v[144:147], v[190:193], v[100:103]
	v_mfma_f32_16x16x32_bf16 v[96:99], v[152:155], v[190:193], v[96:99]
	v_mfma_f32_16x16x32_bf16 v[84:87], v[144:147], v[202:205], v[84:87]
	v_mfma_f32_16x16x32_bf16 v[80:83], v[152:155], v[202:205], v[80:83]
	v_mfma_f32_16x16x32_bf16 v[68:71], v[144:147], v[210:213], v[68:71]
	v_mfma_f32_16x16x32_bf16 v[64:67], v[152:155], v[210:213], v[64:67]
	v_mfma_f32_16x16x32_bf16 v[116:119], v[148:151], v[186:189], v[116:119]
	v_mfma_f32_16x16x32_bf16 v[112:115], v[166:169], v[186:189], v[112:115]
	v_mfma_f32_16x16x32_bf16 v[100:103], v[148:151], v[198:201], v[100:103]
	v_mfma_f32_16x16x32_bf16 v[96:99], v[166:169], v[198:201], v[96:99]
	v_mfma_f32_16x16x32_bf16 v[84:87], v[148:151], v[206:209], v[84:87]
	v_mfma_f32_16x16x32_bf16 v[80:83], v[166:169], v[206:209], v[80:83]
	v_mfma_f32_16x16x32_bf16 v[68:71], v[148:151], v[214:217], v[68:71]
	v_mfma_f32_16x16x32_bf16 v[64:67], v[166:169], v[214:217], v[64:67]
	s_barrier
	s_add_i32 s4, s45, s37
	v_lshl_add_u64 v[174:175], v[174:175], 0, s[14:15]
	s_mov_b32 m0, s4
	ds_read_b128 v[170:173], v197 offset:49152
	ds_read_b128 v[186:189], v197 offset:50176
	ds_read_b128 v[190:193], v197 offset:51200
	ds_read_b128 v[198:201], v197 offset:52224
	ds_read_b128 v[202:205], v197 offset:53248
	ds_read_b128 v[206:209], v197 offset:54272
	ds_read_b128 v[210:213], v197 offset:55296
	ds_read_b128 v[214:217], v197 offset:56320
	global_load_lds_dwordx4 v[174:175], off
	v_lshl_add_u64 v[174:175], v[222:223], 0, s[14:15]
	s_add_i32 m0, s4, 0x2000
	s_add_i32 s4, s54, s37
	global_load_lds_dwordx4 v[174:175], off
	v_lshl_add_u64 v[174:175], v[224:225], 0, s[14:15]
	s_mov_b32 m0, s4
	s_nop 0
	global_load_lds_dwordx4 v[174:175], off
	v_lshl_add_u64 v[174:175], v[226:227], 0, s[14:15]
	s_add_i32 m0, s4, 0x2000
	s_nop 0
	global_load_lds_dwordx4 v[174:175], off
	v_lshl_add_u64 v[174:175], v[228:229], 0, s[14:15]
	s_mov_b32 m0, s59
	s_nop 0
	global_load_lds_dwordx4 v[174:175], off
	v_lshl_add_u64 v[174:175], v[230:231], 0, s[14:15]
	s_mov_b32 m0, s60
	s_nop 0
	global_load_lds_dwordx4 v[174:175], off
	s_waitcnt vmcnt(8)
	s_waitcnt lgkmcnt(0)
	s_barrier
	s_waitcnt lgkmcnt(0)
	v_mfma_f32_16x16x32_bf16 v[60:63], v[128:131], v[170:173], v[60:63]
	s_add_u32 s28, s28, 0x100
	v_mfma_f32_16x16x32_bf16 v[56:59], v[136:139], v[170:173], v[56:59]
	s_addc_u32 s29, s29, 0
	v_mfma_f32_16x16x32_bf16 v[44:47], v[128:131], v[190:193], v[44:47]
	s_add_u32 s10, s10, 0x100
	v_mfma_f32_16x16x32_bf16 v[40:43], v[136:139], v[190:193], v[40:43]
	s_addc_u32 s11, s11, 0
	v_mfma_f32_16x16x32_bf16 v[28:31], v[128:131], v[202:205], v[28:31]
	s_mov_b32 s30, s44
	v_mfma_f32_16x16x32_bf16 v[24:27], v[136:139], v[202:205], v[24:27]
	s_cmp_ge_i32 s44, s58
	v_mfma_f32_16x16x32_bf16 v[12:15], v[128:131], v[210:213], v[12:15]
	s_cselect_b32 s99, 1, 0
	v_readfirstlane_b32 s98, v218
	s_bfe_u32 s98, s98, 0x10008
	s_and_b32 s98, s98, s99
	v_mfma_f32_16x16x32_bf16 v[8:11], v[136:139], v[210:213], v[8:11]
	s_add_i32 s44, s30, 2
	v_mfma_f32_16x16x32_bf16 v[60:63], v[132:135], v[186:189], v[60:63]
	s_add_u32 s4, s28, 0x80
	v_mfma_f32_16x16x32_bf16 v[56:59], v[140:143], v[186:189], v[56:59]
	s_addc_u32 s5, s29, 0
	v_mfma_f32_16x16x32_bf16 v[44:47], v[132:135], v[198:201], v[44:47]
	s_add_i32 s45, 0, 0x10000
	v_mfma_f32_16x16x32_bf16 v[40:43], v[140:143], v[198:201], v[40:43]
	s_cmp_eq_u32 s61, s30
	v_mfma_f32_16x16x32_bf16 v[28:31], v[132:135], v[206:209], v[28:31]
	s_cselect_b32 s31, s25, s5
	v_mfma_f32_16x16x32_bf16 v[24:27], v[140:143], v[206:209], v[24:27]
	s_cselect_b32 s30, s24, s4
	v_mfma_f32_16x16x32_bf16 v[12:15], v[132:135], v[214:217], v[12:15]
	s_cselect_b32 s5, s27, s11
	v_mfma_f32_16x16x32_bf16 v[8:11], v[140:143], v[214:217], v[8:11]
	s_cselect_b32 s4, s26, s10
	v_mfma_f32_16x16x32_bf16 v[52:55], v[144:147], v[170:173], v[52:55]
	s_add_i32 s54, 0, 0x14000
	v_mfma_f32_16x16x32_bf16 v[48:51], v[152:155], v[170:173], v[48:51]
	v_mfma_f32_16x16x32_bf16 v[36:39], v[144:147], v[190:193], v[36:39]
	v_mfma_f32_16x16x32_bf16 v[32:35], v[152:155], v[190:193], v[32:35]
	v_mfma_f32_16x16x32_bf16 v[20:23], v[144:147], v[202:205], v[20:23]
	v_mfma_f32_16x16x32_bf16 v[16:19], v[152:155], v[202:205], v[16:19]
	v_mfma_f32_16x16x32_bf16 v[4:7], v[144:147], v[210:213], v[4:7]
	v_mfma_f32_16x16x32_bf16 v[0:3], v[152:155], v[210:213], v[0:3]
	v_mfma_f32_16x16x32_bf16 v[52:55], v[148:151], v[186:189], v[52:55]
	v_mfma_f32_16x16x32_bf16 v[48:51], v[166:169], v[186:189], v[48:51]
	v_mfma_f32_16x16x32_bf16 v[36:39], v[148:151], v[198:201], v[36:39]
	v_mfma_f32_16x16x32_bf16 v[32:35], v[166:169], v[198:201], v[32:35]
	v_mfma_f32_16x16x32_bf16 v[20:23], v[148:151], v[206:209], v[20:23]
	v_mfma_f32_16x16x32_bf16 v[16:19], v[166:169], v[206:209], v[16:19]
	v_mfma_f32_16x16x32_bf16 v[4:7], v[148:151], v[214:217], v[4:7]
	v_mfma_f32_16x16x32_bf16 v[0:3], v[166:169], v[214:217], v[0:3]
	s_cmp_lg_u32 s98, 0
	s_cbranch_scc1 .Lskf_8_loop
	s_barrier

.LBB0_563:
	s_barrier
	s_andn2_b64 vcc, exec, s[0:1]
	s_mov_b32 s10, s71
	s_mov_b32 s11, s74
	s_mov_b64 s[38:39], s[8:9]
	s_mov_b64 s[0:1], s[56:57]
	s_cbranch_vccz .LBB0_726

.Llbb_5:
	s_add_i32 s44, s16, 2
	s_add_u32 s45, s0, 0x80
	s_addc_u32 s17, s1, 0
	s_add_i32 s64, 0, 0x10000
	s_cmp_eq_u32 s63, s16
	s_cselect_b32 s17, s57, s17
	s_cselect_b32 s16, s56, s45
	v_add_u32_e32 v152, s64, v153
	s_cselect_b32 s47, s9, s39
	s_cselect_b32 s46, s8, s38
	s_add_i32 s45, 0, 0x14000
	ds_read_b128 v[128:131], v152
	ds_read_b128 v[158:161], v152 offset:1024
	ds_read_b128 v[162:165], v152 offset:2048
	ds_read_b128 v[166:169], v152 offset:3072
	v_add_u32_e32 v152, s45, v153
	ds_read_b128 v[170:173], v152
	ds_read_b128 v[174:177], v152 offset:1024
	ds_read_b128 v[194:197], v152 offset:2048
	ds_read_b128 v[206:209], v152 offset:3072
	v_lshl_add_u64 v[178:179], s[0:1], 0, v[148:149]
	s_add_i32 m0, s52, 0xc000
	ds_read_b128 v[210:213], v157
	ds_read_b128 v[214:217], v157 offset:1024
	ds_read_b128 v[220:223], v157 offset:2048
	ds_read_b128 v[224:227], v157 offset:3072
	ds_read_b128 v[228:231], v157 offset:4096
	ds_read_b128 v[232:235], v157 offset:5120
	ds_read_b128 v[236:239], v157 offset:6144
	ds_read_b128 v[240:243], v157 offset:7168
	global_load_lds_dwordx4 v[178:179], off
	v_lshl_add_u64 v[178:179], s[0:1], 0, v[150:151]
	s_add_i32 m0, s52, 0xe000
	s_nop 0
	global_load_lds_dwordx4 v[178:179], off
	s_waitcnt vmcnt(8)
	s_waitcnt lgkmcnt(0)
	s_barrier
	s_waitcnt lgkmcnt(0)
	v_mfma_f32_16x16x32_bf16 v[124:127], v[128:131], v[210:213], 0
	v_mfma_f32_16x16x32_bf16 v[120:123], v[162:165], v[210:213], 0
	v_mfma_f32_16x16x32_bf16 v[108:111], v[128:131], v[220:223], 0
	v_mfma_f32_16x16x32_bf16 v[104:107], v[162:165], v[220:223], 0
	v_mfma_f32_16x16x32_bf16 v[92:95], v[128:131], v[228:231], 0
	v_mfma_f32_16x16x32_bf16 v[88:91], v[162:165], v[228:231], 0
	v_mfma_f32_16x16x32_bf16 v[76:79], v[128:131], v[236:239], 0
	v_mfma_f32_16x16x32_bf16 v[72:75], v[162:165], v[236:239], 0
	v_mfma_f32_16x16x32_bf16 v[124:127], v[158:161], v[214:217], v[124:127]
	v_mfma_f32_16x16x32_bf16 v[120:123], v[166:169], v[214:217], v[120:123]
	v_mfma_f32_16x16x32_bf16 v[108:111], v[158:161], v[224:227], v[108:111]
	v_mfma_f32_16x16x32_bf16 v[104:107], v[166:169], v[224:227], v[104:107]
	v_mfma_f32_16x16x32_bf16 v[92:95], v[158:161], v[232:235], v[92:95]
	v_mfma_f32_16x16x32_bf16 v[88:91], v[166:169], v[232:235], v[88:91]
	v_mfma_f32_16x16x32_bf16 v[76:79], v[158:161], v[240:243], v[76:79]
	v_mfma_f32_16x16x32_bf16 v[72:75], v[166:169], v[240:243], v[72:75]
	v_mfma_f32_16x16x32_bf16 v[116:119], v[170:173], v[210:213], 0
	v_mfma_f32_16x16x32_bf16 v[112:115], v[194:197], v[210:213], 0
	v_mfma_f32_16x16x32_bf16 v[100:103], v[170:173], v[220:223], 0
	v_mfma_f32_16x16x32_bf16 v[96:99], v[194:197], v[220:223], 0
	v_mfma_f32_16x16x32_bf16 v[84:87], v[170:173], v[228:231], 0
	v_mfma_f32_16x16x32_bf16 v[80:83], v[194:197], v[228:231], 0
	v_mfma_f32_16x16x32_bf16 v[68:71], v[170:173], v[236:239], 0
	v_mfma_f32_16x16x32_bf16 v[64:67], v[194:197], v[236:239], 0
	v_mfma_f32_16x16x32_bf16 v[116:119], v[174:177], v[214:217], v[116:119]
	v_mfma_f32_16x16x32_bf16 v[112:115], v[206:209], v[214:217], v[112:115]
	v_mfma_f32_16x16x32_bf16 v[100:103], v[174:177], v[224:227], v[100:103]
	v_mfma_f32_16x16x32_bf16 v[96:99], v[206:209], v[224:227], v[96:99]
	v_mfma_f32_16x16x32_bf16 v[84:87], v[174:177], v[232:235], v[84:87]
	v_mfma_f32_16x16x32_bf16 v[80:83], v[206:209], v[232:235], v[80:83]
	v_mfma_f32_16x16x32_bf16 v[68:71], v[174:177], v[240:243], v[68:71]
	v_mfma_f32_16x16x32_bf16 v[64:67], v[206:209], v[240:243], v[64:67]
	s_barrier
	s_add_i32 s64, s64, s4
	v_lshl_add_u64 v[178:179], s[46:47], 0, v[134:135]
	s_mov_b32 m0, s64
	ds_read_b128 v[210:213], v157 offset:16384
	ds_read_b128 v[214:217], v157 offset:17408
	ds_read_b128 v[220:223], v157 offset:18432
	ds_read_b128 v[224:227], v157 offset:19456
	ds_read_b128 v[228:231], v157 offset:20480
	ds_read_b128 v[232:235], v157 offset:21504
	ds_read_b128 v[236:239], v157 offset:22528
	ds_read_b128 v[240:243], v157 offset:23552
	global_load_lds_dwordx4 v[178:179], off
	s_add_i32 m0, s64, 0x2000
	v_lshl_add_u64 v[198:199], s[46:47], 0, v[138:139]
	s_add_u32 s46, s46, s24
	s_addc_u32 s47, s47, s25
	s_add_i32 s45, s45, s4
	global_load_lds_dwordx4 v[198:199], off
	v_lshl_add_u64 v[244:245], s[46:47], 0, v[134:135]
	s_mov_b32 m0, s45
	v_lshl_add_u64 v[246:247], s[46:47], 0, v[138:139]
	global_load_lds_dwordx4 v[244:245], off
	s_add_i32 m0, s45, 0x2000
	v_lshl_add_u64 v[248:249], s[16:17], 0, v[132:133]
	global_load_lds_dwordx4 v[246:247], off
	s_mov_b32 m0, s52
	v_lshl_add_u64 v[250:251], s[16:17], 0, v[136:137]
	global_load_lds_dwordx4 v[248:249], off
	s_mov_b32 m0, s18
	s_nop 0
	global_load_lds_dwordx4 v[250:251], off
	s_waitcnt vmcnt(8)
	s_waitcnt lgkmcnt(0)
	s_barrier
	s_waitcnt lgkmcnt(0)
	v_mfma_f32_16x16x32_bf16 v[60:63], v[128:131], v[210:213], 0
	v_mfma_f32_16x16x32_bf16 v[56:59], v[162:165], v[210:213], 0
	v_mfma_f32_16x16x32_bf16 v[44:47], v[128:131], v[220:223], 0
	v_mfma_f32_16x16x32_bf16 v[40:43], v[162:165], v[220:223], 0
	v_mfma_f32_16x16x32_bf16 v[28:31], v[128:131], v[228:231], 0
	v_mfma_f32_16x16x32_bf16 v[24:27], v[162:165], v[228:231], 0
	v_mfma_f32_16x16x32_bf16 v[12:15], v[128:131], v[236:239], 0
	v_mfma_f32_16x16x32_bf16 v[8:11], v[162:165], v[236:239], 0
	v_mfma_f32_16x16x32_bf16 v[60:63], v[158:161], v[214:217], v[60:63]
	v_mfma_f32_16x16x32_bf16 v[56:59], v[166:169], v[214:217], v[56:59]
	v_mfma_f32_16x16x32_bf16 v[44:47], v[158:161], v[224:227], v[44:47]
	v_mfma_f32_16x16x32_bf16 v[40:43], v[166:169], v[224:227], v[40:43]
	v_mfma_f32_16x16x32_bf16 v[28:31], v[158:161], v[232:235], v[28:31]
	v_mfma_f32_16x16x32_bf16 v[24:27], v[166:169], v[232:235], v[24:27]
	v_mfma_f32_16x16x32_bf16 v[12:15], v[158:161], v[240:243], v[12:15]
	v_mfma_f32_16x16x32_bf16 v[8:11], v[166:169], v[240:243], v[8:11]
	v_mfma_f32_16x16x32_bf16 v[52:55], v[170:173], v[210:213], 0
	v_mfma_f32_16x16x32_bf16 v[48:51], v[194:197], v[210:213], 0
	v_mfma_f32_16x16x32_bf16 v[36:39], v[170:173], v[220:223], 0
	v_mfma_f32_16x16x32_bf16 v[32:35], v[194:197], v[220:223], 0
	v_mfma_f32_16x16x32_bf16 v[20:23], v[170:173], v[228:231], 0
	v_mfma_f32_16x16x32_bf16 v[16:19], v[194:197], v[228:231], 0
	v_mfma_f32_16x16x32_bf16 v[4:7], v[170:173], v[236:239], 0
	v_mfma_f32_16x16x32_bf16 v[0:3], v[194:197], v[236:239], 0
	v_mfma_f32_16x16x32_bf16 v[52:55], v[174:177], v[214:217], v[52:55]
	v_mfma_f32_16x16x32_bf16 v[48:51], v[206:209], v[214:217], v[48:51]
	v_mfma_f32_16x16x32_bf16 v[36:39], v[174:177], v[224:227], v[36:39]
	v_mfma_f32_16x16x32_bf16 v[32:35], v[206:209], v[224:227], v[32:35]
	v_mfma_f32_16x16x32_bf16 v[20:23], v[174:177], v[232:235], v[20:23]
	v_mfma_f32_16x16x32_bf16 v[16:19], v[206:209], v[232:235], v[16:19]
	v_mfma_f32_16x16x32_bf16 v[4:7], v[174:177], v[240:243], v[4:7]
	v_mfma_f32_16x16x32_bf16 v[0:3], v[206:209], v[240:243], v[0:3]
	s_barrier
	s_add_i32 s45, 0, 0x18000
	v_add_u32_e32 v152, s45, v153
	s_add_i32 s46, 0, 0x1c000
	ds_read_b128 v[128:131], v152
	ds_read_b128 v[158:161], v152 offset:1024
	ds_read_b128 v[162:165], v152 offset:2048
	ds_read_b128 v[166:169], v152 offset:3072
	v_add_u32_e32 v152, s46, v153
	ds_read_b128 v[170:173], v152
	ds_read_b128 v[174:177], v152 offset:1024
	ds_read_b128 v[194:197], v152 offset:2048
	ds_read_b128 v[206:209], v152 offset:3072
	s_add_u32 s16, s16, s24
	s_addc_u32 s17, s17, s25
	s_mov_b32 m0, s19
	v_lshl_add_u64 v[202:203], s[16:17], 0, v[132:133]
	ds_read_b128 v[210:213], v157 offset:32768
	ds_read_b128 v[214:217], v157 offset:33792
	ds_read_b128 v[220:223], v157 offset:34816
	ds_read_b128 v[224:227], v157 offset:35840
	ds_read_b128 v[228:231], v157 offset:36864
	ds_read_b128 v[232:235], v157 offset:37888
	ds_read_b128 v[236:239], v157 offset:38912
	ds_read_b128 v[240:243], v157 offset:39936
	global_load_lds_dwordx4 v[202:203], off
	v_lshl_add_u64 v[202:203], s[16:17], 0, v[136:137]
	s_mov_b32 m0, s33
	s_nop 0
	global_load_lds_dwordx4 v[202:203], off
	s_waitcnt vmcnt(8)
	s_waitcnt lgkmcnt(0)
	s_barrier
	s_waitcnt lgkmcnt(0)
	v_mfma_f32_16x16x32_bf16 v[124:127], v[128:131], v[210:213], v[124:127]
	v_mfma_f32_16x16x32_bf16 v[120:123], v[162:165], v[210:213], v[120:123]
	v_mfma_f32_16x16x32_bf16 v[108:111], v[128:131], v[220:223], v[108:111]
	v_mfma_f32_16x16x32_bf16 v[104:107], v[162:165], v[220:223], v[104:107]
	v_mfma_f32_16x16x32_bf16 v[92:95], v[128:131], v[228:231], v[92:95]
	v_mfma_f32_16x16x32_bf16 v[88:91], v[162:165], v[228:231], v[88:91]
	v_mfma_f32_16x16x32_bf16 v[76:79], v[128:131], v[236:239], v[76:79]
	v_mfma_f32_16x16x32_bf16 v[72:75], v[162:165], v[236:239], v[72:75]
	v_mfma_f32_16x16x32_bf16 v[124:127], v[158:161], v[214:217], v[124:127]
	v_mfma_f32_16x16x32_bf16 v[120:123], v[166:169], v[214:217], v[120:123]
	v_mfma_f32_16x16x32_bf16 v[108:111], v[158:161], v[224:227], v[108:111]
	v_mfma_f32_16x16x32_bf16 v[104:107], v[166:169], v[224:227], v[104:107]
	v_mfma_f32_16x16x32_bf16 v[92:95], v[158:161], v[232:235], v[92:95]
	v_mfma_f32_16x16x32_bf16 v[88:91], v[166:169], v[232:235], v[88:91]
	v_mfma_f32_16x16x32_bf16 v[76:79], v[158:161], v[240:243], v[76:79]
	v_mfma_f32_16x16x32_bf16 v[72:75], v[166:169], v[240:243], v[72:75]
	v_mfma_f32_16x16x32_bf16 v[116:119], v[170:173], v[210:213], v[116:119]
	v_mfma_f32_16x16x32_bf16 v[112:115], v[194:197], v[210:213], v[112:115]
	v_mfma_f32_16x16x32_bf16 v[100:103], v[170:173], v[220:223], v[100:103]
	v_mfma_f32_16x16x32_bf16 v[96:99], v[194:197], v[220:223], v[96:99]
	v_mfma_f32_16x16x32_bf16 v[84:87], v[170:173], v[228:231], v[84:87]
	v_mfma_f32_16x16x32_bf16 v[80:83], v[194:197], v[228:231], v[80:83]
	v_mfma_f32_16x16x32_bf16 v[68:71], v[170:173], v[236:239], v[68:71]
	v_mfma_f32_16x16x32_bf16 v[64:67], v[194:197], v[236:239], v[64:67]
	v_mfma_f32_16x16x32_bf16 v[116:119], v[174:177], v[214:217], v[116:119]
	v_mfma_f32_16x16x32_bf16 v[112:115], v[206:209], v[214:217], v[112:115]
	v_mfma_f32_16x16x32_bf16 v[100:103], v[174:177], v[224:227], v[100:103]
	v_mfma_f32_16x16x32_bf16 v[96:99], v[206:209], v[224:227], v[96:99]
	v_mfma_f32_16x16x32_bf16 v[84:87], v[174:177], v[232:235], v[84:87]
	v_mfma_f32_16x16x32_bf16 v[80:83], v[206:209], v[232:235], v[80:83]
	v_mfma_f32_16x16x32_bf16 v[68:71], v[174:177], v[240:243], v[68:71]
	v_mfma_f32_16x16x32_bf16 v[64:67], v[206:209], v[240:243], v[64:67]
	s_barrier
	s_add_i32 s16, s45, s4
	v_lshl_add_u64 v[178:179], v[178:179], 0, s[12:13]
	s_mov_b32 m0, s16
	ds_read_b128 v[210:213], v157 offset:49152
	ds_read_b128 v[214:217], v157 offset:50176
	ds_read_b128 v[220:223], v157 offset:51200
	ds_read_b128 v[224:227], v157 offset:52224
	ds_read_b128 v[228:231], v157 offset:53248
	ds_read_b128 v[232:235], v157 offset:54272
	ds_read_b128 v[236:239], v157 offset:55296
	ds_read_b128 v[240:243], v157 offset:56320
	global_load_lds_dwordx4 v[178:179], off
	v_lshl_add_u64 v[178:179], v[198:199], 0, s[12:13]
	s_add_i32 m0, s16, 0x2000
	s_add_i32 s16, s46, s4
	global_load_lds_dwordx4 v[178:179], off
	v_lshl_add_u64 v[178:179], v[244:245], 0, s[12:13]
	s_mov_b32 m0, s16
	s_nop 0
	global_load_lds_dwordx4 v[178:179], off
	v_lshl_add_u64 v[178:179], v[246:247], 0, s[12:13]
	s_add_i32 m0, s16, 0x2000
	s_nop 0
	global_load_lds_dwordx4 v[178:179], off
	v_lshl_add_u64 v[178:179], v[248:249], 0, s[12:13]
	s_mov_b32 m0, s59
	s_nop 0
	global_load_lds_dwordx4 v[178:179], off
	v_lshl_add_u64 v[178:179], v[250:251], 0, s[12:13]
	s_mov_b32 m0, s60
	s_nop 0
	global_load_lds_dwordx4 v[178:179], off
	s_waitcnt vmcnt(8)
	s_waitcnt lgkmcnt(0)
	s_barrier
	s_waitcnt lgkmcnt(0)
	v_mfma_f32_16x16x32_bf16 v[60:63], v[128:131], v[210:213], v[60:63]
	s_add_u32 s0, s0, 0x100
	v_mfma_f32_16x16x32_bf16 v[56:59], v[162:165], v[210:213], v[56:59]
	s_addc_u32 s1, s1, 0
	v_mfma_f32_16x16x32_bf16 v[44:47], v[128:131], v[220:223], v[44:47]
	s_add_u32 s38, s38, 0x100
	v_mfma_f32_16x16x32_bf16 v[40:43], v[162:165], v[220:223], v[40:43]
	s_addc_u32 s39, s39, 0
	v_mfma_f32_16x16x32_bf16 v[28:31], v[128:131], v[228:231], v[28:31]
	s_mov_b32 s16, s44
	v_mfma_f32_16x16x32_bf16 v[24:27], v[162:165], v[228:231], v[24:27]
	s_cmp_ge_i32 s44, s68
	v_mfma_f32_16x16x32_bf16 v[12:15], v[128:131], v[236:239], v[12:15]
	s_cselect_b32 s99, 1, 0
	v_readfirstlane_b32 s98, v218
	s_bfe_u32 s98, s98, 0x10008
	s_and_b32 s98, s98, s99
	v_mfma_f32_16x16x32_bf16 v[8:11], v[162:165], v[236:239], v[8:11]
	s_add_i32 s44, s16, 2
	v_mfma_f32_16x16x32_bf16 v[60:63], v[158:161], v[214:217], v[60:63]
	s_add_u32 s45, s0, 0x80
	v_mfma_f32_16x16x32_bf16 v[56:59], v[166:169], v[214:217], v[56:59]
	s_addc_u32 s17, s1, 0
	v_mfma_f32_16x16x32_bf16 v[44:47], v[158:161], v[224:227], v[44:47]
	s_add_i32 s64, 0, 0x10000
	v_mfma_f32_16x16x32_bf16 v[40:43], v[166:169], v[224:227], v[40:43]
	s_cmp_eq_u32 s63, s16
	v_mfma_f32_16x16x32_bf16 v[28:31], v[158:161], v[232:235], v[28:31]
	s_cselect_b32 s17, s57, s17
	v_mfma_f32_16x16x32_bf16 v[24:27], v[166:169], v[232:235], v[24:27]
	s_cselect_b32 s16, s56, s45
	v_mfma_f32_16x16x32_bf16 v[12:15], v[158:161], v[240:243], v[12:15]
	s_cselect_b32 s47, s9, s39
	v_mfma_f32_16x16x32_bf16 v[8:11], v[166:169], v[240:243], v[8:11]
	s_cselect_b32 s46, s8, s38
	v_mfma_f32_16x16x32_bf16 v[52:55], v[170:173], v[210:213], v[52:55]
	s_add_i32 s45, 0, 0x14000
	v_mfma_f32_16x16x32_bf16 v[48:51], v[194:197], v[210:213], v[48:51]
	v_mfma_f32_16x16x32_bf16 v[36:39], v[170:173], v[220:223], v[36:39]
	v_mfma_f32_16x16x32_bf16 v[32:35], v[194:197], v[220:223], v[32:35]
	v_mfma_f32_16x16x32_bf16 v[20:23], v[170:173], v[228:231], v[20:23]
	v_mfma_f32_16x16x32_bf16 v[16:19], v[194:197], v[228:231], v[16:19]
	v_mfma_f32_16x16x32_bf16 v[4:7], v[170:173], v[236:239], v[4:7]
	v_mfma_f32_16x16x32_bf16 v[0:3], v[194:197], v[236:239], v[0:3]
	v_mfma_f32_16x16x32_bf16 v[52:55], v[174:177], v[214:217], v[52:55]
	v_mfma_f32_16x16x32_bf16 v[48:51], v[206:209], v[214:217], v[48:51]
	v_mfma_f32_16x16x32_bf16 v[36:39], v[174:177], v[224:227], v[36:39]
	v_mfma_f32_16x16x32_bf16 v[32:35], v[206:209], v[224:227], v[32:35]
	v_mfma_f32_16x16x32_bf16 v[20:23], v[174:177], v[232:235], v[20:23]
	v_mfma_f32_16x16x32_bf16 v[16:19], v[206:209], v[232:235], v[16:19]
	v_mfma_f32_16x16x32_bf16 v[4:7], v[174:177], v[240:243], v[4:7]
	v_mfma_f32_16x16x32_bf16 v[0:3], v[206:209], v[240:243], v[0:3]
	s_cmp_lg_u32 s98, 0
	s_cbranch_scc1 .Lskf_9_peel
	s_barrier

.LBB0_576:
	v_add_u32_e32 v152, s64, v153
	ds_read_b128 v[128:131], v152
	ds_read_b128 v[158:161], v152 offset:1024
	ds_read_b128 v[162:165], v152 offset:2048
	ds_read_b128 v[166:169], v152 offset:3072
	v_add_u32_e32 v152, s45, v153
	ds_read_b128 v[170:173], v152
	ds_read_b128 v[174:177], v152 offset:1024
	ds_read_b128 v[194:197], v152 offset:2048
	ds_read_b128 v[206:209], v152 offset:3072
	v_lshl_add_u64 v[178:179], s[0:1], 0, v[148:149]
	s_add_i32 m0, s52, 0xc000
	ds_read_b128 v[210:213], v157
	ds_read_b128 v[214:217], v157 offset:1024
	ds_read_b128 v[220:223], v157 offset:2048
	ds_read_b128 v[224:227], v157 offset:3072
	ds_read_b128 v[228:231], v157 offset:4096
	ds_read_b128 v[232:235], v157 offset:5120
	ds_read_b128 v[236:239], v157 offset:6144
	ds_read_b128 v[240:243], v157 offset:7168
	global_load_lds_dwordx4 v[178:179], off
	v_lshl_add_u64 v[178:179], s[0:1], 0, v[150:151]
	s_add_i32 m0, s52, 0xe000
	s_nop 0
	global_load_lds_dwordx4 v[178:179], off
	s_waitcnt vmcnt(8)
	s_waitcnt lgkmcnt(0)
	s_barrier
	s_waitcnt lgkmcnt(0)
	v_mfma_f32_16x16x32_bf16 v[124:127], v[128:131], v[210:213], v[124:127]
	v_mfma_f32_16x16x32_bf16 v[120:123], v[162:165], v[210:213], v[120:123]
	v_mfma_f32_16x16x32_bf16 v[108:111], v[128:131], v[220:223], v[108:111]
	v_mfma_f32_16x16x32_bf16 v[104:107], v[162:165], v[220:223], v[104:107]
	v_mfma_f32_16x16x32_bf16 v[92:95], v[128:131], v[228:231], v[92:95]
	v_mfma_f32_16x16x32_bf16 v[88:91], v[162:165], v[228:231], v[88:91]
	v_mfma_f32_16x16x32_bf16 v[76:79], v[128:131], v[236:239], v[76:79]
	v_mfma_f32_16x16x32_bf16 v[72:75], v[162:165], v[236:239], v[72:75]
	v_mfma_f32_16x16x32_bf16 v[124:127], v[158:161], v[214:217], v[124:127]
	v_mfma_f32_16x16x32_bf16 v[120:123], v[166:169], v[214:217], v[120:123]
	v_mfma_f32_16x16x32_bf16 v[108:111], v[158:161], v[224:227], v[108:111]
	v_mfma_f32_16x16x32_bf16 v[104:107], v[166:169], v[224:227], v[104:107]
	v_mfma_f32_16x16x32_bf16 v[92:95], v[158:161], v[232:235], v[92:95]
	v_mfma_f32_16x16x32_bf16 v[88:91], v[166:169], v[232:235], v[88:91]
	v_mfma_f32_16x16x32_bf16 v[76:79], v[158:161], v[240:243], v[76:79]
	v_mfma_f32_16x16x32_bf16 v[72:75], v[166:169], v[240:243], v[72:75]
	v_mfma_f32_16x16x32_bf16 v[116:119], v[170:173], v[210:213], v[116:119]
	v_mfma_f32_16x16x32_bf16 v[112:115], v[194:197], v[210:213], v[112:115]
	v_mfma_f32_16x16x32_bf16 v[100:103], v[170:173], v[220:223], v[100:103]
	v_mfma_f32_16x16x32_bf16 v[96:99], v[194:197], v[220:223], v[96:99]
	v_mfma_f32_16x16x32_bf16 v[84:87], v[170:173], v[228:231], v[84:87]
	v_mfma_f32_16x16x32_bf16 v[80:83], v[194:197], v[228:231], v[80:83]
	v_mfma_f32_16x16x32_bf16 v[68:71], v[170:173], v[236:239], v[68:71]
	v_mfma_f32_16x16x32_bf16 v[64:67], v[194:197], v[236:239], v[64:67]
	v_mfma_f32_16x16x32_bf16 v[116:119], v[174:177], v[214:217], v[116:119]
	v_mfma_f32_16x16x32_bf16 v[112:115], v[206:209], v[214:217], v[112:115]
	v_mfma_f32_16x16x32_bf16 v[100:103], v[174:177], v[224:227], v[100:103]
	v_mfma_f32_16x16x32_bf16 v[96:99], v[206:209], v[224:227], v[96:99]
	v_mfma_f32_16x16x32_bf16 v[84:87], v[174:177], v[232:235], v[84:87]
	v_mfma_f32_16x16x32_bf16 v[80:83], v[206:209], v[232:235], v[80:83]
	v_mfma_f32_16x16x32_bf16 v[68:71], v[174:177], v[240:243], v[68:71]
	v_mfma_f32_16x16x32_bf16 v[64:67], v[206:209], v[240:243], v[64:67]
	s_barrier
	s_add_i32 s64, s64, s4
	v_lshl_add_u64 v[178:179], s[46:47], 0, v[134:135]
	s_mov_b32 m0, s64
	ds_read_b128 v[210:213], v157 offset:16384
	ds_read_b128 v[214:217], v157 offset:17408
	ds_read_b128 v[220:223], v157 offset:18432
	ds_read_b128 v[224:227], v157 offset:19456
	ds_read_b128 v[228:231], v157 offset:20480
	ds_read_b128 v[232:235], v157 offset:21504
	ds_read_b128 v[236:239], v157 offset:22528
	ds_read_b128 v[240:243], v157 offset:23552
	global_load_lds_dwordx4 v[178:179], off
	s_add_i32 m0, s64, 0x2000
	v_lshl_add_u64 v[198:199], s[46:47], 0, v[138:139]
	s_add_u32 s46, s46, s24
	s_addc_u32 s47, s47, s25
	s_add_i32 s45, s45, s4
	global_load_lds_dwordx4 v[198:199], off
	v_lshl_add_u64 v[244:245], s[46:47], 0, v[134:135]
	s_mov_b32 m0, s45
	v_lshl_add_u64 v[246:247], s[46:47], 0, v[138:139]
	global_load_lds_dwordx4 v[244:245], off
	s_add_i32 m0, s45, 0x2000
	v_lshl_add_u64 v[248:249], s[16:17], 0, v[132:133]
	global_load_lds_dwordx4 v[246:247], off
	s_mov_b32 m0, s52
	v_lshl_add_u64 v[250:251], s[16:17], 0, v[136:137]
	global_load_lds_dwordx4 v[248:249], off
	s_mov_b32 m0, s18
	s_nop 0
	global_load_lds_dwordx4 v[250:251], off
	s_waitcnt vmcnt(8)
	s_waitcnt lgkmcnt(0)
	s_barrier
	s_waitcnt lgkmcnt(0)
	v_mfma_f32_16x16x32_bf16 v[60:63], v[128:131], v[210:213], v[60:63]
	v_mfma_f32_16x16x32_bf16 v[56:59], v[162:165], v[210:213], v[56:59]
	v_mfma_f32_16x16x32_bf16 v[44:47], v[128:131], v[220:223], v[44:47]
	v_mfma_f32_16x16x32_bf16 v[40:43], v[162:165], v[220:223], v[40:43]
	v_mfma_f32_16x16x32_bf16 v[28:31], v[128:131], v[228:231], v[28:31]
	v_mfma_f32_16x16x32_bf16 v[24:27], v[162:165], v[228:231], v[24:27]
	v_mfma_f32_16x16x32_bf16 v[12:15], v[128:131], v[236:239], v[12:15]
	v_mfma_f32_16x16x32_bf16 v[8:11], v[162:165], v[236:239], v[8:11]
	v_mfma_f32_16x16x32_bf16 v[60:63], v[158:161], v[214:217], v[60:63]
	v_mfma_f32_16x16x32_bf16 v[56:59], v[166:169], v[214:217], v[56:59]
	v_mfma_f32_16x16x32_bf16 v[44:47], v[158:161], v[224:227], v[44:47]
	v_mfma_f32_16x16x32_bf16 v[40:43], v[166:169], v[224:227], v[40:43]
	v_mfma_f32_16x16x32_bf16 v[28:31], v[158:161], v[232:235], v[28:31]
	v_mfma_f32_16x16x32_bf16 v[24:27], v[166:169], v[232:235], v[24:27]
	v_mfma_f32_16x16x32_bf16 v[12:15], v[158:161], v[240:243], v[12:15]
	v_mfma_f32_16x16x32_bf16 v[8:11], v[166:169], v[240:243], v[8:11]
	v_mfma_f32_16x16x32_bf16 v[52:55], v[170:173], v[210:213], v[52:55]
	v_mfma_f32_16x16x32_bf16 v[48:51], v[194:197], v[210:213], v[48:51]
	v_mfma_f32_16x16x32_bf16 v[36:39], v[170:173], v[220:223], v[36:39]
	v_mfma_f32_16x16x32_bf16 v[32:35], v[194:197], v[220:223], v[32:35]
	v_mfma_f32_16x16x32_bf16 v[20:23], v[170:173], v[228:231], v[20:23]
	v_mfma_f32_16x16x32_bf16 v[16:19], v[194:197], v[228:231], v[16:19]
	v_mfma_f32_16x16x32_bf16 v[4:7], v[170:173], v[236:239], v[4:7]
	v_mfma_f32_16x16x32_bf16 v[0:3], v[194:197], v[236:239], v[0:3]
	v_mfma_f32_16x16x32_bf16 v[52:55], v[174:177], v[214:217], v[52:55]
	v_mfma_f32_16x16x32_bf16 v[48:51], v[206:209], v[214:217], v[48:51]
	v_mfma_f32_16x16x32_bf16 v[36:39], v[174:177], v[224:227], v[36:39]
	v_mfma_f32_16x16x32_bf16 v[32:35], v[206:209], v[224:227], v[32:35]
	v_mfma_f32_16x16x32_bf16 v[20:23], v[174:177], v[232:235], v[20:23]
	v_mfma_f32_16x16x32_bf16 v[16:19], v[206:209], v[232:235], v[16:19]
	v_mfma_f32_16x16x32_bf16 v[4:7], v[174:177], v[240:243], v[4:7]
	v_mfma_f32_16x16x32_bf16 v[0:3], v[206:209], v[240:243], v[0:3]
	s_barrier
	s_add_i32 s45, 0, 0x18000
	v_add_u32_e32 v152, s45, v153
	s_add_i32 s46, 0, 0x1c000
	ds_read_b128 v[128:131], v152
	ds_read_b128 v[158:161], v152 offset:1024
	ds_read_b128 v[162:165], v152 offset:2048
	ds_read_b128 v[166:169], v152 offset:3072
	v_add_u32_e32 v152, s46, v153
	ds_read_b128 v[170:173], v152
	ds_read_b128 v[174:177], v152 offset:1024
	ds_read_b128 v[194:197], v152 offset:2048
	ds_read_b128 v[206:209], v152 offset:3072
	s_add_u32 s16, s16, s24
	s_addc_u32 s17, s17, s25
	s_mov_b32 m0, s19
	v_lshl_add_u64 v[202:203], s[16:17], 0, v[132:133]
	ds_read_b128 v[210:213], v157 offset:32768
	ds_read_b128 v[214:217], v157 offset:33792
	ds_read_b128 v[220:223], v157 offset:34816
	ds_read_b128 v[224:227], v157 offset:35840
	ds_read_b128 v[228:231], v157 offset:36864
	ds_read_b128 v[232:235], v157 offset:37888
	ds_read_b128 v[236:239], v157 offset:38912
	ds_read_b128 v[240:243], v157 offset:39936
	global_load_lds_dwordx4 v[202:203], off
	v_lshl_add_u64 v[202:203], s[16:17], 0, v[136:137]
	s_mov_b32 m0, s33
	s_nop 0
	global_load_lds_dwordx4 v[202:203], off
	s_waitcnt vmcnt(8)
	s_waitcnt lgkmcnt(0)
	s_barrier
	s_waitcnt lgkmcnt(0)
	v_mfma_f32_16x16x32_bf16 v[124:127], v[128:131], v[210:213], v[124:127]
	v_mfma_f32_16x16x32_bf16 v[120:123], v[162:165], v[210:213], v[120:123]
	v_mfma_f32_16x16x32_bf16 v[108:111], v[128:131], v[220:223], v[108:111]
	v_mfma_f32_16x16x32_bf16 v[104:107], v[162:165], v[220:223], v[104:107]
	v_mfma_f32_16x16x32_bf16 v[92:95], v[128:131], v[228:231], v[92:95]
	v_mfma_f32_16x16x32_bf16 v[88:91], v[162:165], v[228:231], v[88:91]
	v_mfma_f32_16x16x32_bf16 v[76:79], v[128:131], v[236:239], v[76:79]
	v_mfma_f32_16x16x32_bf16 v[72:75], v[162:165], v[236:239], v[72:75]
	v_mfma_f32_16x16x32_bf16 v[124:127], v[158:161], v[214:217], v[124:127]
	v_mfma_f32_16x16x32_bf16 v[120:123], v[166:169], v[214:217], v[120:123]
	v_mfma_f32_16x16x32_bf16 v[108:111], v[158:161], v[224:227], v[108:111]
	v_mfma_f32_16x16x32_bf16 v[104:107], v[166:169], v[224:227], v[104:107]
	v_mfma_f32_16x16x32_bf16 v[92:95], v[158:161], v[232:235], v[92:95]
	v_mfma_f32_16x16x32_bf16 v[88:91], v[166:169], v[232:235], v[88:91]
	v_mfma_f32_16x16x32_bf16 v[76:79], v[158:161], v[240:243], v[76:79]
	v_mfma_f32_16x16x32_bf16 v[72:75], v[166:169], v[240:243], v[72:75]
	v_mfma_f32_16x16x32_bf16 v[116:119], v[170:173], v[210:213], v[116:119]
	v_mfma_f32_16x16x32_bf16 v[112:115], v[194:197], v[210:213], v[112:115]
	v_mfma_f32_16x16x32_bf16 v[100:103], v[170:173], v[220:223], v[100:103]
	v_mfma_f32_16x16x32_bf16 v[96:99], v[194:197], v[220:223], v[96:99]
	v_mfma_f32_16x16x32_bf16 v[84:87], v[170:173], v[228:231], v[84:87]
	v_mfma_f32_16x16x32_bf16 v[80:83], v[194:197], v[228:231], v[80:83]
	v_mfma_f32_16x16x32_bf16 v[68:71], v[170:173], v[236:239], v[68:71]
	v_mfma_f32_16x16x32_bf16 v[64:67], v[194:197], v[236:239], v[64:67]
	v_mfma_f32_16x16x32_bf16 v[116:119], v[174:177], v[214:217], v[116:119]
	v_mfma_f32_16x16x32_bf16 v[112:115], v[206:209], v[214:217], v[112:115]
	v_mfma_f32_16x16x32_bf16 v[100:103], v[174:177], v[224:227], v[100:103]
	v_mfma_f32_16x16x32_bf16 v[96:99], v[206:209], v[224:227], v[96:99]
	v_mfma_f32_16x16x32_bf16 v[84:87], v[174:177], v[232:235], v[84:87]
	v_mfma_f32_16x16x32_bf16 v[80:83], v[206:209], v[232:235], v[80:83]
	v_mfma_f32_16x16x32_bf16 v[68:71], v[174:177], v[240:243], v[68:71]
	v_mfma_f32_16x16x32_bf16 v[64:67], v[206:209], v[240:243], v[64:67]
	s_barrier
	s_add_i32 s16, s45, s4
	v_lshl_add_u64 v[178:179], v[178:179], 0, s[12:13]
	s_mov_b32 m0, s16
	ds_read_b128 v[210:213], v157 offset:49152
	ds_read_b128 v[214:217], v157 offset:50176
	ds_read_b128 v[220:223], v157 offset:51200
	ds_read_b128 v[224:227], v157 offset:52224
	ds_read_b128 v[228:231], v157 offset:53248
	ds_read_b128 v[232:235], v157 offset:54272
	ds_read_b128 v[236:239], v157 offset:55296
	ds_read_b128 v[240:243], v157 offset:56320
	global_load_lds_dwordx4 v[178:179], off
	v_lshl_add_u64 v[178:179], v[198:199], 0, s[12:13]
	s_add_i32 m0, s16, 0x2000
	s_add_i32 s16, s46, s4
	global_load_lds_dwordx4 v[178:179], off
	v_lshl_add_u64 v[178:179], v[244:245], 0, s[12:13]
	s_mov_b32 m0, s16
	s_nop 0
	global_load_lds_dwordx4 v[178:179], off
	v_lshl_add_u64 v[178:179], v[246:247], 0, s[12:13]
	s_add_i32 m0, s16, 0x2000
	s_nop 0
	global_load_lds_dwordx4 v[178:179], off
	v_lshl_add_u64 v[178:179], v[248:249], 0, s[12:13]
	s_mov_b32 m0, s59
	s_nop 0
	global_load_lds_dwordx4 v[178:179], off
	v_lshl_add_u64 v[178:179], v[250:251], 0, s[12:13]
	s_mov_b32 m0, s60
	s_nop 0
	global_load_lds_dwordx4 v[178:179], off
	s_waitcnt vmcnt(8)
	s_waitcnt lgkmcnt(0)
	s_barrier
	s_waitcnt lgkmcnt(0)
	v_mfma_f32_16x16x32_bf16 v[60:63], v[128:131], v[210:213], v[60:63]
	s_add_u32 s0, s0, 0x100
	v_mfma_f32_16x16x32_bf16 v[56:59], v[162:165], v[210:213], v[56:59]
	s_addc_u32 s1, s1, 0
	v_mfma_f32_16x16x32_bf16 v[44:47], v[128:131], v[220:223], v[44:47]
	s_add_u32 s38, s38, 0x100
	v_mfma_f32_16x16x32_bf16 v[40:43], v[162:165], v[220:223], v[40:43]
	s_addc_u32 s39, s39, 0
	v_mfma_f32_16x16x32_bf16 v[28:31], v[128:131], v[228:231], v[28:31]
	s_mov_b32 s16, s44
	v_mfma_f32_16x16x32_bf16 v[24:27], v[162:165], v[228:231], v[24:27]
	s_cmp_ge_i32 s44, s68
	v_mfma_f32_16x16x32_bf16 v[12:15], v[128:131], v[236:239], v[12:15]
	s_cselect_b32 s99, 1, 0
	v_readfirstlane_b32 s98, v218
	s_bfe_u32 s98, s98, 0x10008
	s_and_b32 s98, s98, s99
	v_mfma_f32_16x16x32_bf16 v[8:11], v[162:165], v[236:239], v[8:11]
	s_add_i32 s44, s16, 2
	v_mfma_f32_16x16x32_bf16 v[60:63], v[158:161], v[214:217], v[60:63]
	s_add_u32 s45, s0, 0x80
	v_mfma_f32_16x16x32_bf16 v[56:59], v[166:169], v[214:217], v[56:59]
	s_addc_u32 s17, s1, 0
	v_mfma_f32_16x16x32_bf16 v[44:47], v[158:161], v[224:227], v[44:47]
	s_add_i32 s64, 0, 0x10000
	v_mfma_f32_16x16x32_bf16 v[40:43], v[166:169], v[224:227], v[40:43]
	s_cmp_eq_u32 s63, s16
	v_mfma_f32_16x16x32_bf16 v[28:31], v[158:161], v[232:235], v[28:31]
	s_cselect_b32 s17, s57, s17
	v_mfma_f32_16x16x32_bf16 v[24:27], v[166:169], v[232:235], v[24:27]
	s_cselect_b32 s16, s56, s45
	v_mfma_f32_16x16x32_bf16 v[12:15], v[158:161], v[240:243], v[12:15]
	s_cselect_b32 s47, s9, s39
	v_mfma_f32_16x16x32_bf16 v[8:11], v[166:169], v[240:243], v[8:11]
	s_cselect_b32 s46, s8, s38
	v_mfma_f32_16x16x32_bf16 v[52:55], v[170:173], v[210:213], v[52:55]
	s_add_i32 s45, 0, 0x14000
	v_mfma_f32_16x16x32_bf16 v[48:51], v[194:197], v[210:213], v[48:51]
	v_mfma_f32_16x16x32_bf16 v[36:39], v[170:173], v[220:223], v[36:39]
	v_mfma_f32_16x16x32_bf16 v[32:35], v[194:197], v[220:223], v[32:35]
	v_mfma_f32_16x16x32_bf16 v[20:23], v[170:173], v[228:231], v[20:23]
	v_mfma_f32_16x16x32_bf16 v[16:19], v[194:197], v[228:231], v[16:19]
	v_mfma_f32_16x16x32_bf16 v[4:7], v[170:173], v[236:239], v[4:7]
	v_mfma_f32_16x16x32_bf16 v[0:3], v[194:197], v[236:239], v[0:3]
	v_mfma_f32_16x16x32_bf16 v[52:55], v[174:177], v[214:217], v[52:55]
	v_mfma_f32_16x16x32_bf16 v[48:51], v[206:209], v[214:217], v[48:51]
	v_mfma_f32_16x16x32_bf16 v[36:39], v[174:177], v[224:227], v[36:39]
	v_mfma_f32_16x16x32_bf16 v[32:35], v[206:209], v[224:227], v[32:35]
	v_mfma_f32_16x16x32_bf16 v[20:23], v[174:177], v[232:235], v[20:23]
	v_mfma_f32_16x16x32_bf16 v[16:19], v[206:209], v[232:235], v[16:19]
	v_mfma_f32_16x16x32_bf16 v[4:7], v[174:177], v[240:243], v[4:7]
	v_mfma_f32_16x16x32_bf16 v[0:3], v[206:209], v[240:243], v[0:3]
	s_cmp_lg_u32 s98, 0
	s_cbranch_scc1 .Lskf_9_loop
	s_barrier

.Lpeelx_9:
.LBB0_577:
	s_and_b64 vcc, exec, s[6:7]
	s_cbranch_vccz .LBB0_579
	s_nop 0

.LBB0_785:
	s_barrier
	s_andn2_b64 vcc, exec, s[10:11]
	s_mov_b32 s57, s52
	s_mov_b32 s58, s56
	s_mov_b64 s[30:31], s[26:27]
	s_mov_b64 s[16:17], s[24:25]
	s_cbranch_vccz .LBB0_804

.Llbb_6:
	s_add_i32 s30, s16, 2
	s_add_u32 s31, s28, 0x80
	s_addc_u32 s17, s29, 0
	s_add_i32 s59, 0, 0x10000
	s_cmp_eq_u32 s48, s16
	s_cselect_b32 s17, s25, s17
	s_cselect_b32 s16, s24, s31
	v_add_u32_e32 v140, s59, v143
	s_cselect_b32 s43, s27, s11
	s_cselect_b32 s42, s26, s10
	s_add_i32 s31, 0, 0x14000
	ds_read_b128 v[146:149], v140
	ds_read_b128 v[150:153], v140 offset:1024
	ds_read_b128 v[154:157], v140 offset:2048
	ds_read_b128 v[158:161], v140 offset:3072
	v_add_u32_e32 v140, s31, v143
	ds_read_b128 v[162:165], v140
	ds_read_b128 v[166:169], v140 offset:1024
	ds_read_b128 v[170:173], v140 offset:2048
	ds_read_b128 v[174:177], v140 offset:3072
	v_lshl_add_u64 v[178:179], s[28:29], 0, v[136:137]
	s_add_i32 m0, s37, 0xc000
	ds_read_b128 v[194:197], v145
	ds_read_b128 v[206:209], v145 offset:1024
	ds_read_b128 v[210:213], v145 offset:2048
	ds_read_b128 v[214:217], v145 offset:3072
	ds_read_b128 v[220:223], v145 offset:4096
	ds_read_b128 v[224:227], v145 offset:5120
	ds_read_b128 v[228:231], v145 offset:6144
	ds_read_b128 v[232:235], v145 offset:7168
	global_load_lds_dwordx4 v[178:179], off
	v_lshl_add_u64 v[178:179], s[28:29], 0, v[138:139]
	s_add_i32 m0, s37, 0xe000
	s_nop 0
	global_load_lds_dwordx4 v[178:179], off
	s_waitcnt vmcnt(8)
	s_waitcnt lgkmcnt(0)
	s_barrier
	s_waitcnt lgkmcnt(0)
	v_mfma_f32_16x16x32_bf16 v[124:127], v[146:149], v[194:197], 0
	v_mfma_f32_16x16x32_bf16 v[120:123], v[154:157], v[194:197], 0
	v_mfma_f32_16x16x32_bf16 v[108:111], v[146:149], v[210:213], 0
	v_mfma_f32_16x16x32_bf16 v[104:107], v[154:157], v[210:213], 0
	v_mfma_f32_16x16x32_bf16 v[92:95], v[146:149], v[220:223], 0
	v_mfma_f32_16x16x32_bf16 v[88:91], v[154:157], v[220:223], 0
	v_mfma_f32_16x16x32_bf16 v[76:79], v[146:149], v[228:231], 0
	v_mfma_f32_16x16x32_bf16 v[72:75], v[154:157], v[228:231], 0
	v_mfma_f32_16x16x32_bf16 v[124:127], v[150:153], v[206:209], v[124:127]
	v_mfma_f32_16x16x32_bf16 v[120:123], v[158:161], v[206:209], v[120:123]
	v_mfma_f32_16x16x32_bf16 v[108:111], v[150:153], v[214:217], v[108:111]
	v_mfma_f32_16x16x32_bf16 v[104:107], v[158:161], v[214:217], v[104:107]
	v_mfma_f32_16x16x32_bf16 v[92:95], v[150:153], v[224:227], v[92:95]
	v_mfma_f32_16x16x32_bf16 v[88:91], v[158:161], v[224:227], v[88:91]
	v_mfma_f32_16x16x32_bf16 v[76:79], v[150:153], v[232:235], v[76:79]
	v_mfma_f32_16x16x32_bf16 v[72:75], v[158:161], v[232:235], v[72:75]
	v_mfma_f32_16x16x32_bf16 v[116:119], v[162:165], v[194:197], 0
	v_mfma_f32_16x16x32_bf16 v[112:115], v[170:173], v[194:197], 0
	v_mfma_f32_16x16x32_bf16 v[100:103], v[162:165], v[210:213], 0
	v_mfma_f32_16x16x32_bf16 v[96:99], v[170:173], v[210:213], 0
	v_mfma_f32_16x16x32_bf16 v[84:87], v[162:165], v[220:223], 0
	v_mfma_f32_16x16x32_bf16 v[80:83], v[170:173], v[220:223], 0
	v_mfma_f32_16x16x32_bf16 v[68:71], v[162:165], v[228:231], 0
	v_mfma_f32_16x16x32_bf16 v[64:67], v[170:173], v[228:231], 0
	v_mfma_f32_16x16x32_bf16 v[116:119], v[166:169], v[206:209], v[116:119]
	v_mfma_f32_16x16x32_bf16 v[112:115], v[174:177], v[206:209], v[112:115]
	v_mfma_f32_16x16x32_bf16 v[100:103], v[166:169], v[214:217], v[100:103]
	v_mfma_f32_16x16x32_bf16 v[96:99], v[174:177], v[214:217], v[96:99]
	v_mfma_f32_16x16x32_bf16 v[84:87], v[166:169], v[224:227], v[84:87]
	v_mfma_f32_16x16x32_bf16 v[80:83], v[174:177], v[224:227], v[80:83]
	v_mfma_f32_16x16x32_bf16 v[68:71], v[166:169], v[232:235], v[68:71]
	v_mfma_f32_16x16x32_bf16 v[64:67], v[174:177], v[232:235], v[64:67]
	s_barrier
	s_add_i32 s59, s59, s36
	v_lshl_add_u64 v[178:179], s[42:43], 0, v[132:133]
	s_mov_b32 m0, s59
	ds_read_b128 v[194:197], v145 offset:16384
	ds_read_b128 v[206:209], v145 offset:17408
	ds_read_b128 v[210:213], v145 offset:18432
	ds_read_b128 v[214:217], v145 offset:19456
	ds_read_b128 v[220:223], v145 offset:20480
	ds_read_b128 v[224:227], v145 offset:21504
	ds_read_b128 v[228:231], v145 offset:22528
	ds_read_b128 v[232:235], v145 offset:23552
	global_load_lds_dwordx4 v[178:179], off
	s_add_i32 m0, s59, 0x2000
	v_lshl_add_u64 v[198:199], s[42:43], 0, v[128:129]
	s_add_u32 s42, s42, s0
	s_addc_u32 s43, s43, s1
	s_add_i32 s31, s31, s36
	global_load_lds_dwordx4 v[198:199], off
	v_lshl_add_u64 v[202:203], s[42:43], 0, v[132:133]
	s_mov_b32 m0, s31
	v_lshl_add_u64 v[236:237], s[42:43], 0, v[128:129]
	global_load_lds_dwordx4 v[202:203], off
	s_add_i32 m0, s31, 0x2000
	v_lshl_add_u64 v[238:239], s[16:17], 0, v[134:135]
	global_load_lds_dwordx4 v[236:237], off
	s_mov_b32 m0, s37
	v_lshl_add_u64 v[240:241], s[16:17], 0, v[130:131]
	global_load_lds_dwordx4 v[238:239], off
	s_mov_b32 m0, s38
	s_nop 0
	global_load_lds_dwordx4 v[240:241], off
	s_waitcnt vmcnt(8)
	s_waitcnt lgkmcnt(0)
	s_barrier
	s_waitcnt lgkmcnt(0)
	v_mfma_f32_16x16x32_bf16 v[60:63], v[146:149], v[194:197], 0
	v_mfma_f32_16x16x32_bf16 v[56:59], v[154:157], v[194:197], 0
	v_mfma_f32_16x16x32_bf16 v[44:47], v[146:149], v[210:213], 0
	v_mfma_f32_16x16x32_bf16 v[40:43], v[154:157], v[210:213], 0
	v_mfma_f32_16x16x32_bf16 v[28:31], v[146:149], v[220:223], 0
	v_mfma_f32_16x16x32_bf16 v[24:27], v[154:157], v[220:223], 0
	v_mfma_f32_16x16x32_bf16 v[12:15], v[146:149], v[228:231], 0
	v_mfma_f32_16x16x32_bf16 v[8:11], v[154:157], v[228:231], 0
	v_mfma_f32_16x16x32_bf16 v[60:63], v[150:153], v[206:209], v[60:63]
	v_mfma_f32_16x16x32_bf16 v[56:59], v[158:161], v[206:209], v[56:59]
	v_mfma_f32_16x16x32_bf16 v[44:47], v[150:153], v[214:217], v[44:47]
	v_mfma_f32_16x16x32_bf16 v[40:43], v[158:161], v[214:217], v[40:43]
	v_mfma_f32_16x16x32_bf16 v[28:31], v[150:153], v[224:227], v[28:31]
	v_mfma_f32_16x16x32_bf16 v[24:27], v[158:161], v[224:227], v[24:27]
	v_mfma_f32_16x16x32_bf16 v[12:15], v[150:153], v[232:235], v[12:15]
	v_mfma_f32_16x16x32_bf16 v[8:11], v[158:161], v[232:235], v[8:11]
	v_mfma_f32_16x16x32_bf16 v[52:55], v[162:165], v[194:197], 0
	v_mfma_f32_16x16x32_bf16 v[48:51], v[170:173], v[194:197], 0
	v_mfma_f32_16x16x32_bf16 v[36:39], v[162:165], v[210:213], 0
	v_mfma_f32_16x16x32_bf16 v[32:35], v[170:173], v[210:213], 0
	v_mfma_f32_16x16x32_bf16 v[20:23], v[162:165], v[220:223], 0
	v_mfma_f32_16x16x32_bf16 v[16:19], v[170:173], v[220:223], 0
	v_mfma_f32_16x16x32_bf16 v[4:7], v[162:165], v[228:231], 0
	v_mfma_f32_16x16x32_bf16 v[0:3], v[170:173], v[228:231], 0
	v_mfma_f32_16x16x32_bf16 v[52:55], v[166:169], v[206:209], v[52:55]
	v_mfma_f32_16x16x32_bf16 v[48:51], v[174:177], v[206:209], v[48:51]
	v_mfma_f32_16x16x32_bf16 v[36:39], v[166:169], v[214:217], v[36:39]
	v_mfma_f32_16x16x32_bf16 v[32:35], v[174:177], v[214:217], v[32:35]
	v_mfma_f32_16x16x32_bf16 v[20:23], v[166:169], v[224:227], v[20:23]
	v_mfma_f32_16x16x32_bf16 v[16:19], v[174:177], v[224:227], v[16:19]
	v_mfma_f32_16x16x32_bf16 v[4:7], v[166:169], v[232:235], v[4:7]
	v_mfma_f32_16x16x32_bf16 v[0:3], v[174:177], v[232:235], v[0:3]
	s_barrier
	s_add_i32 s31, 0, 0x18000
	v_add_u32_e32 v140, s31, v143
	s_add_i32 s42, 0, 0x1c000
	ds_read_b128 v[146:149], v140
	ds_read_b128 v[150:153], v140 offset:1024
	ds_read_b128 v[154:157], v140 offset:2048
	ds_read_b128 v[158:161], v140 offset:3072
	v_add_u32_e32 v140, s42, v143
	ds_read_b128 v[162:165], v140
	ds_read_b128 v[166:169], v140 offset:1024
	ds_read_b128 v[170:173], v140 offset:2048
	ds_read_b128 v[174:177], v140 offset:3072
	s_add_u32 s16, s16, s0
	s_addc_u32 s17, s17, s1
	s_mov_b32 m0, s39
	v_lshl_add_u64 v[242:243], s[16:17], 0, v[134:135]
	ds_read_b128 v[194:197], v145 offset:32768
	ds_read_b128 v[206:209], v145 offset:33792
	ds_read_b128 v[210:213], v145 offset:34816
	ds_read_b128 v[214:217], v145 offset:35840
	ds_read_b128 v[220:223], v145 offset:36864
	ds_read_b128 v[224:227], v145 offset:37888
	ds_read_b128 v[228:231], v145 offset:38912
	ds_read_b128 v[232:235], v145 offset:39936
	global_load_lds_dwordx4 v[242:243], off
	v_lshl_add_u64 v[242:243], s[16:17], 0, v[130:131]
	s_mov_b32 m0, s44
	s_nop 0
	global_load_lds_dwordx4 v[242:243], off
	s_waitcnt vmcnt(8)
	s_waitcnt lgkmcnt(0)
	s_barrier
	s_waitcnt lgkmcnt(0)
	v_mfma_f32_16x16x32_bf16 v[124:127], v[146:149], v[194:197], v[124:127]
	v_mfma_f32_16x16x32_bf16 v[120:123], v[154:157], v[194:197], v[120:123]
	v_mfma_f32_16x16x32_bf16 v[108:111], v[146:149], v[210:213], v[108:111]
	v_mfma_f32_16x16x32_bf16 v[104:107], v[154:157], v[210:213], v[104:107]
	v_mfma_f32_16x16x32_bf16 v[92:95], v[146:149], v[220:223], v[92:95]
	v_mfma_f32_16x16x32_bf16 v[88:91], v[154:157], v[220:223], v[88:91]
	v_mfma_f32_16x16x32_bf16 v[76:79], v[146:149], v[228:231], v[76:79]
	v_mfma_f32_16x16x32_bf16 v[72:75], v[154:157], v[228:231], v[72:75]
	v_mfma_f32_16x16x32_bf16 v[124:127], v[150:153], v[206:209], v[124:127]
	v_mfma_f32_16x16x32_bf16 v[120:123], v[158:161], v[206:209], v[120:123]
	v_mfma_f32_16x16x32_bf16 v[108:111], v[150:153], v[214:217], v[108:111]
	v_mfma_f32_16x16x32_bf16 v[104:107], v[158:161], v[214:217], v[104:107]
	v_mfma_f32_16x16x32_bf16 v[92:95], v[150:153], v[224:227], v[92:95]
	v_mfma_f32_16x16x32_bf16 v[88:91], v[158:161], v[224:227], v[88:91]
	v_mfma_f32_16x16x32_bf16 v[76:79], v[150:153], v[232:235], v[76:79]
	v_mfma_f32_16x16x32_bf16 v[72:75], v[158:161], v[232:235], v[72:75]
	v_mfma_f32_16x16x32_bf16 v[116:119], v[162:165], v[194:197], v[116:119]
	v_mfma_f32_16x16x32_bf16 v[112:115], v[170:173], v[194:197], v[112:115]
	v_mfma_f32_16x16x32_bf16 v[100:103], v[162:165], v[210:213], v[100:103]
	v_mfma_f32_16x16x32_bf16 v[96:99], v[170:173], v[210:213], v[96:99]
	v_mfma_f32_16x16x32_bf16 v[84:87], v[162:165], v[220:223], v[84:87]
	v_mfma_f32_16x16x32_bf16 v[80:83], v[170:173], v[220:223], v[80:83]
	v_mfma_f32_16x16x32_bf16 v[68:71], v[162:165], v[228:231], v[68:71]
	v_mfma_f32_16x16x32_bf16 v[64:67], v[170:173], v[228:231], v[64:67]
	v_mfma_f32_16x16x32_bf16 v[116:119], v[166:169], v[206:209], v[116:119]
	v_mfma_f32_16x16x32_bf16 v[112:115], v[174:177], v[206:209], v[112:115]
	v_mfma_f32_16x16x32_bf16 v[100:103], v[166:169], v[214:217], v[100:103]
	v_mfma_f32_16x16x32_bf16 v[96:99], v[174:177], v[214:217], v[96:99]
	v_mfma_f32_16x16x32_bf16 v[84:87], v[166:169], v[224:227], v[84:87]
	v_mfma_f32_16x16x32_bf16 v[80:83], v[174:177], v[224:227], v[80:83]
	v_mfma_f32_16x16x32_bf16 v[68:71], v[166:169], v[232:235], v[68:71]
	v_mfma_f32_16x16x32_bf16 v[64:67], v[174:177], v[232:235], v[64:67]
	s_barrier
	s_add_i32 s16, s31, s36
	v_lshl_add_u64 v[178:179], v[178:179], 0, s[12:13]
	s_mov_b32 m0, s16
	ds_read_b128 v[194:197], v145 offset:49152
	ds_read_b128 v[206:209], v145 offset:50176
	ds_read_b128 v[210:213], v145 offset:51200
	ds_read_b128 v[214:217], v145 offset:52224
	ds_read_b128 v[220:223], v145 offset:53248
	ds_read_b128 v[224:227], v145 offset:54272
	ds_read_b128 v[228:231], v145 offset:55296
	ds_read_b128 v[232:235], v145 offset:56320
	global_load_lds_dwordx4 v[178:179], off
	v_lshl_add_u64 v[178:179], v[198:199], 0, s[12:13]
	s_add_i32 m0, s16, 0x2000
	s_add_i32 s16, s42, s36
	global_load_lds_dwordx4 v[178:179], off
	v_lshl_add_u64 v[178:179], v[202:203], 0, s[12:13]
	s_mov_b32 m0, s16
	s_nop 0
	global_load_lds_dwordx4 v[178:179], off
	v_lshl_add_u64 v[178:179], v[236:237], 0, s[12:13]
	s_add_i32 m0, s16, 0x2000
	s_nop 0
	global_load_lds_dwordx4 v[178:179], off
	v_lshl_add_u64 v[178:179], v[238:239], 0, s[12:13]
	s_mov_b32 m0, s45
	s_nop 0
	global_load_lds_dwordx4 v[178:179], off
	v_lshl_add_u64 v[178:179], v[240:241], 0, s[12:13]
	s_mov_b32 m0, s46
	s_nop 0
	global_load_lds_dwordx4 v[178:179], off
	s_waitcnt vmcnt(8)
	s_waitcnt lgkmcnt(0)
	s_barrier
	s_waitcnt lgkmcnt(0)
	v_mfma_f32_16x16x32_bf16 v[60:63], v[146:149], v[194:197], v[60:63]
	s_add_u32 s28, s28, 0x100
	v_mfma_f32_16x16x32_bf16 v[56:59], v[154:157], v[194:197], v[56:59]
	s_addc_u32 s29, s29, 0
	v_mfma_f32_16x16x32_bf16 v[44:47], v[146:149], v[210:213], v[44:47]
	s_add_u32 s10, s10, 0x100
	v_mfma_f32_16x16x32_bf16 v[40:43], v[154:157], v[210:213], v[40:43]
	s_addc_u32 s11, s11, 0
	v_mfma_f32_16x16x32_bf16 v[28:31], v[146:149], v[220:223], v[28:31]
	s_mov_b32 s16, s30
	v_mfma_f32_16x16x32_bf16 v[24:27], v[154:157], v[220:223], v[24:27]
	s_cmp_ge_i32 s30, s47
	v_mfma_f32_16x16x32_bf16 v[12:15], v[146:149], v[228:231], v[12:15]
	s_cselect_b32 s99, 1, 0
	v_readfirstlane_b32 s98, v218
	s_bfe_u32 s98, s98, 0x10008
	s_and_b32 s98, s98, s99
	v_mfma_f32_16x16x32_bf16 v[8:11], v[154:157], v[228:231], v[8:11]
	s_add_i32 s30, s16, 2
	v_mfma_f32_16x16x32_bf16 v[60:63], v[150:153], v[206:209], v[60:63]
	s_add_u32 s31, s28, 0x80
	v_mfma_f32_16x16x32_bf16 v[56:59], v[158:161], v[206:209], v[56:59]
	s_addc_u32 s17, s29, 0
	v_mfma_f32_16x16x32_bf16 v[44:47], v[150:153], v[214:217], v[44:47]
	s_add_i32 s59, 0, 0x10000
	v_mfma_f32_16x16x32_bf16 v[40:43], v[158:161], v[214:217], v[40:43]
	s_cmp_eq_u32 s48, s16
	v_mfma_f32_16x16x32_bf16 v[28:31], v[150:153], v[224:227], v[28:31]
	s_cselect_b32 s17, s25, s17
	v_mfma_f32_16x16x32_bf16 v[24:27], v[158:161], v[224:227], v[24:27]
	s_cselect_b32 s16, s24, s31
	v_mfma_f32_16x16x32_bf16 v[12:15], v[150:153], v[232:235], v[12:15]
	s_cselect_b32 s43, s27, s11
	v_mfma_f32_16x16x32_bf16 v[8:11], v[158:161], v[232:235], v[8:11]
	s_cselect_b32 s42, s26, s10
	v_mfma_f32_16x16x32_bf16 v[52:55], v[162:165], v[194:197], v[52:55]
	s_add_i32 s31, 0, 0x14000
	v_mfma_f32_16x16x32_bf16 v[48:51], v[170:173], v[194:197], v[48:51]
	v_mfma_f32_16x16x32_bf16 v[36:39], v[162:165], v[210:213], v[36:39]
	v_mfma_f32_16x16x32_bf16 v[32:35], v[170:173], v[210:213], v[32:35]
	v_mfma_f32_16x16x32_bf16 v[20:23], v[162:165], v[220:223], v[20:23]
	v_mfma_f32_16x16x32_bf16 v[16:19], v[170:173], v[220:223], v[16:19]
	v_mfma_f32_16x16x32_bf16 v[4:7], v[162:165], v[228:231], v[4:7]
	v_mfma_f32_16x16x32_bf16 v[0:3], v[170:173], v[228:231], v[0:3]
	v_mfma_f32_16x16x32_bf16 v[52:55], v[166:169], v[206:209], v[52:55]
	v_mfma_f32_16x16x32_bf16 v[48:51], v[174:177], v[206:209], v[48:51]
	v_mfma_f32_16x16x32_bf16 v[36:39], v[166:169], v[214:217], v[36:39]
	v_mfma_f32_16x16x32_bf16 v[32:35], v[174:177], v[214:217], v[32:35]
	v_mfma_f32_16x16x32_bf16 v[20:23], v[166:169], v[224:227], v[20:23]
	v_mfma_f32_16x16x32_bf16 v[16:19], v[174:177], v[224:227], v[16:19]
	v_mfma_f32_16x16x32_bf16 v[4:7], v[166:169], v[232:235], v[4:7]
	v_mfma_f32_16x16x32_bf16 v[0:3], v[174:177], v[232:235], v[0:3]
	s_cmp_lg_u32 s98, 0
	s_cbranch_scc1 .Lskf_10_peel
	s_barrier

.LBB0_798:
	v_add_u32_e32 v140, s59, v143
	ds_read_b128 v[146:149], v140
	ds_read_b128 v[150:153], v140 offset:1024
	ds_read_b128 v[154:157], v140 offset:2048
	ds_read_b128 v[158:161], v140 offset:3072
	v_add_u32_e32 v140, s31, v143
	ds_read_b128 v[162:165], v140
	ds_read_b128 v[166:169], v140 offset:1024
	ds_read_b128 v[170:173], v140 offset:2048
	ds_read_b128 v[174:177], v140 offset:3072
	v_lshl_add_u64 v[178:179], s[28:29], 0, v[136:137]
	s_add_i32 m0, s37, 0xc000
	ds_read_b128 v[194:197], v145
	ds_read_b128 v[206:209], v145 offset:1024
	ds_read_b128 v[210:213], v145 offset:2048
	ds_read_b128 v[214:217], v145 offset:3072
	ds_read_b128 v[220:223], v145 offset:4096
	ds_read_b128 v[224:227], v145 offset:5120
	ds_read_b128 v[228:231], v145 offset:6144
	ds_read_b128 v[232:235], v145 offset:7168
	global_load_lds_dwordx4 v[178:179], off
	v_lshl_add_u64 v[178:179], s[28:29], 0, v[138:139]
	s_add_i32 m0, s37, 0xe000
	s_nop 0
	global_load_lds_dwordx4 v[178:179], off
	s_waitcnt vmcnt(8)
	s_waitcnt lgkmcnt(0)
	s_barrier
	s_waitcnt lgkmcnt(0)
	v_mfma_f32_16x16x32_bf16 v[124:127], v[146:149], v[194:197], v[124:127]
	v_mfma_f32_16x16x32_bf16 v[120:123], v[154:157], v[194:197], v[120:123]
	v_mfma_f32_16x16x32_bf16 v[108:111], v[146:149], v[210:213], v[108:111]
	v_mfma_f32_16x16x32_bf16 v[104:107], v[154:157], v[210:213], v[104:107]
	v_mfma_f32_16x16x32_bf16 v[92:95], v[146:149], v[220:223], v[92:95]
	v_mfma_f32_16x16x32_bf16 v[88:91], v[154:157], v[220:223], v[88:91]
	v_mfma_f32_16x16x32_bf16 v[76:79], v[146:149], v[228:231], v[76:79]
	v_mfma_f32_16x16x32_bf16 v[72:75], v[154:157], v[228:231], v[72:75]
	v_mfma_f32_16x16x32_bf16 v[124:127], v[150:153], v[206:209], v[124:127]
	v_mfma_f32_16x16x32_bf16 v[120:123], v[158:161], v[206:209], v[120:123]
	v_mfma_f32_16x16x32_bf16 v[108:111], v[150:153], v[214:217], v[108:111]
	v_mfma_f32_16x16x32_bf16 v[104:107], v[158:161], v[214:217], v[104:107]
	v_mfma_f32_16x16x32_bf16 v[92:95], v[150:153], v[224:227], v[92:95]
	v_mfma_f32_16x16x32_bf16 v[88:91], v[158:161], v[224:227], v[88:91]
	v_mfma_f32_16x16x32_bf16 v[76:79], v[150:153], v[232:235], v[76:79]
	v_mfma_f32_16x16x32_bf16 v[72:75], v[158:161], v[232:235], v[72:75]
	v_mfma_f32_16x16x32_bf16 v[116:119], v[162:165], v[194:197], v[116:119]
	v_mfma_f32_16x16x32_bf16 v[112:115], v[170:173], v[194:197], v[112:115]
	v_mfma_f32_16x16x32_bf16 v[100:103], v[162:165], v[210:213], v[100:103]
	v_mfma_f32_16x16x32_bf16 v[96:99], v[170:173], v[210:213], v[96:99]
	v_mfma_f32_16x16x32_bf16 v[84:87], v[162:165], v[220:223], v[84:87]
	v_mfma_f32_16x16x32_bf16 v[80:83], v[170:173], v[220:223], v[80:83]
	v_mfma_f32_16x16x32_bf16 v[68:71], v[162:165], v[228:231], v[68:71]
	v_mfma_f32_16x16x32_bf16 v[64:67], v[170:173], v[228:231], v[64:67]
	v_mfma_f32_16x16x32_bf16 v[116:119], v[166:169], v[206:209], v[116:119]
	v_mfma_f32_16x16x32_bf16 v[112:115], v[174:177], v[206:209], v[112:115]
	v_mfma_f32_16x16x32_bf16 v[100:103], v[166:169], v[214:217], v[100:103]
	v_mfma_f32_16x16x32_bf16 v[96:99], v[174:177], v[214:217], v[96:99]
	v_mfma_f32_16x16x32_bf16 v[84:87], v[166:169], v[224:227], v[84:87]
	v_mfma_f32_16x16x32_bf16 v[80:83], v[174:177], v[224:227], v[80:83]
	v_mfma_f32_16x16x32_bf16 v[68:71], v[166:169], v[232:235], v[68:71]
	v_mfma_f32_16x16x32_bf16 v[64:67], v[174:177], v[232:235], v[64:67]
	s_barrier
	s_add_i32 s59, s59, s36
	v_lshl_add_u64 v[178:179], s[42:43], 0, v[132:133]
	s_mov_b32 m0, s59
	ds_read_b128 v[194:197], v145 offset:16384
	ds_read_b128 v[206:209], v145 offset:17408
	ds_read_b128 v[210:213], v145 offset:18432
	ds_read_b128 v[214:217], v145 offset:19456
	ds_read_b128 v[220:223], v145 offset:20480
	ds_read_b128 v[224:227], v145 offset:21504
	ds_read_b128 v[228:231], v145 offset:22528
	ds_read_b128 v[232:235], v145 offset:23552
	global_load_lds_dwordx4 v[178:179], off
	s_add_i32 m0, s59, 0x2000
	v_lshl_add_u64 v[198:199], s[42:43], 0, v[128:129]
	s_add_u32 s42, s42, s0
	s_addc_u32 s43, s43, s1
	s_add_i32 s31, s31, s36
	global_load_lds_dwordx4 v[198:199], off
	v_lshl_add_u64 v[202:203], s[42:43], 0, v[132:133]
	s_mov_b32 m0, s31
	v_lshl_add_u64 v[236:237], s[42:43], 0, v[128:129]
	global_load_lds_dwordx4 v[202:203], off
	s_add_i32 m0, s31, 0x2000
	v_lshl_add_u64 v[238:239], s[16:17], 0, v[134:135]
	global_load_lds_dwordx4 v[236:237], off
	s_mov_b32 m0, s37
	v_lshl_add_u64 v[240:241], s[16:17], 0, v[130:131]
	global_load_lds_dwordx4 v[238:239], off
	s_mov_b32 m0, s38
	s_nop 0
	global_load_lds_dwordx4 v[240:241], off
	s_waitcnt vmcnt(8)
	s_waitcnt lgkmcnt(0)
	s_barrier
	s_waitcnt lgkmcnt(0)
	v_mfma_f32_16x16x32_bf16 v[60:63], v[146:149], v[194:197], v[60:63]
	v_mfma_f32_16x16x32_bf16 v[56:59], v[154:157], v[194:197], v[56:59]
	v_mfma_f32_16x16x32_bf16 v[44:47], v[146:149], v[210:213], v[44:47]
	v_mfma_f32_16x16x32_bf16 v[40:43], v[154:157], v[210:213], v[40:43]
	v_mfma_f32_16x16x32_bf16 v[28:31], v[146:149], v[220:223], v[28:31]
	v_mfma_f32_16x16x32_bf16 v[24:27], v[154:157], v[220:223], v[24:27]
	v_mfma_f32_16x16x32_bf16 v[12:15], v[146:149], v[228:231], v[12:15]
	v_mfma_f32_16x16x32_bf16 v[8:11], v[154:157], v[228:231], v[8:11]
	v_mfma_f32_16x16x32_bf16 v[60:63], v[150:153], v[206:209], v[60:63]
	v_mfma_f32_16x16x32_bf16 v[56:59], v[158:161], v[206:209], v[56:59]
	v_mfma_f32_16x16x32_bf16 v[44:47], v[150:153], v[214:217], v[44:47]
	v_mfma_f32_16x16x32_bf16 v[40:43], v[158:161], v[214:217], v[40:43]
	v_mfma_f32_16x16x32_bf16 v[28:31], v[150:153], v[224:227], v[28:31]
	v_mfma_f32_16x16x32_bf16 v[24:27], v[158:161], v[224:227], v[24:27]
	v_mfma_f32_16x16x32_bf16 v[12:15], v[150:153], v[232:235], v[12:15]
	v_mfma_f32_16x16x32_bf16 v[8:11], v[158:161], v[232:235], v[8:11]
	v_mfma_f32_16x16x32_bf16 v[52:55], v[162:165], v[194:197], v[52:55]
	v_mfma_f32_16x16x32_bf16 v[48:51], v[170:173], v[194:197], v[48:51]
	v_mfma_f32_16x16x32_bf16 v[36:39], v[162:165], v[210:213], v[36:39]
	v_mfma_f32_16x16x32_bf16 v[32:35], v[170:173], v[210:213], v[32:35]
	v_mfma_f32_16x16x32_bf16 v[20:23], v[162:165], v[220:223], v[20:23]
	v_mfma_f32_16x16x32_bf16 v[16:19], v[170:173], v[220:223], v[16:19]
	v_mfma_f32_16x16x32_bf16 v[4:7], v[162:165], v[228:231], v[4:7]
	v_mfma_f32_16x16x32_bf16 v[0:3], v[170:173], v[228:231], v[0:3]
	v_mfma_f32_16x16x32_bf16 v[52:55], v[166:169], v[206:209], v[52:55]
	v_mfma_f32_16x16x32_bf16 v[48:51], v[174:177], v[206:209], v[48:51]
	v_mfma_f32_16x16x32_bf16 v[36:39], v[166:169], v[214:217], v[36:39]
	v_mfma_f32_16x16x32_bf16 v[32:35], v[174:177], v[214:217], v[32:35]
	v_mfma_f32_16x16x32_bf16 v[20:23], v[166:169], v[224:227], v[20:23]
	v_mfma_f32_16x16x32_bf16 v[16:19], v[174:177], v[224:227], v[16:19]
	v_mfma_f32_16x16x32_bf16 v[4:7], v[166:169], v[232:235], v[4:7]
	v_mfma_f32_16x16x32_bf16 v[0:3], v[174:177], v[232:235], v[0:3]
	s_barrier
	s_add_i32 s31, 0, 0x18000
	v_add_u32_e32 v140, s31, v143
	s_add_i32 s42, 0, 0x1c000
	ds_read_b128 v[146:149], v140
	ds_read_b128 v[150:153], v140 offset:1024
	ds_read_b128 v[154:157], v140 offset:2048
	ds_read_b128 v[158:161], v140 offset:3072
	v_add_u32_e32 v140, s42, v143
	ds_read_b128 v[162:165], v140
	ds_read_b128 v[166:169], v140 offset:1024
	ds_read_b128 v[170:173], v140 offset:2048
	ds_read_b128 v[174:177], v140 offset:3072
	s_add_u32 s16, s16, s0
	s_addc_u32 s17, s17, s1
	s_mov_b32 m0, s39
	v_lshl_add_u64 v[242:243], s[16:17], 0, v[134:135]
	ds_read_b128 v[194:197], v145 offset:32768
	ds_read_b128 v[206:209], v145 offset:33792
	ds_read_b128 v[210:213], v145 offset:34816
	ds_read_b128 v[214:217], v145 offset:35840
	ds_read_b128 v[220:223], v145 offset:36864
	ds_read_b128 v[224:227], v145 offset:37888
	ds_read_b128 v[228:231], v145 offset:38912
	ds_read_b128 v[232:235], v145 offset:39936
	global_load_lds_dwordx4 v[242:243], off
	v_lshl_add_u64 v[242:243], s[16:17], 0, v[130:131]
	s_mov_b32 m0, s44
	s_nop 0
	global_load_lds_dwordx4 v[242:243], off
	s_waitcnt vmcnt(8)
	s_waitcnt lgkmcnt(0)
	s_barrier
	s_waitcnt lgkmcnt(0)
	v_mfma_f32_16x16x32_bf16 v[124:127], v[146:149], v[194:197], v[124:127]
	v_mfma_f32_16x16x32_bf16 v[120:123], v[154:157], v[194:197], v[120:123]
	v_mfma_f32_16x16x32_bf16 v[108:111], v[146:149], v[210:213], v[108:111]
	v_mfma_f32_16x16x32_bf16 v[104:107], v[154:157], v[210:213], v[104:107]
	v_mfma_f32_16x16x32_bf16 v[92:95], v[146:149], v[220:223], v[92:95]
	v_mfma_f32_16x16x32_bf16 v[88:91], v[154:157], v[220:223], v[88:91]
	v_mfma_f32_16x16x32_bf16 v[76:79], v[146:149], v[228:231], v[76:79]
	v_mfma_f32_16x16x32_bf16 v[72:75], v[154:157], v[228:231], v[72:75]
	v_mfma_f32_16x16x32_bf16 v[124:127], v[150:153], v[206:209], v[124:127]
	v_mfma_f32_16x16x32_bf16 v[120:123], v[158:161], v[206:209], v[120:123]
	v_mfma_f32_16x16x32_bf16 v[108:111], v[150:153], v[214:217], v[108:111]
	v_mfma_f32_16x16x32_bf16 v[104:107], v[158:161], v[214:217], v[104:107]
	v_mfma_f32_16x16x32_bf16 v[92:95], v[150:153], v[224:227], v[92:95]
	v_mfma_f32_16x16x32_bf16 v[88:91], v[158:161], v[224:227], v[88:91]
	v_mfma_f32_16x16x32_bf16 v[76:79], v[150:153], v[232:235], v[76:79]
	v_mfma_f32_16x16x32_bf16 v[72:75], v[158:161], v[232:235], v[72:75]
	v_mfma_f32_16x16x32_bf16 v[116:119], v[162:165], v[194:197], v[116:119]
	v_mfma_f32_16x16x32_bf16 v[112:115], v[170:173], v[194:197], v[112:115]
	v_mfma_f32_16x16x32_bf16 v[100:103], v[162:165], v[210:213], v[100:103]
	v_mfma_f32_16x16x32_bf16 v[96:99], v[170:173], v[210:213], v[96:99]
	v_mfma_f32_16x16x32_bf16 v[84:87], v[162:165], v[220:223], v[84:87]
	v_mfma_f32_16x16x32_bf16 v[80:83], v[170:173], v[220:223], v[80:83]
	v_mfma_f32_16x16x32_bf16 v[68:71], v[162:165], v[228:231], v[68:71]
	v_mfma_f32_16x16x32_bf16 v[64:67], v[170:173], v[228:231], v[64:67]
	v_mfma_f32_16x16x32_bf16 v[116:119], v[166:169], v[206:209], v[116:119]
	v_mfma_f32_16x16x32_bf16 v[112:115], v[174:177], v[206:209], v[112:115]
	v_mfma_f32_16x16x32_bf16 v[100:103], v[166:169], v[214:217], v[100:103]
	v_mfma_f32_16x16x32_bf16 v[96:99], v[174:177], v[214:217], v[96:99]
	v_mfma_f32_16x16x32_bf16 v[84:87], v[166:169], v[224:227], v[84:87]
	v_mfma_f32_16x16x32_bf16 v[80:83], v[174:177], v[224:227], v[80:83]
	v_mfma_f32_16x16x32_bf16 v[68:71], v[166:169], v[232:235], v[68:71]
	v_mfma_f32_16x16x32_bf16 v[64:67], v[174:177], v[232:235], v[64:67]
	s_barrier
	s_add_i32 s16, s31, s36
	v_lshl_add_u64 v[178:179], v[178:179], 0, s[12:13]
	s_mov_b32 m0, s16
	ds_read_b128 v[194:197], v145 offset:49152
	ds_read_b128 v[206:209], v145 offset:50176
	ds_read_b128 v[210:213], v145 offset:51200
	ds_read_b128 v[214:217], v145 offset:52224
	ds_read_b128 v[220:223], v145 offset:53248
	ds_read_b128 v[224:227], v145 offset:54272
	ds_read_b128 v[228:231], v145 offset:55296
	ds_read_b128 v[232:235], v145 offset:56320
	global_load_lds_dwordx4 v[178:179], off
	v_lshl_add_u64 v[178:179], v[198:199], 0, s[12:13]
	s_add_i32 m0, s16, 0x2000
	s_add_i32 s16, s42, s36
	global_load_lds_dwordx4 v[178:179], off
	v_lshl_add_u64 v[178:179], v[202:203], 0, s[12:13]
	s_mov_b32 m0, s16
	s_nop 0
	global_load_lds_dwordx4 v[178:179], off
	v_lshl_add_u64 v[178:179], v[236:237], 0, s[12:13]
	s_add_i32 m0, s16, 0x2000
	s_nop 0
	global_load_lds_dwordx4 v[178:179], off
	v_lshl_add_u64 v[178:179], v[238:239], 0, s[12:13]
	s_mov_b32 m0, s45
	s_nop 0
	global_load_lds_dwordx4 v[178:179], off
	v_lshl_add_u64 v[178:179], v[240:241], 0, s[12:13]
	s_mov_b32 m0, s46
	s_nop 0
	global_load_lds_dwordx4 v[178:179], off
	s_waitcnt vmcnt(8)
	s_waitcnt lgkmcnt(0)
	s_barrier
	s_waitcnt lgkmcnt(0)
	v_mfma_f32_16x16x32_bf16 v[60:63], v[146:149], v[194:197], v[60:63]
	s_add_u32 s28, s28, 0x100
	v_mfma_f32_16x16x32_bf16 v[56:59], v[154:157], v[194:197], v[56:59]
	s_addc_u32 s29, s29, 0
	v_mfma_f32_16x16x32_bf16 v[44:47], v[146:149], v[210:213], v[44:47]
	s_add_u32 s10, s10, 0x100
	v_mfma_f32_16x16x32_bf16 v[40:43], v[154:157], v[210:213], v[40:43]
	s_addc_u32 s11, s11, 0
	v_mfma_f32_16x16x32_bf16 v[28:31], v[146:149], v[220:223], v[28:31]
	s_mov_b32 s16, s30
	v_mfma_f32_16x16x32_bf16 v[24:27], v[154:157], v[220:223], v[24:27]
	s_cmp_ge_i32 s30, s47
	v_mfma_f32_16x16x32_bf16 v[12:15], v[146:149], v[228:231], v[12:15]
	s_cselect_b32 s99, 1, 0
	v_readfirstlane_b32 s98, v218
	s_bfe_u32 s98, s98, 0x10008
	s_and_b32 s98, s98, s99
	v_mfma_f32_16x16x32_bf16 v[8:11], v[154:157], v[228:231], v[8:11]
	s_add_i32 s30, s16, 2
	v_mfma_f32_16x16x32_bf16 v[60:63], v[150:153], v[206:209], v[60:63]
	s_add_u32 s31, s28, 0x80
	v_mfma_f32_16x16x32_bf16 v[56:59], v[158:161], v[206:209], v[56:59]
	s_addc_u32 s17, s29, 0
	v_mfma_f32_16x16x32_bf16 v[44:47], v[150:153], v[214:217], v[44:47]
	s_add_i32 s59, 0, 0x10000
	v_mfma_f32_16x16x32_bf16 v[40:43], v[158:161], v[214:217], v[40:43]
	s_cmp_eq_u32 s48, s16
	v_mfma_f32_16x16x32_bf16 v[28:31], v[150:153], v[224:227], v[28:31]
	s_cselect_b32 s17, s25, s17
	v_mfma_f32_16x16x32_bf16 v[24:27], v[158:161], v[224:227], v[24:27]
	s_cselect_b32 s16, s24, s31
	v_mfma_f32_16x16x32_bf16 v[12:15], v[150:153], v[232:235], v[12:15]
	s_cselect_b32 s43, s27, s11
	v_mfma_f32_16x16x32_bf16 v[8:11], v[158:161], v[232:235], v[8:11]
	s_cselect_b32 s42, s26, s10
	v_mfma_f32_16x16x32_bf16 v[52:55], v[162:165], v[194:197], v[52:55]
	s_add_i32 s31, 0, 0x14000
	v_mfma_f32_16x16x32_bf16 v[48:51], v[170:173], v[194:197], v[48:51]
	v_mfma_f32_16x16x32_bf16 v[36:39], v[162:165], v[210:213], v[36:39]
	v_mfma_f32_16x16x32_bf16 v[32:35], v[170:173], v[210:213], v[32:35]
	v_mfma_f32_16x16x32_bf16 v[20:23], v[162:165], v[220:223], v[20:23]
	v_mfma_f32_16x16x32_bf16 v[16:19], v[170:173], v[220:223], v[16:19]
	v_mfma_f32_16x16x32_bf16 v[4:7], v[162:165], v[228:231], v[4:7]
	v_mfma_f32_16x16x32_bf16 v[0:3], v[170:173], v[228:231], v[0:3]
	v_mfma_f32_16x16x32_bf16 v[52:55], v[166:169], v[206:209], v[52:55]
	v_mfma_f32_16x16x32_bf16 v[48:51], v[174:177], v[206:209], v[48:51]
	v_mfma_f32_16x16x32_bf16 v[36:39], v[166:169], v[214:217], v[36:39]
	v_mfma_f32_16x16x32_bf16 v[32:35], v[174:177], v[214:217], v[32:35]
	v_mfma_f32_16x16x32_bf16 v[20:23], v[166:169], v[224:227], v[20:23]
	v_mfma_f32_16x16x32_bf16 v[16:19], v[174:177], v[224:227], v[16:19]
	v_mfma_f32_16x16x32_bf16 v[4:7], v[166:169], v[232:235], v[4:7]
	v_mfma_f32_16x16x32_bf16 v[0:3], v[174:177], v[232:235], v[0:3]
	s_cmp_lg_u32 s98, 0
	s_cbranch_scc1 .Lskf_10_loop
	s_barrier

.LBB0_810:
	s_barrier
	s_andn2_b64 vcc, exec, s[10:11]
	s_mov_b32 s57, s52
	s_mov_b32 s58, s56
	s_mov_b64 s[28:29], s[24:25]
	s_mov_b64 s[26:27], s[22:23]
	s_cbranch_vccz .LBB0_829

.Llbb_7:
	s_add_i32 s28, s16, 2
	s_add_u32 s29, s26, 0x80
	s_addc_u32 s17, s27, 0
	s_add_i32 s59, 0, 0x10000
	s_cmp_eq_u32 s48, s16
	s_cselect_b32 s17, s23, s17
	s_cselect_b32 s16, s22, s29
	v_add_u32_e32 v140, s59, v143
	s_cselect_b32 s43, s25, s11
	s_cselect_b32 s42, s24, s10
	s_add_i32 s29, 0, 0x14000
	ds_read_b128 v[146:149], v140
	ds_read_b128 v[150:153], v140 offset:1024
	ds_read_b128 v[154:157], v140 offset:2048
	ds_read_b128 v[158:161], v140 offset:3072
	v_add_u32_e32 v140, s29, v143
	ds_read_b128 v[162:165], v140
	ds_read_b128 v[166:169], v140 offset:1024
	ds_read_b128 v[170:173], v140 offset:2048
	ds_read_b128 v[174:177], v140 offset:3072
	v_lshl_add_u64 v[140:141], s[26:27], 0, v[136:137]
	s_add_i32 m0, s35, 0xc000
	ds_read_b128 v[194:197], v145
	ds_read_b128 v[206:209], v145 offset:1024
	ds_read_b128 v[210:213], v145 offset:2048
	ds_read_b128 v[214:217], v145 offset:3072
	ds_read_b128 v[220:223], v145 offset:4096
	ds_read_b128 v[224:227], v145 offset:5120
	ds_read_b128 v[228:231], v145 offset:6144
	ds_read_b128 v[232:235], v145 offset:7168
	global_load_lds_dwordx4 v[140:141], off
	v_lshl_add_u64 v[140:141], s[26:27], 0, v[138:139]
	s_add_i32 m0, s35, 0xe000
	s_nop 0
	global_load_lds_dwordx4 v[140:141], off
	s_waitcnt vmcnt(8)
	s_waitcnt lgkmcnt(0)
	s_barrier
	s_waitcnt lgkmcnt(0)
	v_mfma_f32_16x16x32_bf16 v[120:123], v[146:149], v[194:197], 0
	v_mfma_f32_16x16x32_bf16 v[124:127], v[154:157], v[194:197], 0
	v_mfma_f32_16x16x32_bf16 v[116:119], v[146:149], v[210:213], 0
	v_mfma_f32_16x16x32_bf16 v[112:115], v[154:157], v[210:213], 0
	v_mfma_f32_16x16x32_bf16 v[108:111], v[146:149], v[220:223], 0
	v_mfma_f32_16x16x32_bf16 v[104:107], v[154:157], v[220:223], 0
	v_mfma_f32_16x16x32_bf16 v[100:103], v[146:149], v[228:231], 0
	v_mfma_f32_16x16x32_bf16 v[96:99], v[154:157], v[228:231], 0
	v_mfma_f32_16x16x32_bf16 v[120:123], v[150:153], v[206:209], v[120:123]
	v_mfma_f32_16x16x32_bf16 v[124:127], v[158:161], v[206:209], v[124:127]
	v_mfma_f32_16x16x32_bf16 v[116:119], v[150:153], v[214:217], v[116:119]
	v_mfma_f32_16x16x32_bf16 v[112:115], v[158:161], v[214:217], v[112:115]
	v_mfma_f32_16x16x32_bf16 v[108:111], v[150:153], v[224:227], v[108:111]
	v_mfma_f32_16x16x32_bf16 v[104:107], v[158:161], v[224:227], v[104:107]
	v_mfma_f32_16x16x32_bf16 v[100:103], v[150:153], v[232:235], v[100:103]
	v_mfma_f32_16x16x32_bf16 v[96:99], v[158:161], v[232:235], v[96:99]
	v_mfma_f32_16x16x32_bf16 v[60:63], v[162:165], v[194:197], 0
	v_mfma_f32_16x16x32_bf16 v[56:59], v[170:173], v[194:197], 0
	v_mfma_f32_16x16x32_bf16 v[52:55], v[162:165], v[210:213], 0
	v_mfma_f32_16x16x32_bf16 v[48:51], v[170:173], v[210:213], 0
	v_mfma_f32_16x16x32_bf16 v[44:47], v[162:165], v[220:223], 0
	v_mfma_f32_16x16x32_bf16 v[40:43], v[170:173], v[220:223], 0
	v_mfma_f32_16x16x32_bf16 v[36:39], v[162:165], v[228:231], 0
	v_mfma_f32_16x16x32_bf16 v[32:35], v[170:173], v[228:231], 0
	v_mfma_f32_16x16x32_bf16 v[60:63], v[166:169], v[206:209], v[60:63]
	v_mfma_f32_16x16x32_bf16 v[56:59], v[174:177], v[206:209], v[56:59]
	v_mfma_f32_16x16x32_bf16 v[52:55], v[166:169], v[214:217], v[52:55]
	v_mfma_f32_16x16x32_bf16 v[48:51], v[174:177], v[214:217], v[48:51]
	v_mfma_f32_16x16x32_bf16 v[44:47], v[166:169], v[224:227], v[44:47]
	v_mfma_f32_16x16x32_bf16 v[40:43], v[174:177], v[224:227], v[40:43]
	v_mfma_f32_16x16x32_bf16 v[36:39], v[166:169], v[232:235], v[36:39]
	v_mfma_f32_16x16x32_bf16 v[32:35], v[174:177], v[232:235], v[32:35]
	s_barrier
	s_add_i32 s59, s59, s34
	v_lshl_add_u64 v[140:141], s[42:43], 0, v[132:133]
	s_mov_b32 m0, s59
	ds_read_b128 v[194:197], v145 offset:16384
	ds_read_b128 v[206:209], v145 offset:17408
	ds_read_b128 v[210:213], v145 offset:18432
	ds_read_b128 v[214:217], v145 offset:19456
	ds_read_b128 v[220:223], v145 offset:20480
	ds_read_b128 v[224:227], v145 offset:21504
	ds_read_b128 v[228:231], v145 offset:22528
	ds_read_b128 v[232:235], v145 offset:23552
	global_load_lds_dwordx4 v[140:141], off
	s_add_i32 m0, s59, 0x2000
	v_lshl_add_u64 v[178:179], s[42:43], 0, v[128:129]
	s_add_u32 s42, s42, s0
	s_addc_u32 s43, s43, s1
	s_add_i32 s29, s29, s34
	global_load_lds_dwordx4 v[178:179], off
	v_lshl_add_u64 v[198:199], s[42:43], 0, v[132:133]
	s_mov_b32 m0, s29
	v_lshl_add_u64 v[202:203], s[42:43], 0, v[128:129]
	global_load_lds_dwordx4 v[198:199], off
	s_add_i32 m0, s29, 0x2000
	v_lshl_add_u64 v[236:237], s[16:17], 0, v[134:135]
	global_load_lds_dwordx4 v[202:203], off
	s_mov_b32 m0, s35
	v_lshl_add_u64 v[238:239], s[16:17], 0, v[130:131]
	global_load_lds_dwordx4 v[236:237], off
	s_mov_b32 m0, s36
	s_nop 0
	global_load_lds_dwordx4 v[238:239], off
	s_waitcnt vmcnt(8)
	s_waitcnt lgkmcnt(0)
	s_barrier
	s_waitcnt lgkmcnt(0)
	v_mfma_f32_16x16x32_bf16 v[92:95], v[146:149], v[194:197], 0
	v_mfma_f32_16x16x32_bf16 v[88:91], v[154:157], v[194:197], 0
	v_mfma_f32_16x16x32_bf16 v[84:87], v[146:149], v[210:213], 0
	v_mfma_f32_16x16x32_bf16 v[80:83], v[154:157], v[210:213], 0
	v_mfma_f32_16x16x32_bf16 v[76:79], v[146:149], v[220:223], 0
	v_mfma_f32_16x16x32_bf16 v[72:75], v[154:157], v[220:223], 0
	v_mfma_f32_16x16x32_bf16 v[68:71], v[146:149], v[228:231], 0
	v_mfma_f32_16x16x32_bf16 v[64:67], v[154:157], v[228:231], 0
	v_mfma_f32_16x16x32_bf16 v[92:95], v[150:153], v[206:209], v[92:95]
	v_mfma_f32_16x16x32_bf16 v[88:91], v[158:161], v[206:209], v[88:91]
	v_mfma_f32_16x16x32_bf16 v[84:87], v[150:153], v[214:217], v[84:87]
	v_mfma_f32_16x16x32_bf16 v[80:83], v[158:161], v[214:217], v[80:83]
	v_mfma_f32_16x16x32_bf16 v[76:79], v[150:153], v[224:227], v[76:79]
	v_mfma_f32_16x16x32_bf16 v[72:75], v[158:161], v[224:227], v[72:75]
	v_mfma_f32_16x16x32_bf16 v[68:71], v[150:153], v[232:235], v[68:71]
	v_mfma_f32_16x16x32_bf16 v[64:67], v[158:161], v[232:235], v[64:67]
	v_mfma_f32_16x16x32_bf16 v[28:31], v[162:165], v[194:197], 0
	v_mfma_f32_16x16x32_bf16 v[24:27], v[170:173], v[194:197], 0
	v_mfma_f32_16x16x32_bf16 v[20:23], v[162:165], v[210:213], 0
	v_mfma_f32_16x16x32_bf16 v[16:19], v[170:173], v[210:213], 0
	v_mfma_f32_16x16x32_bf16 v[12:15], v[162:165], v[220:223], 0
	v_mfma_f32_16x16x32_bf16 v[8:11], v[170:173], v[220:223], 0
	v_mfma_f32_16x16x32_bf16 v[4:7], v[162:165], v[228:231], 0
	v_mfma_f32_16x16x32_bf16 v[0:3], v[170:173], v[228:231], 0
	v_mfma_f32_16x16x32_bf16 v[28:31], v[166:169], v[206:209], v[28:31]
	v_mfma_f32_16x16x32_bf16 v[24:27], v[174:177], v[206:209], v[24:27]
	v_mfma_f32_16x16x32_bf16 v[20:23], v[166:169], v[214:217], v[20:23]
	v_mfma_f32_16x16x32_bf16 v[16:19], v[174:177], v[214:217], v[16:19]
	v_mfma_f32_16x16x32_bf16 v[12:15], v[166:169], v[224:227], v[12:15]
	v_mfma_f32_16x16x32_bf16 v[8:11], v[174:177], v[224:227], v[8:11]
	v_mfma_f32_16x16x32_bf16 v[4:7], v[166:169], v[232:235], v[4:7]
	v_mfma_f32_16x16x32_bf16 v[0:3], v[174:177], v[232:235], v[0:3]
	s_barrier
	s_add_i32 s29, 0, 0x18000
	s_add_i32 s42, 0, 0x1c000
	v_add_u32_e32 v158, s29, v143
	v_add_u32_e32 v174, s42, v143
	ds_read_b128 v[146:149], v158
	ds_read_b128 v[150:153], v158 offset:1024
	ds_read_b128 v[154:157], v158 offset:2048
	ds_read_b128 v[158:161], v158 offset:3072
	ds_read_b128 v[162:165], v174
	ds_read_b128 v[166:169], v174 offset:1024
	ds_read_b128 v[170:173], v174 offset:2048
	ds_read_b128 v[174:177], v174 offset:3072
	s_add_u32 s16, s16, s0
	s_addc_u32 s17, s17, s1
	s_mov_b32 m0, s37
	v_lshl_add_u64 v[240:241], s[16:17], 0, v[134:135]
	ds_read_b128 v[194:197], v145 offset:32768
	ds_read_b128 v[206:209], v145 offset:33792
	ds_read_b128 v[210:213], v145 offset:34816
	ds_read_b128 v[214:217], v145 offset:35840
	ds_read_b128 v[220:223], v145 offset:36864
	ds_read_b128 v[224:227], v145 offset:37888
	ds_read_b128 v[228:231], v145 offset:38912
	ds_read_b128 v[232:235], v145 offset:39936
	global_load_lds_dwordx4 v[240:241], off
	v_lshl_add_u64 v[240:241], s[16:17], 0, v[130:131]
	s_mov_b32 m0, s38
	s_nop 0
	global_load_lds_dwordx4 v[240:241], off
	s_waitcnt vmcnt(8)
	s_waitcnt lgkmcnt(0)
	s_barrier
	s_waitcnt lgkmcnt(0)
	v_mfma_f32_16x16x32_bf16 v[120:123], v[146:149], v[194:197], v[120:123]
	v_mfma_f32_16x16x32_bf16 v[124:127], v[154:157], v[194:197], v[124:127]
	v_mfma_f32_16x16x32_bf16 v[116:119], v[146:149], v[210:213], v[116:119]
	v_mfma_f32_16x16x32_bf16 v[112:115], v[154:157], v[210:213], v[112:115]
	v_mfma_f32_16x16x32_bf16 v[108:111], v[146:149], v[220:223], v[108:111]
	v_mfma_f32_16x16x32_bf16 v[104:107], v[154:157], v[220:223], v[104:107]
	v_mfma_f32_16x16x32_bf16 v[100:103], v[146:149], v[228:231], v[100:103]
	v_mfma_f32_16x16x32_bf16 v[96:99], v[154:157], v[228:231], v[96:99]
	v_mfma_f32_16x16x32_bf16 v[120:123], v[150:153], v[206:209], v[120:123]
	v_mfma_f32_16x16x32_bf16 v[124:127], v[158:161], v[206:209], v[124:127]
	v_mfma_f32_16x16x32_bf16 v[116:119], v[150:153], v[214:217], v[116:119]
	v_mfma_f32_16x16x32_bf16 v[112:115], v[158:161], v[214:217], v[112:115]
	v_mfma_f32_16x16x32_bf16 v[108:111], v[150:153], v[224:227], v[108:111]
	v_mfma_f32_16x16x32_bf16 v[104:107], v[158:161], v[224:227], v[104:107]
	v_mfma_f32_16x16x32_bf16 v[100:103], v[150:153], v[232:235], v[100:103]
	v_mfma_f32_16x16x32_bf16 v[96:99], v[158:161], v[232:235], v[96:99]
	v_mfma_f32_16x16x32_bf16 v[60:63], v[162:165], v[194:197], v[60:63]
	v_mfma_f32_16x16x32_bf16 v[56:59], v[170:173], v[194:197], v[56:59]
	v_mfma_f32_16x16x32_bf16 v[52:55], v[162:165], v[210:213], v[52:55]
	v_mfma_f32_16x16x32_bf16 v[48:51], v[170:173], v[210:213], v[48:51]
	v_mfma_f32_16x16x32_bf16 v[44:47], v[162:165], v[220:223], v[44:47]
	v_mfma_f32_16x16x32_bf16 v[40:43], v[170:173], v[220:223], v[40:43]
	v_mfma_f32_16x16x32_bf16 v[36:39], v[162:165], v[228:231], v[36:39]
	v_mfma_f32_16x16x32_bf16 v[32:35], v[170:173], v[228:231], v[32:35]
	v_mfma_f32_16x16x32_bf16 v[60:63], v[166:169], v[206:209], v[60:63]
	v_mfma_f32_16x16x32_bf16 v[56:59], v[174:177], v[206:209], v[56:59]
	v_mfma_f32_16x16x32_bf16 v[52:55], v[166:169], v[214:217], v[52:55]
	v_mfma_f32_16x16x32_bf16 v[48:51], v[174:177], v[214:217], v[48:51]
	v_mfma_f32_16x16x32_bf16 v[44:47], v[166:169], v[224:227], v[44:47]
	v_mfma_f32_16x16x32_bf16 v[40:43], v[174:177], v[224:227], v[40:43]
	v_mfma_f32_16x16x32_bf16 v[36:39], v[166:169], v[232:235], v[36:39]
	v_mfma_f32_16x16x32_bf16 v[32:35], v[174:177], v[232:235], v[32:35]
	s_barrier
	s_add_i32 s16, s29, s34
	v_lshl_add_u64 v[140:141], v[140:141], 0, s[12:13]
	s_mov_b32 m0, s16
	ds_read_b128 v[194:197], v145 offset:49152
	ds_read_b128 v[206:209], v145 offset:50176
	ds_read_b128 v[210:213], v145 offset:51200
	ds_read_b128 v[214:217], v145 offset:52224
	ds_read_b128 v[220:223], v145 offset:53248
	ds_read_b128 v[224:227], v145 offset:54272
	ds_read_b128 v[228:231], v145 offset:55296
	ds_read_b128 v[232:235], v145 offset:56320
	global_load_lds_dwordx4 v[140:141], off
	v_lshl_add_u64 v[140:141], v[178:179], 0, s[12:13]
	s_add_i32 m0, s16, 0x2000
	s_add_i32 s16, s42, s34
	global_load_lds_dwordx4 v[140:141], off
	v_lshl_add_u64 v[140:141], v[198:199], 0, s[12:13]
	s_mov_b32 m0, s16
	s_nop 0
	global_load_lds_dwordx4 v[140:141], off
	v_lshl_add_u64 v[140:141], v[202:203], 0, s[12:13]
	s_add_i32 m0, s16, 0x2000
	s_nop 0
	global_load_lds_dwordx4 v[140:141], off
	v_lshl_add_u64 v[140:141], v[236:237], 0, s[12:13]
	s_mov_b32 m0, s46
	s_nop 0
	global_load_lds_dwordx4 v[140:141], off
	v_lshl_add_u64 v[140:141], v[238:239], 0, s[12:13]
	s_mov_b32 m0, s47
	s_nop 0
	global_load_lds_dwordx4 v[140:141], off
	s_waitcnt vmcnt(8)
	s_waitcnt lgkmcnt(0)
	s_barrier
	s_waitcnt lgkmcnt(0)
	v_mfma_f32_16x16x32_bf16 v[92:95], v[146:149], v[194:197], v[92:95]
	s_add_u32 s26, s26, 0x100
	v_mfma_f32_16x16x32_bf16 v[88:91], v[154:157], v[194:197], v[88:91]
	s_addc_u32 s27, s27, 0
	v_mfma_f32_16x16x32_bf16 v[84:87], v[146:149], v[210:213], v[84:87]
	s_add_u32 s10, s10, 0x100
	v_mfma_f32_16x16x32_bf16 v[80:83], v[154:157], v[210:213], v[80:83]
	s_addc_u32 s11, s11, 0
	v_mfma_f32_16x16x32_bf16 v[76:79], v[146:149], v[220:223], v[76:79]
	s_mov_b32 s16, s28
	v_mfma_f32_16x16x32_bf16 v[72:75], v[154:157], v[220:223], v[72:75]
	s_cmp_ge_i32 s28, s45
	v_mfma_f32_16x16x32_bf16 v[68:71], v[146:149], v[228:231], v[68:71]
	s_cselect_b32 s99, 1, 0
	v_readfirstlane_b32 s98, v218
	s_bfe_u32 s98, s98, 0x10008
	s_and_b32 s98, s98, s99
	v_mfma_f32_16x16x32_bf16 v[64:67], v[154:157], v[228:231], v[64:67]
	s_add_i32 s28, s16, 2
	v_mfma_f32_16x16x32_bf16 v[92:95], v[150:153], v[206:209], v[92:95]
	s_add_u32 s29, s26, 0x80
	v_mfma_f32_16x16x32_bf16 v[88:91], v[158:161], v[206:209], v[88:91]
	s_addc_u32 s17, s27, 0
	v_mfma_f32_16x16x32_bf16 v[84:87], v[150:153], v[214:217], v[84:87]
	s_add_i32 s59, 0, 0x10000
	v_mfma_f32_16x16x32_bf16 v[80:83], v[158:161], v[214:217], v[80:83]
	s_cmp_eq_u32 s48, s16
	v_mfma_f32_16x16x32_bf16 v[76:79], v[150:153], v[224:227], v[76:79]
	s_cselect_b32 s17, s23, s17
	v_mfma_f32_16x16x32_bf16 v[72:75], v[158:161], v[224:227], v[72:75]
	s_cselect_b32 s16, s22, s29
	v_mfma_f32_16x16x32_bf16 v[68:71], v[150:153], v[232:235], v[68:71]
	s_cselect_b32 s43, s25, s11
	v_mfma_f32_16x16x32_bf16 v[64:67], v[158:161], v[232:235], v[64:67]
	s_cselect_b32 s42, s24, s10
	v_mfma_f32_16x16x32_bf16 v[28:31], v[162:165], v[194:197], v[28:31]
	s_add_i32 s29, 0, 0x14000
	v_mfma_f32_16x16x32_bf16 v[24:27], v[170:173], v[194:197], v[24:27]
	v_mfma_f32_16x16x32_bf16 v[20:23], v[162:165], v[210:213], v[20:23]
	v_mfma_f32_16x16x32_bf16 v[16:19], v[170:173], v[210:213], v[16:19]
	v_mfma_f32_16x16x32_bf16 v[12:15], v[162:165], v[220:223], v[12:15]
	v_mfma_f32_16x16x32_bf16 v[8:11], v[170:173], v[220:223], v[8:11]
	v_mfma_f32_16x16x32_bf16 v[4:7], v[162:165], v[228:231], v[4:7]
	v_mfma_f32_16x16x32_bf16 v[0:3], v[170:173], v[228:231], v[0:3]
	v_mfma_f32_16x16x32_bf16 v[28:31], v[166:169], v[206:209], v[28:31]
	v_mfma_f32_16x16x32_bf16 v[24:27], v[174:177], v[206:209], v[24:27]
	v_mfma_f32_16x16x32_bf16 v[20:23], v[166:169], v[214:217], v[20:23]
	v_mfma_f32_16x16x32_bf16 v[16:19], v[174:177], v[214:217], v[16:19]
	v_mfma_f32_16x16x32_bf16 v[12:15], v[166:169], v[224:227], v[12:15]
	v_mfma_f32_16x16x32_bf16 v[8:11], v[174:177], v[224:227], v[8:11]
	v_mfma_f32_16x16x32_bf16 v[4:7], v[166:169], v[232:235], v[4:7]
	v_mfma_f32_16x16x32_bf16 v[0:3], v[174:177], v[232:235], v[0:3]
	s_cmp_lg_u32 s98, 0
	s_cbranch_scc1 .Lskf_11_peel
	s_barrier

.LBB0_823:
	v_add_u32_e32 v140, s59, v143
	ds_read_b128 v[146:149], v140
	ds_read_b128 v[150:153], v140 offset:1024
	ds_read_b128 v[154:157], v140 offset:2048
	ds_read_b128 v[158:161], v140 offset:3072
	v_add_u32_e32 v140, s29, v143
	ds_read_b128 v[162:165], v140
	ds_read_b128 v[166:169], v140 offset:1024
	ds_read_b128 v[170:173], v140 offset:2048
	ds_read_b128 v[174:177], v140 offset:3072
	v_lshl_add_u64 v[140:141], s[26:27], 0, v[136:137]
	s_add_i32 m0, s35, 0xc000
	ds_read_b128 v[194:197], v145
	ds_read_b128 v[206:209], v145 offset:1024
	ds_read_b128 v[210:213], v145 offset:2048
	ds_read_b128 v[214:217], v145 offset:3072
	ds_read_b128 v[220:223], v145 offset:4096
	ds_read_b128 v[224:227], v145 offset:5120
	ds_read_b128 v[228:231], v145 offset:6144
	ds_read_b128 v[232:235], v145 offset:7168
	global_load_lds_dwordx4 v[140:141], off
	v_lshl_add_u64 v[140:141], s[26:27], 0, v[138:139]
	s_add_i32 m0, s35, 0xe000
	s_nop 0
	global_load_lds_dwordx4 v[140:141], off
	s_waitcnt vmcnt(8)
	s_waitcnt lgkmcnt(0)
	s_barrier
	s_waitcnt lgkmcnt(0)
	v_mfma_f32_16x16x32_bf16 v[120:123], v[146:149], v[194:197], v[120:123]
	v_mfma_f32_16x16x32_bf16 v[124:127], v[154:157], v[194:197], v[124:127]
	v_mfma_f32_16x16x32_bf16 v[116:119], v[146:149], v[210:213], v[116:119]
	v_mfma_f32_16x16x32_bf16 v[112:115], v[154:157], v[210:213], v[112:115]
	v_mfma_f32_16x16x32_bf16 v[108:111], v[146:149], v[220:223], v[108:111]
	v_mfma_f32_16x16x32_bf16 v[104:107], v[154:157], v[220:223], v[104:107]
	v_mfma_f32_16x16x32_bf16 v[100:103], v[146:149], v[228:231], v[100:103]
	v_mfma_f32_16x16x32_bf16 v[96:99], v[154:157], v[228:231], v[96:99]
	v_mfma_f32_16x16x32_bf16 v[120:123], v[150:153], v[206:209], v[120:123]
	v_mfma_f32_16x16x32_bf16 v[124:127], v[158:161], v[206:209], v[124:127]
	v_mfma_f32_16x16x32_bf16 v[116:119], v[150:153], v[214:217], v[116:119]
	v_mfma_f32_16x16x32_bf16 v[112:115], v[158:161], v[214:217], v[112:115]
	v_mfma_f32_16x16x32_bf16 v[108:111], v[150:153], v[224:227], v[108:111]
	v_mfma_f32_16x16x32_bf16 v[104:107], v[158:161], v[224:227], v[104:107]
	v_mfma_f32_16x16x32_bf16 v[100:103], v[150:153], v[232:235], v[100:103]
	v_mfma_f32_16x16x32_bf16 v[96:99], v[158:161], v[232:235], v[96:99]
	v_mfma_f32_16x16x32_bf16 v[60:63], v[162:165], v[194:197], v[60:63]
	v_mfma_f32_16x16x32_bf16 v[56:59], v[170:173], v[194:197], v[56:59]
	v_mfma_f32_16x16x32_bf16 v[52:55], v[162:165], v[210:213], v[52:55]
	v_mfma_f32_16x16x32_bf16 v[48:51], v[170:173], v[210:213], v[48:51]
	v_mfma_f32_16x16x32_bf16 v[44:47], v[162:165], v[220:223], v[44:47]
	v_mfma_f32_16x16x32_bf16 v[40:43], v[170:173], v[220:223], v[40:43]
	v_mfma_f32_16x16x32_bf16 v[36:39], v[162:165], v[228:231], v[36:39]
	v_mfma_f32_16x16x32_bf16 v[32:35], v[170:173], v[228:231], v[32:35]
	v_mfma_f32_16x16x32_bf16 v[60:63], v[166:169], v[206:209], v[60:63]
	v_mfma_f32_16x16x32_bf16 v[56:59], v[174:177], v[206:209], v[56:59]
	v_mfma_f32_16x16x32_bf16 v[52:55], v[166:169], v[214:217], v[52:55]
	v_mfma_f32_16x16x32_bf16 v[48:51], v[174:177], v[214:217], v[48:51]
	v_mfma_f32_16x16x32_bf16 v[44:47], v[166:169], v[224:227], v[44:47]
	v_mfma_f32_16x16x32_bf16 v[40:43], v[174:177], v[224:227], v[40:43]
	v_mfma_f32_16x16x32_bf16 v[36:39], v[166:169], v[232:235], v[36:39]
	v_mfma_f32_16x16x32_bf16 v[32:35], v[174:177], v[232:235], v[32:35]
	s_barrier
	s_add_i32 s59, s59, s34
	v_lshl_add_u64 v[140:141], s[42:43], 0, v[132:133]
	s_mov_b32 m0, s59
	ds_read_b128 v[194:197], v145 offset:16384
	ds_read_b128 v[206:209], v145 offset:17408
	ds_read_b128 v[210:213], v145 offset:18432
	ds_read_b128 v[214:217], v145 offset:19456
	ds_read_b128 v[220:223], v145 offset:20480
	ds_read_b128 v[224:227], v145 offset:21504
	ds_read_b128 v[228:231], v145 offset:22528
	ds_read_b128 v[232:235], v145 offset:23552
	global_load_lds_dwordx4 v[140:141], off
	s_add_i32 m0, s59, 0x2000
	v_lshl_add_u64 v[178:179], s[42:43], 0, v[128:129]
	s_add_u32 s42, s42, s0
	s_addc_u32 s43, s43, s1
	s_add_i32 s29, s29, s34
	global_load_lds_dwordx4 v[178:179], off
	v_lshl_add_u64 v[198:199], s[42:43], 0, v[132:133]
	s_mov_b32 m0, s29
	v_lshl_add_u64 v[202:203], s[42:43], 0, v[128:129]
	global_load_lds_dwordx4 v[198:199], off
	s_add_i32 m0, s29, 0x2000
	v_lshl_add_u64 v[236:237], s[16:17], 0, v[134:135]
	global_load_lds_dwordx4 v[202:203], off
	s_mov_b32 m0, s35
	v_lshl_add_u64 v[238:239], s[16:17], 0, v[130:131]
	global_load_lds_dwordx4 v[236:237], off
	s_mov_b32 m0, s36
	s_nop 0
	global_load_lds_dwordx4 v[238:239], off
	s_waitcnt vmcnt(8)
	s_waitcnt lgkmcnt(0)
	s_barrier
	s_waitcnt lgkmcnt(0)
	v_mfma_f32_16x16x32_bf16 v[92:95], v[146:149], v[194:197], v[92:95]
	v_mfma_f32_16x16x32_bf16 v[88:91], v[154:157], v[194:197], v[88:91]
	v_mfma_f32_16x16x32_bf16 v[84:87], v[146:149], v[210:213], v[84:87]
	v_mfma_f32_16x16x32_bf16 v[80:83], v[154:157], v[210:213], v[80:83]
	v_mfma_f32_16x16x32_bf16 v[76:79], v[146:149], v[220:223], v[76:79]
	v_mfma_f32_16x16x32_bf16 v[72:75], v[154:157], v[220:223], v[72:75]
	v_mfma_f32_16x16x32_bf16 v[68:71], v[146:149], v[228:231], v[68:71]
	v_mfma_f32_16x16x32_bf16 v[64:67], v[154:157], v[228:231], v[64:67]
	v_mfma_f32_16x16x32_bf16 v[92:95], v[150:153], v[206:209], v[92:95]
	v_mfma_f32_16x16x32_bf16 v[88:91], v[158:161], v[206:209], v[88:91]
	v_mfma_f32_16x16x32_bf16 v[84:87], v[150:153], v[214:217], v[84:87]
	v_mfma_f32_16x16x32_bf16 v[80:83], v[158:161], v[214:217], v[80:83]
	v_mfma_f32_16x16x32_bf16 v[76:79], v[150:153], v[224:227], v[76:79]
	v_mfma_f32_16x16x32_bf16 v[72:75], v[158:161], v[224:227], v[72:75]
	v_mfma_f32_16x16x32_bf16 v[68:71], v[150:153], v[232:235], v[68:71]
	v_mfma_f32_16x16x32_bf16 v[64:67], v[158:161], v[232:235], v[64:67]
	v_mfma_f32_16x16x32_bf16 v[28:31], v[162:165], v[194:197], v[28:31]
	v_mfma_f32_16x16x32_bf16 v[24:27], v[170:173], v[194:197], v[24:27]
	v_mfma_f32_16x16x32_bf16 v[20:23], v[162:165], v[210:213], v[20:23]
	v_mfma_f32_16x16x32_bf16 v[16:19], v[170:173], v[210:213], v[16:19]
	v_mfma_f32_16x16x32_bf16 v[12:15], v[162:165], v[220:223], v[12:15]
	v_mfma_f32_16x16x32_bf16 v[8:11], v[170:173], v[220:223], v[8:11]
	v_mfma_f32_16x16x32_bf16 v[4:7], v[162:165], v[228:231], v[4:7]
	v_mfma_f32_16x16x32_bf16 v[0:3], v[170:173], v[228:231], v[0:3]
	v_mfma_f32_16x16x32_bf16 v[28:31], v[166:169], v[206:209], v[28:31]
	v_mfma_f32_16x16x32_bf16 v[24:27], v[174:177], v[206:209], v[24:27]
	v_mfma_f32_16x16x32_bf16 v[20:23], v[166:169], v[214:217], v[20:23]
	v_mfma_f32_16x16x32_bf16 v[16:19], v[174:177], v[214:217], v[16:19]
	v_mfma_f32_16x16x32_bf16 v[12:15], v[166:169], v[224:227], v[12:15]
	v_mfma_f32_16x16x32_bf16 v[8:11], v[174:177], v[224:227], v[8:11]
	v_mfma_f32_16x16x32_bf16 v[4:7], v[166:169], v[232:235], v[4:7]
	v_mfma_f32_16x16x32_bf16 v[0:3], v[174:177], v[232:235], v[0:3]
	s_barrier
	s_add_i32 s29, 0, 0x18000
	s_add_i32 s42, 0, 0x1c000
	v_add_u32_e32 v158, s29, v143
	v_add_u32_e32 v174, s42, v143
	ds_read_b128 v[146:149], v158
	ds_read_b128 v[150:153], v158 offset:1024
	ds_read_b128 v[154:157], v158 offset:2048
	ds_read_b128 v[158:161], v158 offset:3072
	ds_read_b128 v[162:165], v174
	ds_read_b128 v[166:169], v174 offset:1024
	ds_read_b128 v[170:173], v174 offset:2048
	ds_read_b128 v[174:177], v174 offset:3072
	s_add_u32 s16, s16, s0
	s_addc_u32 s17, s17, s1
	s_mov_b32 m0, s37
	v_lshl_add_u64 v[240:241], s[16:17], 0, v[134:135]
	ds_read_b128 v[194:197], v145 offset:32768
	ds_read_b128 v[206:209], v145 offset:33792
	ds_read_b128 v[210:213], v145 offset:34816
	ds_read_b128 v[214:217], v145 offset:35840
	ds_read_b128 v[220:223], v145 offset:36864
	ds_read_b128 v[224:227], v145 offset:37888
	ds_read_b128 v[228:231], v145 offset:38912
	ds_read_b128 v[232:235], v145 offset:39936
	global_load_lds_dwordx4 v[240:241], off
	v_lshl_add_u64 v[240:241], s[16:17], 0, v[130:131]
	s_mov_b32 m0, s38
	s_nop 0
	global_load_lds_dwordx4 v[240:241], off
	s_waitcnt vmcnt(8)
	s_waitcnt lgkmcnt(0)
	s_barrier
	s_waitcnt lgkmcnt(0)
	v_mfma_f32_16x16x32_bf16 v[120:123], v[146:149], v[194:197], v[120:123]
	v_mfma_f32_16x16x32_bf16 v[124:127], v[154:157], v[194:197], v[124:127]
	v_mfma_f32_16x16x32_bf16 v[116:119], v[146:149], v[210:213], v[116:119]
	v_mfma_f32_16x16x32_bf16 v[112:115], v[154:157], v[210:213], v[112:115]
	v_mfma_f32_16x16x32_bf16 v[108:111], v[146:149], v[220:223], v[108:111]
	v_mfma_f32_16x16x32_bf16 v[104:107], v[154:157], v[220:223], v[104:107]
	v_mfma_f32_16x16x32_bf16 v[100:103], v[146:149], v[228:231], v[100:103]
	v_mfma_f32_16x16x32_bf16 v[96:99], v[154:157], v[228:231], v[96:99]
	v_mfma_f32_16x16x32_bf16 v[120:123], v[150:153], v[206:209], v[120:123]
	v_mfma_f32_16x16x32_bf16 v[124:127], v[158:161], v[206:209], v[124:127]
	v_mfma_f32_16x16x32_bf16 v[116:119], v[150:153], v[214:217], v[116:119]
	v_mfma_f32_16x16x32_bf16 v[112:115], v[158:161], v[214:217], v[112:115]
	v_mfma_f32_16x16x32_bf16 v[108:111], v[150:153], v[224:227], v[108:111]
	v_mfma_f32_16x16x32_bf16 v[104:107], v[158:161], v[224:227], v[104:107]
	v_mfma_f32_16x16x32_bf16 v[100:103], v[150:153], v[232:235], v[100:103]
	v_mfma_f32_16x16x32_bf16 v[96:99], v[158:161], v[232:235], v[96:99]
	v_mfma_f32_16x16x32_bf16 v[60:63], v[162:165], v[194:197], v[60:63]
	v_mfma_f32_16x16x32_bf16 v[56:59], v[170:173], v[194:197], v[56:59]
	v_mfma_f32_16x16x32_bf16 v[52:55], v[162:165], v[210:213], v[52:55]
	v_mfma_f32_16x16x32_bf16 v[48:51], v[170:173], v[210:213], v[48:51]
	v_mfma_f32_16x16x32_bf16 v[44:47], v[162:165], v[220:223], v[44:47]
	v_mfma_f32_16x16x32_bf16 v[40:43], v[170:173], v[220:223], v[40:43]
	v_mfma_f32_16x16x32_bf16 v[36:39], v[162:165], v[228:231], v[36:39]
	v_mfma_f32_16x16x32_bf16 v[32:35], v[170:173], v[228:231], v[32:35]
	v_mfma_f32_16x16x32_bf16 v[60:63], v[166:169], v[206:209], v[60:63]
	v_mfma_f32_16x16x32_bf16 v[56:59], v[174:177], v[206:209], v[56:59]
	v_mfma_f32_16x16x32_bf16 v[52:55], v[166:169], v[214:217], v[52:55]
	v_mfma_f32_16x16x32_bf16 v[48:51], v[174:177], v[214:217], v[48:51]
	v_mfma_f32_16x16x32_bf16 v[44:47], v[166:169], v[224:227], v[44:47]
	v_mfma_f32_16x16x32_bf16 v[40:43], v[174:177], v[224:227], v[40:43]
	v_mfma_f32_16x16x32_bf16 v[36:39], v[166:169], v[232:235], v[36:39]
	v_mfma_f32_16x16x32_bf16 v[32:35], v[174:177], v[232:235], v[32:35]
	s_barrier
	s_add_i32 s16, s29, s34
	v_lshl_add_u64 v[140:141], v[140:141], 0, s[12:13]
	s_mov_b32 m0, s16
	ds_read_b128 v[194:197], v145 offset:49152
	ds_read_b128 v[206:209], v145 offset:50176
	ds_read_b128 v[210:213], v145 offset:51200
	ds_read_b128 v[214:217], v145 offset:52224
	ds_read_b128 v[220:223], v145 offset:53248
	ds_read_b128 v[224:227], v145 offset:54272
	ds_read_b128 v[228:231], v145 offset:55296
	ds_read_b128 v[232:235], v145 offset:56320
	global_load_lds_dwordx4 v[140:141], off
	v_lshl_add_u64 v[140:141], v[178:179], 0, s[12:13]
	s_add_i32 m0, s16, 0x2000
	s_add_i32 s16, s42, s34
	global_load_lds_dwordx4 v[140:141], off
	v_lshl_add_u64 v[140:141], v[198:199], 0, s[12:13]
	s_mov_b32 m0, s16
	s_nop 0
	global_load_lds_dwordx4 v[140:141], off
	v_lshl_add_u64 v[140:141], v[202:203], 0, s[12:13]
	s_add_i32 m0, s16, 0x2000
	s_nop 0
	global_load_lds_dwordx4 v[140:141], off
	v_lshl_add_u64 v[140:141], v[236:237], 0, s[12:13]
	s_mov_b32 m0, s46
	s_nop 0
	global_load_lds_dwordx4 v[140:141], off
	v_lshl_add_u64 v[140:141], v[238:239], 0, s[12:13]
	s_mov_b32 m0, s47
	s_nop 0
	global_load_lds_dwordx4 v[140:141], off
	s_waitcnt vmcnt(8)
	s_waitcnt lgkmcnt(0)
	s_barrier
	s_waitcnt lgkmcnt(0)
	v_mfma_f32_16x16x32_bf16 v[92:95], v[146:149], v[194:197], v[92:95]
	s_add_u32 s26, s26, 0x100
	v_mfma_f32_16x16x32_bf16 v[88:91], v[154:157], v[194:197], v[88:91]
	s_addc_u32 s27, s27, 0
	v_mfma_f32_16x16x32_bf16 v[84:87], v[146:149], v[210:213], v[84:87]
	s_add_u32 s10, s10, 0x100
	v_mfma_f32_16x16x32_bf16 v[80:83], v[154:157], v[210:213], v[80:83]
	s_addc_u32 s11, s11, 0
	v_mfma_f32_16x16x32_bf16 v[76:79], v[146:149], v[220:223], v[76:79]
	s_mov_b32 s16, s28
	v_mfma_f32_16x16x32_bf16 v[72:75], v[154:157], v[220:223], v[72:75]
	s_cmp_ge_i32 s28, s45
	v_mfma_f32_16x16x32_bf16 v[68:71], v[146:149], v[228:231], v[68:71]
	s_cselect_b32 s99, 1, 0
	v_readfirstlane_b32 s98, v218
	s_bfe_u32 s98, s98, 0x10008
	s_and_b32 s98, s98, s99
	v_mfma_f32_16x16x32_bf16 v[64:67], v[154:157], v[228:231], v[64:67]
	s_add_i32 s28, s16, 2
	v_mfma_f32_16x16x32_bf16 v[92:95], v[150:153], v[206:209], v[92:95]
	s_add_u32 s29, s26, 0x80
	v_mfma_f32_16x16x32_bf16 v[88:91], v[158:161], v[206:209], v[88:91]
	s_addc_u32 s17, s27, 0
	v_mfma_f32_16x16x32_bf16 v[84:87], v[150:153], v[214:217], v[84:87]
	s_add_i32 s59, 0, 0x10000
	v_mfma_f32_16x16x32_bf16 v[80:83], v[158:161], v[214:217], v[80:83]
	s_cmp_eq_u32 s48, s16
	v_mfma_f32_16x16x32_bf16 v[76:79], v[150:153], v[224:227], v[76:79]
	s_cselect_b32 s17, s23, s17
	v_mfma_f32_16x16x32_bf16 v[72:75], v[158:161], v[224:227], v[72:75]
	s_cselect_b32 s16, s22, s29
	v_mfma_f32_16x16x32_bf16 v[68:71], v[150:153], v[232:235], v[68:71]
	s_cselect_b32 s43, s25, s11
	v_mfma_f32_16x16x32_bf16 v[64:67], v[158:161], v[232:235], v[64:67]
	s_cselect_b32 s42, s24, s10
	v_mfma_f32_16x16x32_bf16 v[28:31], v[162:165], v[194:197], v[28:31]
	s_add_i32 s29, 0, 0x14000
	v_mfma_f32_16x16x32_bf16 v[24:27], v[170:173], v[194:197], v[24:27]
	v_mfma_f32_16x16x32_bf16 v[20:23], v[162:165], v[210:213], v[20:23]
	v_mfma_f32_16x16x32_bf16 v[16:19], v[170:173], v[210:213], v[16:19]
	v_mfma_f32_16x16x32_bf16 v[12:15], v[162:165], v[220:223], v[12:15]
	v_mfma_f32_16x16x32_bf16 v[8:11], v[170:173], v[220:223], v[8:11]
	v_mfma_f32_16x16x32_bf16 v[4:7], v[162:165], v[228:231], v[4:7]
	v_mfma_f32_16x16x32_bf16 v[0:3], v[170:173], v[228:231], v[0:3]
	v_mfma_f32_16x16x32_bf16 v[28:31], v[166:169], v[206:209], v[28:31]
	v_mfma_f32_16x16x32_bf16 v[24:27], v[174:177], v[206:209], v[24:27]
	v_mfma_f32_16x16x32_bf16 v[20:23], v[166:169], v[214:217], v[20:23]
	v_mfma_f32_16x16x32_bf16 v[16:19], v[174:177], v[214:217], v[16:19]
	v_mfma_f32_16x16x32_bf16 v[12:15], v[166:169], v[224:227], v[12:15]
	v_mfma_f32_16x16x32_bf16 v[8:11], v[174:177], v[224:227], v[8:11]
	v_mfma_f32_16x16x32_bf16 v[4:7], v[166:169], v[232:235], v[4:7]
	v_mfma_f32_16x16x32_bf16 v[0:3], v[174:177], v[232:235], v[0:3]
	s_cmp_lg_u32 s98, 0
	s_cbranch_scc1 .Lskf_11_loop
	s_barrier

.Lpeelx_11:
.LBB0_824:
	s_and_b64 vcc, exec, s[20:21]
	s_cbranch_vccz .LBB0_826
	s_nop 0

.LBB0_835:
	s_barrier
	s_andn2_b64 vcc, exec, s[0:1]
	s_mov_b32 s62, s60
	s_mov_b32 s34, s61
	s_mov_b64 s[30:31], s[28:29]
	s_mov_b64 s[0:1], s[26:27]
	s_cbranch_vccz .LBB0_882

.Llbb_8:
	s_add_i32 s30, s16, 2
	s_add_u32 s31, s0, 0x80
	s_addc_u32 s17, s1, 0
	s_add_i32 s35, 0, 0x10000
	s_cmp_eq_u32 s57, s16
	s_cselect_b32 s17, s27, s17
	s_cselect_b32 s16, s26, s31
	s_cselect_b32 s43, s29, s11
	s_cselect_b32 s42, s28, s10
	s_add_i32 s31, 0, 0x14000
	v_add_u32_e32 v156, s35, v164
	v_add_u32_e32 v167, s31, v164
	ds_read_b128 v[144:147], v156
	ds_read_b128 v[148:151], v156 offset:1024
	ds_read_b128 v[152:155], v156 offset:2048
	ds_read_b128 v[156:159], v156 offset:3072
	ds_read_b128 v[160:163], v167
	ds_read_b128 v[168:171], v167 offset:1024
	ds_read_b128 v[172:175], v167 offset:2048
	ds_read_b128 v[176:179], v167 offset:3072
	v_lshl_add_u64 v[198:199], s[0:1], 0, v[140:141]
	s_add_i32 m0, s39, 0xc000
	ds_read_b128 v[194:197], v166
	ds_read_b128 v[206:209], v166 offset:1024
	ds_read_b128 v[210:213], v166 offset:2048
	ds_read_b128 v[214:217], v166 offset:3072
	ds_read_b128 v[220:223], v166 offset:4096
	ds_read_b128 v[224:227], v166 offset:5120
	ds_read_b128 v[228:231], v166 offset:6144
	ds_read_b128 v[232:235], v166 offset:7168
	global_load_lds_dwordx4 v[198:199], off
	v_lshl_add_u64 v[198:199], s[0:1], 0, v[142:143]
	s_add_i32 m0, s39, 0xe000
	s_nop 0
	global_load_lds_dwordx4 v[198:199], off
	s_waitcnt vmcnt(8)
	s_waitcnt lgkmcnt(0)
	s_barrier
	s_waitcnt lgkmcnt(0)
	v_mfma_f32_16x16x32_bf16 v[124:127], v[144:147], v[194:197], 0
	v_mfma_f32_16x16x32_bf16 v[120:123], v[152:155], v[194:197], 0
	v_mfma_f32_16x16x32_bf16 v[108:111], v[144:147], v[210:213], 0
	v_mfma_f32_16x16x32_bf16 v[104:107], v[152:155], v[210:213], 0
	v_mfma_f32_16x16x32_bf16 v[92:95], v[144:147], v[220:223], 0
	v_mfma_f32_16x16x32_bf16 v[88:91], v[152:155], v[220:223], 0
	v_mfma_f32_16x16x32_bf16 v[76:79], v[144:147], v[228:231], 0
	v_mfma_f32_16x16x32_bf16 v[72:75], v[152:155], v[228:231], 0
	v_mfma_f32_16x16x32_bf16 v[124:127], v[148:151], v[206:209], v[124:127]
	v_mfma_f32_16x16x32_bf16 v[120:123], v[156:159], v[206:209], v[120:123]
	v_mfma_f32_16x16x32_bf16 v[108:111], v[148:151], v[214:217], v[108:111]
	v_mfma_f32_16x16x32_bf16 v[104:107], v[156:159], v[214:217], v[104:107]
	v_mfma_f32_16x16x32_bf16 v[92:95], v[148:151], v[224:227], v[92:95]
	v_mfma_f32_16x16x32_bf16 v[88:91], v[156:159], v[224:227], v[88:91]
	v_mfma_f32_16x16x32_bf16 v[76:79], v[148:151], v[232:235], v[76:79]
	v_mfma_f32_16x16x32_bf16 v[72:75], v[156:159], v[232:235], v[72:75]
	v_mfma_f32_16x16x32_bf16 v[116:119], v[160:163], v[194:197], 0
	v_mfma_f32_16x16x32_bf16 v[112:115], v[172:175], v[194:197], 0
	v_mfma_f32_16x16x32_bf16 v[100:103], v[160:163], v[210:213], 0
	v_mfma_f32_16x16x32_bf16 v[96:99], v[172:175], v[210:213], 0
	v_mfma_f32_16x16x32_bf16 v[84:87], v[160:163], v[220:223], 0
	v_mfma_f32_16x16x32_bf16 v[80:83], v[172:175], v[220:223], 0
	v_mfma_f32_16x16x32_bf16 v[68:71], v[160:163], v[228:231], 0
	v_mfma_f32_16x16x32_bf16 v[64:67], v[172:175], v[228:231], 0
	v_mfma_f32_16x16x32_bf16 v[116:119], v[168:171], v[206:209], v[116:119]
	v_mfma_f32_16x16x32_bf16 v[112:115], v[176:179], v[206:209], v[112:115]
	v_mfma_f32_16x16x32_bf16 v[100:103], v[168:171], v[214:217], v[100:103]
	v_mfma_f32_16x16x32_bf16 v[96:99], v[176:179], v[214:217], v[96:99]
	v_mfma_f32_16x16x32_bf16 v[84:87], v[168:171], v[224:227], v[84:87]
	v_mfma_f32_16x16x32_bf16 v[80:83], v[176:179], v[224:227], v[80:83]
	v_mfma_f32_16x16x32_bf16 v[68:71], v[168:171], v[232:235], v[68:71]
	v_mfma_f32_16x16x32_bf16 v[64:67], v[176:179], v[232:235], v[64:67]
	s_barrier
	s_add_i32 s35, s35, s38
	v_lshl_add_u64 v[198:199], s[42:43], 0, v[132:133]
	s_mov_b32 m0, s35
	ds_read_b128 v[194:197], v166 offset:16384
	ds_read_b128 v[206:209], v166 offset:17408
	ds_read_b128 v[210:213], v166 offset:18432
	ds_read_b128 v[214:217], v166 offset:19456
	ds_read_b128 v[220:223], v166 offset:20480
	ds_read_b128 v[224:227], v166 offset:21504
	ds_read_b128 v[228:231], v166 offset:22528
	ds_read_b128 v[232:235], v166 offset:23552
	global_load_lds_dwordx4 v[198:199], off
	s_add_i32 m0, s35, 0x2000
	v_lshl_add_u64 v[202:203], s[42:43], 0, v[128:129]
	s_add_u32 s42, s42, s6
	s_addc_u32 s43, s43, s7
	s_add_i32 s31, s31, s38
	global_load_lds_dwordx4 v[202:203], off
	v_lshl_add_u64 v[236:237], s[42:43], 0, v[132:133]
	s_mov_b32 m0, s31
	v_lshl_add_u64 v[238:239], s[42:43], 0, v[128:129]
	global_load_lds_dwordx4 v[236:237], off
	s_add_i32 m0, s31, 0x2000
	v_lshl_add_u64 v[240:241], s[16:17], 0, v[134:135]
	global_load_lds_dwordx4 v[238:239], off
	s_mov_b32 m0, s39
	v_lshl_add_u64 v[242:243], s[16:17], 0, v[130:131]
	global_load_lds_dwordx4 v[240:241], off
	s_mov_b32 m0, s44
	s_nop 0
	global_load_lds_dwordx4 v[242:243], off
	s_waitcnt vmcnt(8)
	s_waitcnt lgkmcnt(0)
	s_barrier
	s_waitcnt lgkmcnt(0)
	v_mfma_f32_16x16x32_bf16 v[60:63], v[144:147], v[194:197], 0
	v_mfma_f32_16x16x32_bf16 v[56:59], v[152:155], v[194:197], 0
	v_mfma_f32_16x16x32_bf16 v[44:47], v[144:147], v[210:213], 0
	v_mfma_f32_16x16x32_bf16 v[40:43], v[152:155], v[210:213], 0
	v_mfma_f32_16x16x32_bf16 v[28:31], v[144:147], v[220:223], 0
	v_mfma_f32_16x16x32_bf16 v[24:27], v[152:155], v[220:223], 0
	v_mfma_f32_16x16x32_bf16 v[12:15], v[144:147], v[228:231], 0
	v_mfma_f32_16x16x32_bf16 v[8:11], v[152:155], v[228:231], 0
	v_mfma_f32_16x16x32_bf16 v[60:63], v[148:151], v[206:209], v[60:63]
	v_mfma_f32_16x16x32_bf16 v[56:59], v[156:159], v[206:209], v[56:59]
	v_mfma_f32_16x16x32_bf16 v[44:47], v[148:151], v[214:217], v[44:47]
	v_mfma_f32_16x16x32_bf16 v[40:43], v[156:159], v[214:217], v[40:43]
	v_mfma_f32_16x16x32_bf16 v[28:31], v[148:151], v[224:227], v[28:31]
	v_mfma_f32_16x16x32_bf16 v[24:27], v[156:159], v[224:227], v[24:27]
	v_mfma_f32_16x16x32_bf16 v[12:15], v[148:151], v[232:235], v[12:15]
	v_mfma_f32_16x16x32_bf16 v[8:11], v[156:159], v[232:235], v[8:11]
	v_mfma_f32_16x16x32_bf16 v[52:55], v[160:163], v[194:197], 0
	v_mfma_f32_16x16x32_bf16 v[48:51], v[172:175], v[194:197], 0
	v_mfma_f32_16x16x32_bf16 v[36:39], v[160:163], v[210:213], 0
	v_mfma_f32_16x16x32_bf16 v[32:35], v[172:175], v[210:213], 0
	v_mfma_f32_16x16x32_bf16 v[20:23], v[160:163], v[220:223], 0
	v_mfma_f32_16x16x32_bf16 v[16:19], v[172:175], v[220:223], 0
	v_mfma_f32_16x16x32_bf16 v[4:7], v[160:163], v[228:231], 0
	v_mfma_f32_16x16x32_bf16 v[0:3], v[172:175], v[228:231], 0
	v_mfma_f32_16x16x32_bf16 v[52:55], v[168:171], v[206:209], v[52:55]
	v_mfma_f32_16x16x32_bf16 v[48:51], v[176:179], v[206:209], v[48:51]
	v_mfma_f32_16x16x32_bf16 v[36:39], v[168:171], v[214:217], v[36:39]
	v_mfma_f32_16x16x32_bf16 v[32:35], v[176:179], v[214:217], v[32:35]
	v_mfma_f32_16x16x32_bf16 v[20:23], v[168:171], v[224:227], v[20:23]
	v_mfma_f32_16x16x32_bf16 v[16:19], v[176:179], v[224:227], v[16:19]
	v_mfma_f32_16x16x32_bf16 v[4:7], v[168:171], v[232:235], v[4:7]
	v_mfma_f32_16x16x32_bf16 v[0:3], v[176:179], v[232:235], v[0:3]
	s_barrier
	s_add_i32 s31, 0, 0x18000
	s_add_i32 s35, 0, 0x1c000
	v_add_u32_e32 v156, s31, v164
	v_add_u32_e32 v167, s35, v164
	ds_read_b128 v[144:147], v156
	ds_read_b128 v[148:151], v156 offset:1024
	ds_read_b128 v[152:155], v156 offset:2048
	ds_read_b128 v[156:159], v156 offset:3072
	ds_read_b128 v[160:163], v167
	ds_read_b128 v[168:171], v167 offset:1024
	ds_read_b128 v[172:175], v167 offset:2048
	ds_read_b128 v[176:179], v167 offset:3072
	s_add_u32 s16, s16, s6
	s_addc_u32 s17, s17, s7
	s_mov_b32 m0, s45
	v_lshl_add_u64 v[244:245], s[16:17], 0, v[134:135]
	ds_read_b128 v[194:197], v166 offset:32768
	ds_read_b128 v[206:209], v166 offset:33792
	ds_read_b128 v[210:213], v166 offset:34816
	ds_read_b128 v[214:217], v166 offset:35840
	ds_read_b128 v[220:223], v166 offset:36864
	ds_read_b128 v[224:227], v166 offset:37888
	ds_read_b128 v[228:231], v166 offset:38912
	ds_read_b128 v[232:235], v166 offset:39936
	global_load_lds_dwordx4 v[244:245], off
	v_lshl_add_u64 v[244:245], s[16:17], 0, v[130:131]
	s_mov_b32 m0, s46
	s_nop 0
	global_load_lds_dwordx4 v[244:245], off
	s_waitcnt vmcnt(8)
	s_waitcnt lgkmcnt(0)
	s_barrier
	s_waitcnt lgkmcnt(0)
	v_mfma_f32_16x16x32_bf16 v[124:127], v[144:147], v[194:197], v[124:127]
	v_mfma_f32_16x16x32_bf16 v[120:123], v[152:155], v[194:197], v[120:123]
	v_mfma_f32_16x16x32_bf16 v[108:111], v[144:147], v[210:213], v[108:111]
	v_mfma_f32_16x16x32_bf16 v[104:107], v[152:155], v[210:213], v[104:107]
	v_mfma_f32_16x16x32_bf16 v[92:95], v[144:147], v[220:223], v[92:95]
	v_mfma_f32_16x16x32_bf16 v[88:91], v[152:155], v[220:223], v[88:91]
	v_mfma_f32_16x16x32_bf16 v[76:79], v[144:147], v[228:231], v[76:79]
	v_mfma_f32_16x16x32_bf16 v[72:75], v[152:155], v[228:231], v[72:75]
	v_mfma_f32_16x16x32_bf16 v[124:127], v[148:151], v[206:209], v[124:127]
	v_mfma_f32_16x16x32_bf16 v[120:123], v[156:159], v[206:209], v[120:123]
	v_mfma_f32_16x16x32_bf16 v[108:111], v[148:151], v[214:217], v[108:111]
	v_mfma_f32_16x16x32_bf16 v[104:107], v[156:159], v[214:217], v[104:107]
	v_mfma_f32_16x16x32_bf16 v[92:95], v[148:151], v[224:227], v[92:95]
	v_mfma_f32_16x16x32_bf16 v[88:91], v[156:159], v[224:227], v[88:91]
	v_mfma_f32_16x16x32_bf16 v[76:79], v[148:151], v[232:235], v[76:79]
	v_mfma_f32_16x16x32_bf16 v[72:75], v[156:159], v[232:235], v[72:75]
	v_mfma_f32_16x16x32_bf16 v[116:119], v[160:163], v[194:197], v[116:119]
	v_mfma_f32_16x16x32_bf16 v[112:115], v[172:175], v[194:197], v[112:115]
	v_mfma_f32_16x16x32_bf16 v[100:103], v[160:163], v[210:213], v[100:103]
	v_mfma_f32_16x16x32_bf16 v[96:99], v[172:175], v[210:213], v[96:99]
	v_mfma_f32_16x16x32_bf16 v[84:87], v[160:163], v[220:223], v[84:87]
	v_mfma_f32_16x16x32_bf16 v[80:83], v[172:175], v[220:223], v[80:83]
	v_mfma_f32_16x16x32_bf16 v[68:71], v[160:163], v[228:231], v[68:71]
	v_mfma_f32_16x16x32_bf16 v[64:67], v[172:175], v[228:231], v[64:67]
	v_mfma_f32_16x16x32_bf16 v[116:119], v[168:171], v[206:209], v[116:119]
	v_mfma_f32_16x16x32_bf16 v[112:115], v[176:179], v[206:209], v[112:115]
	v_mfma_f32_16x16x32_bf16 v[100:103], v[168:171], v[214:217], v[100:103]
	v_mfma_f32_16x16x32_bf16 v[96:99], v[176:179], v[214:217], v[96:99]
	v_mfma_f32_16x16x32_bf16 v[84:87], v[168:171], v[224:227], v[84:87]
	v_mfma_f32_16x16x32_bf16 v[80:83], v[176:179], v[224:227], v[80:83]
	v_mfma_f32_16x16x32_bf16 v[68:71], v[168:171], v[232:235], v[68:71]
	v_mfma_f32_16x16x32_bf16 v[64:67], v[176:179], v[232:235], v[64:67]
	s_barrier
	s_add_i32 s16, s31, s38
	v_lshl_add_u64 v[198:199], v[198:199], 0, s[12:13]
	s_mov_b32 m0, s16
	ds_read_b128 v[194:197], v166 offset:49152
	ds_read_b128 v[206:209], v166 offset:50176
	ds_read_b128 v[210:213], v166 offset:51200
	ds_read_b128 v[214:217], v166 offset:52224
	ds_read_b128 v[220:223], v166 offset:53248
	ds_read_b128 v[224:227], v166 offset:54272
	ds_read_b128 v[228:231], v166 offset:55296
	ds_read_b128 v[232:235], v166 offset:56320
	global_load_lds_dwordx4 v[198:199], off
	v_lshl_add_u64 v[198:199], v[202:203], 0, s[12:13]
	s_add_i32 m0, s16, 0x2000
	s_add_i32 s16, s35, s38
	global_load_lds_dwordx4 v[198:199], off
	v_lshl_add_u64 v[198:199], v[236:237], 0, s[12:13]
	s_mov_b32 m0, s16
	s_nop 0
	global_load_lds_dwordx4 v[198:199], off
	v_lshl_add_u64 v[198:199], v[238:239], 0, s[12:13]
	s_add_i32 m0, s16, 0x2000
	s_nop 0
	global_load_lds_dwordx4 v[198:199], off
	v_lshl_add_u64 v[198:199], v[240:241], 0, s[12:13]
	s_mov_b32 m0, s47
	s_nop 0
	global_load_lds_dwordx4 v[198:199], off
	v_lshl_add_u64 v[198:199], v[242:243], 0, s[12:13]
	s_mov_b32 m0, s48
	s_nop 0
	global_load_lds_dwordx4 v[198:199], off
	s_waitcnt vmcnt(8)
	s_waitcnt lgkmcnt(0)
	s_barrier
	s_waitcnt lgkmcnt(0)
	v_mfma_f32_16x16x32_bf16 v[60:63], v[144:147], v[194:197], v[60:63]
	s_add_u32 s0, s0, 0x100
	v_mfma_f32_16x16x32_bf16 v[56:59], v[152:155], v[194:197], v[56:59]
	s_addc_u32 s1, s1, 0
	v_mfma_f32_16x16x32_bf16 v[44:47], v[144:147], v[210:213], v[44:47]
	s_add_u32 s10, s10, 0x100
	v_mfma_f32_16x16x32_bf16 v[40:43], v[152:155], v[210:213], v[40:43]
	s_addc_u32 s11, s11, 0
	v_mfma_f32_16x16x32_bf16 v[28:31], v[144:147], v[220:223], v[28:31]
	s_mov_b32 s16, s30
	v_mfma_f32_16x16x32_bf16 v[24:27], v[152:155], v[220:223], v[24:27]
	s_cmp_ge_i32 s30, s49
	v_mfma_f32_16x16x32_bf16 v[12:15], v[144:147], v[228:231], v[12:15]
	s_cselect_b32 s99, 1, 0
	v_readfirstlane_b32 s98, v218
	s_bfe_u32 s98, s98, 0x10008
	s_and_b32 s98, s98, s99
	v_mfma_f32_16x16x32_bf16 v[8:11], v[152:155], v[228:231], v[8:11]
	s_add_i32 s30, s16, 2
	v_mfma_f32_16x16x32_bf16 v[60:63], v[148:151], v[206:209], v[60:63]
	s_add_u32 s31, s0, 0x80
	v_mfma_f32_16x16x32_bf16 v[56:59], v[156:159], v[206:209], v[56:59]
	s_addc_u32 s17, s1, 0
	v_mfma_f32_16x16x32_bf16 v[44:47], v[148:151], v[214:217], v[44:47]
	s_add_i32 s35, 0, 0x10000
	v_mfma_f32_16x16x32_bf16 v[40:43], v[156:159], v[214:217], v[40:43]
	s_cmp_eq_u32 s57, s16
	v_mfma_f32_16x16x32_bf16 v[28:31], v[148:151], v[224:227], v[28:31]
	s_cselect_b32 s17, s27, s17
	v_mfma_f32_16x16x32_bf16 v[24:27], v[156:159], v[224:227], v[24:27]
	s_cselect_b32 s16, s26, s31
	v_mfma_f32_16x16x32_bf16 v[12:15], v[148:151], v[232:235], v[12:15]
	s_cselect_b32 s43, s29, s11
	v_mfma_f32_16x16x32_bf16 v[8:11], v[156:159], v[232:235], v[8:11]
	s_cselect_b32 s42, s28, s10
	v_mfma_f32_16x16x32_bf16 v[52:55], v[160:163], v[194:197], v[52:55]
	s_add_i32 s31, 0, 0x14000
	v_mfma_f32_16x16x32_bf16 v[48:51], v[172:175], v[194:197], v[48:51]
	v_mfma_f32_16x16x32_bf16 v[36:39], v[160:163], v[210:213], v[36:39]
	v_mfma_f32_16x16x32_bf16 v[32:35], v[172:175], v[210:213], v[32:35]
	v_mfma_f32_16x16x32_bf16 v[20:23], v[160:163], v[220:223], v[20:23]
	v_mfma_f32_16x16x32_bf16 v[16:19], v[172:175], v[220:223], v[16:19]
	v_mfma_f32_16x16x32_bf16 v[4:7], v[160:163], v[228:231], v[4:7]
	v_mfma_f32_16x16x32_bf16 v[0:3], v[172:175], v[228:231], v[0:3]
	v_mfma_f32_16x16x32_bf16 v[52:55], v[168:171], v[206:209], v[52:55]
	v_mfma_f32_16x16x32_bf16 v[48:51], v[176:179], v[206:209], v[48:51]
	v_mfma_f32_16x16x32_bf16 v[36:39], v[168:171], v[214:217], v[36:39]
	v_mfma_f32_16x16x32_bf16 v[32:35], v[176:179], v[214:217], v[32:35]
	v_mfma_f32_16x16x32_bf16 v[20:23], v[168:171], v[224:227], v[20:23]
	v_mfma_f32_16x16x32_bf16 v[16:19], v[176:179], v[224:227], v[16:19]
	v_mfma_f32_16x16x32_bf16 v[4:7], v[168:171], v[232:235], v[4:7]
	v_mfma_f32_16x16x32_bf16 v[0:3], v[176:179], v[232:235], v[0:3]
	s_cmp_lg_u32 s98, 0
	s_cbranch_scc1 .Lskf_12_peel
	s_barrier

.LBB0_844:
	v_add_u32_e32 v156, s35, v164
	v_add_u32_e32 v167, s31, v164
	ds_read_b128 v[144:147], v156
	ds_read_b128 v[148:151], v156 offset:1024
	ds_read_b128 v[152:155], v156 offset:2048
	ds_read_b128 v[156:159], v156 offset:3072
	ds_read_b128 v[160:163], v167
	ds_read_b128 v[168:171], v167 offset:1024
	ds_read_b128 v[172:175], v167 offset:2048
	ds_read_b128 v[176:179], v167 offset:3072
	v_lshl_add_u64 v[198:199], s[0:1], 0, v[140:141]
	s_add_i32 m0, s39, 0xc000
	ds_read_b128 v[194:197], v166
	ds_read_b128 v[206:209], v166 offset:1024
	ds_read_b128 v[210:213], v166 offset:2048
	ds_read_b128 v[214:217], v166 offset:3072
	ds_read_b128 v[220:223], v166 offset:4096
	ds_read_b128 v[224:227], v166 offset:5120
	ds_read_b128 v[228:231], v166 offset:6144
	ds_read_b128 v[232:235], v166 offset:7168
	global_load_lds_dwordx4 v[198:199], off
	v_lshl_add_u64 v[198:199], s[0:1], 0, v[142:143]
	s_add_i32 m0, s39, 0xe000
	s_nop 0
	global_load_lds_dwordx4 v[198:199], off
	s_waitcnt vmcnt(8)
	s_waitcnt lgkmcnt(0)
	s_barrier
	s_waitcnt lgkmcnt(0)
	v_mfma_f32_16x16x32_bf16 v[124:127], v[144:147], v[194:197], v[124:127]
	v_mfma_f32_16x16x32_bf16 v[120:123], v[152:155], v[194:197], v[120:123]
	v_mfma_f32_16x16x32_bf16 v[108:111], v[144:147], v[210:213], v[108:111]
	v_mfma_f32_16x16x32_bf16 v[104:107], v[152:155], v[210:213], v[104:107]
	v_mfma_f32_16x16x32_bf16 v[92:95], v[144:147], v[220:223], v[92:95]
	v_mfma_f32_16x16x32_bf16 v[88:91], v[152:155], v[220:223], v[88:91]
	v_mfma_f32_16x16x32_bf16 v[76:79], v[144:147], v[228:231], v[76:79]
	v_mfma_f32_16x16x32_bf16 v[72:75], v[152:155], v[228:231], v[72:75]
	v_mfma_f32_16x16x32_bf16 v[124:127], v[148:151], v[206:209], v[124:127]
	v_mfma_f32_16x16x32_bf16 v[120:123], v[156:159], v[206:209], v[120:123]
	v_mfma_f32_16x16x32_bf16 v[108:111], v[148:151], v[214:217], v[108:111]
	v_mfma_f32_16x16x32_bf16 v[104:107], v[156:159], v[214:217], v[104:107]
	v_mfma_f32_16x16x32_bf16 v[92:95], v[148:151], v[224:227], v[92:95]
	v_mfma_f32_16x16x32_bf16 v[88:91], v[156:159], v[224:227], v[88:91]
	v_mfma_f32_16x16x32_bf16 v[76:79], v[148:151], v[232:235], v[76:79]
	v_mfma_f32_16x16x32_bf16 v[72:75], v[156:159], v[232:235], v[72:75]
	v_mfma_f32_16x16x32_bf16 v[116:119], v[160:163], v[194:197], v[116:119]
	v_mfma_f32_16x16x32_bf16 v[112:115], v[172:175], v[194:197], v[112:115]
	v_mfma_f32_16x16x32_bf16 v[100:103], v[160:163], v[210:213], v[100:103]
	v_mfma_f32_16x16x32_bf16 v[96:99], v[172:175], v[210:213], v[96:99]
	v_mfma_f32_16x16x32_bf16 v[84:87], v[160:163], v[220:223], v[84:87]
	v_mfma_f32_16x16x32_bf16 v[80:83], v[172:175], v[220:223], v[80:83]
	v_mfma_f32_16x16x32_bf16 v[68:71], v[160:163], v[228:231], v[68:71]
	v_mfma_f32_16x16x32_bf16 v[64:67], v[172:175], v[228:231], v[64:67]
	v_mfma_f32_16x16x32_bf16 v[116:119], v[168:171], v[206:209], v[116:119]
	v_mfma_f32_16x16x32_bf16 v[112:115], v[176:179], v[206:209], v[112:115]
	v_mfma_f32_16x16x32_bf16 v[100:103], v[168:171], v[214:217], v[100:103]
	v_mfma_f32_16x16x32_bf16 v[96:99], v[176:179], v[214:217], v[96:99]
	v_mfma_f32_16x16x32_bf16 v[84:87], v[168:171], v[224:227], v[84:87]
	v_mfma_f32_16x16x32_bf16 v[80:83], v[176:179], v[224:227], v[80:83]
	v_mfma_f32_16x16x32_bf16 v[68:71], v[168:171], v[232:235], v[68:71]
	v_mfma_f32_16x16x32_bf16 v[64:67], v[176:179], v[232:235], v[64:67]
	s_barrier
	s_add_i32 s35, s35, s38
	v_lshl_add_u64 v[198:199], s[42:43], 0, v[132:133]
	s_mov_b32 m0, s35
	ds_read_b128 v[194:197], v166 offset:16384
	ds_read_b128 v[206:209], v166 offset:17408
	ds_read_b128 v[210:213], v166 offset:18432
	ds_read_b128 v[214:217], v166 offset:19456
	ds_read_b128 v[220:223], v166 offset:20480
	ds_read_b128 v[224:227], v166 offset:21504
	ds_read_b128 v[228:231], v166 offset:22528
	ds_read_b128 v[232:235], v166 offset:23552
	global_load_lds_dwordx4 v[198:199], off
	s_add_i32 m0, s35, 0x2000
	v_lshl_add_u64 v[202:203], s[42:43], 0, v[128:129]
	s_add_u32 s42, s42, s6
	s_addc_u32 s43, s43, s7
	s_add_i32 s31, s31, s38
	global_load_lds_dwordx4 v[202:203], off
	v_lshl_add_u64 v[236:237], s[42:43], 0, v[132:133]
	s_mov_b32 m0, s31
	v_lshl_add_u64 v[238:239], s[42:43], 0, v[128:129]
	global_load_lds_dwordx4 v[236:237], off
	s_add_i32 m0, s31, 0x2000
	v_lshl_add_u64 v[240:241], s[16:17], 0, v[134:135]
	global_load_lds_dwordx4 v[238:239], off
	s_mov_b32 m0, s39
	v_lshl_add_u64 v[242:243], s[16:17], 0, v[130:131]
	global_load_lds_dwordx4 v[240:241], off
	s_mov_b32 m0, s44
	s_nop 0
	global_load_lds_dwordx4 v[242:243], off
	s_waitcnt vmcnt(8)
	s_waitcnt lgkmcnt(0)
	s_barrier
	s_waitcnt lgkmcnt(0)
	v_mfma_f32_16x16x32_bf16 v[60:63], v[144:147], v[194:197], v[60:63]
	v_mfma_f32_16x16x32_bf16 v[56:59], v[152:155], v[194:197], v[56:59]
	v_mfma_f32_16x16x32_bf16 v[44:47], v[144:147], v[210:213], v[44:47]
	v_mfma_f32_16x16x32_bf16 v[40:43], v[152:155], v[210:213], v[40:43]
	v_mfma_f32_16x16x32_bf16 v[28:31], v[144:147], v[220:223], v[28:31]
	v_mfma_f32_16x16x32_bf16 v[24:27], v[152:155], v[220:223], v[24:27]
	v_mfma_f32_16x16x32_bf16 v[12:15], v[144:147], v[228:231], v[12:15]
	v_mfma_f32_16x16x32_bf16 v[8:11], v[152:155], v[228:231], v[8:11]
	v_mfma_f32_16x16x32_bf16 v[60:63], v[148:151], v[206:209], v[60:63]
	v_mfma_f32_16x16x32_bf16 v[56:59], v[156:159], v[206:209], v[56:59]
	v_mfma_f32_16x16x32_bf16 v[44:47], v[148:151], v[214:217], v[44:47]
	v_mfma_f32_16x16x32_bf16 v[40:43], v[156:159], v[214:217], v[40:43]
	v_mfma_f32_16x16x32_bf16 v[28:31], v[148:151], v[224:227], v[28:31]
	v_mfma_f32_16x16x32_bf16 v[24:27], v[156:159], v[224:227], v[24:27]
	v_mfma_f32_16x16x32_bf16 v[12:15], v[148:151], v[232:235], v[12:15]
	v_mfma_f32_16x16x32_bf16 v[8:11], v[156:159], v[232:235], v[8:11]
	v_mfma_f32_16x16x32_bf16 v[52:55], v[160:163], v[194:197], v[52:55]
	v_mfma_f32_16x16x32_bf16 v[48:51], v[172:175], v[194:197], v[48:51]
	v_mfma_f32_16x16x32_bf16 v[36:39], v[160:163], v[210:213], v[36:39]
	v_mfma_f32_16x16x32_bf16 v[32:35], v[172:175], v[210:213], v[32:35]
	v_mfma_f32_16x16x32_bf16 v[20:23], v[160:163], v[220:223], v[20:23]
	v_mfma_f32_16x16x32_bf16 v[16:19], v[172:175], v[220:223], v[16:19]
	v_mfma_f32_16x16x32_bf16 v[4:7], v[160:163], v[228:231], v[4:7]
	v_mfma_f32_16x16x32_bf16 v[0:3], v[172:175], v[228:231], v[0:3]
	v_mfma_f32_16x16x32_bf16 v[52:55], v[168:171], v[206:209], v[52:55]
	v_mfma_f32_16x16x32_bf16 v[48:51], v[176:179], v[206:209], v[48:51]
	v_mfma_f32_16x16x32_bf16 v[36:39], v[168:171], v[214:217], v[36:39]
	v_mfma_f32_16x16x32_bf16 v[32:35], v[176:179], v[214:217], v[32:35]
	v_mfma_f32_16x16x32_bf16 v[20:23], v[168:171], v[224:227], v[20:23]
	v_mfma_f32_16x16x32_bf16 v[16:19], v[176:179], v[224:227], v[16:19]
	v_mfma_f32_16x16x32_bf16 v[4:7], v[168:171], v[232:235], v[4:7]
	v_mfma_f32_16x16x32_bf16 v[0:3], v[176:179], v[232:235], v[0:3]
	s_barrier
	s_add_i32 s31, 0, 0x18000
	s_add_i32 s35, 0, 0x1c000
	v_add_u32_e32 v156, s31, v164
	v_add_u32_e32 v167, s35, v164
	ds_read_b128 v[144:147], v156
	ds_read_b128 v[148:151], v156 offset:1024
	ds_read_b128 v[152:155], v156 offset:2048
	ds_read_b128 v[156:159], v156 offset:3072
	ds_read_b128 v[160:163], v167
	ds_read_b128 v[168:171], v167 offset:1024
	ds_read_b128 v[172:175], v167 offset:2048
	ds_read_b128 v[176:179], v167 offset:3072
	s_add_u32 s16, s16, s6
	s_addc_u32 s17, s17, s7
	s_mov_b32 m0, s45
	v_lshl_add_u64 v[244:245], s[16:17], 0, v[134:135]
	ds_read_b128 v[194:197], v166 offset:32768
	ds_read_b128 v[206:209], v166 offset:33792
	ds_read_b128 v[210:213], v166 offset:34816
	ds_read_b128 v[214:217], v166 offset:35840
	ds_read_b128 v[220:223], v166 offset:36864
	ds_read_b128 v[224:227], v166 offset:37888
	ds_read_b128 v[228:231], v166 offset:38912
	ds_read_b128 v[232:235], v166 offset:39936
	global_load_lds_dwordx4 v[244:245], off
	v_lshl_add_u64 v[244:245], s[16:17], 0, v[130:131]
	s_mov_b32 m0, s46
	s_nop 0
	global_load_lds_dwordx4 v[244:245], off
	s_waitcnt vmcnt(8)
	s_waitcnt lgkmcnt(0)
	s_barrier
	s_waitcnt lgkmcnt(0)
	v_mfma_f32_16x16x32_bf16 v[124:127], v[144:147], v[194:197], v[124:127]
	v_mfma_f32_16x16x32_bf16 v[120:123], v[152:155], v[194:197], v[120:123]
	v_mfma_f32_16x16x32_bf16 v[108:111], v[144:147], v[210:213], v[108:111]
	v_mfma_f32_16x16x32_bf16 v[104:107], v[152:155], v[210:213], v[104:107]
	v_mfma_f32_16x16x32_bf16 v[92:95], v[144:147], v[220:223], v[92:95]
	v_mfma_f32_16x16x32_bf16 v[88:91], v[152:155], v[220:223], v[88:91]
	v_mfma_f32_16x16x32_bf16 v[76:79], v[144:147], v[228:231], v[76:79]
	v_mfma_f32_16x16x32_bf16 v[72:75], v[152:155], v[228:231], v[72:75]
	v_mfma_f32_16x16x32_bf16 v[124:127], v[148:151], v[206:209], v[124:127]
	v_mfma_f32_16x16x32_bf16 v[120:123], v[156:159], v[206:209], v[120:123]
	v_mfma_f32_16x16x32_bf16 v[108:111], v[148:151], v[214:217], v[108:111]
	v_mfma_f32_16x16x32_bf16 v[104:107], v[156:159], v[214:217], v[104:107]
	v_mfma_f32_16x16x32_bf16 v[92:95], v[148:151], v[224:227], v[92:95]
	v_mfma_f32_16x16x32_bf16 v[88:91], v[156:159], v[224:227], v[88:91]
	v_mfma_f32_16x16x32_bf16 v[76:79], v[148:151], v[232:235], v[76:79]
	v_mfma_f32_16x16x32_bf16 v[72:75], v[156:159], v[232:235], v[72:75]
	v_mfma_f32_16x16x32_bf16 v[116:119], v[160:163], v[194:197], v[116:119]
	v_mfma_f32_16x16x32_bf16 v[112:115], v[172:175], v[194:197], v[112:115]
	v_mfma_f32_16x16x32_bf16 v[100:103], v[160:163], v[210:213], v[100:103]
	v_mfma_f32_16x16x32_bf16 v[96:99], v[172:175], v[210:213], v[96:99]
	v_mfma_f32_16x16x32_bf16 v[84:87], v[160:163], v[220:223], v[84:87]
	v_mfma_f32_16x16x32_bf16 v[80:83], v[172:175], v[220:223], v[80:83]
	v_mfma_f32_16x16x32_bf16 v[68:71], v[160:163], v[228:231], v[68:71]
	v_mfma_f32_16x16x32_bf16 v[64:67], v[172:175], v[228:231], v[64:67]
	v_mfma_f32_16x16x32_bf16 v[116:119], v[168:171], v[206:209], v[116:119]
	v_mfma_f32_16x16x32_bf16 v[112:115], v[176:179], v[206:209], v[112:115]
	v_mfma_f32_16x16x32_bf16 v[100:103], v[168:171], v[214:217], v[100:103]
	v_mfma_f32_16x16x32_bf16 v[96:99], v[176:179], v[214:217], v[96:99]
	v_mfma_f32_16x16x32_bf16 v[84:87], v[168:171], v[224:227], v[84:87]
	v_mfma_f32_16x16x32_bf16 v[80:83], v[176:179], v[224:227], v[80:83]
	v_mfma_f32_16x16x32_bf16 v[68:71], v[168:171], v[232:235], v[68:71]
	v_mfma_f32_16x16x32_bf16 v[64:67], v[176:179], v[232:235], v[64:67]
	s_barrier
	s_add_i32 s16, s31, s38
	v_lshl_add_u64 v[198:199], v[198:199], 0, s[12:13]
	s_mov_b32 m0, s16
	ds_read_b128 v[194:197], v166 offset:49152
	ds_read_b128 v[206:209], v166 offset:50176
	ds_read_b128 v[210:213], v166 offset:51200
	ds_read_b128 v[214:217], v166 offset:52224
	ds_read_b128 v[220:223], v166 offset:53248
	ds_read_b128 v[224:227], v166 offset:54272
	ds_read_b128 v[228:231], v166 offset:55296
	ds_read_b128 v[232:235], v166 offset:56320
	global_load_lds_dwordx4 v[198:199], off
	v_lshl_add_u64 v[198:199], v[202:203], 0, s[12:13]
	s_add_i32 m0, s16, 0x2000
	s_add_i32 s16, s35, s38
	global_load_lds_dwordx4 v[198:199], off
	v_lshl_add_u64 v[198:199], v[236:237], 0, s[12:13]
	s_mov_b32 m0, s16
	s_nop 0
	global_load_lds_dwordx4 v[198:199], off
	v_lshl_add_u64 v[198:199], v[238:239], 0, s[12:13]
	s_add_i32 m0, s16, 0x2000
	s_nop 0
	global_load_lds_dwordx4 v[198:199], off
	v_lshl_add_u64 v[198:199], v[240:241], 0, s[12:13]
	s_mov_b32 m0, s47
	s_nop 0
	global_load_lds_dwordx4 v[198:199], off
	v_lshl_add_u64 v[198:199], v[242:243], 0, s[12:13]
	s_mov_b32 m0, s48
	s_nop 0
	global_load_lds_dwordx4 v[198:199], off
	s_waitcnt vmcnt(8)
	s_waitcnt lgkmcnt(0)
	s_barrier
	s_waitcnt lgkmcnt(0)
	v_mfma_f32_16x16x32_bf16 v[60:63], v[144:147], v[194:197], v[60:63]
	s_add_u32 s0, s0, 0x100
	v_mfma_f32_16x16x32_bf16 v[56:59], v[152:155], v[194:197], v[56:59]
	s_addc_u32 s1, s1, 0
	v_mfma_f32_16x16x32_bf16 v[44:47], v[144:147], v[210:213], v[44:47]
	s_add_u32 s10, s10, 0x100
	v_mfma_f32_16x16x32_bf16 v[40:43], v[152:155], v[210:213], v[40:43]
	s_addc_u32 s11, s11, 0
	v_mfma_f32_16x16x32_bf16 v[28:31], v[144:147], v[220:223], v[28:31]
	s_mov_b32 s16, s30
	v_mfma_f32_16x16x32_bf16 v[24:27], v[152:155], v[220:223], v[24:27]
	s_cmp_ge_i32 s30, s49
	v_mfma_f32_16x16x32_bf16 v[12:15], v[144:147], v[228:231], v[12:15]
	s_cselect_b32 s99, 1, 0
	v_readfirstlane_b32 s98, v218
	s_bfe_u32 s98, s98, 0x10008
	s_and_b32 s98, s98, s99
	v_mfma_f32_16x16x32_bf16 v[8:11], v[152:155], v[228:231], v[8:11]
	s_add_i32 s30, s16, 2
	v_mfma_f32_16x16x32_bf16 v[60:63], v[148:151], v[206:209], v[60:63]
	s_add_u32 s31, s0, 0x80
	v_mfma_f32_16x16x32_bf16 v[56:59], v[156:159], v[206:209], v[56:59]
	s_addc_u32 s17, s1, 0
	v_mfma_f32_16x16x32_bf16 v[44:47], v[148:151], v[214:217], v[44:47]
	s_add_i32 s35, 0, 0x10000
	v_mfma_f32_16x16x32_bf16 v[40:43], v[156:159], v[214:217], v[40:43]
	s_cmp_eq_u32 s57, s16
	v_mfma_f32_16x16x32_bf16 v[28:31], v[148:151], v[224:227], v[28:31]
	s_cselect_b32 s17, s27, s17
	v_mfma_f32_16x16x32_bf16 v[24:27], v[156:159], v[224:227], v[24:27]
	s_cselect_b32 s16, s26, s31
	v_mfma_f32_16x16x32_bf16 v[12:15], v[148:151], v[232:235], v[12:15]
	s_cselect_b32 s43, s29, s11
	v_mfma_f32_16x16x32_bf16 v[8:11], v[156:159], v[232:235], v[8:11]
	s_cselect_b32 s42, s28, s10
	v_mfma_f32_16x16x32_bf16 v[52:55], v[160:163], v[194:197], v[52:55]
	s_add_i32 s31, 0, 0x14000
	v_mfma_f32_16x16x32_bf16 v[48:51], v[172:175], v[194:197], v[48:51]
	v_mfma_f32_16x16x32_bf16 v[36:39], v[160:163], v[210:213], v[36:39]
	v_mfma_f32_16x16x32_bf16 v[32:35], v[172:175], v[210:213], v[32:35]
	v_mfma_f32_16x16x32_bf16 v[20:23], v[160:163], v[220:223], v[20:23]
	v_mfma_f32_16x16x32_bf16 v[16:19], v[172:175], v[220:223], v[16:19]
	v_mfma_f32_16x16x32_bf16 v[4:7], v[160:163], v[228:231], v[4:7]
	v_mfma_f32_16x16x32_bf16 v[0:3], v[172:175], v[228:231], v[0:3]
	v_mfma_f32_16x16x32_bf16 v[52:55], v[168:171], v[206:209], v[52:55]
	v_mfma_f32_16x16x32_bf16 v[48:51], v[176:179], v[206:209], v[48:51]
	v_mfma_f32_16x16x32_bf16 v[36:39], v[168:171], v[214:217], v[36:39]
	v_mfma_f32_16x16x32_bf16 v[32:35], v[176:179], v[214:217], v[32:35]
	v_mfma_f32_16x16x32_bf16 v[20:23], v[168:171], v[224:227], v[20:23]
	v_mfma_f32_16x16x32_bf16 v[16:19], v[176:179], v[224:227], v[16:19]
	v_mfma_f32_16x16x32_bf16 v[4:7], v[168:171], v[232:235], v[4:7]
	v_mfma_f32_16x16x32_bf16 v[0:3], v[176:179], v[232:235], v[0:3]
	s_cmp_lg_u32 s98, 0
	s_cbranch_scc1 .Lskf_12_loop
	s_barrier

.LBB0_1040:
	s_barrier
	s_andn2_b64 vcc, exec, s[10:11]
	s_mov_b32 s60, s58
	s_mov_b32 s61, s59
	s_mov_b64 s[30:31], s[26:27]
	s_mov_b64 s[28:29], s[24:25]
	s_cbranch_vccz .LBB0_1075

.Llbb_9:
	s_add_i32 s30, s16, 2
	s_add_u32 s31, s28, 0x80
	s_addc_u32 s17, s29, 0
	s_add_i32 s62, 0, 0x10000
	s_cmp_eq_u32 s56, s16
	s_cselect_b32 s17, s25, s17
	s_cselect_b32 s16, s24, s31
	s_cselect_b32 s45, s27, s11
	s_cselect_b32 s44, s26, s10
	s_add_i32 s31, 0, 0x14000
	v_add_u32_e32 v140, s62, v199
	v_add_u32_e32 v166, s31, v199
	ds_read_b128 v[128:131], v140
	ds_read_b128 v[132:135], v140 offset:1024
	ds_read_b128 v[136:139], v140 offset:2048
	ds_read_b128 v[140:143], v140 offset:3072
	ds_read_b128 v[144:147], v166
	ds_read_b128 v[148:151], v166 offset:1024
	ds_read_b128 v[152:155], v166 offset:2048
	ds_read_b128 v[166:169], v166 offset:3072
	v_lshl_add_u64 v[178:179], s[28:29], 0, v[162:163]
	s_add_i32 m0, s37, 0xc000
	ds_read_b128 v[170:173], v206
	ds_read_b128 v[174:177], v206 offset:1024
	ds_read_b128 v[194:197], v206 offset:2048
	ds_read_b128 v[208:211], v206 offset:3072
	ds_read_b128 v[212:215], v206 offset:4096
	ds_read_b128 v[220:223], v206 offset:5120
	ds_read_b128 v[224:227], v206 offset:6144
	ds_read_b128 v[228:231], v206 offset:7168
	global_load_lds_dwordx4 v[178:179], off
	v_lshl_add_u64 v[178:179], s[28:29], 0, v[164:165]
	s_add_i32 m0, s37, 0xe000
	s_nop 0
	global_load_lds_dwordx4 v[178:179], off
	s_waitcnt vmcnt(8)
	s_waitcnt lgkmcnt(0)
	s_barrier
	s_waitcnt lgkmcnt(0)
	v_mfma_f32_16x16x32_bf16 v[120:123], v[128:131], v[170:173], 0
	v_mfma_f32_16x16x32_bf16 v[124:127], v[136:139], v[170:173], 0
	v_mfma_f32_16x16x32_bf16 v[108:111], v[128:131], v[194:197], 0
	v_mfma_f32_16x16x32_bf16 v[104:107], v[136:139], v[194:197], 0
	v_mfma_f32_16x16x32_bf16 v[92:95], v[128:131], v[212:215], 0
	v_mfma_f32_16x16x32_bf16 v[88:91], v[136:139], v[212:215], 0
	v_mfma_f32_16x16x32_bf16 v[76:79], v[128:131], v[224:227], 0
	v_mfma_f32_16x16x32_bf16 v[72:75], v[136:139], v[224:227], 0
	v_mfma_f32_16x16x32_bf16 v[120:123], v[132:135], v[174:177], v[120:123]
	v_mfma_f32_16x16x32_bf16 v[124:127], v[140:143], v[174:177], v[124:127]
	v_mfma_f32_16x16x32_bf16 v[108:111], v[132:135], v[208:211], v[108:111]
	v_mfma_f32_16x16x32_bf16 v[104:107], v[140:143], v[208:211], v[104:107]
	v_mfma_f32_16x16x32_bf16 v[92:95], v[132:135], v[220:223], v[92:95]
	v_mfma_f32_16x16x32_bf16 v[88:91], v[140:143], v[220:223], v[88:91]
	v_mfma_f32_16x16x32_bf16 v[76:79], v[132:135], v[228:231], v[76:79]
	v_mfma_f32_16x16x32_bf16 v[72:75], v[140:143], v[228:231], v[72:75]
	v_mfma_f32_16x16x32_bf16 v[116:119], v[144:147], v[170:173], 0
	v_mfma_f32_16x16x32_bf16 v[112:115], v[152:155], v[170:173], 0
	v_mfma_f32_16x16x32_bf16 v[100:103], v[144:147], v[194:197], 0
	v_mfma_f32_16x16x32_bf16 v[96:99], v[152:155], v[194:197], 0
	v_mfma_f32_16x16x32_bf16 v[84:87], v[144:147], v[212:215], 0
	v_mfma_f32_16x16x32_bf16 v[80:83], v[152:155], v[212:215], 0
	v_mfma_f32_16x16x32_bf16 v[68:71], v[144:147], v[224:227], 0
	v_mfma_f32_16x16x32_bf16 v[64:67], v[152:155], v[224:227], 0
	v_mfma_f32_16x16x32_bf16 v[116:119], v[148:151], v[174:177], v[116:119]
	v_mfma_f32_16x16x32_bf16 v[112:115], v[166:169], v[174:177], v[112:115]
	v_mfma_f32_16x16x32_bf16 v[100:103], v[148:151], v[208:211], v[100:103]
	v_mfma_f32_16x16x32_bf16 v[96:99], v[166:169], v[208:211], v[96:99]
	v_mfma_f32_16x16x32_bf16 v[84:87], v[148:151], v[220:223], v[84:87]
	v_mfma_f32_16x16x32_bf16 v[80:83], v[166:169], v[220:223], v[80:83]
	v_mfma_f32_16x16x32_bf16 v[68:71], v[148:151], v[228:231], v[68:71]
	v_mfma_f32_16x16x32_bf16 v[64:67], v[166:169], v[228:231], v[64:67]
	s_barrier
	s_add_i32 s62, s62, s36
	v_lshl_add_u64 v[178:179], s[44:45], 0, v[180:181]
	s_mov_b32 m0, s62
	ds_read_b128 v[170:173], v206 offset:16384
	ds_read_b128 v[174:177], v206 offset:17408
	ds_read_b128 v[194:197], v206 offset:18432
	ds_read_b128 v[208:211], v206 offset:19456
	ds_read_b128 v[212:215], v206 offset:20480
	ds_read_b128 v[220:223], v206 offset:21504
	ds_read_b128 v[224:227], v206 offset:22528
	ds_read_b128 v[228:231], v206 offset:23552
	global_load_lds_dwordx4 v[178:179], off
	s_add_i32 m0, s62, 0x2000
	v_lshl_add_u64 v[202:203], s[44:45], 0, v[156:157]
	s_add_u32 s44, s44, s6
	s_addc_u32 s45, s45, s7
	s_add_i32 s31, s31, s36
	global_load_lds_dwordx4 v[202:203], off
	v_lshl_add_u64 v[216:217], s[44:45], 0, v[180:181]
	s_mov_b32 m0, s31
	v_lshl_add_u64 v[232:233], s[44:45], 0, v[156:157]
	global_load_lds_dwordx4 v[216:217], off
	s_add_i32 m0, s31, 0x2000
	v_lshl_add_u64 v[234:235], s[16:17], 0, v[160:161]
	global_load_lds_dwordx4 v[232:233], off
	s_mov_b32 m0, s37
	v_lshl_add_u64 v[236:237], s[16:17], 0, v[158:159]
	global_load_lds_dwordx4 v[234:235], off
	s_mov_b32 m0, s38
	s_nop 0
	global_load_lds_dwordx4 v[236:237], off
	s_waitcnt vmcnt(8)
	s_waitcnt lgkmcnt(0)
	s_barrier
	s_waitcnt lgkmcnt(0)
	v_mfma_f32_16x16x32_bf16 v[60:63], v[128:131], v[170:173], 0
	v_mfma_f32_16x16x32_bf16 v[56:59], v[136:139], v[170:173], 0
	v_mfma_f32_16x16x32_bf16 v[44:47], v[128:131], v[194:197], 0
	v_mfma_f32_16x16x32_bf16 v[40:43], v[136:139], v[194:197], 0
	v_mfma_f32_16x16x32_bf16 v[28:31], v[128:131], v[212:215], 0
	v_mfma_f32_16x16x32_bf16 v[24:27], v[136:139], v[212:215], 0
	v_mfma_f32_16x16x32_bf16 v[12:15], v[128:131], v[224:227], 0
	v_mfma_f32_16x16x32_bf16 v[8:11], v[136:139], v[224:227], 0
	v_mfma_f32_16x16x32_bf16 v[60:63], v[132:135], v[174:177], v[60:63]
	v_mfma_f32_16x16x32_bf16 v[56:59], v[140:143], v[174:177], v[56:59]
	v_mfma_f32_16x16x32_bf16 v[44:47], v[132:135], v[208:211], v[44:47]
	v_mfma_f32_16x16x32_bf16 v[40:43], v[140:143], v[208:211], v[40:43]
	v_mfma_f32_16x16x32_bf16 v[28:31], v[132:135], v[220:223], v[28:31]
	v_mfma_f32_16x16x32_bf16 v[24:27], v[140:143], v[220:223], v[24:27]
	v_mfma_f32_16x16x32_bf16 v[12:15], v[132:135], v[228:231], v[12:15]
	v_mfma_f32_16x16x32_bf16 v[8:11], v[140:143], v[228:231], v[8:11]
	v_mfma_f32_16x16x32_bf16 v[52:55], v[144:147], v[170:173], 0
	v_mfma_f32_16x16x32_bf16 v[48:51], v[152:155], v[170:173], 0
	v_mfma_f32_16x16x32_bf16 v[36:39], v[144:147], v[194:197], 0
	v_mfma_f32_16x16x32_bf16 v[32:35], v[152:155], v[194:197], 0
	v_mfma_f32_16x16x32_bf16 v[20:23], v[144:147], v[212:215], 0
	v_mfma_f32_16x16x32_bf16 v[16:19], v[152:155], v[212:215], 0
	v_mfma_f32_16x16x32_bf16 v[4:7], v[144:147], v[224:227], 0
	v_mfma_f32_16x16x32_bf16 v[0:3], v[152:155], v[224:227], 0
	v_mfma_f32_16x16x32_bf16 v[52:55], v[148:151], v[174:177], v[52:55]
	v_mfma_f32_16x16x32_bf16 v[48:51], v[166:169], v[174:177], v[48:51]
	v_mfma_f32_16x16x32_bf16 v[36:39], v[148:151], v[208:211], v[36:39]
	v_mfma_f32_16x16x32_bf16 v[32:35], v[166:169], v[208:211], v[32:35]
	v_mfma_f32_16x16x32_bf16 v[20:23], v[148:151], v[220:223], v[20:23]
	v_mfma_f32_16x16x32_bf16 v[16:19], v[166:169], v[220:223], v[16:19]
	v_mfma_f32_16x16x32_bf16 v[4:7], v[148:151], v[228:231], v[4:7]
	v_mfma_f32_16x16x32_bf16 v[0:3], v[166:169], v[228:231], v[0:3]
	s_barrier
	s_add_i32 s31, 0, 0x18000
	s_add_i32 s44, 0, 0x1c000
	v_add_u32_e32 v140, s31, v199
	v_add_u32_e32 v166, s44, v199
	ds_read_b128 v[128:131], v140
	ds_read_b128 v[132:135], v140 offset:1024
	ds_read_b128 v[136:139], v140 offset:2048
	ds_read_b128 v[140:143], v140 offset:3072
	ds_read_b128 v[144:147], v166
	ds_read_b128 v[148:151], v166 offset:1024
	ds_read_b128 v[152:155], v166 offset:2048
	ds_read_b128 v[166:169], v166 offset:3072
	s_add_u32 s16, s16, s6
	s_addc_u32 s17, s17, s7
	s_mov_b32 m0, s39
	v_lshl_add_u64 v[238:239], s[16:17], 0, v[160:161]
	ds_read_b128 v[170:173], v206 offset:32768
	ds_read_b128 v[174:177], v206 offset:33792
	ds_read_b128 v[194:197], v206 offset:34816
	ds_read_b128 v[208:211], v206 offset:35840
	ds_read_b128 v[212:215], v206 offset:36864
	ds_read_b128 v[220:223], v206 offset:37888
	ds_read_b128 v[224:227], v206 offset:38912
	ds_read_b128 v[228:231], v206 offset:39936
	global_load_lds_dwordx4 v[238:239], off
	v_lshl_add_u64 v[238:239], s[16:17], 0, v[158:159]
	s_mov_b32 m0, s46
	s_nop 0
	global_load_lds_dwordx4 v[238:239], off
	s_waitcnt vmcnt(8)
	s_waitcnt lgkmcnt(0)
	s_barrier
	s_waitcnt lgkmcnt(0)
	v_mfma_f32_16x16x32_bf16 v[120:123], v[128:131], v[170:173], v[120:123]
	v_mfma_f32_16x16x32_bf16 v[124:127], v[136:139], v[170:173], v[124:127]
	v_mfma_f32_16x16x32_bf16 v[108:111], v[128:131], v[194:197], v[108:111]
	v_mfma_f32_16x16x32_bf16 v[104:107], v[136:139], v[194:197], v[104:107]
	v_mfma_f32_16x16x32_bf16 v[92:95], v[128:131], v[212:215], v[92:95]
	v_mfma_f32_16x16x32_bf16 v[88:91], v[136:139], v[212:215], v[88:91]
	v_mfma_f32_16x16x32_bf16 v[76:79], v[128:131], v[224:227], v[76:79]
	v_mfma_f32_16x16x32_bf16 v[72:75], v[136:139], v[224:227], v[72:75]
	v_mfma_f32_16x16x32_bf16 v[120:123], v[132:135], v[174:177], v[120:123]
	v_mfma_f32_16x16x32_bf16 v[124:127], v[140:143], v[174:177], v[124:127]
	v_mfma_f32_16x16x32_bf16 v[108:111], v[132:135], v[208:211], v[108:111]
	v_mfma_f32_16x16x32_bf16 v[104:107], v[140:143], v[208:211], v[104:107]
	v_mfma_f32_16x16x32_bf16 v[92:95], v[132:135], v[220:223], v[92:95]
	v_mfma_f32_16x16x32_bf16 v[88:91], v[140:143], v[220:223], v[88:91]
	v_mfma_f32_16x16x32_bf16 v[76:79], v[132:135], v[228:231], v[76:79]
	v_mfma_f32_16x16x32_bf16 v[72:75], v[140:143], v[228:231], v[72:75]
	v_mfma_f32_16x16x32_bf16 v[116:119], v[144:147], v[170:173], v[116:119]
	v_mfma_f32_16x16x32_bf16 v[112:115], v[152:155], v[170:173], v[112:115]
	v_mfma_f32_16x16x32_bf16 v[100:103], v[144:147], v[194:197], v[100:103]
	v_mfma_f32_16x16x32_bf16 v[96:99], v[152:155], v[194:197], v[96:99]
	v_mfma_f32_16x16x32_bf16 v[84:87], v[144:147], v[212:215], v[84:87]
	v_mfma_f32_16x16x32_bf16 v[80:83], v[152:155], v[212:215], v[80:83]
	v_mfma_f32_16x16x32_bf16 v[68:71], v[144:147], v[224:227], v[68:71]
	v_mfma_f32_16x16x32_bf16 v[64:67], v[152:155], v[224:227], v[64:67]
	v_mfma_f32_16x16x32_bf16 v[116:119], v[148:151], v[174:177], v[116:119]
	v_mfma_f32_16x16x32_bf16 v[112:115], v[166:169], v[174:177], v[112:115]
	v_mfma_f32_16x16x32_bf16 v[100:103], v[148:151], v[208:211], v[100:103]
	v_mfma_f32_16x16x32_bf16 v[96:99], v[166:169], v[208:211], v[96:99]
	v_mfma_f32_16x16x32_bf16 v[84:87], v[148:151], v[220:223], v[84:87]
	v_mfma_f32_16x16x32_bf16 v[80:83], v[166:169], v[220:223], v[80:83]
	v_mfma_f32_16x16x32_bf16 v[68:71], v[148:151], v[228:231], v[68:71]
	v_mfma_f32_16x16x32_bf16 v[64:67], v[166:169], v[228:231], v[64:67]
	s_barrier
	s_add_i32 s16, s31, s36
	v_lshl_add_u64 v[178:179], v[178:179], 0, s[12:13]
	s_mov_b32 m0, s16
	ds_read_b128 v[170:173], v206 offset:49152
	ds_read_b128 v[174:177], v206 offset:50176
	ds_read_b128 v[194:197], v206 offset:51200
	ds_read_b128 v[208:211], v206 offset:52224
	ds_read_b128 v[212:215], v206 offset:53248
	ds_read_b128 v[220:223], v206 offset:54272
	ds_read_b128 v[224:227], v206 offset:55296
	ds_read_b128 v[228:231], v206 offset:56320
	global_load_lds_dwordx4 v[178:179], off
	v_lshl_add_u64 v[178:179], v[202:203], 0, s[12:13]
	s_add_i32 m0, s16, 0x2000
	s_add_i32 s16, s44, s36
	global_load_lds_dwordx4 v[178:179], off
	v_lshl_add_u64 v[178:179], v[216:217], 0, s[12:13]
	s_mov_b32 m0, s16
	s_nop 0
	global_load_lds_dwordx4 v[178:179], off
	v_lshl_add_u64 v[178:179], v[232:233], 0, s[12:13]
	s_add_i32 m0, s16, 0x2000
	s_nop 0
	global_load_lds_dwordx4 v[178:179], off
	v_lshl_add_u64 v[178:179], v[234:235], 0, s[12:13]
	s_mov_b32 m0, s49
	s_nop 0
	global_load_lds_dwordx4 v[178:179], off
	v_lshl_add_u64 v[178:179], v[236:237], 0, s[12:13]
	s_mov_b32 m0, s52
	s_nop 0
	global_load_lds_dwordx4 v[178:179], off
	s_waitcnt vmcnt(8)
	s_waitcnt lgkmcnt(0)
	s_barrier
	s_waitcnt lgkmcnt(0)
	v_mfma_f32_16x16x32_bf16 v[60:63], v[128:131], v[170:173], v[60:63]
	s_add_u32 s28, s28, 0x100
	v_mfma_f32_16x16x32_bf16 v[56:59], v[136:139], v[170:173], v[56:59]
	s_addc_u32 s29, s29, 0
	v_mfma_f32_16x16x32_bf16 v[44:47], v[128:131], v[194:197], v[44:47]
	s_add_u32 s10, s10, 0x100
	v_mfma_f32_16x16x32_bf16 v[40:43], v[136:139], v[194:197], v[40:43]
	s_addc_u32 s11, s11, 0
	v_mfma_f32_16x16x32_bf16 v[28:31], v[128:131], v[212:215], v[28:31]
	s_mov_b32 s16, s30
	v_mfma_f32_16x16x32_bf16 v[24:27], v[136:139], v[212:215], v[24:27]
	s_cmp_ge_i32 s30, s48
	v_mfma_f32_16x16x32_bf16 v[12:15], v[128:131], v[224:227], v[12:15]
	s_cselect_b32 s99, 1, 0
	v_readfirstlane_b32 s98, v218
	s_bfe_u32 s98, s98, 0x10008
	s_and_b32 s98, s98, s99
	v_mfma_f32_16x16x32_bf16 v[8:11], v[136:139], v[224:227], v[8:11]
	s_add_i32 s30, s16, 2
	v_mfma_f32_16x16x32_bf16 v[60:63], v[132:135], v[174:177], v[60:63]
	s_add_u32 s31, s28, 0x80
	v_mfma_f32_16x16x32_bf16 v[56:59], v[140:143], v[174:177], v[56:59]
	s_addc_u32 s17, s29, 0
	v_mfma_f32_16x16x32_bf16 v[44:47], v[132:135], v[208:211], v[44:47]
	s_add_i32 s62, 0, 0x10000
	v_mfma_f32_16x16x32_bf16 v[40:43], v[140:143], v[208:211], v[40:43]
	s_cmp_eq_u32 s56, s16
	v_mfma_f32_16x16x32_bf16 v[28:31], v[132:135], v[220:223], v[28:31]
	s_cselect_b32 s17, s25, s17
	v_mfma_f32_16x16x32_bf16 v[24:27], v[140:143], v[220:223], v[24:27]
	s_cselect_b32 s16, s24, s31
	v_mfma_f32_16x16x32_bf16 v[12:15], v[132:135], v[228:231], v[12:15]
	s_cselect_b32 s45, s27, s11
	v_mfma_f32_16x16x32_bf16 v[8:11], v[140:143], v[228:231], v[8:11]
	s_cselect_b32 s44, s26, s10
	v_mfma_f32_16x16x32_bf16 v[52:55], v[144:147], v[170:173], v[52:55]
	s_add_i32 s31, 0, 0x14000
	v_mfma_f32_16x16x32_bf16 v[48:51], v[152:155], v[170:173], v[48:51]
	v_mfma_f32_16x16x32_bf16 v[36:39], v[144:147], v[194:197], v[36:39]
	v_mfma_f32_16x16x32_bf16 v[32:35], v[152:155], v[194:197], v[32:35]
	v_mfma_f32_16x16x32_bf16 v[20:23], v[144:147], v[212:215], v[20:23]
	v_mfma_f32_16x16x32_bf16 v[16:19], v[152:155], v[212:215], v[16:19]
	v_mfma_f32_16x16x32_bf16 v[4:7], v[144:147], v[224:227], v[4:7]
	v_mfma_f32_16x16x32_bf16 v[0:3], v[152:155], v[224:227], v[0:3]
	v_mfma_f32_16x16x32_bf16 v[52:55], v[148:151], v[174:177], v[52:55]
	v_mfma_f32_16x16x32_bf16 v[48:51], v[166:169], v[174:177], v[48:51]
	v_mfma_f32_16x16x32_bf16 v[36:39], v[148:151], v[208:211], v[36:39]
	v_mfma_f32_16x16x32_bf16 v[32:35], v[166:169], v[208:211], v[32:35]
	v_mfma_f32_16x16x32_bf16 v[20:23], v[148:151], v[220:223], v[20:23]
	v_mfma_f32_16x16x32_bf16 v[16:19], v[166:169], v[220:223], v[16:19]
	v_mfma_f32_16x16x32_bf16 v[4:7], v[148:151], v[228:231], v[4:7]
	v_mfma_f32_16x16x32_bf16 v[0:3], v[166:169], v[228:231], v[0:3]
	s_cmp_lg_u32 s98, 0
	s_cbranch_scc1 .Lskf_13_peel
	s_barrier

.LBB0_1053:
	v_add_u32_e32 v140, s62, v199
	v_add_u32_e32 v166, s31, v199
	ds_read_b128 v[128:131], v140
	ds_read_b128 v[132:135], v140 offset:1024
	ds_read_b128 v[136:139], v140 offset:2048
	ds_read_b128 v[140:143], v140 offset:3072
	ds_read_b128 v[144:147], v166
	ds_read_b128 v[148:151], v166 offset:1024
	ds_read_b128 v[152:155], v166 offset:2048
	ds_read_b128 v[166:169], v166 offset:3072
	v_lshl_add_u64 v[178:179], s[28:29], 0, v[162:163]
	s_add_i32 m0, s37, 0xc000
	ds_read_b128 v[170:173], v206
	ds_read_b128 v[174:177], v206 offset:1024
	ds_read_b128 v[194:197], v206 offset:2048
	ds_read_b128 v[208:211], v206 offset:3072
	ds_read_b128 v[212:215], v206 offset:4096
	ds_read_b128 v[220:223], v206 offset:5120
	ds_read_b128 v[224:227], v206 offset:6144
	ds_read_b128 v[228:231], v206 offset:7168
	global_load_lds_dwordx4 v[178:179], off
	v_lshl_add_u64 v[178:179], s[28:29], 0, v[164:165]
	s_add_i32 m0, s37, 0xe000
	s_nop 0
	global_load_lds_dwordx4 v[178:179], off
	s_waitcnt vmcnt(8)
	s_waitcnt lgkmcnt(0)
	s_barrier
	s_waitcnt lgkmcnt(0)
	v_mfma_f32_16x16x32_bf16 v[120:123], v[128:131], v[170:173], v[120:123]
	v_mfma_f32_16x16x32_bf16 v[124:127], v[136:139], v[170:173], v[124:127]
	v_mfma_f32_16x16x32_bf16 v[108:111], v[128:131], v[194:197], v[108:111]
	v_mfma_f32_16x16x32_bf16 v[104:107], v[136:139], v[194:197], v[104:107]
	v_mfma_f32_16x16x32_bf16 v[92:95], v[128:131], v[212:215], v[92:95]
	v_mfma_f32_16x16x32_bf16 v[88:91], v[136:139], v[212:215], v[88:91]
	v_mfma_f32_16x16x32_bf16 v[76:79], v[128:131], v[224:227], v[76:79]
	v_mfma_f32_16x16x32_bf16 v[72:75], v[136:139], v[224:227], v[72:75]
	v_mfma_f32_16x16x32_bf16 v[120:123], v[132:135], v[174:177], v[120:123]
	v_mfma_f32_16x16x32_bf16 v[124:127], v[140:143], v[174:177], v[124:127]
	v_mfma_f32_16x16x32_bf16 v[108:111], v[132:135], v[208:211], v[108:111]
	v_mfma_f32_16x16x32_bf16 v[104:107], v[140:143], v[208:211], v[104:107]
	v_mfma_f32_16x16x32_bf16 v[92:95], v[132:135], v[220:223], v[92:95]
	v_mfma_f32_16x16x32_bf16 v[88:91], v[140:143], v[220:223], v[88:91]
	v_mfma_f32_16x16x32_bf16 v[76:79], v[132:135], v[228:231], v[76:79]
	v_mfma_f32_16x16x32_bf16 v[72:75], v[140:143], v[228:231], v[72:75]
	v_mfma_f32_16x16x32_bf16 v[116:119], v[144:147], v[170:173], v[116:119]
	v_mfma_f32_16x16x32_bf16 v[112:115], v[152:155], v[170:173], v[112:115]
	v_mfma_f32_16x16x32_bf16 v[100:103], v[144:147], v[194:197], v[100:103]
	v_mfma_f32_16x16x32_bf16 v[96:99], v[152:155], v[194:197], v[96:99]
	v_mfma_f32_16x16x32_bf16 v[84:87], v[144:147], v[212:215], v[84:87]
	v_mfma_f32_16x16x32_bf16 v[80:83], v[152:155], v[212:215], v[80:83]
	v_mfma_f32_16x16x32_bf16 v[68:71], v[144:147], v[224:227], v[68:71]
	v_mfma_f32_16x16x32_bf16 v[64:67], v[152:155], v[224:227], v[64:67]
	v_mfma_f32_16x16x32_bf16 v[116:119], v[148:151], v[174:177], v[116:119]
	v_mfma_f32_16x16x32_bf16 v[112:115], v[166:169], v[174:177], v[112:115]
	v_mfma_f32_16x16x32_bf16 v[100:103], v[148:151], v[208:211], v[100:103]
	v_mfma_f32_16x16x32_bf16 v[96:99], v[166:169], v[208:211], v[96:99]
	v_mfma_f32_16x16x32_bf16 v[84:87], v[148:151], v[220:223], v[84:87]
	v_mfma_f32_16x16x32_bf16 v[80:83], v[166:169], v[220:223], v[80:83]
	v_mfma_f32_16x16x32_bf16 v[68:71], v[148:151], v[228:231], v[68:71]
	v_mfma_f32_16x16x32_bf16 v[64:67], v[166:169], v[228:231], v[64:67]
	s_barrier
	s_add_i32 s62, s62, s36
	v_lshl_add_u64 v[178:179], s[44:45], 0, v[180:181]
	s_mov_b32 m0, s62
	ds_read_b128 v[170:173], v206 offset:16384
	ds_read_b128 v[174:177], v206 offset:17408
	ds_read_b128 v[194:197], v206 offset:18432
	ds_read_b128 v[208:211], v206 offset:19456
	ds_read_b128 v[212:215], v206 offset:20480
	ds_read_b128 v[220:223], v206 offset:21504
	ds_read_b128 v[224:227], v206 offset:22528
	ds_read_b128 v[228:231], v206 offset:23552
	global_load_lds_dwordx4 v[178:179], off
	s_add_i32 m0, s62, 0x2000
	v_lshl_add_u64 v[202:203], s[44:45], 0, v[156:157]
	s_add_u32 s44, s44, s6
	s_addc_u32 s45, s45, s7
	s_add_i32 s31, s31, s36
	global_load_lds_dwordx4 v[202:203], off
	v_lshl_add_u64 v[216:217], s[44:45], 0, v[180:181]
	s_mov_b32 m0, s31
	v_lshl_add_u64 v[232:233], s[44:45], 0, v[156:157]
	global_load_lds_dwordx4 v[216:217], off
	s_add_i32 m0, s31, 0x2000
	v_lshl_add_u64 v[234:235], s[16:17], 0, v[160:161]
	global_load_lds_dwordx4 v[232:233], off
	s_mov_b32 m0, s37
	v_lshl_add_u64 v[236:237], s[16:17], 0, v[158:159]
	global_load_lds_dwordx4 v[234:235], off
	s_mov_b32 m0, s38
	s_nop 0
	global_load_lds_dwordx4 v[236:237], off
	s_waitcnt vmcnt(8)
	s_waitcnt lgkmcnt(0)
	s_barrier
	s_waitcnt lgkmcnt(0)
	v_mfma_f32_16x16x32_bf16 v[60:63], v[128:131], v[170:173], v[60:63]
	v_mfma_f32_16x16x32_bf16 v[56:59], v[136:139], v[170:173], v[56:59]
	v_mfma_f32_16x16x32_bf16 v[44:47], v[128:131], v[194:197], v[44:47]
	v_mfma_f32_16x16x32_bf16 v[40:43], v[136:139], v[194:197], v[40:43]
	v_mfma_f32_16x16x32_bf16 v[28:31], v[128:131], v[212:215], v[28:31]
	v_mfma_f32_16x16x32_bf16 v[24:27], v[136:139], v[212:215], v[24:27]
	v_mfma_f32_16x16x32_bf16 v[12:15], v[128:131], v[224:227], v[12:15]
	v_mfma_f32_16x16x32_bf16 v[8:11], v[136:139], v[224:227], v[8:11]
	v_mfma_f32_16x16x32_bf16 v[60:63], v[132:135], v[174:177], v[60:63]
	v_mfma_f32_16x16x32_bf16 v[56:59], v[140:143], v[174:177], v[56:59]
	v_mfma_f32_16x16x32_bf16 v[44:47], v[132:135], v[208:211], v[44:47]
	v_mfma_f32_16x16x32_bf16 v[40:43], v[140:143], v[208:211], v[40:43]
	v_mfma_f32_16x16x32_bf16 v[28:31], v[132:135], v[220:223], v[28:31]
	v_mfma_f32_16x16x32_bf16 v[24:27], v[140:143], v[220:223], v[24:27]
	v_mfma_f32_16x16x32_bf16 v[12:15], v[132:135], v[228:231], v[12:15]
	v_mfma_f32_16x16x32_bf16 v[8:11], v[140:143], v[228:231], v[8:11]
	v_mfma_f32_16x16x32_bf16 v[52:55], v[144:147], v[170:173], v[52:55]
	v_mfma_f32_16x16x32_bf16 v[48:51], v[152:155], v[170:173], v[48:51]
	v_mfma_f32_16x16x32_bf16 v[36:39], v[144:147], v[194:197], v[36:39]
	v_mfma_f32_16x16x32_bf16 v[32:35], v[152:155], v[194:197], v[32:35]
	v_mfma_f32_16x16x32_bf16 v[20:23], v[144:147], v[212:215], v[20:23]
	v_mfma_f32_16x16x32_bf16 v[16:19], v[152:155], v[212:215], v[16:19]
	v_mfma_f32_16x16x32_bf16 v[4:7], v[144:147], v[224:227], v[4:7]
	v_mfma_f32_16x16x32_bf16 v[0:3], v[152:155], v[224:227], v[0:3]
	v_mfma_f32_16x16x32_bf16 v[52:55], v[148:151], v[174:177], v[52:55]
	v_mfma_f32_16x16x32_bf16 v[48:51], v[166:169], v[174:177], v[48:51]
	v_mfma_f32_16x16x32_bf16 v[36:39], v[148:151], v[208:211], v[36:39]
	v_mfma_f32_16x16x32_bf16 v[32:35], v[166:169], v[208:211], v[32:35]
	v_mfma_f32_16x16x32_bf16 v[20:23], v[148:151], v[220:223], v[20:23]
	v_mfma_f32_16x16x32_bf16 v[16:19], v[166:169], v[220:223], v[16:19]
	v_mfma_f32_16x16x32_bf16 v[4:7], v[148:151], v[228:231], v[4:7]
	v_mfma_f32_16x16x32_bf16 v[0:3], v[166:169], v[228:231], v[0:3]
	s_barrier
	s_add_i32 s31, 0, 0x18000
	s_add_i32 s44, 0, 0x1c000
	v_add_u32_e32 v140, s31, v199
	v_add_u32_e32 v166, s44, v199
	ds_read_b128 v[128:131], v140
	ds_read_b128 v[132:135], v140 offset:1024
	ds_read_b128 v[136:139], v140 offset:2048
	ds_read_b128 v[140:143], v140 offset:3072
	ds_read_b128 v[144:147], v166
	ds_read_b128 v[148:151], v166 offset:1024
	ds_read_b128 v[152:155], v166 offset:2048
	ds_read_b128 v[166:169], v166 offset:3072
	s_add_u32 s16, s16, s6
	s_addc_u32 s17, s17, s7
	s_mov_b32 m0, s39
	v_lshl_add_u64 v[238:239], s[16:17], 0, v[160:161]
	ds_read_b128 v[170:173], v206 offset:32768
	ds_read_b128 v[174:177], v206 offset:33792
	ds_read_b128 v[194:197], v206 offset:34816
	ds_read_b128 v[208:211], v206 offset:35840
	ds_read_b128 v[212:215], v206 offset:36864
	ds_read_b128 v[220:223], v206 offset:37888
	ds_read_b128 v[224:227], v206 offset:38912
	ds_read_b128 v[228:231], v206 offset:39936
	global_load_lds_dwordx4 v[238:239], off
	v_lshl_add_u64 v[238:239], s[16:17], 0, v[158:159]
	s_mov_b32 m0, s46
	s_nop 0
	global_load_lds_dwordx4 v[238:239], off
	s_waitcnt vmcnt(8)
	s_waitcnt lgkmcnt(0)
	s_barrier
	s_waitcnt lgkmcnt(0)
	v_mfma_f32_16x16x32_bf16 v[120:123], v[128:131], v[170:173], v[120:123]
	v_mfma_f32_16x16x32_bf16 v[124:127], v[136:139], v[170:173], v[124:127]
	v_mfma_f32_16x16x32_bf16 v[108:111], v[128:131], v[194:197], v[108:111]
	v_mfma_f32_16x16x32_bf16 v[104:107], v[136:139], v[194:197], v[104:107]
	v_mfma_f32_16x16x32_bf16 v[92:95], v[128:131], v[212:215], v[92:95]
	v_mfma_f32_16x16x32_bf16 v[88:91], v[136:139], v[212:215], v[88:91]
	v_mfma_f32_16x16x32_bf16 v[76:79], v[128:131], v[224:227], v[76:79]
	v_mfma_f32_16x16x32_bf16 v[72:75], v[136:139], v[224:227], v[72:75]
	v_mfma_f32_16x16x32_bf16 v[120:123], v[132:135], v[174:177], v[120:123]
	v_mfma_f32_16x16x32_bf16 v[124:127], v[140:143], v[174:177], v[124:127]
	v_mfma_f32_16x16x32_bf16 v[108:111], v[132:135], v[208:211], v[108:111]
	v_mfma_f32_16x16x32_bf16 v[104:107], v[140:143], v[208:211], v[104:107]
	v_mfma_f32_16x16x32_bf16 v[92:95], v[132:135], v[220:223], v[92:95]
	v_mfma_f32_16x16x32_bf16 v[88:91], v[140:143], v[220:223], v[88:91]
	v_mfma_f32_16x16x32_bf16 v[76:79], v[132:135], v[228:231], v[76:79]
	v_mfma_f32_16x16x32_bf16 v[72:75], v[140:143], v[228:231], v[72:75]
	v_mfma_f32_16x16x32_bf16 v[116:119], v[144:147], v[170:173], v[116:119]
	v_mfma_f32_16x16x32_bf16 v[112:115], v[152:155], v[170:173], v[112:115]
	v_mfma_f32_16x16x32_bf16 v[100:103], v[144:147], v[194:197], v[100:103]
	v_mfma_f32_16x16x32_bf16 v[96:99], v[152:155], v[194:197], v[96:99]
	v_mfma_f32_16x16x32_bf16 v[84:87], v[144:147], v[212:215], v[84:87]
	v_mfma_f32_16x16x32_bf16 v[80:83], v[152:155], v[212:215], v[80:83]
	v_mfma_f32_16x16x32_bf16 v[68:71], v[144:147], v[224:227], v[68:71]
	v_mfma_f32_16x16x32_bf16 v[64:67], v[152:155], v[224:227], v[64:67]
	v_mfma_f32_16x16x32_bf16 v[116:119], v[148:151], v[174:177], v[116:119]
	v_mfma_f32_16x16x32_bf16 v[112:115], v[166:169], v[174:177], v[112:115]
	v_mfma_f32_16x16x32_bf16 v[100:103], v[148:151], v[208:211], v[100:103]
	v_mfma_f32_16x16x32_bf16 v[96:99], v[166:169], v[208:211], v[96:99]
	v_mfma_f32_16x16x32_bf16 v[84:87], v[148:151], v[220:223], v[84:87]
	v_mfma_f32_16x16x32_bf16 v[80:83], v[166:169], v[220:223], v[80:83]
	v_mfma_f32_16x16x32_bf16 v[68:71], v[148:151], v[228:231], v[68:71]
	v_mfma_f32_16x16x32_bf16 v[64:67], v[166:169], v[228:231], v[64:67]
	s_barrier
	s_add_i32 s16, s31, s36
	v_lshl_add_u64 v[178:179], v[178:179], 0, s[12:13]
	s_mov_b32 m0, s16
	ds_read_b128 v[170:173], v206 offset:49152
	ds_read_b128 v[174:177], v206 offset:50176
	ds_read_b128 v[194:197], v206 offset:51200
	ds_read_b128 v[208:211], v206 offset:52224
	ds_read_b128 v[212:215], v206 offset:53248
	ds_read_b128 v[220:223], v206 offset:54272
	ds_read_b128 v[224:227], v206 offset:55296
	ds_read_b128 v[228:231], v206 offset:56320
	global_load_lds_dwordx4 v[178:179], off
	v_lshl_add_u64 v[178:179], v[202:203], 0, s[12:13]
	s_add_i32 m0, s16, 0x2000
	s_add_i32 s16, s44, s36
	global_load_lds_dwordx4 v[178:179], off
	v_lshl_add_u64 v[178:179], v[216:217], 0, s[12:13]
	s_mov_b32 m0, s16
	s_nop 0
	global_load_lds_dwordx4 v[178:179], off
	v_lshl_add_u64 v[178:179], v[232:233], 0, s[12:13]
	s_add_i32 m0, s16, 0x2000
	s_nop 0
	global_load_lds_dwordx4 v[178:179], off
	v_lshl_add_u64 v[178:179], v[234:235], 0, s[12:13]
	s_mov_b32 m0, s49
	s_nop 0
	global_load_lds_dwordx4 v[178:179], off
	v_lshl_add_u64 v[178:179], v[236:237], 0, s[12:13]
	s_mov_b32 m0, s52
	s_nop 0
	global_load_lds_dwordx4 v[178:179], off
	s_waitcnt vmcnt(8)
	s_waitcnt lgkmcnt(0)
	s_barrier
	s_waitcnt lgkmcnt(0)
	v_mfma_f32_16x16x32_bf16 v[60:63], v[128:131], v[170:173], v[60:63]
	s_add_u32 s28, s28, 0x100
	v_mfma_f32_16x16x32_bf16 v[56:59], v[136:139], v[170:173], v[56:59]
	s_addc_u32 s29, s29, 0
	v_mfma_f32_16x16x32_bf16 v[44:47], v[128:131], v[194:197], v[44:47]
	s_add_u32 s10, s10, 0x100
	v_mfma_f32_16x16x32_bf16 v[40:43], v[136:139], v[194:197], v[40:43]
	s_addc_u32 s11, s11, 0
	v_mfma_f32_16x16x32_bf16 v[28:31], v[128:131], v[212:215], v[28:31]
	s_mov_b32 s16, s30
	v_mfma_f32_16x16x32_bf16 v[24:27], v[136:139], v[212:215], v[24:27]
	s_cmp_ge_i32 s30, s48
	v_mfma_f32_16x16x32_bf16 v[12:15], v[128:131], v[224:227], v[12:15]
	s_cselect_b32 s99, 1, 0
	v_readfirstlane_b32 s98, v218
	s_bfe_u32 s98, s98, 0x10008
	s_and_b32 s98, s98, s99
	v_mfma_f32_16x16x32_bf16 v[8:11], v[136:139], v[224:227], v[8:11]
	s_add_i32 s30, s16, 2
	v_mfma_f32_16x16x32_bf16 v[60:63], v[132:135], v[174:177], v[60:63]
	s_add_u32 s31, s28, 0x80
	v_mfma_f32_16x16x32_bf16 v[56:59], v[140:143], v[174:177], v[56:59]
	s_addc_u32 s17, s29, 0
	v_mfma_f32_16x16x32_bf16 v[44:47], v[132:135], v[208:211], v[44:47]
	s_add_i32 s62, 0, 0x10000
	v_mfma_f32_16x16x32_bf16 v[40:43], v[140:143], v[208:211], v[40:43]
	s_cmp_eq_u32 s56, s16
	v_mfma_f32_16x16x32_bf16 v[28:31], v[132:135], v[220:223], v[28:31]
	s_cselect_b32 s17, s25, s17
	v_mfma_f32_16x16x32_bf16 v[24:27], v[140:143], v[220:223], v[24:27]
	s_cselect_b32 s16, s24, s31
	v_mfma_f32_16x16x32_bf16 v[12:15], v[132:135], v[228:231], v[12:15]
	s_cselect_b32 s45, s27, s11
	v_mfma_f32_16x16x32_bf16 v[8:11], v[140:143], v[228:231], v[8:11]
	s_cselect_b32 s44, s26, s10
	v_mfma_f32_16x16x32_bf16 v[52:55], v[144:147], v[170:173], v[52:55]
	s_add_i32 s31, 0, 0x14000
	v_mfma_f32_16x16x32_bf16 v[48:51], v[152:155], v[170:173], v[48:51]
	v_mfma_f32_16x16x32_bf16 v[36:39], v[144:147], v[194:197], v[36:39]
	v_mfma_f32_16x16x32_bf16 v[32:35], v[152:155], v[194:197], v[32:35]
	v_mfma_f32_16x16x32_bf16 v[20:23], v[144:147], v[212:215], v[20:23]
	v_mfma_f32_16x16x32_bf16 v[16:19], v[152:155], v[212:215], v[16:19]
	v_mfma_f32_16x16x32_bf16 v[4:7], v[144:147], v[224:227], v[4:7]
	v_mfma_f32_16x16x32_bf16 v[0:3], v[152:155], v[224:227], v[0:3]
	v_mfma_f32_16x16x32_bf16 v[52:55], v[148:151], v[174:177], v[52:55]
	v_mfma_f32_16x16x32_bf16 v[48:51], v[166:169], v[174:177], v[48:51]
	v_mfma_f32_16x16x32_bf16 v[36:39], v[148:151], v[208:211], v[36:39]
	v_mfma_f32_16x16x32_bf16 v[32:35], v[166:169], v[208:211], v[32:35]
	v_mfma_f32_16x16x32_bf16 v[20:23], v[148:151], v[220:223], v[20:23]
	v_mfma_f32_16x16x32_bf16 v[16:19], v[166:169], v[220:223], v[16:19]
	v_mfma_f32_16x16x32_bf16 v[4:7], v[148:151], v[228:231], v[4:7]
	v_mfma_f32_16x16x32_bf16 v[0:3], v[166:169], v[228:231], v[0:3]
	s_cmp_lg_u32 s98, 0
	s_cbranch_scc1 .Lskf_13_loop
	s_barrier

.Llbb_10:
	s_add_i32 s30, s16, 2
	s_add_u32 s31, s28, 0x80
	s_addc_u32 s17, s29, 0
	s_add_i32 s63, 0, 0x10000
	s_cmp_eq_u32 s56, s16
	s_cselect_b32 s17, s25, s17
	s_cselect_b32 s16, s24, s31
	s_cselect_b32 s45, s27, s11
	s_cselect_b32 s44, s26, s10
	s_add_i32 s31, 0, 0x14000
	v_add_u32_e32 v156, s63, v151
	v_add_u32_e32 v172, s31, v151
	ds_read_b128 v[128:131], v156
	ds_read_b128 v[142:145], v156 offset:1024
	ds_read_b128 v[146:149], v156 offset:2048
	ds_read_b128 v[156:159], v156 offset:3072
	ds_read_b128 v[160:163], v172
	ds_read_b128 v[164:167], v172 offset:1024
	ds_read_b128 v[168:171], v172 offset:2048
	ds_read_b128 v[172:175], v172 offset:3072
	v_lshl_add_u64 v[198:199], s[28:29], 0, v[138:139]
	s_add_i32 m0, s37, 0xc000
	ds_read_b128 v[176:179], v155
	ds_read_b128 v[194:197], v155 offset:1024
	ds_read_b128 v[206:209], v155 offset:2048
	ds_read_b128 v[210:213], v155 offset:3072
	ds_read_b128 v[214:217], v155 offset:4096
	ds_read_b128 v[220:223], v155 offset:5120
	ds_read_b128 v[224:227], v155 offset:6144
	ds_read_b128 v[228:231], v155 offset:7168
	global_load_lds_dwordx4 v[198:199], off
	v_lshl_add_u64 v[198:199], s[28:29], 0, v[140:141]
	s_add_i32 m0, s37, 0xe000
	s_nop 0
	global_load_lds_dwordx4 v[198:199], off
	s_waitcnt vmcnt(8)
	s_waitcnt lgkmcnt(0)
	s_barrier
	s_waitcnt lgkmcnt(0)
	v_mfma_f32_16x16x32_bf16 v[120:123], v[128:131], v[176:179], 0
	v_mfma_f32_16x16x32_bf16 v[116:119], v[146:149], v[176:179], 0
	v_mfma_f32_16x16x32_bf16 v[108:111], v[128:131], v[206:209], 0
	v_mfma_f32_16x16x32_bf16 v[100:103], v[146:149], v[206:209], 0
	v_mfma_f32_16x16x32_bf16 v[92:95], v[128:131], v[214:217], 0
	v_mfma_f32_16x16x32_bf16 v[84:87], v[146:149], v[214:217], 0
	v_mfma_f32_16x16x32_bf16 v[76:79], v[128:131], v[224:227], 0
	v_mfma_f32_16x16x32_bf16 v[68:71], v[146:149], v[224:227], 0
	v_mfma_f32_16x16x32_bf16 v[120:123], v[142:145], v[194:197], v[120:123]
	v_mfma_f32_16x16x32_bf16 v[116:119], v[156:159], v[194:197], v[116:119]
	v_mfma_f32_16x16x32_bf16 v[108:111], v[142:145], v[210:213], v[108:111]
	v_mfma_f32_16x16x32_bf16 v[100:103], v[156:159], v[210:213], v[100:103]
	v_mfma_f32_16x16x32_bf16 v[92:95], v[142:145], v[220:223], v[92:95]
	v_mfma_f32_16x16x32_bf16 v[84:87], v[156:159], v[220:223], v[84:87]
	v_mfma_f32_16x16x32_bf16 v[76:79], v[142:145], v[228:231], v[76:79]
	v_mfma_f32_16x16x32_bf16 v[68:71], v[156:159], v[228:231], v[68:71]
	v_mfma_f32_16x16x32_bf16 v[124:127], v[160:163], v[176:179], 0
	v_mfma_f32_16x16x32_bf16 v[112:115], v[168:171], v[176:179], 0
	v_mfma_f32_16x16x32_bf16 v[104:107], v[160:163], v[206:209], 0
	v_mfma_f32_16x16x32_bf16 v[96:99], v[168:171], v[206:209], 0
	v_mfma_f32_16x16x32_bf16 v[88:91], v[160:163], v[214:217], 0
	v_mfma_f32_16x16x32_bf16 v[80:83], v[168:171], v[214:217], 0
	v_mfma_f32_16x16x32_bf16 v[72:75], v[160:163], v[224:227], 0
	v_mfma_f32_16x16x32_bf16 v[64:67], v[168:171], v[224:227], 0
	v_mfma_f32_16x16x32_bf16 v[124:127], v[164:167], v[194:197], v[124:127]
	v_mfma_f32_16x16x32_bf16 v[112:115], v[172:175], v[194:197], v[112:115]
	v_mfma_f32_16x16x32_bf16 v[104:107], v[164:167], v[210:213], v[104:107]
	v_mfma_f32_16x16x32_bf16 v[96:99], v[172:175], v[210:213], v[96:99]
	v_mfma_f32_16x16x32_bf16 v[88:91], v[164:167], v[220:223], v[88:91]
	v_mfma_f32_16x16x32_bf16 v[80:83], v[172:175], v[220:223], v[80:83]
	v_mfma_f32_16x16x32_bf16 v[72:75], v[164:167], v[228:231], v[72:75]
	v_mfma_f32_16x16x32_bf16 v[64:67], v[172:175], v[228:231], v[64:67]
	s_barrier
	s_add_i32 s63, s63, s36
	v_lshl_add_u64 v[198:199], s[44:45], 0, v[180:181]
	s_mov_b32 m0, s63
	ds_read_b128 v[176:179], v155 offset:16384
	ds_read_b128 v[194:197], v155 offset:17408
	ds_read_b128 v[206:209], v155 offset:18432
	ds_read_b128 v[210:213], v155 offset:19456
	ds_read_b128 v[214:217], v155 offset:20480
	ds_read_b128 v[220:223], v155 offset:21504
	ds_read_b128 v[224:227], v155 offset:22528
	ds_read_b128 v[228:231], v155 offset:23552
	global_load_lds_dwordx4 v[198:199], off
	s_add_i32 m0, s63, 0x2000
	v_lshl_add_u64 v[202:203], s[44:45], 0, v[132:133]
	s_add_u32 s44, s44, s6
	s_addc_u32 s45, s45, s7
	s_add_i32 s31, s31, s36
	global_load_lds_dwordx4 v[202:203], off
	v_lshl_add_u64 v[232:233], s[44:45], 0, v[180:181]
	s_mov_b32 m0, s31
	v_lshl_add_u64 v[234:235], s[44:45], 0, v[132:133]
	global_load_lds_dwordx4 v[232:233], off
	s_add_i32 m0, s31, 0x2000
	v_lshl_add_u64 v[236:237], s[16:17], 0, v[136:137]
	global_load_lds_dwordx4 v[234:235], off
	s_mov_b32 m0, s37
	v_lshl_add_u64 v[238:239], s[16:17], 0, v[134:135]
	global_load_lds_dwordx4 v[236:237], off
	s_mov_b32 m0, s38
	s_nop 0
	global_load_lds_dwordx4 v[238:239], off
	s_waitcnt vmcnt(8)
	s_waitcnt lgkmcnt(0)
	s_barrier
	s_waitcnt lgkmcnt(0)
	v_mfma_f32_16x16x32_bf16 v[60:63], v[128:131], v[176:179], 0
	v_mfma_f32_16x16x32_bf16 v[52:55], v[146:149], v[176:179], 0
	v_mfma_f32_16x16x32_bf16 v[44:47], v[128:131], v[206:209], 0
	v_mfma_f32_16x16x32_bf16 v[36:39], v[146:149], v[206:209], 0
	v_mfma_f32_16x16x32_bf16 v[28:31], v[128:131], v[214:217], 0
	v_mfma_f32_16x16x32_bf16 v[20:23], v[146:149], v[214:217], 0
	v_mfma_f32_16x16x32_bf16 v[12:15], v[128:131], v[224:227], 0
	v_mfma_f32_16x16x32_bf16 v[4:7], v[146:149], v[224:227], 0
	v_mfma_f32_16x16x32_bf16 v[60:63], v[142:145], v[194:197], v[60:63]
	v_mfma_f32_16x16x32_bf16 v[52:55], v[156:159], v[194:197], v[52:55]
	v_mfma_f32_16x16x32_bf16 v[44:47], v[142:145], v[210:213], v[44:47]
	v_mfma_f32_16x16x32_bf16 v[36:39], v[156:159], v[210:213], v[36:39]
	v_mfma_f32_16x16x32_bf16 v[28:31], v[142:145], v[220:223], v[28:31]
	v_mfma_f32_16x16x32_bf16 v[20:23], v[156:159], v[220:223], v[20:23]
	v_mfma_f32_16x16x32_bf16 v[12:15], v[142:145], v[228:231], v[12:15]
	v_mfma_f32_16x16x32_bf16 v[4:7], v[156:159], v[228:231], v[4:7]
	v_mfma_f32_16x16x32_bf16 v[56:59], v[160:163], v[176:179], 0
	v_mfma_f32_16x16x32_bf16 v[48:51], v[168:171], v[176:179], 0
	v_mfma_f32_16x16x32_bf16 v[40:43], v[160:163], v[206:209], 0
	v_mfma_f32_16x16x32_bf16 v[32:35], v[168:171], v[206:209], 0
	v_mfma_f32_16x16x32_bf16 v[24:27], v[160:163], v[214:217], 0
	v_mfma_f32_16x16x32_bf16 v[16:19], v[168:171], v[214:217], 0
	v_mfma_f32_16x16x32_bf16 v[8:11], v[160:163], v[224:227], 0
	v_mfma_f32_16x16x32_bf16 v[0:3], v[168:171], v[224:227], 0
	v_mfma_f32_16x16x32_bf16 v[56:59], v[164:167], v[194:197], v[56:59]
	v_mfma_f32_16x16x32_bf16 v[48:51], v[172:175], v[194:197], v[48:51]
	v_mfma_f32_16x16x32_bf16 v[40:43], v[164:167], v[210:213], v[40:43]
	v_mfma_f32_16x16x32_bf16 v[32:35], v[172:175], v[210:213], v[32:35]
	v_mfma_f32_16x16x32_bf16 v[24:27], v[164:167], v[220:223], v[24:27]
	v_mfma_f32_16x16x32_bf16 v[16:19], v[172:175], v[220:223], v[16:19]
	v_mfma_f32_16x16x32_bf16 v[8:11], v[164:167], v[228:231], v[8:11]
	v_mfma_f32_16x16x32_bf16 v[0:3], v[172:175], v[228:231], v[0:3]
	s_barrier
	s_add_i32 s31, 0, 0x18000
	s_add_i32 s44, 0, 0x1c000
	v_add_u32_e32 v156, s31, v151
	v_add_u32_e32 v172, s44, v151
	ds_read_b128 v[128:131], v156
	ds_read_b128 v[142:145], v156 offset:1024
	ds_read_b128 v[146:149], v156 offset:2048
	ds_read_b128 v[156:159], v156 offset:3072
	ds_read_b128 v[160:163], v172
	ds_read_b128 v[164:167], v172 offset:1024
	ds_read_b128 v[168:171], v172 offset:2048
	ds_read_b128 v[172:175], v172 offset:3072
	s_add_u32 s16, s16, s6
	s_addc_u32 s17, s17, s7
	s_mov_b32 m0, s39
	v_lshl_add_u64 v[240:241], s[16:17], 0, v[136:137]
	ds_read_b128 v[176:179], v155 offset:32768
	ds_read_b128 v[194:197], v155 offset:33792
	ds_read_b128 v[206:209], v155 offset:34816
	ds_read_b128 v[210:213], v155 offset:35840
	ds_read_b128 v[214:217], v155 offset:36864
	ds_read_b128 v[220:223], v155 offset:37888
	ds_read_b128 v[224:227], v155 offset:38912
	ds_read_b128 v[228:231], v155 offset:39936
	global_load_lds_dwordx4 v[240:241], off
	v_lshl_add_u64 v[240:241], s[16:17], 0, v[134:135]
	s_mov_b32 m0, s46
	s_nop 0
	global_load_lds_dwordx4 v[240:241], off
	s_waitcnt vmcnt(8)
	s_waitcnt lgkmcnt(0)
	s_barrier
	s_waitcnt lgkmcnt(0)
	v_mfma_f32_16x16x32_bf16 v[120:123], v[128:131], v[176:179], v[120:123]
	v_mfma_f32_16x16x32_bf16 v[116:119], v[146:149], v[176:179], v[116:119]
	v_mfma_f32_16x16x32_bf16 v[108:111], v[128:131], v[206:209], v[108:111]
	v_mfma_f32_16x16x32_bf16 v[100:103], v[146:149], v[206:209], v[100:103]
	v_mfma_f32_16x16x32_bf16 v[92:95], v[128:131], v[214:217], v[92:95]
	v_mfma_f32_16x16x32_bf16 v[84:87], v[146:149], v[214:217], v[84:87]
	v_mfma_f32_16x16x32_bf16 v[76:79], v[128:131], v[224:227], v[76:79]
	v_mfma_f32_16x16x32_bf16 v[68:71], v[146:149], v[224:227], v[68:71]
	v_mfma_f32_16x16x32_bf16 v[120:123], v[142:145], v[194:197], v[120:123]
	v_mfma_f32_16x16x32_bf16 v[116:119], v[156:159], v[194:197], v[116:119]
	v_mfma_f32_16x16x32_bf16 v[108:111], v[142:145], v[210:213], v[108:111]
	v_mfma_f32_16x16x32_bf16 v[100:103], v[156:159], v[210:213], v[100:103]
	v_mfma_f32_16x16x32_bf16 v[92:95], v[142:145], v[220:223], v[92:95]
	v_mfma_f32_16x16x32_bf16 v[84:87], v[156:159], v[220:223], v[84:87]
	v_mfma_f32_16x16x32_bf16 v[76:79], v[142:145], v[228:231], v[76:79]
	v_mfma_f32_16x16x32_bf16 v[68:71], v[156:159], v[228:231], v[68:71]
	v_mfma_f32_16x16x32_bf16 v[124:127], v[160:163], v[176:179], v[124:127]
	v_mfma_f32_16x16x32_bf16 v[112:115], v[168:171], v[176:179], v[112:115]
	v_mfma_f32_16x16x32_bf16 v[104:107], v[160:163], v[206:209], v[104:107]
	v_mfma_f32_16x16x32_bf16 v[96:99], v[168:171], v[206:209], v[96:99]
	v_mfma_f32_16x16x32_bf16 v[88:91], v[160:163], v[214:217], v[88:91]
	v_mfma_f32_16x16x32_bf16 v[80:83], v[168:171], v[214:217], v[80:83]
	v_mfma_f32_16x16x32_bf16 v[72:75], v[160:163], v[224:227], v[72:75]
	v_mfma_f32_16x16x32_bf16 v[64:67], v[168:171], v[224:227], v[64:67]
	v_mfma_f32_16x16x32_bf16 v[124:127], v[164:167], v[194:197], v[124:127]
	v_mfma_f32_16x16x32_bf16 v[112:115], v[172:175], v[194:197], v[112:115]
	v_mfma_f32_16x16x32_bf16 v[104:107], v[164:167], v[210:213], v[104:107]
	v_mfma_f32_16x16x32_bf16 v[96:99], v[172:175], v[210:213], v[96:99]
	v_mfma_f32_16x16x32_bf16 v[88:91], v[164:167], v[220:223], v[88:91]
	v_mfma_f32_16x16x32_bf16 v[80:83], v[172:175], v[220:223], v[80:83]
	v_mfma_f32_16x16x32_bf16 v[72:75], v[164:167], v[228:231], v[72:75]
	v_mfma_f32_16x16x32_bf16 v[64:67], v[172:175], v[228:231], v[64:67]
	s_barrier
	s_add_i32 s16, s31, s36
	v_lshl_add_u64 v[198:199], v[198:199], 0, s[12:13]
	s_mov_b32 m0, s16
	ds_read_b128 v[176:179], v155 offset:49152
	ds_read_b128 v[194:197], v155 offset:50176
	ds_read_b128 v[206:209], v155 offset:51200
	ds_read_b128 v[210:213], v155 offset:52224
	ds_read_b128 v[214:217], v155 offset:53248
	ds_read_b128 v[220:223], v155 offset:54272
	ds_read_b128 v[224:227], v155 offset:55296
	ds_read_b128 v[228:231], v155 offset:56320
	global_load_lds_dwordx4 v[198:199], off
	v_lshl_add_u64 v[198:199], v[202:203], 0, s[12:13]
	s_add_i32 m0, s16, 0x2000
	s_add_i32 s16, s44, s36
	global_load_lds_dwordx4 v[198:199], off
	v_lshl_add_u64 v[198:199], v[232:233], 0, s[12:13]
	s_mov_b32 m0, s16
	s_nop 0
	global_load_lds_dwordx4 v[198:199], off
	v_lshl_add_u64 v[198:199], v[234:235], 0, s[12:13]
	s_add_i32 m0, s16, 0x2000
	s_nop 0
	global_load_lds_dwordx4 v[198:199], off
	v_lshl_add_u64 v[198:199], v[236:237], 0, s[12:13]
	s_mov_b32 m0, s49
	s_nop 0
	global_load_lds_dwordx4 v[198:199], off
	v_lshl_add_u64 v[198:199], v[238:239], 0, s[12:13]
	s_mov_b32 m0, s52
	s_nop 0
	global_load_lds_dwordx4 v[198:199], off
	s_waitcnt vmcnt(8)
	s_waitcnt lgkmcnt(0)
	s_barrier
	s_waitcnt lgkmcnt(0)
	v_mfma_f32_16x16x32_bf16 v[60:63], v[128:131], v[176:179], v[60:63]
	s_add_u32 s28, s28, 0x100
	v_mfma_f32_16x16x32_bf16 v[52:55], v[146:149], v[176:179], v[52:55]
	s_addc_u32 s29, s29, 0
	v_mfma_f32_16x16x32_bf16 v[44:47], v[128:131], v[206:209], v[44:47]
	s_add_u32 s10, s10, 0x100
	v_mfma_f32_16x16x32_bf16 v[36:39], v[146:149], v[206:209], v[36:39]
	s_addc_u32 s11, s11, 0
	v_mfma_f32_16x16x32_bf16 v[28:31], v[128:131], v[214:217], v[28:31]
	s_mov_b32 s16, s30
	v_mfma_f32_16x16x32_bf16 v[20:23], v[146:149], v[214:217], v[20:23]
	s_cmp_ge_i32 s30, s47
	v_mfma_f32_16x16x32_bf16 v[12:15], v[128:131], v[224:227], v[12:15]
	s_cselect_b32 s99, 1, 0
	v_readfirstlane_b32 s98, v218
	s_bfe_u32 s98, s98, 0x10008
	s_and_b32 s98, s98, s99
	v_mfma_f32_16x16x32_bf16 v[4:7], v[146:149], v[224:227], v[4:7]
	s_add_i32 s30, s16, 2
	v_mfma_f32_16x16x32_bf16 v[60:63], v[142:145], v[194:197], v[60:63]
	s_add_u32 s31, s28, 0x80
	v_mfma_f32_16x16x32_bf16 v[52:55], v[156:159], v[194:197], v[52:55]
	s_addc_u32 s17, s29, 0
	v_mfma_f32_16x16x32_bf16 v[44:47], v[142:145], v[210:213], v[44:47]
	s_add_i32 s63, 0, 0x10000
	v_mfma_f32_16x16x32_bf16 v[36:39], v[156:159], v[210:213], v[36:39]
	s_cmp_eq_u32 s56, s16
	v_mfma_f32_16x16x32_bf16 v[28:31], v[142:145], v[220:223], v[28:31]
	s_cselect_b32 s17, s25, s17
	v_mfma_f32_16x16x32_bf16 v[20:23], v[156:159], v[220:223], v[20:23]
	s_cselect_b32 s16, s24, s31
	v_mfma_f32_16x16x32_bf16 v[12:15], v[142:145], v[228:231], v[12:15]
	s_cselect_b32 s45, s27, s11
	v_mfma_f32_16x16x32_bf16 v[4:7], v[156:159], v[228:231], v[4:7]
	s_cselect_b32 s44, s26, s10
	v_mfma_f32_16x16x32_bf16 v[56:59], v[160:163], v[176:179], v[56:59]
	s_add_i32 s31, 0, 0x14000
	v_mfma_f32_16x16x32_bf16 v[48:51], v[168:171], v[176:179], v[48:51]
	v_mfma_f32_16x16x32_bf16 v[40:43], v[160:163], v[206:209], v[40:43]
	v_mfma_f32_16x16x32_bf16 v[32:35], v[168:171], v[206:209], v[32:35]
	v_mfma_f32_16x16x32_bf16 v[24:27], v[160:163], v[214:217], v[24:27]
	v_mfma_f32_16x16x32_bf16 v[16:19], v[168:171], v[214:217], v[16:19]
	v_mfma_f32_16x16x32_bf16 v[8:11], v[160:163], v[224:227], v[8:11]
	v_mfma_f32_16x16x32_bf16 v[0:3], v[168:171], v[224:227], v[0:3]
	v_mfma_f32_16x16x32_bf16 v[56:59], v[164:167], v[194:197], v[56:59]
	v_mfma_f32_16x16x32_bf16 v[48:51], v[172:175], v[194:197], v[48:51]
	v_mfma_f32_16x16x32_bf16 v[40:43], v[164:167], v[210:213], v[40:43]
	v_mfma_f32_16x16x32_bf16 v[32:35], v[172:175], v[210:213], v[32:35]
	v_mfma_f32_16x16x32_bf16 v[24:27], v[164:167], v[220:223], v[24:27]
	v_mfma_f32_16x16x32_bf16 v[16:19], v[172:175], v[220:223], v[16:19]
	v_mfma_f32_16x16x32_bf16 v[8:11], v[164:167], v[228:231], v[8:11]
	v_mfma_f32_16x16x32_bf16 v[0:3], v[172:175], v[228:231], v[0:3]
	s_cmp_lg_u32 s98, 0
	s_cbranch_scc1 .Lskf_14_peel
	s_barrier

.LBB0_1144:
	v_add_u32_e32 v156, s63, v151
	v_add_u32_e32 v172, s31, v151
	ds_read_b128 v[128:131], v156
	ds_read_b128 v[142:145], v156 offset:1024
	ds_read_b128 v[146:149], v156 offset:2048
	ds_read_b128 v[156:159], v156 offset:3072
	ds_read_b128 v[160:163], v172
	ds_read_b128 v[164:167], v172 offset:1024
	ds_read_b128 v[168:171], v172 offset:2048
	ds_read_b128 v[172:175], v172 offset:3072
	v_lshl_add_u64 v[198:199], s[28:29], 0, v[138:139]
	s_add_i32 m0, s37, 0xc000
	ds_read_b128 v[176:179], v155
	ds_read_b128 v[194:197], v155 offset:1024
	ds_read_b128 v[206:209], v155 offset:2048
	ds_read_b128 v[210:213], v155 offset:3072
	ds_read_b128 v[214:217], v155 offset:4096
	ds_read_b128 v[220:223], v155 offset:5120
	ds_read_b128 v[224:227], v155 offset:6144
	ds_read_b128 v[228:231], v155 offset:7168
	global_load_lds_dwordx4 v[198:199], off
	v_lshl_add_u64 v[198:199], s[28:29], 0, v[140:141]
	s_add_i32 m0, s37, 0xe000
	s_nop 0
	global_load_lds_dwordx4 v[198:199], off
	s_waitcnt vmcnt(8)
	s_waitcnt lgkmcnt(0)
	s_barrier
	s_waitcnt lgkmcnt(0)
	v_mfma_f32_16x16x32_bf16 v[120:123], v[128:131], v[176:179], v[120:123]
	v_mfma_f32_16x16x32_bf16 v[116:119], v[146:149], v[176:179], v[116:119]
	v_mfma_f32_16x16x32_bf16 v[108:111], v[128:131], v[206:209], v[108:111]
	v_mfma_f32_16x16x32_bf16 v[100:103], v[146:149], v[206:209], v[100:103]
	v_mfma_f32_16x16x32_bf16 v[92:95], v[128:131], v[214:217], v[92:95]
	v_mfma_f32_16x16x32_bf16 v[84:87], v[146:149], v[214:217], v[84:87]
	v_mfma_f32_16x16x32_bf16 v[76:79], v[128:131], v[224:227], v[76:79]
	v_mfma_f32_16x16x32_bf16 v[68:71], v[146:149], v[224:227], v[68:71]
	v_mfma_f32_16x16x32_bf16 v[120:123], v[142:145], v[194:197], v[120:123]
	v_mfma_f32_16x16x32_bf16 v[116:119], v[156:159], v[194:197], v[116:119]
	v_mfma_f32_16x16x32_bf16 v[108:111], v[142:145], v[210:213], v[108:111]
	v_mfma_f32_16x16x32_bf16 v[100:103], v[156:159], v[210:213], v[100:103]
	v_mfma_f32_16x16x32_bf16 v[92:95], v[142:145], v[220:223], v[92:95]
	v_mfma_f32_16x16x32_bf16 v[84:87], v[156:159], v[220:223], v[84:87]
	v_mfma_f32_16x16x32_bf16 v[76:79], v[142:145], v[228:231], v[76:79]
	v_mfma_f32_16x16x32_bf16 v[68:71], v[156:159], v[228:231], v[68:71]
	v_mfma_f32_16x16x32_bf16 v[124:127], v[160:163], v[176:179], v[124:127]
	v_mfma_f32_16x16x32_bf16 v[112:115], v[168:171], v[176:179], v[112:115]
	v_mfma_f32_16x16x32_bf16 v[104:107], v[160:163], v[206:209], v[104:107]
	v_mfma_f32_16x16x32_bf16 v[96:99], v[168:171], v[206:209], v[96:99]
	v_mfma_f32_16x16x32_bf16 v[88:91], v[160:163], v[214:217], v[88:91]
	v_mfma_f32_16x16x32_bf16 v[80:83], v[168:171], v[214:217], v[80:83]
	v_mfma_f32_16x16x32_bf16 v[72:75], v[160:163], v[224:227], v[72:75]
	v_mfma_f32_16x16x32_bf16 v[64:67], v[168:171], v[224:227], v[64:67]
	v_mfma_f32_16x16x32_bf16 v[124:127], v[164:167], v[194:197], v[124:127]
	v_mfma_f32_16x16x32_bf16 v[112:115], v[172:175], v[194:197], v[112:115]
	v_mfma_f32_16x16x32_bf16 v[104:107], v[164:167], v[210:213], v[104:107]
	v_mfma_f32_16x16x32_bf16 v[96:99], v[172:175], v[210:213], v[96:99]
	v_mfma_f32_16x16x32_bf16 v[88:91], v[164:167], v[220:223], v[88:91]
	v_mfma_f32_16x16x32_bf16 v[80:83], v[172:175], v[220:223], v[80:83]
	v_mfma_f32_16x16x32_bf16 v[72:75], v[164:167], v[228:231], v[72:75]
	v_mfma_f32_16x16x32_bf16 v[64:67], v[172:175], v[228:231], v[64:67]
	s_barrier
	s_add_i32 s63, s63, s36
	v_lshl_add_u64 v[198:199], s[44:45], 0, v[180:181]
	s_mov_b32 m0, s63
	ds_read_b128 v[176:179], v155 offset:16384
	ds_read_b128 v[194:197], v155 offset:17408
	ds_read_b128 v[206:209], v155 offset:18432
	ds_read_b128 v[210:213], v155 offset:19456
	ds_read_b128 v[214:217], v155 offset:20480
	ds_read_b128 v[220:223], v155 offset:21504
	ds_read_b128 v[224:227], v155 offset:22528
	ds_read_b128 v[228:231], v155 offset:23552
	global_load_lds_dwordx4 v[198:199], off
	s_add_i32 m0, s63, 0x2000
	v_lshl_add_u64 v[202:203], s[44:45], 0, v[132:133]
	s_add_u32 s44, s44, s6
	s_addc_u32 s45, s45, s7
	s_add_i32 s31, s31, s36
	global_load_lds_dwordx4 v[202:203], off
	v_lshl_add_u64 v[232:233], s[44:45], 0, v[180:181]
	s_mov_b32 m0, s31
	v_lshl_add_u64 v[234:235], s[44:45], 0, v[132:133]
	global_load_lds_dwordx4 v[232:233], off
	s_add_i32 m0, s31, 0x2000
	v_lshl_add_u64 v[236:237], s[16:17], 0, v[136:137]
	global_load_lds_dwordx4 v[234:235], off
	s_mov_b32 m0, s37
	v_lshl_add_u64 v[238:239], s[16:17], 0, v[134:135]
	global_load_lds_dwordx4 v[236:237], off
	s_mov_b32 m0, s38
	s_nop 0
	global_load_lds_dwordx4 v[238:239], off
	s_waitcnt vmcnt(8)
	s_waitcnt lgkmcnt(0)
	s_barrier
	s_waitcnt lgkmcnt(0)
	v_mfma_f32_16x16x32_bf16 v[60:63], v[128:131], v[176:179], v[60:63]
	v_mfma_f32_16x16x32_bf16 v[52:55], v[146:149], v[176:179], v[52:55]
	v_mfma_f32_16x16x32_bf16 v[44:47], v[128:131], v[206:209], v[44:47]
	v_mfma_f32_16x16x32_bf16 v[36:39], v[146:149], v[206:209], v[36:39]
	v_mfma_f32_16x16x32_bf16 v[28:31], v[128:131], v[214:217], v[28:31]
	v_mfma_f32_16x16x32_bf16 v[20:23], v[146:149], v[214:217], v[20:23]
	v_mfma_f32_16x16x32_bf16 v[12:15], v[128:131], v[224:227], v[12:15]
	v_mfma_f32_16x16x32_bf16 v[4:7], v[146:149], v[224:227], v[4:7]
	v_mfma_f32_16x16x32_bf16 v[60:63], v[142:145], v[194:197], v[60:63]
	v_mfma_f32_16x16x32_bf16 v[52:55], v[156:159], v[194:197], v[52:55]
	v_mfma_f32_16x16x32_bf16 v[44:47], v[142:145], v[210:213], v[44:47]
	v_mfma_f32_16x16x32_bf16 v[36:39], v[156:159], v[210:213], v[36:39]
	v_mfma_f32_16x16x32_bf16 v[28:31], v[142:145], v[220:223], v[28:31]
	v_mfma_f32_16x16x32_bf16 v[20:23], v[156:159], v[220:223], v[20:23]
	v_mfma_f32_16x16x32_bf16 v[12:15], v[142:145], v[228:231], v[12:15]
	v_mfma_f32_16x16x32_bf16 v[4:7], v[156:159], v[228:231], v[4:7]
	v_mfma_f32_16x16x32_bf16 v[56:59], v[160:163], v[176:179], v[56:59]
	v_mfma_f32_16x16x32_bf16 v[48:51], v[168:171], v[176:179], v[48:51]
	v_mfma_f32_16x16x32_bf16 v[40:43], v[160:163], v[206:209], v[40:43]
	v_mfma_f32_16x16x32_bf16 v[32:35], v[168:171], v[206:209], v[32:35]
	v_mfma_f32_16x16x32_bf16 v[24:27], v[160:163], v[214:217], v[24:27]
	v_mfma_f32_16x16x32_bf16 v[16:19], v[168:171], v[214:217], v[16:19]
	v_mfma_f32_16x16x32_bf16 v[8:11], v[160:163], v[224:227], v[8:11]
	v_mfma_f32_16x16x32_bf16 v[0:3], v[168:171], v[224:227], v[0:3]
	v_mfma_f32_16x16x32_bf16 v[56:59], v[164:167], v[194:197], v[56:59]
	v_mfma_f32_16x16x32_bf16 v[48:51], v[172:175], v[194:197], v[48:51]
	v_mfma_f32_16x16x32_bf16 v[40:43], v[164:167], v[210:213], v[40:43]
	v_mfma_f32_16x16x32_bf16 v[32:35], v[172:175], v[210:213], v[32:35]
	v_mfma_f32_16x16x32_bf16 v[24:27], v[164:167], v[220:223], v[24:27]
	v_mfma_f32_16x16x32_bf16 v[16:19], v[172:175], v[220:223], v[16:19]
	v_mfma_f32_16x16x32_bf16 v[8:11], v[164:167], v[228:231], v[8:11]
	v_mfma_f32_16x16x32_bf16 v[0:3], v[172:175], v[228:231], v[0:3]
	s_barrier
	s_add_i32 s31, 0, 0x18000
	s_add_i32 s44, 0, 0x1c000
	v_add_u32_e32 v156, s31, v151
	v_add_u32_e32 v172, s44, v151
	ds_read_b128 v[128:131], v156
	ds_read_b128 v[142:145], v156 offset:1024
	ds_read_b128 v[146:149], v156 offset:2048
	ds_read_b128 v[156:159], v156 offset:3072
	ds_read_b128 v[160:163], v172
	ds_read_b128 v[164:167], v172 offset:1024
	ds_read_b128 v[168:171], v172 offset:2048
	ds_read_b128 v[172:175], v172 offset:3072
	s_add_u32 s16, s16, s6
	s_addc_u32 s17, s17, s7
	s_mov_b32 m0, s39
	v_lshl_add_u64 v[240:241], s[16:17], 0, v[136:137]
	ds_read_b128 v[176:179], v155 offset:32768
	ds_read_b128 v[194:197], v155 offset:33792
	ds_read_b128 v[206:209], v155 offset:34816
	ds_read_b128 v[210:213], v155 offset:35840
	ds_read_b128 v[214:217], v155 offset:36864
	ds_read_b128 v[220:223], v155 offset:37888
	ds_read_b128 v[224:227], v155 offset:38912
	ds_read_b128 v[228:231], v155 offset:39936
	global_load_lds_dwordx4 v[240:241], off
	v_lshl_add_u64 v[240:241], s[16:17], 0, v[134:135]
	s_mov_b32 m0, s46
	s_nop 0
	global_load_lds_dwordx4 v[240:241], off
	s_waitcnt vmcnt(8)
	s_waitcnt lgkmcnt(0)
	s_barrier
	s_waitcnt lgkmcnt(0)
	v_mfma_f32_16x16x32_bf16 v[120:123], v[128:131], v[176:179], v[120:123]
	v_mfma_f32_16x16x32_bf16 v[116:119], v[146:149], v[176:179], v[116:119]
	v_mfma_f32_16x16x32_bf16 v[108:111], v[128:131], v[206:209], v[108:111]
	v_mfma_f32_16x16x32_bf16 v[100:103], v[146:149], v[206:209], v[100:103]
	v_mfma_f32_16x16x32_bf16 v[92:95], v[128:131], v[214:217], v[92:95]
	v_mfma_f32_16x16x32_bf16 v[84:87], v[146:149], v[214:217], v[84:87]
	v_mfma_f32_16x16x32_bf16 v[76:79], v[128:131], v[224:227], v[76:79]
	v_mfma_f32_16x16x32_bf16 v[68:71], v[146:149], v[224:227], v[68:71]
	v_mfma_f32_16x16x32_bf16 v[120:123], v[142:145], v[194:197], v[120:123]
	v_mfma_f32_16x16x32_bf16 v[116:119], v[156:159], v[194:197], v[116:119]
	v_mfma_f32_16x16x32_bf16 v[108:111], v[142:145], v[210:213], v[108:111]
	v_mfma_f32_16x16x32_bf16 v[100:103], v[156:159], v[210:213], v[100:103]
	v_mfma_f32_16x16x32_bf16 v[92:95], v[142:145], v[220:223], v[92:95]
	v_mfma_f32_16x16x32_bf16 v[84:87], v[156:159], v[220:223], v[84:87]
	v_mfma_f32_16x16x32_bf16 v[76:79], v[142:145], v[228:231], v[76:79]
	v_mfma_f32_16x16x32_bf16 v[68:71], v[156:159], v[228:231], v[68:71]
	v_mfma_f32_16x16x32_bf16 v[124:127], v[160:163], v[176:179], v[124:127]
	v_mfma_f32_16x16x32_bf16 v[112:115], v[168:171], v[176:179], v[112:115]
	v_mfma_f32_16x16x32_bf16 v[104:107], v[160:163], v[206:209], v[104:107]
	v_mfma_f32_16x16x32_bf16 v[96:99], v[168:171], v[206:209], v[96:99]
	v_mfma_f32_16x16x32_bf16 v[88:91], v[160:163], v[214:217], v[88:91]
	v_mfma_f32_16x16x32_bf16 v[80:83], v[168:171], v[214:217], v[80:83]
	v_mfma_f32_16x16x32_bf16 v[72:75], v[160:163], v[224:227], v[72:75]
	v_mfma_f32_16x16x32_bf16 v[64:67], v[168:171], v[224:227], v[64:67]
	v_mfma_f32_16x16x32_bf16 v[124:127], v[164:167], v[194:197], v[124:127]
	v_mfma_f32_16x16x32_bf16 v[112:115], v[172:175], v[194:197], v[112:115]
	v_mfma_f32_16x16x32_bf16 v[104:107], v[164:167], v[210:213], v[104:107]
	v_mfma_f32_16x16x32_bf16 v[96:99], v[172:175], v[210:213], v[96:99]
	v_mfma_f32_16x16x32_bf16 v[88:91], v[164:167], v[220:223], v[88:91]
	v_mfma_f32_16x16x32_bf16 v[80:83], v[172:175], v[220:223], v[80:83]
	v_mfma_f32_16x16x32_bf16 v[72:75], v[164:167], v[228:231], v[72:75]
	v_mfma_f32_16x16x32_bf16 v[64:67], v[172:175], v[228:231], v[64:67]
	s_barrier
	s_add_i32 s16, s31, s36
	v_lshl_add_u64 v[198:199], v[198:199], 0, s[12:13]
	s_mov_b32 m0, s16
	ds_read_b128 v[176:179], v155 offset:49152
	ds_read_b128 v[194:197], v155 offset:50176
	ds_read_b128 v[206:209], v155 offset:51200
	ds_read_b128 v[210:213], v155 offset:52224
	ds_read_b128 v[214:217], v155 offset:53248
	ds_read_b128 v[220:223], v155 offset:54272
	ds_read_b128 v[224:227], v155 offset:55296
	ds_read_b128 v[228:231], v155 offset:56320
	global_load_lds_dwordx4 v[198:199], off
	v_lshl_add_u64 v[198:199], v[202:203], 0, s[12:13]
	s_add_i32 m0, s16, 0x2000
	s_add_i32 s16, s44, s36
	global_load_lds_dwordx4 v[198:199], off
	v_lshl_add_u64 v[198:199], v[232:233], 0, s[12:13]
	s_mov_b32 m0, s16
	s_nop 0
	global_load_lds_dwordx4 v[198:199], off
	v_lshl_add_u64 v[198:199], v[234:235], 0, s[12:13]
	s_add_i32 m0, s16, 0x2000
	s_nop 0
	global_load_lds_dwordx4 v[198:199], off
	v_lshl_add_u64 v[198:199], v[236:237], 0, s[12:13]
	s_mov_b32 m0, s49
	s_nop 0
	global_load_lds_dwordx4 v[198:199], off
	v_lshl_add_u64 v[198:199], v[238:239], 0, s[12:13]
	s_mov_b32 m0, s52
	s_nop 0
	global_load_lds_dwordx4 v[198:199], off
	s_waitcnt vmcnt(8)
	s_waitcnt lgkmcnt(0)
	s_barrier
	s_waitcnt lgkmcnt(0)
	v_mfma_f32_16x16x32_bf16 v[60:63], v[128:131], v[176:179], v[60:63]
	s_add_u32 s28, s28, 0x100
	v_mfma_f32_16x16x32_bf16 v[52:55], v[146:149], v[176:179], v[52:55]
	s_addc_u32 s29, s29, 0
	v_mfma_f32_16x16x32_bf16 v[44:47], v[128:131], v[206:209], v[44:47]
	s_add_u32 s10, s10, 0x100
	v_mfma_f32_16x16x32_bf16 v[36:39], v[146:149], v[206:209], v[36:39]
	s_addc_u32 s11, s11, 0
	v_mfma_f32_16x16x32_bf16 v[28:31], v[128:131], v[214:217], v[28:31]
	s_mov_b32 s16, s30
	v_mfma_f32_16x16x32_bf16 v[20:23], v[146:149], v[214:217], v[20:23]
	s_cmp_ge_i32 s30, s47
	v_mfma_f32_16x16x32_bf16 v[12:15], v[128:131], v[224:227], v[12:15]
	s_cselect_b32 s99, 1, 0
	v_readfirstlane_b32 s98, v218
	s_bfe_u32 s98, s98, 0x10008
	s_and_b32 s98, s98, s99
	v_mfma_f32_16x16x32_bf16 v[4:7], v[146:149], v[224:227], v[4:7]
	s_add_i32 s30, s16, 2
	v_mfma_f32_16x16x32_bf16 v[60:63], v[142:145], v[194:197], v[60:63]
	s_add_u32 s31, s28, 0x80
	v_mfma_f32_16x16x32_bf16 v[52:55], v[156:159], v[194:197], v[52:55]
	s_addc_u32 s17, s29, 0
	v_mfma_f32_16x16x32_bf16 v[44:47], v[142:145], v[210:213], v[44:47]
	s_add_i32 s63, 0, 0x10000
	v_mfma_f32_16x16x32_bf16 v[36:39], v[156:159], v[210:213], v[36:39]
	s_cmp_eq_u32 s56, s16
	v_mfma_f32_16x16x32_bf16 v[28:31], v[142:145], v[220:223], v[28:31]
	s_cselect_b32 s17, s25, s17
	v_mfma_f32_16x16x32_bf16 v[20:23], v[156:159], v[220:223], v[20:23]
	s_cselect_b32 s16, s24, s31
	v_mfma_f32_16x16x32_bf16 v[12:15], v[142:145], v[228:231], v[12:15]
	s_cselect_b32 s45, s27, s11
	v_mfma_f32_16x16x32_bf16 v[4:7], v[156:159], v[228:231], v[4:7]
	s_cselect_b32 s44, s26, s10
	v_mfma_f32_16x16x32_bf16 v[56:59], v[160:163], v[176:179], v[56:59]
	s_add_i32 s31, 0, 0x14000
	v_mfma_f32_16x16x32_bf16 v[48:51], v[168:171], v[176:179], v[48:51]
	v_mfma_f32_16x16x32_bf16 v[40:43], v[160:163], v[206:209], v[40:43]
	v_mfma_f32_16x16x32_bf16 v[32:35], v[168:171], v[206:209], v[32:35]
	v_mfma_f32_16x16x32_bf16 v[24:27], v[160:163], v[214:217], v[24:27]
	v_mfma_f32_16x16x32_bf16 v[16:19], v[168:171], v[214:217], v[16:19]
	v_mfma_f32_16x16x32_bf16 v[8:11], v[160:163], v[224:227], v[8:11]
	v_mfma_f32_16x16x32_bf16 v[0:3], v[168:171], v[224:227], v[0:3]
	v_mfma_f32_16x16x32_bf16 v[56:59], v[164:167], v[194:197], v[56:59]
	v_mfma_f32_16x16x32_bf16 v[48:51], v[172:175], v[194:197], v[48:51]
	v_mfma_f32_16x16x32_bf16 v[40:43], v[164:167], v[210:213], v[40:43]
	v_mfma_f32_16x16x32_bf16 v[32:35], v[172:175], v[210:213], v[32:35]
	v_mfma_f32_16x16x32_bf16 v[24:27], v[164:167], v[220:223], v[24:27]
	v_mfma_f32_16x16x32_bf16 v[16:19], v[172:175], v[220:223], v[16:19]
	v_mfma_f32_16x16x32_bf16 v[8:11], v[164:167], v[228:231], v[8:11]
	v_mfma_f32_16x16x32_bf16 v[0:3], v[172:175], v[228:231], v[0:3]
	s_cmp_lg_u32 s98, 0
	s_cbranch_scc1 .Lskf_14_loop
	s_barrier

.LBB0_1146:
	s_nop 0
	s_lshl_b32 s10, s61, 8
	s_add_i32 s10, s10, s48
	s_cmp_eq_u32 s61, s62
	s_cbranch_scc1 .LBB0_1150

.LBB0_1211:
	s_barrier
	s_andn2_b64 vcc, exec, s[10:11]
	s_mov_b32 s58, s56
	s_mov_b32 s59, s57
	s_mov_b64 s[28:29], s[24:25]
	s_mov_b64 s[26:27], s[22:23]
	s_cbranch_vccz .LBB0_1247

.Llbb_11:
	s_add_i32 s44, s28, 2
	s_add_u32 s45, s26, 0x80
	s_addc_u32 s29, s27, 0
	s_add_i32 s62, 0, 0x10000
	s_cmp_eq_u32 s49, s28
	s_cselect_b32 s29, s23, s29
	s_cselect_b32 s28, s22, s45
	s_cselect_b32 s61, s25, s11
	s_cselect_b32 s60, s24, s10
	s_add_i32 s45, 0, 0x14000
	v_add_u32_e32 v140, s62, v199
	v_add_u32_e32 v166, s45, v199
	ds_read_b128 v[128:131], v140
	ds_read_b128 v[132:135], v140 offset:1024
	ds_read_b128 v[136:139], v140 offset:2048
	ds_read_b128 v[140:143], v140 offset:3072
	ds_read_b128 v[144:147], v166
	ds_read_b128 v[148:151], v166 offset:1024
	ds_read_b128 v[152:155], v166 offset:2048
	ds_read_b128 v[166:169], v166 offset:3072
	v_lshl_add_u64 v[178:179], s[26:27], 0, v[162:163]
	s_add_i32 m0, s35, 0xc000
	ds_read_b128 v[170:173], v206
	ds_read_b128 v[174:177], v206 offset:1024
	ds_read_b128 v[194:197], v206 offset:2048
	ds_read_b128 v[208:211], v206 offset:3072
	ds_read_b128 v[212:215], v206 offset:4096
	ds_read_b128 v[220:223], v206 offset:5120
	ds_read_b128 v[224:227], v206 offset:6144
	ds_read_b128 v[228:231], v206 offset:7168
	global_load_lds_dwordx4 v[178:179], off
	v_lshl_add_u64 v[178:179], s[26:27], 0, v[164:165]
	s_add_i32 m0, s35, 0xe000
	s_nop 0
	global_load_lds_dwordx4 v[178:179], off
	s_waitcnt vmcnt(8)
	s_waitcnt lgkmcnt(0)
	s_barrier
	s_waitcnt lgkmcnt(0)
	v_mfma_f32_16x16x32_bf16 v[120:123], v[128:131], v[170:173], 0
	v_mfma_f32_16x16x32_bf16 v[124:127], v[136:139], v[170:173], 0
	v_mfma_f32_16x16x32_bf16 v[108:111], v[128:131], v[194:197], 0
	v_mfma_f32_16x16x32_bf16 v[104:107], v[136:139], v[194:197], 0
	v_mfma_f32_16x16x32_bf16 v[92:95], v[128:131], v[212:215], 0
	v_mfma_f32_16x16x32_bf16 v[88:91], v[136:139], v[212:215], 0
	v_mfma_f32_16x16x32_bf16 v[76:79], v[128:131], v[224:227], 0
	v_mfma_f32_16x16x32_bf16 v[72:75], v[136:139], v[224:227], 0
	v_mfma_f32_16x16x32_bf16 v[120:123], v[132:135], v[174:177], v[120:123]
	v_mfma_f32_16x16x32_bf16 v[124:127], v[140:143], v[174:177], v[124:127]
	v_mfma_f32_16x16x32_bf16 v[108:111], v[132:135], v[208:211], v[108:111]
	v_mfma_f32_16x16x32_bf16 v[104:107], v[140:143], v[208:211], v[104:107]
	v_mfma_f32_16x16x32_bf16 v[92:95], v[132:135], v[220:223], v[92:95]
	v_mfma_f32_16x16x32_bf16 v[88:91], v[140:143], v[220:223], v[88:91]
	v_mfma_f32_16x16x32_bf16 v[76:79], v[132:135], v[228:231], v[76:79]
	v_mfma_f32_16x16x32_bf16 v[72:75], v[140:143], v[228:231], v[72:75]
	v_mfma_f32_16x16x32_bf16 v[116:119], v[144:147], v[170:173], 0
	v_mfma_f32_16x16x32_bf16 v[112:115], v[152:155], v[170:173], 0
	v_mfma_f32_16x16x32_bf16 v[100:103], v[144:147], v[194:197], 0
	v_mfma_f32_16x16x32_bf16 v[96:99], v[152:155], v[194:197], 0
	v_mfma_f32_16x16x32_bf16 v[84:87], v[144:147], v[212:215], 0
	v_mfma_f32_16x16x32_bf16 v[80:83], v[152:155], v[212:215], 0
	v_mfma_f32_16x16x32_bf16 v[68:71], v[144:147], v[224:227], 0
	v_mfma_f32_16x16x32_bf16 v[64:67], v[152:155], v[224:227], 0
	v_mfma_f32_16x16x32_bf16 v[116:119], v[148:151], v[174:177], v[116:119]
	v_mfma_f32_16x16x32_bf16 v[112:115], v[166:169], v[174:177], v[112:115]
	v_mfma_f32_16x16x32_bf16 v[100:103], v[148:151], v[208:211], v[100:103]
	v_mfma_f32_16x16x32_bf16 v[96:99], v[166:169], v[208:211], v[96:99]
	v_mfma_f32_16x16x32_bf16 v[84:87], v[148:151], v[220:223], v[84:87]
	v_mfma_f32_16x16x32_bf16 v[80:83], v[166:169], v[220:223], v[80:83]
	v_mfma_f32_16x16x32_bf16 v[68:71], v[148:151], v[228:231], v[68:71]
	v_mfma_f32_16x16x32_bf16 v[64:67], v[166:169], v[228:231], v[64:67]
	s_barrier
	s_add_i32 s62, s62, s34
	v_lshl_add_u64 v[178:179], s[60:61], 0, v[180:181]
	s_mov_b32 m0, s62
	ds_read_b128 v[170:173], v206 offset:16384
	ds_read_b128 v[174:177], v206 offset:17408
	ds_read_b128 v[194:197], v206 offset:18432
	ds_read_b128 v[208:211], v206 offset:19456
	ds_read_b128 v[212:215], v206 offset:20480
	ds_read_b128 v[220:223], v206 offset:21504
	ds_read_b128 v[224:227], v206 offset:22528
	ds_read_b128 v[228:231], v206 offset:23552
	global_load_lds_dwordx4 v[178:179], off
	s_add_i32 m0, s62, 0x2000
	v_lshl_add_u64 v[202:203], s[60:61], 0, v[156:157]
	s_add_u32 s60, s60, s6
	s_addc_u32 s61, s61, s7
	s_add_i32 s45, s45, s34
	global_load_lds_dwordx4 v[202:203], off
	v_lshl_add_u64 v[216:217], s[60:61], 0, v[180:181]
	s_mov_b32 m0, s45
	v_lshl_add_u64 v[232:233], s[60:61], 0, v[156:157]
	global_load_lds_dwordx4 v[216:217], off
	s_add_i32 m0, s45, 0x2000
	v_lshl_add_u64 v[234:235], s[28:29], 0, v[160:161]
	global_load_lds_dwordx4 v[232:233], off
	s_mov_b32 m0, s35
	v_lshl_add_u64 v[236:237], s[28:29], 0, v[158:159]
	global_load_lds_dwordx4 v[234:235], off
	s_mov_b32 m0, s36
	s_nop 0
	global_load_lds_dwordx4 v[236:237], off
	s_waitcnt vmcnt(8)
	s_waitcnt lgkmcnt(0)
	s_barrier
	s_waitcnt lgkmcnt(0)
	v_mfma_f32_16x16x32_bf16 v[60:63], v[128:131], v[170:173], 0
	v_mfma_f32_16x16x32_bf16 v[56:59], v[136:139], v[170:173], 0
	v_mfma_f32_16x16x32_bf16 v[44:47], v[128:131], v[194:197], 0
	v_mfma_f32_16x16x32_bf16 v[40:43], v[136:139], v[194:197], 0
	v_mfma_f32_16x16x32_bf16 v[28:31], v[128:131], v[212:215], 0
	v_mfma_f32_16x16x32_bf16 v[24:27], v[136:139], v[212:215], 0
	v_mfma_f32_16x16x32_bf16 v[12:15], v[128:131], v[224:227], 0
	v_mfma_f32_16x16x32_bf16 v[8:11], v[136:139], v[224:227], 0
	v_mfma_f32_16x16x32_bf16 v[60:63], v[132:135], v[174:177], v[60:63]
	v_mfma_f32_16x16x32_bf16 v[56:59], v[140:143], v[174:177], v[56:59]
	v_mfma_f32_16x16x32_bf16 v[44:47], v[132:135], v[208:211], v[44:47]
	v_mfma_f32_16x16x32_bf16 v[40:43], v[140:143], v[208:211], v[40:43]
	v_mfma_f32_16x16x32_bf16 v[28:31], v[132:135], v[220:223], v[28:31]
	v_mfma_f32_16x16x32_bf16 v[24:27], v[140:143], v[220:223], v[24:27]
	v_mfma_f32_16x16x32_bf16 v[12:15], v[132:135], v[228:231], v[12:15]
	v_mfma_f32_16x16x32_bf16 v[8:11], v[140:143], v[228:231], v[8:11]
	v_mfma_f32_16x16x32_bf16 v[52:55], v[144:147], v[170:173], 0
	v_mfma_f32_16x16x32_bf16 v[48:51], v[152:155], v[170:173], 0
	v_mfma_f32_16x16x32_bf16 v[36:39], v[144:147], v[194:197], 0
	v_mfma_f32_16x16x32_bf16 v[32:35], v[152:155], v[194:197], 0
	v_mfma_f32_16x16x32_bf16 v[20:23], v[144:147], v[212:215], 0
	v_mfma_f32_16x16x32_bf16 v[16:19], v[152:155], v[212:215], 0
	v_mfma_f32_16x16x32_bf16 v[4:7], v[144:147], v[224:227], 0
	v_mfma_f32_16x16x32_bf16 v[0:3], v[152:155], v[224:227], 0
	v_mfma_f32_16x16x32_bf16 v[52:55], v[148:151], v[174:177], v[52:55]
	v_mfma_f32_16x16x32_bf16 v[48:51], v[166:169], v[174:177], v[48:51]
	v_mfma_f32_16x16x32_bf16 v[36:39], v[148:151], v[208:211], v[36:39]
	v_mfma_f32_16x16x32_bf16 v[32:35], v[166:169], v[208:211], v[32:35]
	v_mfma_f32_16x16x32_bf16 v[20:23], v[148:151], v[220:223], v[20:23]
	v_mfma_f32_16x16x32_bf16 v[16:19], v[166:169], v[220:223], v[16:19]
	v_mfma_f32_16x16x32_bf16 v[4:7], v[148:151], v[228:231], v[4:7]
	v_mfma_f32_16x16x32_bf16 v[0:3], v[166:169], v[228:231], v[0:3]
	s_barrier
	s_add_i32 s45, 0, 0x18000
	s_add_i32 s60, 0, 0x1c000
	v_add_u32_e32 v140, s45, v199
	v_add_u32_e32 v166, s60, v199
	ds_read_b128 v[128:131], v140
	ds_read_b128 v[132:135], v140 offset:1024
	ds_read_b128 v[136:139], v140 offset:2048
	ds_read_b128 v[140:143], v140 offset:3072
	ds_read_b128 v[144:147], v166
	ds_read_b128 v[148:151], v166 offset:1024
	ds_read_b128 v[152:155], v166 offset:2048
	ds_read_b128 v[166:169], v166 offset:3072
	s_add_u32 s28, s28, s6
	s_addc_u32 s29, s29, s7
	s_mov_b32 m0, s37
	v_lshl_add_u64 v[238:239], s[28:29], 0, v[160:161]
	ds_read_b128 v[170:173], v206 offset:32768
	ds_read_b128 v[174:177], v206 offset:33792
	ds_read_b128 v[194:197], v206 offset:34816
	ds_read_b128 v[208:211], v206 offset:35840
	ds_read_b128 v[212:215], v206 offset:36864
	ds_read_b128 v[220:223], v206 offset:37888
	ds_read_b128 v[224:227], v206 offset:38912
	ds_read_b128 v[228:231], v206 offset:39936
	global_load_lds_dwordx4 v[238:239], off
	v_lshl_add_u64 v[238:239], s[28:29], 0, v[158:159]
	s_mov_b32 m0, s38
	s_nop 0
	global_load_lds_dwordx4 v[238:239], off
	s_waitcnt vmcnt(8)
	s_waitcnt lgkmcnt(0)
	s_barrier
	s_waitcnt lgkmcnt(0)
	v_mfma_f32_16x16x32_bf16 v[120:123], v[128:131], v[170:173], v[120:123]
	v_mfma_f32_16x16x32_bf16 v[124:127], v[136:139], v[170:173], v[124:127]
	v_mfma_f32_16x16x32_bf16 v[108:111], v[128:131], v[194:197], v[108:111]
	v_mfma_f32_16x16x32_bf16 v[104:107], v[136:139], v[194:197], v[104:107]
	v_mfma_f32_16x16x32_bf16 v[92:95], v[128:131], v[212:215], v[92:95]
	v_mfma_f32_16x16x32_bf16 v[88:91], v[136:139], v[212:215], v[88:91]
	v_mfma_f32_16x16x32_bf16 v[76:79], v[128:131], v[224:227], v[76:79]
	v_mfma_f32_16x16x32_bf16 v[72:75], v[136:139], v[224:227], v[72:75]
	v_mfma_f32_16x16x32_bf16 v[120:123], v[132:135], v[174:177], v[120:123]
	v_mfma_f32_16x16x32_bf16 v[124:127], v[140:143], v[174:177], v[124:127]
	v_mfma_f32_16x16x32_bf16 v[108:111], v[132:135], v[208:211], v[108:111]
	v_mfma_f32_16x16x32_bf16 v[104:107], v[140:143], v[208:211], v[104:107]
	v_mfma_f32_16x16x32_bf16 v[92:95], v[132:135], v[220:223], v[92:95]
	v_mfma_f32_16x16x32_bf16 v[88:91], v[140:143], v[220:223], v[88:91]
	v_mfma_f32_16x16x32_bf16 v[76:79], v[132:135], v[228:231], v[76:79]
	v_mfma_f32_16x16x32_bf16 v[72:75], v[140:143], v[228:231], v[72:75]
	v_mfma_f32_16x16x32_bf16 v[116:119], v[144:147], v[170:173], v[116:119]
	v_mfma_f32_16x16x32_bf16 v[112:115], v[152:155], v[170:173], v[112:115]
	v_mfma_f32_16x16x32_bf16 v[100:103], v[144:147], v[194:197], v[100:103]
	v_mfma_f32_16x16x32_bf16 v[96:99], v[152:155], v[194:197], v[96:99]
	v_mfma_f32_16x16x32_bf16 v[84:87], v[144:147], v[212:215], v[84:87]
	v_mfma_f32_16x16x32_bf16 v[80:83], v[152:155], v[212:215], v[80:83]
	v_mfma_f32_16x16x32_bf16 v[68:71], v[144:147], v[224:227], v[68:71]
	v_mfma_f32_16x16x32_bf16 v[64:67], v[152:155], v[224:227], v[64:67]
	v_mfma_f32_16x16x32_bf16 v[116:119], v[148:151], v[174:177], v[116:119]
	v_mfma_f32_16x16x32_bf16 v[112:115], v[166:169], v[174:177], v[112:115]
	v_mfma_f32_16x16x32_bf16 v[100:103], v[148:151], v[208:211], v[100:103]
	v_mfma_f32_16x16x32_bf16 v[96:99], v[166:169], v[208:211], v[96:99]
	v_mfma_f32_16x16x32_bf16 v[84:87], v[148:151], v[220:223], v[84:87]
	v_mfma_f32_16x16x32_bf16 v[80:83], v[166:169], v[220:223], v[80:83]
	v_mfma_f32_16x16x32_bf16 v[68:71], v[148:151], v[228:231], v[68:71]
	v_mfma_f32_16x16x32_bf16 v[64:67], v[166:169], v[228:231], v[64:67]
	s_barrier
	s_add_i32 s28, s45, s34
	v_lshl_add_u64 v[178:179], v[178:179], 0, s[12:13]
	s_mov_b32 m0, s28
	ds_read_b128 v[170:173], v206 offset:49152
	ds_read_b128 v[174:177], v206 offset:50176
	ds_read_b128 v[194:197], v206 offset:51200
	ds_read_b128 v[208:211], v206 offset:52224
	ds_read_b128 v[212:215], v206 offset:53248
	ds_read_b128 v[220:223], v206 offset:54272
	ds_read_b128 v[224:227], v206 offset:55296
	ds_read_b128 v[228:231], v206 offset:56320
	global_load_lds_dwordx4 v[178:179], off
	v_lshl_add_u64 v[178:179], v[202:203], 0, s[12:13]
	s_add_i32 m0, s28, 0x2000
	s_add_i32 s28, s60, s34
	global_load_lds_dwordx4 v[178:179], off
	v_lshl_add_u64 v[178:179], v[216:217], 0, s[12:13]
	s_mov_b32 m0, s28
	s_nop 0
	global_load_lds_dwordx4 v[178:179], off
	v_lshl_add_u64 v[178:179], v[232:233], 0, s[12:13]
	s_add_i32 m0, s28, 0x2000
	s_nop 0
	global_load_lds_dwordx4 v[178:179], off
	v_lshl_add_u64 v[178:179], v[234:235], 0, s[12:13]
	s_mov_b32 m0, s47
	s_nop 0
	global_load_lds_dwordx4 v[178:179], off
	v_lshl_add_u64 v[178:179], v[236:237], 0, s[12:13]
	s_mov_b32 m0, s48
	s_nop 0
	global_load_lds_dwordx4 v[178:179], off
	s_waitcnt vmcnt(8)
	s_waitcnt lgkmcnt(0)
	s_barrier
	s_waitcnt lgkmcnt(0)
	v_mfma_f32_16x16x32_bf16 v[60:63], v[128:131], v[170:173], v[60:63]
	s_add_u32 s26, s26, 0x100
	v_mfma_f32_16x16x32_bf16 v[56:59], v[136:139], v[170:173], v[56:59]
	s_addc_u32 s27, s27, 0
	v_mfma_f32_16x16x32_bf16 v[44:47], v[128:131], v[194:197], v[44:47]
	s_add_u32 s10, s10, 0x100
	v_mfma_f32_16x16x32_bf16 v[40:43], v[136:139], v[194:197], v[40:43]
	s_addc_u32 s11, s11, 0
	v_mfma_f32_16x16x32_bf16 v[28:31], v[128:131], v[212:215], v[28:31]
	s_mov_b32 s28, s44
	v_mfma_f32_16x16x32_bf16 v[24:27], v[136:139], v[212:215], v[24:27]
	s_cmp_ge_i32 s44, s46
	v_mfma_f32_16x16x32_bf16 v[12:15], v[128:131], v[224:227], v[12:15]
	s_cselect_b32 s99, 1, 0
	v_readfirstlane_b32 s98, v218
	s_bfe_u32 s98, s98, 0x10008
	s_and_b32 s98, s98, s99
	v_mfma_f32_16x16x32_bf16 v[8:11], v[136:139], v[224:227], v[8:11]
	s_add_i32 s44, s28, 2
	v_mfma_f32_16x16x32_bf16 v[60:63], v[132:135], v[174:177], v[60:63]
	s_add_u32 s45, s26, 0x80
	v_mfma_f32_16x16x32_bf16 v[56:59], v[140:143], v[174:177], v[56:59]
	s_addc_u32 s29, s27, 0
	v_mfma_f32_16x16x32_bf16 v[44:47], v[132:135], v[208:211], v[44:47]
	s_add_i32 s62, 0, 0x10000
	v_mfma_f32_16x16x32_bf16 v[40:43], v[140:143], v[208:211], v[40:43]
	s_cmp_eq_u32 s49, s28
	v_mfma_f32_16x16x32_bf16 v[28:31], v[132:135], v[220:223], v[28:31]
	s_cselect_b32 s29, s23, s29
	v_mfma_f32_16x16x32_bf16 v[24:27], v[140:143], v[220:223], v[24:27]
	s_cselect_b32 s28, s22, s45
	v_mfma_f32_16x16x32_bf16 v[12:15], v[132:135], v[228:231], v[12:15]
	s_cselect_b32 s61, s25, s11
	v_mfma_f32_16x16x32_bf16 v[8:11], v[140:143], v[228:231], v[8:11]
	s_cselect_b32 s60, s24, s10
	v_mfma_f32_16x16x32_bf16 v[52:55], v[144:147], v[170:173], v[52:55]
	s_add_i32 s45, 0, 0x14000
	v_mfma_f32_16x16x32_bf16 v[48:51], v[152:155], v[170:173], v[48:51]
	v_mfma_f32_16x16x32_bf16 v[36:39], v[144:147], v[194:197], v[36:39]
	v_mfma_f32_16x16x32_bf16 v[32:35], v[152:155], v[194:197], v[32:35]
	v_mfma_f32_16x16x32_bf16 v[20:23], v[144:147], v[212:215], v[20:23]
	v_mfma_f32_16x16x32_bf16 v[16:19], v[152:155], v[212:215], v[16:19]
	v_mfma_f32_16x16x32_bf16 v[4:7], v[144:147], v[224:227], v[4:7]
	v_mfma_f32_16x16x32_bf16 v[0:3], v[152:155], v[224:227], v[0:3]
	v_mfma_f32_16x16x32_bf16 v[52:55], v[148:151], v[174:177], v[52:55]
	v_mfma_f32_16x16x32_bf16 v[48:51], v[166:169], v[174:177], v[48:51]
	v_mfma_f32_16x16x32_bf16 v[36:39], v[148:151], v[208:211], v[36:39]
	v_mfma_f32_16x16x32_bf16 v[32:35], v[166:169], v[208:211], v[32:35]
	v_mfma_f32_16x16x32_bf16 v[20:23], v[148:151], v[220:223], v[20:23]
	v_mfma_f32_16x16x32_bf16 v[16:19], v[166:169], v[220:223], v[16:19]
	v_mfma_f32_16x16x32_bf16 v[4:7], v[148:151], v[228:231], v[4:7]
	v_mfma_f32_16x16x32_bf16 v[0:3], v[166:169], v[228:231], v[0:3]
	s_cmp_lg_u32 s98, 0
	s_cbranch_scc1 .Lskf_15_peel
	s_barrier

.LBB0_1224:
	v_add_u32_e32 v140, s62, v199
	v_add_u32_e32 v166, s45, v199
	ds_read_b128 v[128:131], v140
	ds_read_b128 v[132:135], v140 offset:1024
	ds_read_b128 v[136:139], v140 offset:2048
	ds_read_b128 v[140:143], v140 offset:3072
	ds_read_b128 v[144:147], v166
	ds_read_b128 v[148:151], v166 offset:1024
	ds_read_b128 v[152:155], v166 offset:2048
	ds_read_b128 v[166:169], v166 offset:3072
	v_lshl_add_u64 v[178:179], s[26:27], 0, v[162:163]
	s_add_i32 m0, s35, 0xc000
	ds_read_b128 v[170:173], v206
	ds_read_b128 v[174:177], v206 offset:1024
	ds_read_b128 v[194:197], v206 offset:2048
	ds_read_b128 v[208:211], v206 offset:3072
	ds_read_b128 v[212:215], v206 offset:4096
	ds_read_b128 v[220:223], v206 offset:5120
	ds_read_b128 v[224:227], v206 offset:6144
	ds_read_b128 v[228:231], v206 offset:7168
	global_load_lds_dwordx4 v[178:179], off
	v_lshl_add_u64 v[178:179], s[26:27], 0, v[164:165]
	s_add_i32 m0, s35, 0xe000
	s_nop 0
	global_load_lds_dwordx4 v[178:179], off
	s_waitcnt vmcnt(8)
	s_waitcnt lgkmcnt(0)
	s_barrier
	s_waitcnt lgkmcnt(0)
	v_mfma_f32_16x16x32_bf16 v[120:123], v[128:131], v[170:173], v[120:123]
	v_mfma_f32_16x16x32_bf16 v[124:127], v[136:139], v[170:173], v[124:127]
	v_mfma_f32_16x16x32_bf16 v[108:111], v[128:131], v[194:197], v[108:111]
	v_mfma_f32_16x16x32_bf16 v[104:107], v[136:139], v[194:197], v[104:107]
	v_mfma_f32_16x16x32_bf16 v[92:95], v[128:131], v[212:215], v[92:95]
	v_mfma_f32_16x16x32_bf16 v[88:91], v[136:139], v[212:215], v[88:91]
	v_mfma_f32_16x16x32_bf16 v[76:79], v[128:131], v[224:227], v[76:79]
	v_mfma_f32_16x16x32_bf16 v[72:75], v[136:139], v[224:227], v[72:75]
	v_mfma_f32_16x16x32_bf16 v[120:123], v[132:135], v[174:177], v[120:123]
	v_mfma_f32_16x16x32_bf16 v[124:127], v[140:143], v[174:177], v[124:127]
	v_mfma_f32_16x16x32_bf16 v[108:111], v[132:135], v[208:211], v[108:111]
	v_mfma_f32_16x16x32_bf16 v[104:107], v[140:143], v[208:211], v[104:107]
	v_mfma_f32_16x16x32_bf16 v[92:95], v[132:135], v[220:223], v[92:95]
	v_mfma_f32_16x16x32_bf16 v[88:91], v[140:143], v[220:223], v[88:91]
	v_mfma_f32_16x16x32_bf16 v[76:79], v[132:135], v[228:231], v[76:79]
	v_mfma_f32_16x16x32_bf16 v[72:75], v[140:143], v[228:231], v[72:75]
	v_mfma_f32_16x16x32_bf16 v[116:119], v[144:147], v[170:173], v[116:119]
	v_mfma_f32_16x16x32_bf16 v[112:115], v[152:155], v[170:173], v[112:115]
	v_mfma_f32_16x16x32_bf16 v[100:103], v[144:147], v[194:197], v[100:103]
	v_mfma_f32_16x16x32_bf16 v[96:99], v[152:155], v[194:197], v[96:99]
	v_mfma_f32_16x16x32_bf16 v[84:87], v[144:147], v[212:215], v[84:87]
	v_mfma_f32_16x16x32_bf16 v[80:83], v[152:155], v[212:215], v[80:83]
	v_mfma_f32_16x16x32_bf16 v[68:71], v[144:147], v[224:227], v[68:71]
	v_mfma_f32_16x16x32_bf16 v[64:67], v[152:155], v[224:227], v[64:67]
	v_mfma_f32_16x16x32_bf16 v[116:119], v[148:151], v[174:177], v[116:119]
	v_mfma_f32_16x16x32_bf16 v[112:115], v[166:169], v[174:177], v[112:115]
	v_mfma_f32_16x16x32_bf16 v[100:103], v[148:151], v[208:211], v[100:103]
	v_mfma_f32_16x16x32_bf16 v[96:99], v[166:169], v[208:211], v[96:99]
	v_mfma_f32_16x16x32_bf16 v[84:87], v[148:151], v[220:223], v[84:87]
	v_mfma_f32_16x16x32_bf16 v[80:83], v[166:169], v[220:223], v[80:83]
	v_mfma_f32_16x16x32_bf16 v[68:71], v[148:151], v[228:231], v[68:71]
	v_mfma_f32_16x16x32_bf16 v[64:67], v[166:169], v[228:231], v[64:67]
	s_barrier
	s_add_i32 s62, s62, s34
	v_lshl_add_u64 v[178:179], s[60:61], 0, v[180:181]
	s_mov_b32 m0, s62
	ds_read_b128 v[170:173], v206 offset:16384
	ds_read_b128 v[174:177], v206 offset:17408
	ds_read_b128 v[194:197], v206 offset:18432
	ds_read_b128 v[208:211], v206 offset:19456
	ds_read_b128 v[212:215], v206 offset:20480
	ds_read_b128 v[220:223], v206 offset:21504
	ds_read_b128 v[224:227], v206 offset:22528
	ds_read_b128 v[228:231], v206 offset:23552
	global_load_lds_dwordx4 v[178:179], off
	s_add_i32 m0, s62, 0x2000
	v_lshl_add_u64 v[202:203], s[60:61], 0, v[156:157]
	s_add_u32 s60, s60, s6
	s_addc_u32 s61, s61, s7
	s_add_i32 s45, s45, s34
	global_load_lds_dwordx4 v[202:203], off
	v_lshl_add_u64 v[216:217], s[60:61], 0, v[180:181]
	s_mov_b32 m0, s45
	v_lshl_add_u64 v[232:233], s[60:61], 0, v[156:157]
	global_load_lds_dwordx4 v[216:217], off
	s_add_i32 m0, s45, 0x2000
	v_lshl_add_u64 v[234:235], s[28:29], 0, v[160:161]
	global_load_lds_dwordx4 v[232:233], off
	s_mov_b32 m0, s35
	v_lshl_add_u64 v[236:237], s[28:29], 0, v[158:159]
	global_load_lds_dwordx4 v[234:235], off
	s_mov_b32 m0, s36
	s_nop 0
	global_load_lds_dwordx4 v[236:237], off
	s_waitcnt vmcnt(8)
	s_waitcnt lgkmcnt(0)
	s_barrier
	s_waitcnt lgkmcnt(0)
	v_mfma_f32_16x16x32_bf16 v[60:63], v[128:131], v[170:173], v[60:63]
	v_mfma_f32_16x16x32_bf16 v[56:59], v[136:139], v[170:173], v[56:59]
	v_mfma_f32_16x16x32_bf16 v[44:47], v[128:131], v[194:197], v[44:47]
	v_mfma_f32_16x16x32_bf16 v[40:43], v[136:139], v[194:197], v[40:43]
	v_mfma_f32_16x16x32_bf16 v[28:31], v[128:131], v[212:215], v[28:31]
	v_mfma_f32_16x16x32_bf16 v[24:27], v[136:139], v[212:215], v[24:27]
	v_mfma_f32_16x16x32_bf16 v[12:15], v[128:131], v[224:227], v[12:15]
	v_mfma_f32_16x16x32_bf16 v[8:11], v[136:139], v[224:227], v[8:11]
	v_mfma_f32_16x16x32_bf16 v[60:63], v[132:135], v[174:177], v[60:63]
	v_mfma_f32_16x16x32_bf16 v[56:59], v[140:143], v[174:177], v[56:59]
	v_mfma_f32_16x16x32_bf16 v[44:47], v[132:135], v[208:211], v[44:47]
	v_mfma_f32_16x16x32_bf16 v[40:43], v[140:143], v[208:211], v[40:43]
	v_mfma_f32_16x16x32_bf16 v[28:31], v[132:135], v[220:223], v[28:31]
	v_mfma_f32_16x16x32_bf16 v[24:27], v[140:143], v[220:223], v[24:27]
	v_mfma_f32_16x16x32_bf16 v[12:15], v[132:135], v[228:231], v[12:15]
	v_mfma_f32_16x16x32_bf16 v[8:11], v[140:143], v[228:231], v[8:11]
	v_mfma_f32_16x16x32_bf16 v[52:55], v[144:147], v[170:173], v[52:55]
	v_mfma_f32_16x16x32_bf16 v[48:51], v[152:155], v[170:173], v[48:51]
	v_mfma_f32_16x16x32_bf16 v[36:39], v[144:147], v[194:197], v[36:39]
	v_mfma_f32_16x16x32_bf16 v[32:35], v[152:155], v[194:197], v[32:35]
	v_mfma_f32_16x16x32_bf16 v[20:23], v[144:147], v[212:215], v[20:23]
	v_mfma_f32_16x16x32_bf16 v[16:19], v[152:155], v[212:215], v[16:19]
	v_mfma_f32_16x16x32_bf16 v[4:7], v[144:147], v[224:227], v[4:7]
	v_mfma_f32_16x16x32_bf16 v[0:3], v[152:155], v[224:227], v[0:3]
	v_mfma_f32_16x16x32_bf16 v[52:55], v[148:151], v[174:177], v[52:55]
	v_mfma_f32_16x16x32_bf16 v[48:51], v[166:169], v[174:177], v[48:51]
	v_mfma_f32_16x16x32_bf16 v[36:39], v[148:151], v[208:211], v[36:39]
	v_mfma_f32_16x16x32_bf16 v[32:35], v[166:169], v[208:211], v[32:35]
	v_mfma_f32_16x16x32_bf16 v[20:23], v[148:151], v[220:223], v[20:23]
	v_mfma_f32_16x16x32_bf16 v[16:19], v[166:169], v[220:223], v[16:19]
	v_mfma_f32_16x16x32_bf16 v[4:7], v[148:151], v[228:231], v[4:7]
	v_mfma_f32_16x16x32_bf16 v[0:3], v[166:169], v[228:231], v[0:3]
	s_barrier
	s_add_i32 s45, 0, 0x18000
	s_add_i32 s60, 0, 0x1c000
	v_add_u32_e32 v140, s45, v199
	v_add_u32_e32 v166, s60, v199
	ds_read_b128 v[128:131], v140
	ds_read_b128 v[132:135], v140 offset:1024
	ds_read_b128 v[136:139], v140 offset:2048
	ds_read_b128 v[140:143], v140 offset:3072
	ds_read_b128 v[144:147], v166
	ds_read_b128 v[148:151], v166 offset:1024
	ds_read_b128 v[152:155], v166 offset:2048
	ds_read_b128 v[166:169], v166 offset:3072
	s_add_u32 s28, s28, s6
	s_addc_u32 s29, s29, s7
	s_mov_b32 m0, s37
	v_lshl_add_u64 v[238:239], s[28:29], 0, v[160:161]
	ds_read_b128 v[170:173], v206 offset:32768
	ds_read_b128 v[174:177], v206 offset:33792
	ds_read_b128 v[194:197], v206 offset:34816
	ds_read_b128 v[208:211], v206 offset:35840
	ds_read_b128 v[212:215], v206 offset:36864
	ds_read_b128 v[220:223], v206 offset:37888
	ds_read_b128 v[224:227], v206 offset:38912
	ds_read_b128 v[228:231], v206 offset:39936
	global_load_lds_dwordx4 v[238:239], off
	v_lshl_add_u64 v[238:239], s[28:29], 0, v[158:159]
	s_mov_b32 m0, s38
	s_nop 0
	global_load_lds_dwordx4 v[238:239], off
	s_waitcnt vmcnt(8)
	s_waitcnt lgkmcnt(0)
	s_barrier
	s_waitcnt lgkmcnt(0)
	v_mfma_f32_16x16x32_bf16 v[120:123], v[128:131], v[170:173], v[120:123]
	v_mfma_f32_16x16x32_bf16 v[124:127], v[136:139], v[170:173], v[124:127]
	v_mfma_f32_16x16x32_bf16 v[108:111], v[128:131], v[194:197], v[108:111]
	v_mfma_f32_16x16x32_bf16 v[104:107], v[136:139], v[194:197], v[104:107]
	v_mfma_f32_16x16x32_bf16 v[92:95], v[128:131], v[212:215], v[92:95]
	v_mfma_f32_16x16x32_bf16 v[88:91], v[136:139], v[212:215], v[88:91]
	v_mfma_f32_16x16x32_bf16 v[76:79], v[128:131], v[224:227], v[76:79]
	v_mfma_f32_16x16x32_bf16 v[72:75], v[136:139], v[224:227], v[72:75]
	v_mfma_f32_16x16x32_bf16 v[120:123], v[132:135], v[174:177], v[120:123]
	v_mfma_f32_16x16x32_bf16 v[124:127], v[140:143], v[174:177], v[124:127]
	v_mfma_f32_16x16x32_bf16 v[108:111], v[132:135], v[208:211], v[108:111]
	v_mfma_f32_16x16x32_bf16 v[104:107], v[140:143], v[208:211], v[104:107]
	v_mfma_f32_16x16x32_bf16 v[92:95], v[132:135], v[220:223], v[92:95]
	v_mfma_f32_16x16x32_bf16 v[88:91], v[140:143], v[220:223], v[88:91]
	v_mfma_f32_16x16x32_bf16 v[76:79], v[132:135], v[228:231], v[76:79]
	v_mfma_f32_16x16x32_bf16 v[72:75], v[140:143], v[228:231], v[72:75]
	v_mfma_f32_16x16x32_bf16 v[116:119], v[144:147], v[170:173], v[116:119]
	v_mfma_f32_16x16x32_bf16 v[112:115], v[152:155], v[170:173], v[112:115]
	v_mfma_f32_16x16x32_bf16 v[100:103], v[144:147], v[194:197], v[100:103]
	v_mfma_f32_16x16x32_bf16 v[96:99], v[152:155], v[194:197], v[96:99]
	v_mfma_f32_16x16x32_bf16 v[84:87], v[144:147], v[212:215], v[84:87]
	v_mfma_f32_16x16x32_bf16 v[80:83], v[152:155], v[212:215], v[80:83]
	v_mfma_f32_16x16x32_bf16 v[68:71], v[144:147], v[224:227], v[68:71]
	v_mfma_f32_16x16x32_bf16 v[64:67], v[152:155], v[224:227], v[64:67]
	v_mfma_f32_16x16x32_bf16 v[116:119], v[148:151], v[174:177], v[116:119]
	v_mfma_f32_16x16x32_bf16 v[112:115], v[166:169], v[174:177], v[112:115]
	v_mfma_f32_16x16x32_bf16 v[100:103], v[148:151], v[208:211], v[100:103]
	v_mfma_f32_16x16x32_bf16 v[96:99], v[166:169], v[208:211], v[96:99]
	v_mfma_f32_16x16x32_bf16 v[84:87], v[148:151], v[220:223], v[84:87]
	v_mfma_f32_16x16x32_bf16 v[80:83], v[166:169], v[220:223], v[80:83]
	v_mfma_f32_16x16x32_bf16 v[68:71], v[148:151], v[228:231], v[68:71]
	v_mfma_f32_16x16x32_bf16 v[64:67], v[166:169], v[228:231], v[64:67]
	s_barrier
	s_add_i32 s28, s45, s34
	v_lshl_add_u64 v[178:179], v[178:179], 0, s[12:13]
	s_mov_b32 m0, s28
	ds_read_b128 v[170:173], v206 offset:49152
	ds_read_b128 v[174:177], v206 offset:50176
	ds_read_b128 v[194:197], v206 offset:51200
	ds_read_b128 v[208:211], v206 offset:52224
	ds_read_b128 v[212:215], v206 offset:53248
	ds_read_b128 v[220:223], v206 offset:54272
	ds_read_b128 v[224:227], v206 offset:55296
	ds_read_b128 v[228:231], v206 offset:56320
	global_load_lds_dwordx4 v[178:179], off
	v_lshl_add_u64 v[178:179], v[202:203], 0, s[12:13]
	s_add_i32 m0, s28, 0x2000
	s_add_i32 s28, s60, s34
	global_load_lds_dwordx4 v[178:179], off
	v_lshl_add_u64 v[178:179], v[216:217], 0, s[12:13]
	s_mov_b32 m0, s28
	s_nop 0
	global_load_lds_dwordx4 v[178:179], off
	v_lshl_add_u64 v[178:179], v[232:233], 0, s[12:13]
	s_add_i32 m0, s28, 0x2000
	s_nop 0
	global_load_lds_dwordx4 v[178:179], off
	v_lshl_add_u64 v[178:179], v[234:235], 0, s[12:13]
	s_mov_b32 m0, s47
	s_nop 0
	global_load_lds_dwordx4 v[178:179], off
	v_lshl_add_u64 v[178:179], v[236:237], 0, s[12:13]
	s_mov_b32 m0, s48
	s_nop 0
	global_load_lds_dwordx4 v[178:179], off
	s_waitcnt vmcnt(8)
	s_waitcnt lgkmcnt(0)
	s_barrier
	s_waitcnt lgkmcnt(0)
	v_mfma_f32_16x16x32_bf16 v[60:63], v[128:131], v[170:173], v[60:63]
	s_add_u32 s26, s26, 0x100
	v_mfma_f32_16x16x32_bf16 v[56:59], v[136:139], v[170:173], v[56:59]
	s_addc_u32 s27, s27, 0
	v_mfma_f32_16x16x32_bf16 v[44:47], v[128:131], v[194:197], v[44:47]
	s_add_u32 s10, s10, 0x100
	v_mfma_f32_16x16x32_bf16 v[40:43], v[136:139], v[194:197], v[40:43]
	s_addc_u32 s11, s11, 0
	v_mfma_f32_16x16x32_bf16 v[28:31], v[128:131], v[212:215], v[28:31]
	s_mov_b32 s28, s44
	v_mfma_f32_16x16x32_bf16 v[24:27], v[136:139], v[212:215], v[24:27]
	s_cmp_ge_i32 s44, s46
	v_mfma_f32_16x16x32_bf16 v[12:15], v[128:131], v[224:227], v[12:15]
	s_cselect_b32 s99, 1, 0
	v_readfirstlane_b32 s98, v218
	s_bfe_u32 s98, s98, 0x10008
	s_and_b32 s98, s98, s99
	v_mfma_f32_16x16x32_bf16 v[8:11], v[136:139], v[224:227], v[8:11]
	s_add_i32 s44, s28, 2
	v_mfma_f32_16x16x32_bf16 v[60:63], v[132:135], v[174:177], v[60:63]
	s_add_u32 s45, s26, 0x80
	v_mfma_f32_16x16x32_bf16 v[56:59], v[140:143], v[174:177], v[56:59]
	s_addc_u32 s29, s27, 0
	v_mfma_f32_16x16x32_bf16 v[44:47], v[132:135], v[208:211], v[44:47]
	s_add_i32 s62, 0, 0x10000
	v_mfma_f32_16x16x32_bf16 v[40:43], v[140:143], v[208:211], v[40:43]
	s_cmp_eq_u32 s49, s28
	v_mfma_f32_16x16x32_bf16 v[28:31], v[132:135], v[220:223], v[28:31]
	s_cselect_b32 s29, s23, s29
	v_mfma_f32_16x16x32_bf16 v[24:27], v[140:143], v[220:223], v[24:27]
	s_cselect_b32 s28, s22, s45
	v_mfma_f32_16x16x32_bf16 v[12:15], v[132:135], v[228:231], v[12:15]
	s_cselect_b32 s61, s25, s11
	v_mfma_f32_16x16x32_bf16 v[8:11], v[140:143], v[228:231], v[8:11]
	s_cselect_b32 s60, s24, s10
	v_mfma_f32_16x16x32_bf16 v[52:55], v[144:147], v[170:173], v[52:55]
	s_add_i32 s45, 0, 0x14000
	v_mfma_f32_16x16x32_bf16 v[48:51], v[152:155], v[170:173], v[48:51]
	v_mfma_f32_16x16x32_bf16 v[36:39], v[144:147], v[194:197], v[36:39]
	v_mfma_f32_16x16x32_bf16 v[32:35], v[152:155], v[194:197], v[32:35]
	v_mfma_f32_16x16x32_bf16 v[20:23], v[144:147], v[212:215], v[20:23]
	v_mfma_f32_16x16x32_bf16 v[16:19], v[152:155], v[212:215], v[16:19]
	v_mfma_f32_16x16x32_bf16 v[4:7], v[144:147], v[224:227], v[4:7]
	v_mfma_f32_16x16x32_bf16 v[0:3], v[152:155], v[224:227], v[0:3]
	v_mfma_f32_16x16x32_bf16 v[52:55], v[148:151], v[174:177], v[52:55]
	v_mfma_f32_16x16x32_bf16 v[48:51], v[166:169], v[174:177], v[48:51]
	v_mfma_f32_16x16x32_bf16 v[36:39], v[148:151], v[208:211], v[36:39]
	v_mfma_f32_16x16x32_bf16 v[32:35], v[166:169], v[208:211], v[32:35]
	v_mfma_f32_16x16x32_bf16 v[20:23], v[148:151], v[220:223], v[20:23]
	v_mfma_f32_16x16x32_bf16 v[16:19], v[166:169], v[220:223], v[16:19]
	v_mfma_f32_16x16x32_bf16 v[4:7], v[148:151], v[228:231], v[4:7]
	v_mfma_f32_16x16x32_bf16 v[0:3], v[166:169], v[228:231], v[0:3]
	s_cmp_lg_u32 s98, 0
	s_cbranch_scc1 .Lskf_15_loop
	s_barrier

.LBB0_1226:
	s_and_b64 vcc, exec, s[20:21]
	s_cbranch_vccz .LBB0_1228
	s_nop 0
